# k20 + in-proj gates epilogue: fbias fetched with s_load_dword instead of vector load + vmcnt(0) per value (32 drained round trips per gates tile removed)
# baseline (speedup 1.0000x reference)
.LBB0_556:
	s_and_saveexec_b64 s[4:5], s[10:11]
	s_xor_b64 s[16:17], exec, s[4:5]
	s_cbranch_execz .LBB0_574
	v_readlane_b32 s4, v254, 26
	v_readlane_b32 s5, v254, 27
	s_nop 4
	s_load_dword s4, s[4:5], 0x0
	s_waitcnt lgkmcnt(0)
	v_mov_b32_e32 v0, s4
	v_add_f32_e32 v0, v186, v0
	v_cmp_nlt_f32_e32 vcc, 0, v0
	s_and_saveexec_b64 s[4:5], vcc
	s_xor_b64 s[4:5], exec, s[4:5]
	s_cbranch_execz .LBB0_559
	v_mul_f32_e32 v186, 0x3fb8aa3b, v0
	v_exp_f32_e32 v186, v186
	s_mov_b32 s31, 0x3f2aaaab
	v_add_f32_e32 v192, 1.0, v186
	v_frexp_mant_f32_e32 v194, v192
	v_cvt_f64_f32_e32 v[190:191], v192
	v_frexp_exp_i32_f64_e32 v190, v[190:191]
	v_cmp_gt_f32_e32 vcc, s31, v194
	v_add_f32_e32 v193, -1.0, v192
	v_sub_f32_e32 v195, v193, v192
	v_subbrev_co_u32_e32 v202, vcc, 0, v190, vcc
	v_sub_u32_e32 v190, 0, v202
	v_sub_f32_e32 v193, v186, v193
	v_add_f32_e32 v195, 1.0, v195
	v_ldexp_f32 v191, v192, v190
	v_add_f32_e32 v193, v193, v195
	v_add_f32_e32 v192, -1.0, v191
	v_add_f32_e32 v194, 1.0, v191
	v_ldexp_f32 v190, v193, v190
	v_add_f32_e32 v193, 1.0, v192
	v_add_f32_e32 v195, -1.0, v194
	v_sub_f32_e32 v193, v191, v193
	v_sub_f32_e32 v191, v191, v195
	v_add_f32_e32 v193, v190, v193
	v_add_f32_e32 v190, v190, v191
	v_add_f32_e32 v203, v194, v190
	v_rcp_f32_e32 v228, v203
	v_sub_f32_e32 v191, v203, v194
	v_sub_f32_e32 v205, v190, v191
	v_add_f32_e32 v191, v192, v193
	v_mul_f32_e32 v230, v191, v228
	v_sub_f32_e32 v190, v191, v192
	v_mul_f32_e32 v192, v203, v230
	v_fma_f32 v194, v230, v203, -v192
	v_fmac_f32_e32 v194, v230, v205
	v_sub_f32_e32 v229, v193, v190
	v_add_f32_e32 v190, v192, v194
	v_sub_f32_e32 v193, v191, v190
	v_pk_add_f32 v[196:197], v[190:191], v[192:193] neg_lo:[0,1] neg_hi:[0,1]
	v_mov_b32_e32 v195, v190
	v_pk_add_f32 v[190:191], v[196:197], v[194:195] neg_lo:[0,1] neg_hi:[0,1]
	s_mov_b32 s31, 0x3f317218
	v_add_f32_e32 v191, v229, v191
	v_add_f32_e32 v190, v190, v191
	v_add_f32_e32 v191, v193, v190
	v_mul_f32_e32 v229, v228, v191
	v_mul_f32_e32 v192, v203, v229
	v_fma_f32 v194, v229, v203, -v192
	v_fmac_f32_e32 v194, v229, v205
	v_sub_f32_e32 v193, v193, v191
	v_add_f32_e32 v203, v190, v193
	v_add_f32_e32 v190, v192, v194
	v_sub_f32_e32 v193, v191, v190
	v_pk_add_f32 v[196:197], v[190:191], v[192:193] neg_lo:[0,1] neg_hi:[0,1]
	v_mov_b32_e32 v195, v190
	v_pk_add_f32 v[190:191], v[196:197], v[194:195] neg_lo:[0,1] neg_hi:[0,1]
	s_nop 0
	v_add_f32_e32 v191, v203, v191
	v_add_f32_e32 v190, v190, v191
	v_add_f32_e32 v191, v230, v229
	v_add_f32_e32 v190, v193, v190
	v_sub_f32_e32 v192, v191, v230
	v_mul_f32_e32 v190, v228, v190
	v_sub_f32_e32 v192, v229, v192
	v_add_f32_e32 v192, v192, v190
	v_add_f32_e32 v194, v191, v192
	v_mul_f32_e32 v195, v194, v194
	v_fmamk_f32 v190, v195, 0x3e9b6dac, v236
	v_fmaak_f32 v205, v195, v190, 0x3f2aaada
	v_cvt_f32_i32_e32 v190, v202
	v_sub_f32_e32 v191, v194, v191
	v_sub_f32_e32 v191, v192, v191
	v_ldexp_f32 v196, v191, 1
	v_mul_f32_e32 v191, v194, v195
	v_ldexp_f32 v193, v194, 1
	v_pk_mul_f32 v[194:195], v[190:191], v[204:205]
	s_nop 0
	v_fma_f32 v192, v190, s31, -v194
	v_fmac_f32_e32 v192, 0xb102e308, v190
	v_pk_add_f32 v[190:191], v[194:195], v[192:193]
	s_mov_b32 s31, 0x7f800000
	v_sub_f32_e32 v193, v191, v193
	v_sub_f32_e32 v193, v195, v193
	v_add_f32_e32 v197, v196, v193
	v_mov_b32_e32 v196, v194
	v_pk_add_f32 v[194:195], v[190:191], v[194:195] neg_lo:[0,1] neg_hi:[0,1]
	v_pk_add_f32 v[228:229], v[190:191], v[196:197]
	v_mov_b32_e32 v193, v190
	v_mov_b32_e32 v195, v229
	v_pk_add_f32 v[230:231], v[192:193], v[194:195] neg_lo:[0,1] neg_hi:[0,1]
	v_pk_add_f32 v[192:193], v[192:193], v[194:195]
	v_mov_b32_e32 v196, v197
	v_pk_add_f32 v[194:195], v[192:193], v[190:191] op_sel:[1,0] op_sel_hi:[0,1] neg_lo:[0,1] neg_hi:[0,1]
	v_pk_add_f32 v[232:233], v[228:229], v[194:195] op_sel_hi:[1,0] neg_lo:[0,1] neg_hi:[0,1]
	v_mov_b32_e32 v228, v229
	v_mov_b32_e32 v229, v193
	v_pk_mov_b32 v[194:195], v[190:191], v[194:195] op_sel:[1,0]
	v_mov_b32_e32 v197, v190
	v_pk_add_f32 v[194:195], v[228:229], v[194:195] neg_lo:[0,1] neg_hi:[0,1]
	v_mov_b32_e32 v232, v230
	v_pk_add_f32 v[190:191], v[196:197], v[194:195] neg_lo:[0,1] neg_hi:[0,1]
	v_mov_b32_e32 v231, v193
	v_pk_add_f32 v[194:195], v[232:233], v[190:191]
	v_cmp_neq_f32_e32 vcc, s31, v186
	v_pk_add_f32 v[196:197], v[194:195], v[194:195] op_sel:[0,1] op_sel_hi:[1,0]
	s_mov_b32 s31, 0x33800000
	v_pk_add_f32 v[192:193], v[192:193], v[196:197] op_sel:[1,0] op_sel_hi:[0,1]
	v_mov_b32_e32 v195, v192
	v_pk_add_f32 v[228:229], v[194:195], v[230:231] neg_lo:[0,1] neg_hi:[0,1]
	v_mov_b32_e32 v191, v196
	v_sub_f32_e32 v193, v194, v228
	v_pk_add_f32 v[190:191], v[190:191], v[228:229] neg_lo:[0,1] neg_hi:[0,1]
	v_sub_f32_e32 v193, v230, v193
	v_add_f32_e32 v190, v190, v193
	v_add_f32_e32 v190, v190, v191
	v_add_f32_e32 v190, v192, v190
	v_cndmask_b32_e32 v190, v237, v190, vcc
	v_cmp_ngt_f32_e32 vcc, -1.0, v186
	s_nop 1
	v_cndmask_b32_e32 v190, v238, v190, vcc
	v_cmp_neq_f32_e32 vcc, -1.0, v186
	s_nop 1
	v_cndmask_b32_e32 v190, v239, v190, vcc
	v_cmp_lt_f32_e64 vcc, |v186|, s31
	s_nop 1
	v_cndmask_b32_e32 v186, v190, v186, vcc
	v_sub_f32_e32 v186, v0, v186

.LBB0_561:
	s_or_b64 exec, exec, s[4:5]
	v_lshlrev_b32_e32 v192, 2, v252
	v_lshlrev_b32_e32 v0, 2, v225
	v_ashrrev_i32_e32 v193, 31, v192
	v_lshl_add_u64 v[190:191], s[84:85], 0, v[0:1]
	v_lshlrev_b64 v[194:195], 13, v[192:193]
	v_lshl_add_u64 v[194:195], v[190:191], 0, v[194:195]
	v_readlane_b32 s4, v254, 26
	global_store_dword v[194:195], v186, off
	v_readlane_b32 s5, v254, 27
	s_nop 4
	s_load_dword s4, s[4:5], 0x4
	s_waitcnt lgkmcnt(0)
	v_mov_b32_e32 v0, s4
	v_add_f32_e32 v0, v187, v0
	v_cmp_nlt_f32_e32 vcc, 0, v0
	s_and_saveexec_b64 s[4:5], vcc
	s_xor_b64 s[4:5], exec, s[4:5]
	s_cbranch_execz .LBB0_563
	v_mul_f32_e32 v186, 0x3fb8aa3b, v0
	v_exp_f32_e32 v193, v186
	s_mov_b32 s31, 0x3f2aaaab
	v_add_f32_e32 v194, 1.0, v193
	v_frexp_mant_f32_e32 v196, v194
	v_cvt_f64_f32_e32 v[186:187], v194
	v_frexp_exp_i32_f64_e32 v186, v[186:187]
	v_cmp_gt_f32_e32 vcc, s31, v196
	v_add_f32_e32 v195, -1.0, v194
	v_sub_f32_e32 v197, v195, v194
	v_subbrev_co_u32_e32 v202, vcc, 0, v186, vcc
	v_sub_u32_e32 v186, 0, v202
	v_sub_f32_e32 v195, v193, v195
	v_add_f32_e32 v197, 1.0, v197
	v_ldexp_f32 v187, v194, v186
	v_add_f32_e32 v195, v195, v197
	v_add_f32_e32 v194, -1.0, v187
	v_add_f32_e32 v196, 1.0, v187
	v_ldexp_f32 v186, v195, v186
	v_add_f32_e32 v195, 1.0, v194
	v_add_f32_e32 v197, -1.0, v196
	v_sub_f32_e32 v195, v187, v195
	v_sub_f32_e32 v187, v187, v197
	v_add_f32_e32 v195, v186, v195
	v_add_f32_e32 v186, v186, v187
	v_add_f32_e32 v203, v196, v186
	v_rcp_f32_e32 v225, v203
	v_sub_f32_e32 v187, v203, v196
	v_sub_f32_e32 v205, v186, v187
	v_add_f32_e32 v187, v194, v195
	v_mul_f32_e32 v231, v187, v225
	v_sub_f32_e32 v186, v187, v194
	v_mul_f32_e32 v194, v203, v231
	v_fma_f32 v196, v231, v203, -v194
	v_fmac_f32_e32 v196, v231, v205
	v_sub_f32_e32 v230, v195, v186
	v_add_f32_e32 v186, v194, v196
	v_sub_f32_e32 v195, v187, v186
	v_pk_add_f32 v[228:229], v[186:187], v[194:195] neg_lo:[0,1] neg_hi:[0,1]
	v_mov_b32_e32 v197, v186
	v_pk_add_f32 v[186:187], v[228:229], v[196:197] neg_lo:[0,1] neg_hi:[0,1]
	s_mov_b32 s31, 0x3f317218
	v_add_f32_e32 v187, v230, v187
	v_add_f32_e32 v186, v186, v187
	v_add_f32_e32 v187, v195, v186
	v_mul_f32_e32 v230, v225, v187
	v_mul_f32_e32 v194, v203, v230
	v_fma_f32 v196, v230, v203, -v194
	v_fmac_f32_e32 v196, v230, v205
	v_sub_f32_e32 v195, v195, v187
	v_add_f32_e32 v203, v186, v195
	v_add_f32_e32 v186, v194, v196
	v_sub_f32_e32 v195, v187, v186
	v_pk_add_f32 v[228:229], v[186:187], v[194:195] neg_lo:[0,1] neg_hi:[0,1]
	v_mov_b32_e32 v197, v186
	v_pk_add_f32 v[186:187], v[228:229], v[196:197] neg_lo:[0,1] neg_hi:[0,1]
	s_nop 0
	v_add_f32_e32 v187, v203, v187
	v_add_f32_e32 v186, v186, v187
	v_add_f32_e32 v187, v231, v230
	v_add_f32_e32 v186, v195, v186
	v_sub_f32_e32 v194, v187, v231
	v_mul_f32_e32 v186, v225, v186
	v_sub_f32_e32 v194, v230, v194
	v_add_f32_e32 v194, v194, v186
	v_add_f32_e32 v196, v187, v194
	v_mul_f32_e32 v197, v196, v196
	v_fmamk_f32 v186, v197, 0x3e9b6dac, v236
	v_fmaak_f32 v205, v197, v186, 0x3f2aaada
	v_cvt_f32_i32_e32 v186, v202
	v_sub_f32_e32 v187, v196, v187
	v_sub_f32_e32 v187, v194, v187
	v_ldexp_f32 v202, v187, 1
	v_mul_f32_e32 v187, v196, v197
	v_ldexp_f32 v195, v196, 1
	v_pk_mul_f32 v[196:197], v[186:187], v[204:205]
	s_nop 0
	v_fma_f32 v194, v186, s31, -v196
	v_fmac_f32_e32 v194, 0xb102e308, v186
	v_pk_add_f32 v[186:187], v[196:197], v[194:195]
	v_mov_b32_e32 v228, v196
	v_sub_f32_e32 v195, v187, v195
	v_sub_f32_e32 v195, v197, v195
	v_add_f32_e32 v229, v202, v195
	v_pk_add_f32 v[196:197], v[186:187], v[196:197] neg_lo:[0,1] neg_hi:[0,1]
	v_pk_add_f32 v[230:231], v[186:187], v[228:229]
	v_mov_b32_e32 v195, v186
	v_mov_b32_e32 v197, v231
	v_pk_add_f32 v[232:233], v[194:195], v[196:197] neg_lo:[0,1] neg_hi:[0,1]
	v_pk_add_f32 v[194:195], v[194:195], v[196:197]
	v_mov_b32_e32 v228, v229
	v_pk_add_f32 v[196:197], v[194:195], v[186:187] op_sel:[1,0] op_sel_hi:[0,1] neg_lo:[0,1] neg_hi:[0,1]
	v_pk_add_f32 v[202:203], v[230:231], v[196:197] op_sel_hi:[1,0] neg_lo:[0,1] neg_hi:[0,1]
	v_mov_b32_e32 v230, v231
	v_mov_b32_e32 v231, v195
	v_pk_mov_b32 v[196:197], v[186:187], v[196:197] op_sel:[1,0]
	v_mov_b32_e32 v229, v186
	v_pk_add_f32 v[196:197], v[230:231], v[196:197] neg_lo:[0,1] neg_hi:[0,1]
	v_mov_b32_e32 v202, v232
	v_pk_add_f32 v[186:187], v[228:229], v[196:197] neg_lo:[0,1] neg_hi:[0,1]
	v_mov_b32_e32 v233, v195
	v_pk_add_f32 v[196:197], v[202:203], v[186:187]
	s_mov_b32 s31, 0x7f800000
	v_pk_add_f32 v[202:203], v[196:197], v[196:197] op_sel:[0,1] op_sel_hi:[1,0]
	v_cmp_neq_f32_e32 vcc, s31, v193
	v_pk_add_f32 v[194:195], v[194:195], v[202:203] op_sel:[1,0] op_sel_hi:[0,1]
	v_mov_b32_e32 v197, v194
	v_pk_add_f32 v[228:229], v[196:197], v[232:233] neg_lo:[0,1] neg_hi:[0,1]
	v_mov_b32_e32 v187, v202
	v_sub_f32_e32 v195, v196, v228
	v_pk_add_f32 v[186:187], v[186:187], v[228:229] neg_lo:[0,1] neg_hi:[0,1]
	v_sub_f32_e32 v195, v232, v195
	v_add_f32_e32 v186, v186, v195
	v_add_f32_e32 v186, v186, v187
	v_add_f32_e32 v186, v194, v186
	v_cndmask_b32_e32 v186, v237, v186, vcc
	v_cmp_ngt_f32_e32 vcc, -1.0, v193
	s_mov_b32 s31, 0x33800000
	s_nop 0
	v_cndmask_b32_e32 v186, v238, v186, vcc
	v_cmp_neq_f32_e32 vcc, -1.0, v193
	s_nop 1
	v_cndmask_b32_e32 v186, v239, v186, vcc
	v_cmp_lt_f32_e64 vcc, |v193|, s31
	s_nop 1
	v_cndmask_b32_e32 v186, v186, v193, vcc
	v_sub_f32_e32 v186, v0, v186

.LBB0_565:
	s_or_b64 exec, exec, s[4:5]
	v_or_b32_e32 v194, 1, v192
	v_ashrrev_i32_e32 v195, 31, v194
	v_lshlrev_b64 v[194:195], 13, v[194:195]
	v_lshl_add_u64 v[194:195], v[190:191], 0, v[194:195]
	v_readlane_b32 s4, v254, 26
	global_store_dword v[194:195], v186, off
	v_readlane_b32 s5, v254, 27
	s_nop 4
	s_load_dword s4, s[4:5], 0x8
	s_waitcnt lgkmcnt(0)
	v_mov_b32_e32 v0, s4
	v_add_f32_e32 v0, v188, v0
	v_cmp_nlt_f32_e32 vcc, 0, v0
	s_and_saveexec_b64 s[4:5], vcc
	s_xor_b64 s[4:5], exec, s[4:5]
	s_cbranch_execz .LBB0_567
	v_mul_f32_e32 v186, 0x3fb8aa3b, v0
	v_exp_f32_e32 v188, v186
	s_mov_b32 s31, 0x3f2aaaab
	v_add_f32_e32 v193, 1.0, v188
	v_frexp_mant_f32_e32 v195, v193
	v_cvt_f64_f32_e32 v[186:187], v193
	v_frexp_exp_i32_f64_e32 v186, v[186:187]
	v_cmp_gt_f32_e32 vcc, s31, v195
	v_add_f32_e32 v194, -1.0, v193
	v_sub_f32_e32 v196, v194, v193
	v_subbrev_co_u32_e32 v225, vcc, 0, v186, vcc
	v_sub_u32_e32 v186, 0, v225
	v_sub_f32_e32 v194, v188, v194
	v_add_f32_e32 v196, 1.0, v196
	v_ldexp_f32 v187, v193, v186
	v_add_f32_e32 v194, v194, v196
	v_add_f32_e32 v193, -1.0, v187
	v_add_f32_e32 v195, 1.0, v187
	v_ldexp_f32 v186, v194, v186
	v_add_f32_e32 v194, 1.0, v193
	v_add_f32_e32 v196, -1.0, v195
	v_sub_f32_e32 v194, v187, v194
	v_sub_f32_e32 v187, v187, v196
	v_add_f32_e32 v194, v186, v194
	v_add_f32_e32 v186, v186, v187
	v_add_f32_e32 v205, v195, v186
	v_rcp_f32_e32 v229, v205
	v_sub_f32_e32 v187, v205, v195
	v_sub_f32_e32 v228, v186, v187
	v_add_f32_e32 v187, v193, v194
	v_sub_f32_e32 v186, v187, v193
	v_mul_f32_e32 v230, v187, v229
	v_sub_f32_e32 v193, v194, v186
	v_mul_f32_e32 v194, v205, v230
	v_fma_f32 v196, v230, v205, -v194
	v_fmac_f32_e32 v196, v230, v228
	v_add_f32_e32 v186, v194, v196
	v_sub_f32_e32 v195, v187, v186
	v_pk_add_f32 v[202:203], v[186:187], v[194:195] neg_lo:[0,1] neg_hi:[0,1]
	v_mov_b32_e32 v197, v186
	v_pk_add_f32 v[186:187], v[202:203], v[196:197] neg_lo:[0,1] neg_hi:[0,1]
	s_mov_b32 s31, 0x3f317218
	v_add_f32_e32 v187, v193, v187
	v_add_f32_e32 v186, v186, v187
	v_add_f32_e32 v187, v195, v186
	v_mul_f32_e32 v193, v229, v187
	v_mul_f32_e32 v194, v205, v193
	v_fma_f32 v196, v193, v205, -v194
	v_fmac_f32_e32 v196, v193, v228
	v_sub_f32_e32 v195, v195, v187
	v_add_f32_e32 v205, v186, v195
	v_add_f32_e32 v186, v194, v196
	v_sub_f32_e32 v195, v187, v186
	v_pk_add_f32 v[202:203], v[186:187], v[194:195] neg_lo:[0,1] neg_hi:[0,1]
	v_mov_b32_e32 v197, v186
	v_pk_add_f32 v[186:187], v[202:203], v[196:197] neg_lo:[0,1] neg_hi:[0,1]
	s_nop 0
	v_add_f32_e32 v187, v205, v187
	v_add_f32_e32 v186, v186, v187
	v_add_f32_e32 v187, v230, v193
	v_add_f32_e32 v186, v195, v186
	v_sub_f32_e32 v194, v187, v230
	v_mul_f32_e32 v186, v229, v186
	v_sub_f32_e32 v193, v193, v194
	v_add_f32_e32 v193, v193, v186
	v_add_f32_e32 v194, v187, v193
	v_mul_f32_e32 v196, v194, v194
	v_fmamk_f32 v186, v196, 0x3e9b6dac, v236
	v_fmaak_f32 v205, v196, v186, 0x3f2aaada
	v_cvt_f32_i32_e32 v186, v225
	v_sub_f32_e32 v187, v194, v187
	v_sub_f32_e32 v187, v193, v187
	v_ldexp_f32 v193, v187, 1
	v_mul_f32_e32 v187, v194, v196
	v_pk_mul_f32 v[196:197], v[186:187], v[204:205]
	v_ldexp_f32 v195, v194, 1
	v_fma_f32 v194, v186, s31, -v196
	v_fmac_f32_e32 v194, 0xb102e308, v186
	v_pk_add_f32 v[186:187], v[196:197], v[194:195]
	v_mov_b32_e32 v202, v196
	v_sub_f32_e32 v195, v187, v195
	v_sub_f32_e32 v195, v197, v195
	v_add_f32_e32 v203, v193, v195
	v_pk_add_f32 v[196:197], v[186:187], v[196:197] neg_lo:[0,1] neg_hi:[0,1]
	v_pk_add_f32 v[228:229], v[186:187], v[202:203]
	v_mov_b32_e32 v195, v186
	v_mov_b32_e32 v197, v229
	v_pk_add_f32 v[230:231], v[194:195], v[196:197] neg_lo:[0,1] neg_hi:[0,1]
	v_pk_add_f32 v[194:195], v[194:195], v[196:197]
	v_mov_b32_e32 v202, v203
	v_pk_add_f32 v[196:197], v[194:195], v[186:187] op_sel:[1,0] op_sel_hi:[0,1] neg_lo:[0,1] neg_hi:[0,1]
	v_pk_add_f32 v[232:233], v[228:229], v[196:197] op_sel_hi:[1,0] neg_lo:[0,1] neg_hi:[0,1]
	v_mov_b32_e32 v228, v229
	v_mov_b32_e32 v229, v195
	v_pk_mov_b32 v[196:197], v[186:187], v[196:197] op_sel:[1,0]
	v_mov_b32_e32 v203, v186
	v_pk_add_f32 v[196:197], v[228:229], v[196:197] neg_lo:[0,1] neg_hi:[0,1]
	v_mov_b32_e32 v232, v230
	v_pk_add_f32 v[186:187], v[202:203], v[196:197] neg_lo:[0,1] neg_hi:[0,1]
	v_mov_b32_e32 v231, v195
	v_pk_add_f32 v[196:197], v[232:233], v[186:187]
	s_mov_b32 s31, 0x7f800000
	v_pk_add_f32 v[202:203], v[196:197], v[196:197] op_sel:[0,1] op_sel_hi:[1,0]
	v_cmp_neq_f32_e32 vcc, s31, v188
	v_pk_add_f32 v[194:195], v[194:195], v[202:203] op_sel:[1,0] op_sel_hi:[0,1]
	v_mov_b32_e32 v197, v194
	v_pk_add_f32 v[228:229], v[196:197], v[230:231] neg_lo:[0,1] neg_hi:[0,1]
	v_mov_b32_e32 v187, v202
	v_sub_f32_e32 v193, v196, v228
	v_pk_add_f32 v[186:187], v[186:187], v[228:229] neg_lo:[0,1] neg_hi:[0,1]
	v_sub_f32_e32 v193, v230, v193
	v_add_f32_e32 v186, v186, v193
	v_add_f32_e32 v186, v186, v187
	v_add_f32_e32 v186, v194, v186
	v_cndmask_b32_e32 v186, v237, v186, vcc
	v_cmp_ngt_f32_e32 vcc, -1.0, v188
	s_mov_b32 s31, 0x33800000
	s_nop 0
	v_cndmask_b32_e32 v186, v238, v186, vcc
	v_cmp_neq_f32_e32 vcc, -1.0, v188
	s_nop 1
	v_cndmask_b32_e32 v186, v239, v186, vcc
	v_cmp_lt_f32_e64 vcc, |v188|, s31
	s_nop 1
	v_cndmask_b32_e32 v186, v186, v188, vcc
	v_sub_f32_e32 v186, v0, v186

.LBB0_569:
	s_or_b64 exec, exec, s[4:5]
	v_or_b32_e32 v194, 2, v192
	v_ashrrev_i32_e32 v195, 31, v194
	v_lshlrev_b64 v[194:195], 13, v[194:195]
	v_lshl_add_u64 v[194:195], v[190:191], 0, v[194:195]
	v_readlane_b32 s4, v254, 26
	global_store_dword v[194:195], v186, off
	v_readlane_b32 s5, v254, 27
	s_nop 4
	s_load_dword s4, s[4:5], 0xc
	s_waitcnt lgkmcnt(0)
	v_mov_b32_e32 v0, s4
	v_add_f32_e32 v0, v189, v0
	v_cmp_nlt_f32_e32 vcc, 0, v0
	s_and_saveexec_b64 s[4:5], vcc
	s_xor_b64 s[4:5], exec, s[4:5]
	s_cbranch_execz .LBB0_571
	v_mul_f32_e32 v186, 0x3fb8aa3b, v0
	v_exp_f32_e32 v193, v186
	s_mov_b32 s31, 0x3f2aaaab
	v_add_f32_e32 v188, 1.0, v193
	v_frexp_mant_f32_e32 v194, v188
	v_cvt_f64_f32_e32 v[186:187], v188
	v_frexp_exp_i32_f64_e32 v186, v[186:187]
	v_cmp_gt_f32_e32 vcc, s31, v194
	v_add_f32_e32 v189, -1.0, v188
	v_sub_f32_e32 v195, v189, v188
	v_subbrev_co_u32_e32 v202, vcc, 0, v186, vcc
	v_sub_u32_e32 v186, 0, v202
	v_sub_f32_e32 v189, v193, v189
	v_add_f32_e32 v195, 1.0, v195
	v_ldexp_f32 v187, v188, v186
	v_add_f32_e32 v189, v189, v195
	v_add_f32_e32 v188, -1.0, v187
	v_add_f32_e32 v194, 1.0, v187
	v_ldexp_f32 v186, v189, v186
	v_add_f32_e32 v189, 1.0, v188
	v_add_f32_e32 v195, -1.0, v194
	v_sub_f32_e32 v189, v187, v189
	v_sub_f32_e32 v187, v187, v195
	v_add_f32_e32 v189, v186, v189
	v_add_f32_e32 v186, v186, v187
	v_add_f32_e32 v203, v194, v186
	v_rcp_f32_e32 v225, v203
	v_sub_f32_e32 v187, v203, v194
	v_sub_f32_e32 v205, v186, v187
	v_add_f32_e32 v187, v188, v189
	v_mul_f32_e32 v229, v187, v225
	v_sub_f32_e32 v186, v187, v188
	v_mul_f32_e32 v188, v203, v229
	v_fma_f32 v194, v229, v203, -v188
	v_fmac_f32_e32 v194, v229, v205
	v_sub_f32_e32 v228, v189, v186
	v_add_f32_e32 v186, v188, v194
	v_sub_f32_e32 v189, v187, v186
	v_pk_add_f32 v[196:197], v[186:187], v[188:189] neg_lo:[0,1] neg_hi:[0,1]
	v_mov_b32_e32 v195, v186
	v_pk_add_f32 v[186:187], v[196:197], v[194:195] neg_lo:[0,1] neg_hi:[0,1]
	s_mov_b32 s31, 0x3f317218
	v_add_f32_e32 v187, v228, v187
	v_add_f32_e32 v186, v186, v187
	v_add_f32_e32 v187, v189, v186
	v_mul_f32_e32 v228, v225, v187
	v_mul_f32_e32 v188, v203, v228
	v_fma_f32 v194, v228, v203, -v188
	v_fmac_f32_e32 v194, v228, v205
	v_sub_f32_e32 v189, v189, v187
	v_add_f32_e32 v203, v186, v189
	v_add_f32_e32 v186, v188, v194
	v_sub_f32_e32 v189, v187, v186
	v_pk_add_f32 v[196:197], v[186:187], v[188:189] neg_lo:[0,1] neg_hi:[0,1]
	v_mov_b32_e32 v195, v186
	v_pk_add_f32 v[186:187], v[196:197], v[194:195] neg_lo:[0,1] neg_hi:[0,1]
	s_nop 0
	v_add_f32_e32 v187, v203, v187
	v_add_f32_e32 v186, v186, v187
	v_add_f32_e32 v187, v229, v228
	v_add_f32_e32 v186, v189, v186
	v_sub_f32_e32 v188, v187, v229
	v_mul_f32_e32 v186, v225, v186
	v_sub_f32_e32 v188, v228, v188
	v_add_f32_e32 v188, v188, v186
	v_add_f32_e32 v194, v187, v188
	v_mul_f32_e32 v195, v194, v194
	v_fmamk_f32 v186, v195, 0x3e9b6dac, v236
	v_fmaak_f32 v205, v195, v186, 0x3f2aaada
	v_cvt_f32_i32_e32 v186, v202
	v_sub_f32_e32 v187, v194, v187
	v_sub_f32_e32 v187, v188, v187
	v_ldexp_f32 v196, v187, 1
	v_mul_f32_e32 v187, v194, v195
	v_ldexp_f32 v189, v194, 1
	v_pk_mul_f32 v[194:195], v[186:187], v[204:205]
	s_nop 0
	v_fma_f32 v188, v186, s31, -v194
	v_fmac_f32_e32 v188, 0xb102e308, v186
	v_pk_add_f32 v[186:187], v[194:195], v[188:189]
	s_mov_b32 s31, 0x7f800000
	v_sub_f32_e32 v189, v187, v189
	v_sub_f32_e32 v189, v195, v189
	v_add_f32_e32 v197, v196, v189
	v_mov_b32_e32 v196, v194
	v_pk_add_f32 v[194:195], v[186:187], v[194:195] neg_lo:[0,1] neg_hi:[0,1]
	v_pk_add_f32 v[202:203], v[186:187], v[196:197]
	v_mov_b32_e32 v189, v186
	v_mov_b32_e32 v195, v203
	v_pk_add_f32 v[228:229], v[188:189], v[194:195] neg_lo:[0,1] neg_hi:[0,1]
	v_pk_add_f32 v[188:189], v[188:189], v[194:195]
	v_mov_b32_e32 v196, v197
	v_pk_add_f32 v[194:195], v[188:189], v[186:187] op_sel:[1,0] op_sel_hi:[0,1] neg_lo:[0,1] neg_hi:[0,1]
	v_pk_add_f32 v[230:231], v[202:203], v[194:195] op_sel_hi:[1,0] neg_lo:[0,1] neg_hi:[0,1]
	v_mov_b32_e32 v202, v203
	v_mov_b32_e32 v203, v189
	v_pk_mov_b32 v[194:195], v[186:187], v[194:195] op_sel:[1,0]
	v_mov_b32_e32 v197, v186
	v_pk_add_f32 v[194:195], v[202:203], v[194:195] neg_lo:[0,1] neg_hi:[0,1]
	v_mov_b32_e32 v230, v228
	v_pk_add_f32 v[186:187], v[196:197], v[194:195] neg_lo:[0,1] neg_hi:[0,1]
	v_mov_b32_e32 v229, v189
	v_pk_add_f32 v[194:195], v[230:231], v[186:187]
	v_cmp_neq_f32_e32 vcc, s31, v193
	v_pk_add_f32 v[196:197], v[194:195], v[194:195] op_sel:[0,1] op_sel_hi:[1,0]
	s_mov_b32 s31, 0x33800000
	v_pk_add_f32 v[188:189], v[188:189], v[196:197] op_sel:[1,0] op_sel_hi:[0,1]
	v_mov_b32_e32 v195, v188
	v_pk_add_f32 v[202:203], v[194:195], v[228:229] neg_lo:[0,1] neg_hi:[0,1]
	v_mov_b32_e32 v187, v196
	v_sub_f32_e32 v189, v194, v202
	v_pk_add_f32 v[186:187], v[186:187], v[202:203] neg_lo:[0,1] neg_hi:[0,1]
	v_sub_f32_e32 v189, v228, v189
	v_add_f32_e32 v186, v186, v189
	v_add_f32_e32 v186, v186, v187
	v_add_f32_e32 v186, v188, v186
	v_cndmask_b32_e32 v186, v237, v186, vcc
	v_cmp_ngt_f32_e32 vcc, -1.0, v193
	s_nop 1
	v_cndmask_b32_e32 v186, v238, v186, vcc
	v_cmp_neq_f32_e32 vcc, -1.0, v193
	s_nop 1
	v_cndmask_b32_e32 v186, v239, v186, vcc
	v_cmp_lt_f32_e64 vcc, |v193|, s31
	s_nop 1
	v_cndmask_b32_e32 v186, v186, v193, vcc
	v_sub_f32_e32 v186, v0, v186

.LBB0_596:
	s_and_saveexec_b64 s[4:5], s[10:11]
	s_xor_b64 s[72:73], exec, s[4:5]
	s_cbranch_execz .LBB0_614
	v_readlane_b32 s4, v254, 26
	v_readlane_b32 s5, v254, 27
	s_nop 4
	s_load_dword s4, s[4:5], 0x0
	s_waitcnt lgkmcnt(0)
	v_mov_b32_e32 v0, s4
	v_add_f32_e32 v0, v178, v0
	v_cmp_nlt_f32_e32 vcc, 0, v0
	s_and_saveexec_b64 s[4:5], vcc
	s_xor_b64 s[4:5], exec, s[4:5]
	s_cbranch_execz .LBB0_599
	v_mul_f32_e32 v178, 0x3fb8aa3b, v0
	v_exp_f32_e32 v178, v178
	s_mov_b32 s31, 0x3f2aaaab
	v_add_f32_e32 v184, 1.0, v178
	v_frexp_mant_f32_e32 v186, v184
	v_cvt_f64_f32_e32 v[182:183], v184
	v_frexp_exp_i32_f64_e32 v182, v[182:183]
	v_cmp_gt_f32_e32 vcc, s31, v186
	v_add_f32_e32 v185, -1.0, v184
	v_sub_f32_e32 v187, v185, v184
	v_subbrev_co_u32_e32 v190, vcc, 0, v182, vcc
	v_sub_u32_e32 v182, 0, v190
	v_sub_f32_e32 v185, v178, v185
	v_add_f32_e32 v187, 1.0, v187
	v_ldexp_f32 v183, v184, v182
	v_add_f32_e32 v185, v185, v187
	v_add_f32_e32 v184, -1.0, v183
	v_add_f32_e32 v186, 1.0, v183
	v_ldexp_f32 v182, v185, v182
	v_add_f32_e32 v185, 1.0, v184
	v_add_f32_e32 v187, -1.0, v186
	v_sub_f32_e32 v185, v183, v185
	v_sub_f32_e32 v183, v183, v187
	v_add_f32_e32 v185, v182, v185
	v_add_f32_e32 v182, v182, v183
	v_add_f32_e32 v191, v186, v182
	v_rcp_f32_e32 v193, v191
	v_sub_f32_e32 v183, v191, v186
	v_sub_f32_e32 v192, v182, v183
	v_add_f32_e32 v183, v184, v185
	v_mul_f32_e32 v195, v183, v193
	v_sub_f32_e32 v182, v183, v184
	v_mul_f32_e32 v184, v191, v195
	v_fma_f32 v186, v195, v191, -v184
	v_fmac_f32_e32 v186, v195, v192
	v_sub_f32_e32 v194, v185, v182
	v_add_f32_e32 v182, v184, v186
	v_sub_f32_e32 v185, v183, v182
	v_pk_add_f32 v[188:189], v[182:183], v[184:185] neg_lo:[0,1] neg_hi:[0,1]
	v_mov_b32_e32 v187, v182
	v_pk_add_f32 v[182:183], v[188:189], v[186:187] neg_lo:[0,1] neg_hi:[0,1]
	s_mov_b32 s31, 0x3f317218
	v_add_f32_e32 v183, v194, v183
	v_add_f32_e32 v182, v182, v183
	v_add_f32_e32 v183, v185, v182
	v_mul_f32_e32 v194, v193, v183
	v_mul_f32_e32 v184, v191, v194
	v_fma_f32 v186, v194, v191, -v184
	v_fmac_f32_e32 v186, v194, v192
	v_sub_f32_e32 v185, v185, v183
	v_add_f32_e32 v191, v182, v185
	v_add_f32_e32 v182, v184, v186
	v_sub_f32_e32 v185, v183, v182
	v_pk_add_f32 v[188:189], v[182:183], v[184:185] neg_lo:[0,1] neg_hi:[0,1]
	v_mov_b32_e32 v187, v182
	v_pk_add_f32 v[182:183], v[188:189], v[186:187] neg_lo:[0,1] neg_hi:[0,1]
	s_nop 0
	v_add_f32_e32 v183, v191, v183
	v_add_f32_e32 v182, v182, v183
	v_add_f32_e32 v183, v195, v194
	v_add_f32_e32 v182, v185, v182
	v_sub_f32_e32 v184, v183, v195
	v_mul_f32_e32 v182, v193, v182
	v_sub_f32_e32 v184, v194, v184
	v_add_f32_e32 v184, v184, v182
	v_add_f32_e32 v186, v183, v184
	v_mul_f32_e32 v187, v186, v186
	v_fmamk_f32 v182, v187, 0x3e9b6dac, v236
	v_fmaak_f32 v205, v187, v182, 0x3f2aaada
	v_cvt_f32_i32_e32 v182, v190
	v_sub_f32_e32 v183, v186, v183
	v_sub_f32_e32 v183, v184, v183
	v_ldexp_f32 v188, v183, 1
	v_mul_f32_e32 v183, v186, v187
	v_ldexp_f32 v185, v186, 1
	v_pk_mul_f32 v[186:187], v[182:183], v[204:205]
	s_nop 0
	v_fma_f32 v184, v182, s31, -v186
	v_fmac_f32_e32 v184, 0xb102e308, v182
	v_pk_add_f32 v[182:183], v[186:187], v[184:185]
	s_mov_b32 s31, 0x7f800000
	v_sub_f32_e32 v185, v183, v185
	v_sub_f32_e32 v185, v187, v185
	v_add_f32_e32 v189, v188, v185
	v_mov_b32_e32 v188, v186
	v_pk_add_f32 v[186:187], v[182:183], v[186:187] neg_lo:[0,1] neg_hi:[0,1]
	v_pk_add_f32 v[190:191], v[182:183], v[188:189]
	v_mov_b32_e32 v185, v182
	v_mov_b32_e32 v187, v191
	v_pk_add_f32 v[192:193], v[184:185], v[186:187] neg_lo:[0,1] neg_hi:[0,1]
	v_pk_add_f32 v[184:185], v[184:185], v[186:187]
	v_mov_b32_e32 v188, v189
	v_pk_add_f32 v[186:187], v[184:185], v[182:183] op_sel:[1,0] op_sel_hi:[0,1] neg_lo:[0,1] neg_hi:[0,1]
	v_pk_add_f32 v[194:195], v[190:191], v[186:187] op_sel_hi:[1,0] neg_lo:[0,1] neg_hi:[0,1]
	v_mov_b32_e32 v190, v191
	v_mov_b32_e32 v191, v185
	v_pk_mov_b32 v[186:187], v[182:183], v[186:187] op_sel:[1,0]
	v_mov_b32_e32 v189, v182
	v_pk_add_f32 v[186:187], v[190:191], v[186:187] neg_lo:[0,1] neg_hi:[0,1]
	v_mov_b32_e32 v194, v192
	v_pk_add_f32 v[182:183], v[188:189], v[186:187] neg_lo:[0,1] neg_hi:[0,1]
	v_mov_b32_e32 v193, v185
	v_pk_add_f32 v[186:187], v[194:195], v[182:183]
	v_cmp_neq_f32_e32 vcc, s31, v178
	v_pk_add_f32 v[188:189], v[186:187], v[186:187] op_sel:[0,1] op_sel_hi:[1,0]
	s_mov_b32 s31, 0x33800000
	v_pk_add_f32 v[184:185], v[184:185], v[188:189] op_sel:[1,0] op_sel_hi:[0,1]
	v_mov_b32_e32 v187, v184
	v_pk_add_f32 v[190:191], v[186:187], v[192:193] neg_lo:[0,1] neg_hi:[0,1]
	v_mov_b32_e32 v183, v188
	v_sub_f32_e32 v185, v186, v190
	v_pk_add_f32 v[182:183], v[182:183], v[190:191] neg_lo:[0,1] neg_hi:[0,1]
	v_sub_f32_e32 v185, v192, v185
	v_add_f32_e32 v182, v182, v185
	v_add_f32_e32 v182, v182, v183
	v_add_f32_e32 v182, v184, v182
	v_cndmask_b32_e32 v182, v237, v182, vcc
	v_cmp_ngt_f32_e32 vcc, -1.0, v178
	s_nop 1
	v_cndmask_b32_e32 v182, v238, v182, vcc
	v_cmp_neq_f32_e32 vcc, -1.0, v178
	s_nop 1
	v_cndmask_b32_e32 v182, v239, v182, vcc
	v_cmp_lt_f32_e64 vcc, |v178|, s31
	s_nop 1
	v_cndmask_b32_e32 v178, v182, v178, vcc
	v_sub_f32_e32 v178, v0, v178

.LBB0_601:
	s_or_b64 exec, exec, s[4:5]
	v_lshlrev_b32_e32 v184, 2, v225
	v_lshlrev_b32_e32 v0, 2, v228
	v_ashrrev_i32_e32 v185, 31, v184
	v_lshl_add_u64 v[182:183], s[84:85], 0, v[0:1]
	v_lshlrev_b64 v[186:187], 13, v[184:185]
	v_lshl_add_u64 v[186:187], v[182:183], 0, v[186:187]
	v_readlane_b32 s4, v254, 26
	global_store_dword v[186:187], v178, off
	v_readlane_b32 s5, v254, 27
	s_nop 4
	s_load_dword s4, s[4:5], 0x4
	s_waitcnt lgkmcnt(0)
	v_mov_b32_e32 v0, s4
	v_add_f32_e32 v0, v179, v0
	v_cmp_nlt_f32_e32 vcc, 0, v0
	s_and_saveexec_b64 s[4:5], vcc
	s_xor_b64 s[4:5], exec, s[4:5]
	s_cbranch_execz .LBB0_603
	v_mul_f32_e32 v178, 0x3fb8aa3b, v0
	v_exp_f32_e32 v185, v178
	s_mov_b32 s31, 0x3f2aaaab
	v_add_f32_e32 v186, 1.0, v185
	v_frexp_mant_f32_e32 v188, v186
	v_cvt_f64_f32_e32 v[178:179], v186
	v_frexp_exp_i32_f64_e32 v178, v[178:179]
	v_cmp_gt_f32_e32 vcc, s31, v188
	v_add_f32_e32 v187, -1.0, v186
	v_sub_f32_e32 v189, v187, v186
	v_subbrev_co_u32_e32 v192, vcc, 0, v178, vcc
	v_sub_u32_e32 v178, 0, v192
	v_sub_f32_e32 v187, v185, v187
	v_add_f32_e32 v189, 1.0, v189
	v_ldexp_f32 v179, v186, v178
	v_add_f32_e32 v187, v187, v189
	v_add_f32_e32 v186, -1.0, v179
	v_add_f32_e32 v188, 1.0, v179
	v_ldexp_f32 v178, v187, v178
	v_add_f32_e32 v187, 1.0, v186
	v_add_f32_e32 v189, -1.0, v188
	v_sub_f32_e32 v187, v179, v187
	v_sub_f32_e32 v179, v179, v189
	v_add_f32_e32 v187, v178, v187
	v_add_f32_e32 v178, v178, v179
	v_add_f32_e32 v193, v188, v178
	v_rcp_f32_e32 v195, v193
	v_sub_f32_e32 v179, v193, v188
	v_sub_f32_e32 v194, v178, v179
	v_add_f32_e32 v179, v186, v187
	v_mul_f32_e32 v202, v179, v195
	v_sub_f32_e32 v178, v179, v186
	v_mul_f32_e32 v186, v193, v202
	v_fma_f32 v188, v202, v193, -v186
	v_fmac_f32_e32 v188, v202, v194
	v_sub_f32_e32 v197, v187, v178
	v_add_f32_e32 v178, v186, v188
	v_sub_f32_e32 v187, v179, v178
	v_pk_add_f32 v[190:191], v[178:179], v[186:187] neg_lo:[0,1] neg_hi:[0,1]
	v_mov_b32_e32 v189, v178
	v_pk_add_f32 v[178:179], v[190:191], v[188:189] neg_lo:[0,1] neg_hi:[0,1]
	s_mov_b32 s31, 0x3f317218
	v_add_f32_e32 v179, v197, v179
	v_add_f32_e32 v178, v178, v179
	v_add_f32_e32 v179, v187, v178
	v_mul_f32_e32 v197, v195, v179
	v_mul_f32_e32 v186, v193, v197
	v_fma_f32 v188, v197, v193, -v186
	v_fmac_f32_e32 v188, v197, v194
	v_sub_f32_e32 v187, v187, v179
	v_add_f32_e32 v193, v178, v187
	v_add_f32_e32 v178, v186, v188
	v_sub_f32_e32 v187, v179, v178
	v_pk_add_f32 v[190:191], v[178:179], v[186:187] neg_lo:[0,1] neg_hi:[0,1]
	v_mov_b32_e32 v189, v178
	v_pk_add_f32 v[178:179], v[190:191], v[188:189] neg_lo:[0,1] neg_hi:[0,1]
	s_nop 0
	v_add_f32_e32 v179, v193, v179
	v_add_f32_e32 v178, v178, v179
	v_add_f32_e32 v179, v202, v197
	v_add_f32_e32 v178, v187, v178
	v_sub_f32_e32 v186, v179, v202
	v_mul_f32_e32 v178, v195, v178
	v_sub_f32_e32 v186, v197, v186
	v_add_f32_e32 v186, v186, v178
	v_add_f32_e32 v188, v179, v186
	v_mul_f32_e32 v189, v188, v188
	v_fmamk_f32 v178, v189, 0x3e9b6dac, v236
	v_fmaak_f32 v205, v189, v178, 0x3f2aaada
	v_cvt_f32_i32_e32 v178, v192
	v_sub_f32_e32 v179, v188, v179
	v_sub_f32_e32 v179, v186, v179
	v_ldexp_f32 v190, v179, 1
	v_mul_f32_e32 v179, v188, v189
	v_ldexp_f32 v187, v188, 1
	v_pk_mul_f32 v[188:189], v[178:179], v[204:205]
	s_nop 0
	v_fma_f32 v186, v178, s31, -v188
	v_fmac_f32_e32 v186, 0xb102e308, v178
	v_pk_add_f32 v[178:179], v[188:189], v[186:187]
	s_mov_b32 s31, 0x7f800000
	v_sub_f32_e32 v187, v179, v187
	v_sub_f32_e32 v187, v189, v187
	v_add_f32_e32 v191, v190, v187
	v_mov_b32_e32 v190, v188
	v_pk_add_f32 v[188:189], v[178:179], v[188:189] neg_lo:[0,1] neg_hi:[0,1]
	v_pk_add_f32 v[192:193], v[178:179], v[190:191]
	v_mov_b32_e32 v187, v178
	v_mov_b32_e32 v189, v193
	v_pk_add_f32 v[194:195], v[186:187], v[188:189] neg_lo:[0,1] neg_hi:[0,1]
	v_pk_add_f32 v[186:187], v[186:187], v[188:189]
	v_mov_b32_e32 v190, v191
	v_pk_add_f32 v[188:189], v[186:187], v[178:179] op_sel:[1,0] op_sel_hi:[0,1] neg_lo:[0,1] neg_hi:[0,1]
	v_pk_add_f32 v[202:203], v[192:193], v[188:189] op_sel_hi:[1,0] neg_lo:[0,1] neg_hi:[0,1]
	v_mov_b32_e32 v192, v193
	v_mov_b32_e32 v193, v187
	v_pk_mov_b32 v[188:189], v[178:179], v[188:189] op_sel:[1,0]
	v_mov_b32_e32 v191, v178
	v_pk_add_f32 v[188:189], v[192:193], v[188:189] neg_lo:[0,1] neg_hi:[0,1]
	v_mov_b32_e32 v202, v194
	v_pk_add_f32 v[178:179], v[190:191], v[188:189] neg_lo:[0,1] neg_hi:[0,1]
	v_mov_b32_e32 v195, v187
	v_pk_add_f32 v[188:189], v[202:203], v[178:179]
	v_cmp_neq_f32_e32 vcc, s31, v185
	v_pk_add_f32 v[190:191], v[188:189], v[188:189] op_sel:[0,1] op_sel_hi:[1,0]
	s_mov_b32 s31, 0x33800000
	v_pk_add_f32 v[186:187], v[186:187], v[190:191] op_sel:[1,0] op_sel_hi:[0,1]
	v_mov_b32_e32 v189, v186
	v_pk_add_f32 v[192:193], v[188:189], v[194:195] neg_lo:[0,1] neg_hi:[0,1]
	v_mov_b32_e32 v179, v190
	v_sub_f32_e32 v187, v188, v192
	v_pk_add_f32 v[178:179], v[178:179], v[192:193] neg_lo:[0,1] neg_hi:[0,1]
	v_sub_f32_e32 v187, v194, v187
	v_add_f32_e32 v178, v178, v187
	v_add_f32_e32 v178, v178, v179
	v_add_f32_e32 v178, v186, v178
	v_cndmask_b32_e32 v178, v237, v178, vcc
	v_cmp_ngt_f32_e32 vcc, -1.0, v185
	s_nop 1
	v_cndmask_b32_e32 v178, v238, v178, vcc
	v_cmp_neq_f32_e32 vcc, -1.0, v185
	s_nop 1
	v_cndmask_b32_e32 v178, v239, v178, vcc
	v_cmp_lt_f32_e64 vcc, |v185|, s31
	s_nop 1
	v_cndmask_b32_e32 v178, v178, v185, vcc
	v_sub_f32_e32 v178, v0, v178

.LBB0_605:
	s_or_b64 exec, exec, s[4:5]
	v_or_b32_e32 v186, 1, v184
	v_ashrrev_i32_e32 v187, 31, v186
	v_lshlrev_b64 v[186:187], 13, v[186:187]
	v_lshl_add_u64 v[186:187], v[182:183], 0, v[186:187]
	v_readlane_b32 s4, v254, 26
	global_store_dword v[186:187], v178, off
	v_readlane_b32 s5, v254, 27
	s_nop 4
	s_load_dword s4, s[4:5], 0x8
	s_waitcnt lgkmcnt(0)
	v_mov_b32_e32 v0, s4
	v_add_f32_e32 v0, v180, v0
	v_cmp_nlt_f32_e32 vcc, 0, v0
	s_and_saveexec_b64 s[4:5], vcc
	s_xor_b64 s[4:5], exec, s[4:5]
	s_cbranch_execz .LBB0_607
	v_mul_f32_e32 v178, 0x3fb8aa3b, v0
	v_exp_f32_e32 v180, v178
	s_mov_b32 s31, 0x3f2aaaab
	v_add_f32_e32 v185, 1.0, v180
	v_frexp_mant_f32_e32 v187, v185
	v_cvt_f64_f32_e32 v[178:179], v185
	v_frexp_exp_i32_f64_e32 v178, v[178:179]
	v_cmp_gt_f32_e32 vcc, s31, v187
	v_add_f32_e32 v186, -1.0, v185
	v_sub_f32_e32 v188, v186, v185
	v_subbrev_co_u32_e32 v192, vcc, 0, v178, vcc
	v_sub_u32_e32 v178, 0, v192
	v_sub_f32_e32 v186, v180, v186
	v_add_f32_e32 v188, 1.0, v188
	v_ldexp_f32 v179, v185, v178
	v_add_f32_e32 v186, v186, v188
	v_add_f32_e32 v185, -1.0, v179
	v_add_f32_e32 v187, 1.0, v179
	v_ldexp_f32 v178, v186, v178
	v_add_f32_e32 v186, 1.0, v185
	v_add_f32_e32 v188, -1.0, v187
	v_sub_f32_e32 v186, v179, v186
	v_sub_f32_e32 v179, v179, v188
	v_add_f32_e32 v186, v178, v186
	v_add_f32_e32 v178, v178, v179
	v_add_f32_e32 v193, v187, v178
	v_rcp_f32_e32 v195, v193
	v_sub_f32_e32 v179, v193, v187
	v_sub_f32_e32 v194, v178, v179
	v_add_f32_e32 v179, v185, v186
	v_sub_f32_e32 v178, v179, v185
	v_mul_f32_e32 v197, v179, v195
	v_sub_f32_e32 v185, v186, v178
	v_mul_f32_e32 v186, v193, v197
	v_fma_f32 v188, v197, v193, -v186
	v_fmac_f32_e32 v188, v197, v194
	v_add_f32_e32 v178, v186, v188
	v_sub_f32_e32 v187, v179, v178
	v_pk_add_f32 v[190:191], v[178:179], v[186:187] neg_lo:[0,1] neg_hi:[0,1]
	v_mov_b32_e32 v189, v178
	v_pk_add_f32 v[178:179], v[190:191], v[188:189] neg_lo:[0,1] neg_hi:[0,1]
	s_mov_b32 s31, 0x3f317218
	v_add_f32_e32 v179, v185, v179
	v_add_f32_e32 v178, v178, v179
	v_add_f32_e32 v179, v187, v178
	v_mul_f32_e32 v185, v195, v179
	v_mul_f32_e32 v186, v193, v185
	v_fma_f32 v188, v185, v193, -v186
	v_fmac_f32_e32 v188, v185, v194
	v_sub_f32_e32 v187, v187, v179
	v_add_f32_e32 v193, v178, v187
	v_add_f32_e32 v178, v186, v188
	v_sub_f32_e32 v187, v179, v178
	v_pk_add_f32 v[190:191], v[178:179], v[186:187] neg_lo:[0,1] neg_hi:[0,1]
	v_mov_b32_e32 v189, v178
	v_pk_add_f32 v[178:179], v[190:191], v[188:189] neg_lo:[0,1] neg_hi:[0,1]
	s_nop 0
	v_add_f32_e32 v179, v193, v179
	v_add_f32_e32 v178, v178, v179
	v_add_f32_e32 v179, v197, v185
	v_add_f32_e32 v178, v187, v178
	v_sub_f32_e32 v186, v179, v197
	v_mul_f32_e32 v178, v195, v178
	v_sub_f32_e32 v185, v185, v186
	v_add_f32_e32 v185, v185, v178
	v_add_f32_e32 v186, v179, v185
	v_mul_f32_e32 v188, v186, v186
	v_fmamk_f32 v178, v188, 0x3e9b6dac, v236
	v_fmaak_f32 v205, v188, v178, 0x3f2aaada
	v_cvt_f32_i32_e32 v178, v192
	v_sub_f32_e32 v179, v186, v179
	v_sub_f32_e32 v179, v185, v179
	v_ldexp_f32 v185, v179, 1
	v_mul_f32_e32 v179, v186, v188
	v_pk_mul_f32 v[188:189], v[178:179], v[204:205]
	v_ldexp_f32 v187, v186, 1
	v_fma_f32 v186, v178, s31, -v188
	v_fmac_f32_e32 v186, 0xb102e308, v178
	v_pk_add_f32 v[178:179], v[188:189], v[186:187]
	v_mov_b32_e32 v190, v188
	v_sub_f32_e32 v187, v179, v187
	v_sub_f32_e32 v187, v189, v187
	v_add_f32_e32 v191, v185, v187
	v_pk_add_f32 v[188:189], v[178:179], v[188:189] neg_lo:[0,1] neg_hi:[0,1]
	v_pk_add_f32 v[192:193], v[178:179], v[190:191]
	v_mov_b32_e32 v187, v178
	v_mov_b32_e32 v189, v193
	v_pk_add_f32 v[194:195], v[186:187], v[188:189] neg_lo:[0,1] neg_hi:[0,1]
	v_pk_add_f32 v[186:187], v[186:187], v[188:189]
	v_mov_b32_e32 v190, v191
	v_pk_add_f32 v[188:189], v[186:187], v[178:179] op_sel:[1,0] op_sel_hi:[0,1] neg_lo:[0,1] neg_hi:[0,1]
	v_pk_add_f32 v[202:203], v[192:193], v[188:189] op_sel_hi:[1,0] neg_lo:[0,1] neg_hi:[0,1]
	v_mov_b32_e32 v192, v193
	v_mov_b32_e32 v193, v187
	v_pk_mov_b32 v[188:189], v[178:179], v[188:189] op_sel:[1,0]
	v_mov_b32_e32 v191, v178
	v_pk_add_f32 v[188:189], v[192:193], v[188:189] neg_lo:[0,1] neg_hi:[0,1]
	v_mov_b32_e32 v202, v194
	v_pk_add_f32 v[178:179], v[190:191], v[188:189] neg_lo:[0,1] neg_hi:[0,1]
	v_mov_b32_e32 v195, v187
	v_pk_add_f32 v[188:189], v[202:203], v[178:179]
	s_mov_b32 s31, 0x7f800000
	v_pk_add_f32 v[190:191], v[188:189], v[188:189] op_sel:[0,1] op_sel_hi:[1,0]
	v_cmp_neq_f32_e32 vcc, s31, v180
	v_pk_add_f32 v[186:187], v[186:187], v[190:191] op_sel:[1,0] op_sel_hi:[0,1]
	v_mov_b32_e32 v189, v186
	v_pk_add_f32 v[192:193], v[188:189], v[194:195] neg_lo:[0,1] neg_hi:[0,1]
	v_mov_b32_e32 v179, v190
	v_sub_f32_e32 v185, v188, v192
	v_pk_add_f32 v[178:179], v[178:179], v[192:193] neg_lo:[0,1] neg_hi:[0,1]
	v_sub_f32_e32 v185, v194, v185
	v_add_f32_e32 v178, v178, v185
	v_add_f32_e32 v178, v178, v179
	v_add_f32_e32 v178, v186, v178
	v_cndmask_b32_e32 v178, v237, v178, vcc
	v_cmp_ngt_f32_e32 vcc, -1.0, v180
	s_mov_b32 s31, 0x33800000
	s_nop 0
	v_cndmask_b32_e32 v178, v238, v178, vcc
	v_cmp_neq_f32_e32 vcc, -1.0, v180
	s_nop 1
	v_cndmask_b32_e32 v178, v239, v178, vcc
	v_cmp_lt_f32_e64 vcc, |v180|, s31
	s_nop 1
	v_cndmask_b32_e32 v178, v178, v180, vcc
	v_sub_f32_e32 v178, v0, v178

.LBB0_609:
	s_or_b64 exec, exec, s[4:5]
	v_or_b32_e32 v186, 2, v184
	v_ashrrev_i32_e32 v187, 31, v186
	v_lshlrev_b64 v[186:187], 13, v[186:187]
	v_lshl_add_u64 v[186:187], v[182:183], 0, v[186:187]
	v_readlane_b32 s4, v254, 26
	global_store_dword v[186:187], v178, off
	v_readlane_b32 s5, v254, 27
	s_nop 4
	s_load_dword s4, s[4:5], 0xc
	s_waitcnt lgkmcnt(0)
	v_mov_b32_e32 v0, s4
	v_add_f32_e32 v0, v181, v0
	v_cmp_nlt_f32_e32 vcc, 0, v0
	s_and_saveexec_b64 s[4:5], vcc
	s_xor_b64 s[4:5], exec, s[4:5]
	s_cbranch_execz .LBB0_611
	v_mul_f32_e32 v178, 0x3fb8aa3b, v0
	v_exp_f32_e32 v185, v178
	s_mov_b32 s31, 0x3f2aaaab
	v_add_f32_e32 v180, 1.0, v185
	v_frexp_mant_f32_e32 v186, v180
	v_cvt_f64_f32_e32 v[178:179], v180
	v_frexp_exp_i32_f64_e32 v178, v[178:179]
	v_cmp_gt_f32_e32 vcc, s31, v186
	v_add_f32_e32 v181, -1.0, v180
	v_sub_f32_e32 v187, v181, v180
	v_subbrev_co_u32_e32 v190, vcc, 0, v178, vcc
	v_sub_u32_e32 v178, 0, v190
	v_sub_f32_e32 v181, v185, v181
	v_add_f32_e32 v187, 1.0, v187
	v_ldexp_f32 v179, v180, v178
	v_add_f32_e32 v181, v181, v187
	v_add_f32_e32 v180, -1.0, v179
	v_add_f32_e32 v186, 1.0, v179
	v_ldexp_f32 v178, v181, v178
	v_add_f32_e32 v181, 1.0, v180
	v_add_f32_e32 v187, -1.0, v186
	v_sub_f32_e32 v181, v179, v181
	v_sub_f32_e32 v179, v179, v187
	v_add_f32_e32 v181, v178, v181
	v_add_f32_e32 v178, v178, v179
	v_add_f32_e32 v191, v186, v178
	v_rcp_f32_e32 v193, v191
	v_sub_f32_e32 v179, v191, v186
	v_sub_f32_e32 v192, v178, v179
	v_add_f32_e32 v179, v180, v181
	v_mul_f32_e32 v195, v179, v193
	v_sub_f32_e32 v178, v179, v180
	v_mul_f32_e32 v180, v191, v195
	v_fma_f32 v186, v195, v191, -v180
	v_fmac_f32_e32 v186, v195, v192
	v_sub_f32_e32 v194, v181, v178
	v_add_f32_e32 v178, v180, v186
	v_sub_f32_e32 v181, v179, v178
	v_pk_add_f32 v[188:189], v[178:179], v[180:181] neg_lo:[0,1] neg_hi:[0,1]
	v_mov_b32_e32 v187, v178
	v_pk_add_f32 v[178:179], v[188:189], v[186:187] neg_lo:[0,1] neg_hi:[0,1]
	s_mov_b32 s31, 0x3f317218
	v_add_f32_e32 v179, v194, v179
	v_add_f32_e32 v178, v178, v179
	v_add_f32_e32 v179, v181, v178
	v_mul_f32_e32 v194, v193, v179
	v_mul_f32_e32 v180, v191, v194
	v_fma_f32 v186, v194, v191, -v180
	v_fmac_f32_e32 v186, v194, v192
	v_sub_f32_e32 v181, v181, v179
	v_add_f32_e32 v191, v178, v181
	v_add_f32_e32 v178, v180, v186
	v_sub_f32_e32 v181, v179, v178
	v_pk_add_f32 v[188:189], v[178:179], v[180:181] neg_lo:[0,1] neg_hi:[0,1]
	v_mov_b32_e32 v187, v178
	v_pk_add_f32 v[178:179], v[188:189], v[186:187] neg_lo:[0,1] neg_hi:[0,1]
	s_nop 0
	v_add_f32_e32 v179, v191, v179
	v_add_f32_e32 v178, v178, v179
	v_add_f32_e32 v179, v195, v194
	v_add_f32_e32 v178, v181, v178
	v_sub_f32_e32 v180, v179, v195
	v_mul_f32_e32 v178, v193, v178
	v_sub_f32_e32 v180, v194, v180
	v_add_f32_e32 v180, v180, v178
	v_add_f32_e32 v186, v179, v180
	v_mul_f32_e32 v187, v186, v186
	v_fmamk_f32 v178, v187, 0x3e9b6dac, v236
	v_fmaak_f32 v205, v187, v178, 0x3f2aaada
	v_cvt_f32_i32_e32 v178, v190
	v_sub_f32_e32 v179, v186, v179
	v_sub_f32_e32 v179, v180, v179
	v_ldexp_f32 v188, v179, 1
	v_mul_f32_e32 v179, v186, v187
	v_ldexp_f32 v181, v186, 1
	v_pk_mul_f32 v[186:187], v[178:179], v[204:205]
	s_nop 0
	v_fma_f32 v180, v178, s31, -v186
	v_fmac_f32_e32 v180, 0xb102e308, v178
	v_pk_add_f32 v[178:179], v[186:187], v[180:181]
	s_mov_b32 s31, 0x7f800000
	v_sub_f32_e32 v181, v179, v181
	v_sub_f32_e32 v181, v187, v181
	v_add_f32_e32 v189, v188, v181
	v_mov_b32_e32 v188, v186
	v_pk_add_f32 v[186:187], v[178:179], v[186:187] neg_lo:[0,1] neg_hi:[0,1]
	v_pk_add_f32 v[190:191], v[178:179], v[188:189]
	v_mov_b32_e32 v181, v178
	v_mov_b32_e32 v187, v191
	v_pk_add_f32 v[192:193], v[180:181], v[186:187] neg_lo:[0,1] neg_hi:[0,1]
	v_pk_add_f32 v[180:181], v[180:181], v[186:187]
	v_mov_b32_e32 v188, v189
	v_pk_add_f32 v[186:187], v[180:181], v[178:179] op_sel:[1,0] op_sel_hi:[0,1] neg_lo:[0,1] neg_hi:[0,1]
	v_pk_add_f32 v[194:195], v[190:191], v[186:187] op_sel_hi:[1,0] neg_lo:[0,1] neg_hi:[0,1]
	v_mov_b32_e32 v190, v191
	v_mov_b32_e32 v191, v181
	v_pk_mov_b32 v[186:187], v[178:179], v[186:187] op_sel:[1,0]
	v_mov_b32_e32 v189, v178
	v_pk_add_f32 v[186:187], v[190:191], v[186:187] neg_lo:[0,1] neg_hi:[0,1]
	v_mov_b32_e32 v194, v192
	v_pk_add_f32 v[178:179], v[188:189], v[186:187] neg_lo:[0,1] neg_hi:[0,1]
	v_mov_b32_e32 v193, v181
	v_pk_add_f32 v[186:187], v[194:195], v[178:179]
	v_cmp_neq_f32_e32 vcc, s31, v185
	v_pk_add_f32 v[188:189], v[186:187], v[186:187] op_sel:[0,1] op_sel_hi:[1,0]
	s_mov_b32 s31, 0x33800000
	v_pk_add_f32 v[180:181], v[180:181], v[188:189] op_sel:[1,0] op_sel_hi:[0,1]
	v_mov_b32_e32 v187, v180
	v_pk_add_f32 v[190:191], v[186:187], v[192:193] neg_lo:[0,1] neg_hi:[0,1]
	v_mov_b32_e32 v179, v188
	v_sub_f32_e32 v181, v186, v190
	v_pk_add_f32 v[178:179], v[178:179], v[190:191] neg_lo:[0,1] neg_hi:[0,1]
	v_sub_f32_e32 v181, v192, v181
	v_add_f32_e32 v178, v178, v181
	v_add_f32_e32 v178, v178, v179
	v_add_f32_e32 v178, v180, v178
	v_cndmask_b32_e32 v178, v237, v178, vcc
	v_cmp_ngt_f32_e32 vcc, -1.0, v185
	s_nop 1
	v_cndmask_b32_e32 v178, v238, v178, vcc
	v_cmp_neq_f32_e32 vcc, -1.0, v185
	s_nop 1
	v_cndmask_b32_e32 v178, v239, v178, vcc
	v_cmp_lt_f32_e64 vcc, |v185|, s31
	s_nop 1
	v_cndmask_b32_e32 v178, v178, v185, vcc
	v_sub_f32_e32 v178, v0, v178

.LBB0_636:
	s_and_saveexec_b64 s[4:5], s[10:11]
	s_xor_b64 s[72:73], exec, s[4:5]
	s_cbranch_execz .LBB0_654
	v_readlane_b32 s4, v254, 26
	v_readlane_b32 s5, v254, 27
	s_nop 4
	s_load_dword s4, s[4:5], 0x0
	s_waitcnt lgkmcnt(0)
	v_mov_b32_e32 v0, s4
	v_add_f32_e32 v0, v170, v0
	v_cmp_nlt_f32_e32 vcc, 0, v0
	s_and_saveexec_b64 s[4:5], vcc
	s_xor_b64 s[4:5], exec, s[4:5]
	s_cbranch_execz .LBB0_639
	v_mul_f32_e32 v170, 0x3fb8aa3b, v0
	v_exp_f32_e32 v170, v170
	s_mov_b32 s31, 0x3f2aaaab
	v_add_f32_e32 v176, 1.0, v170
	v_frexp_mant_f32_e32 v178, v176
	v_cvt_f64_f32_e32 v[174:175], v176
	v_frexp_exp_i32_f64_e32 v174, v[174:175]
	v_cmp_gt_f32_e32 vcc, s31, v178
	v_add_f32_e32 v177, -1.0, v176
	v_sub_f32_e32 v179, v177, v176
	v_subbrev_co_u32_e32 v182, vcc, 0, v174, vcc
	v_sub_u32_e32 v174, 0, v182
	v_sub_f32_e32 v177, v170, v177
	v_add_f32_e32 v179, 1.0, v179
	v_ldexp_f32 v175, v176, v174
	v_add_f32_e32 v177, v177, v179
	v_add_f32_e32 v176, -1.0, v175
	v_add_f32_e32 v178, 1.0, v175
	v_ldexp_f32 v174, v177, v174
	v_add_f32_e32 v177, 1.0, v176
	v_add_f32_e32 v179, -1.0, v178
	v_sub_f32_e32 v177, v175, v177
	v_sub_f32_e32 v175, v175, v179
	v_add_f32_e32 v177, v174, v177
	v_add_f32_e32 v174, v174, v175
	v_add_f32_e32 v183, v178, v174
	v_rcp_f32_e32 v185, v183
	v_sub_f32_e32 v175, v183, v178
	v_sub_f32_e32 v184, v174, v175
	v_add_f32_e32 v175, v176, v177
	v_mul_f32_e32 v187, v175, v185
	v_sub_f32_e32 v174, v175, v176
	v_mul_f32_e32 v176, v183, v187
	v_fma_f32 v178, v187, v183, -v176
	v_fmac_f32_e32 v178, v187, v184
	v_sub_f32_e32 v186, v177, v174
	v_add_f32_e32 v174, v176, v178
	v_sub_f32_e32 v177, v175, v174
	v_pk_add_f32 v[180:181], v[174:175], v[176:177] neg_lo:[0,1] neg_hi:[0,1]
	v_mov_b32_e32 v179, v174
	v_pk_add_f32 v[174:175], v[180:181], v[178:179] neg_lo:[0,1] neg_hi:[0,1]
	s_mov_b32 s31, 0x3f317218
	v_add_f32_e32 v175, v186, v175
	v_add_f32_e32 v174, v174, v175
	v_add_f32_e32 v175, v177, v174
	v_mul_f32_e32 v186, v185, v175
	v_mul_f32_e32 v176, v183, v186
	v_fma_f32 v178, v186, v183, -v176
	v_fmac_f32_e32 v178, v186, v184
	v_sub_f32_e32 v177, v177, v175
	v_add_f32_e32 v183, v174, v177
	v_add_f32_e32 v174, v176, v178
	v_sub_f32_e32 v177, v175, v174
	v_pk_add_f32 v[180:181], v[174:175], v[176:177] neg_lo:[0,1] neg_hi:[0,1]
	v_mov_b32_e32 v179, v174
	v_pk_add_f32 v[174:175], v[180:181], v[178:179] neg_lo:[0,1] neg_hi:[0,1]
	s_nop 0
	v_add_f32_e32 v175, v183, v175
	v_add_f32_e32 v174, v174, v175
	v_add_f32_e32 v175, v187, v186
	v_add_f32_e32 v174, v177, v174
	v_sub_f32_e32 v176, v175, v187
	v_mul_f32_e32 v174, v185, v174
	v_sub_f32_e32 v176, v186, v176
	v_add_f32_e32 v176, v176, v174
	v_add_f32_e32 v178, v175, v176
	v_mul_f32_e32 v179, v178, v178
	v_fmamk_f32 v174, v179, 0x3e9b6dac, v236
	v_fmaak_f32 v205, v179, v174, 0x3f2aaada
	v_cvt_f32_i32_e32 v174, v182
	v_sub_f32_e32 v175, v178, v175
	v_sub_f32_e32 v175, v176, v175
	v_ldexp_f32 v180, v175, 1
	v_mul_f32_e32 v175, v178, v179
	v_ldexp_f32 v177, v178, 1
	v_pk_mul_f32 v[178:179], v[174:175], v[204:205]
	s_nop 0
	v_fma_f32 v176, v174, s31, -v178
	v_fmac_f32_e32 v176, 0xb102e308, v174
	v_pk_add_f32 v[174:175], v[178:179], v[176:177]
	s_mov_b32 s31, 0x7f800000
	v_sub_f32_e32 v177, v175, v177
	v_sub_f32_e32 v177, v179, v177
	v_add_f32_e32 v181, v180, v177
	v_mov_b32_e32 v180, v178
	v_pk_add_f32 v[178:179], v[174:175], v[178:179] neg_lo:[0,1] neg_hi:[0,1]
	v_pk_add_f32 v[182:183], v[174:175], v[180:181]
	v_mov_b32_e32 v177, v174
	v_mov_b32_e32 v179, v183
	v_pk_add_f32 v[184:185], v[176:177], v[178:179] neg_lo:[0,1] neg_hi:[0,1]
	v_pk_add_f32 v[176:177], v[176:177], v[178:179]
	v_mov_b32_e32 v180, v181
	v_pk_add_f32 v[178:179], v[176:177], v[174:175] op_sel:[1,0] op_sel_hi:[0,1] neg_lo:[0,1] neg_hi:[0,1]
	v_pk_add_f32 v[186:187], v[182:183], v[178:179] op_sel_hi:[1,0] neg_lo:[0,1] neg_hi:[0,1]
	v_mov_b32_e32 v182, v183
	v_mov_b32_e32 v183, v177
	v_pk_mov_b32 v[178:179], v[174:175], v[178:179] op_sel:[1,0]
	v_mov_b32_e32 v181, v174
	v_pk_add_f32 v[178:179], v[182:183], v[178:179] neg_lo:[0,1] neg_hi:[0,1]
	v_mov_b32_e32 v186, v184
	v_pk_add_f32 v[174:175], v[180:181], v[178:179] neg_lo:[0,1] neg_hi:[0,1]
	v_mov_b32_e32 v185, v177
	v_pk_add_f32 v[178:179], v[186:187], v[174:175]
	v_cmp_neq_f32_e32 vcc, s31, v170
	v_pk_add_f32 v[180:181], v[178:179], v[178:179] op_sel:[0,1] op_sel_hi:[1,0]
	s_mov_b32 s31, 0x33800000
	v_pk_add_f32 v[176:177], v[176:177], v[180:181] op_sel:[1,0] op_sel_hi:[0,1]
	v_mov_b32_e32 v179, v176
	v_pk_add_f32 v[182:183], v[178:179], v[184:185] neg_lo:[0,1] neg_hi:[0,1]
	v_mov_b32_e32 v175, v180
	v_sub_f32_e32 v177, v178, v182
	v_pk_add_f32 v[174:175], v[174:175], v[182:183] neg_lo:[0,1] neg_hi:[0,1]
	v_sub_f32_e32 v177, v184, v177
	v_add_f32_e32 v174, v174, v177
	v_add_f32_e32 v174, v174, v175
	v_add_f32_e32 v174, v176, v174
	v_cndmask_b32_e32 v174, v237, v174, vcc
	v_cmp_ngt_f32_e32 vcc, -1.0, v170
	s_nop 1
	v_cndmask_b32_e32 v174, v238, v174, vcc
	v_cmp_neq_f32_e32 vcc, -1.0, v170
	s_nop 1
	v_cndmask_b32_e32 v174, v239, v174, vcc
	v_cmp_lt_f32_e64 vcc, |v170|, s31
	s_nop 1
	v_cndmask_b32_e32 v170, v174, v170, vcc
	v_sub_f32_e32 v170, v0, v170

.LBB0_641:
	s_or_b64 exec, exec, s[4:5]
	v_lshlrev_b32_e32 v176, 2, v189
	v_lshlrev_b32_e32 v0, 2, v190
	v_ashrrev_i32_e32 v177, 31, v176
	v_lshl_add_u64 v[174:175], s[84:85], 0, v[0:1]
	v_lshlrev_b64 v[178:179], 13, v[176:177]
	v_lshl_add_u64 v[178:179], v[174:175], 0, v[178:179]
	v_readlane_b32 s4, v254, 26
	global_store_dword v[178:179], v170, off
	v_readlane_b32 s5, v254, 27
	s_nop 4
	s_load_dword s4, s[4:5], 0x4
	s_waitcnt lgkmcnt(0)
	v_mov_b32_e32 v0, s4
	v_add_f32_e32 v0, v171, v0
	v_cmp_nlt_f32_e32 vcc, 0, v0
	s_and_saveexec_b64 s[4:5], vcc
	s_xor_b64 s[4:5], exec, s[4:5]
	s_cbranch_execz .LBB0_643
	v_mul_f32_e32 v170, 0x3fb8aa3b, v0
	v_exp_f32_e32 v177, v170
	s_mov_b32 s31, 0x3f2aaaab
	v_add_f32_e32 v178, 1.0, v177
	v_frexp_mant_f32_e32 v180, v178
	v_cvt_f64_f32_e32 v[170:171], v178
	v_frexp_exp_i32_f64_e32 v170, v[170:171]
	v_cmp_gt_f32_e32 vcc, s31, v180
	v_add_f32_e32 v179, -1.0, v178
	v_sub_f32_e32 v181, v179, v178
	v_subbrev_co_u32_e32 v184, vcc, 0, v170, vcc
	v_sub_u32_e32 v170, 0, v184
	v_sub_f32_e32 v179, v177, v179
	v_add_f32_e32 v181, 1.0, v181
	v_ldexp_f32 v171, v178, v170
	v_add_f32_e32 v179, v179, v181
	v_add_f32_e32 v178, -1.0, v171
	v_add_f32_e32 v180, 1.0, v171
	v_ldexp_f32 v170, v179, v170
	v_add_f32_e32 v179, 1.0, v178
	v_add_f32_e32 v181, -1.0, v180
	v_sub_f32_e32 v179, v171, v179
	v_sub_f32_e32 v171, v171, v181
	v_add_f32_e32 v179, v170, v179
	v_add_f32_e32 v170, v170, v171
	v_add_f32_e32 v185, v180, v170
	v_rcp_f32_e32 v187, v185
	v_sub_f32_e32 v171, v185, v180
	v_sub_f32_e32 v186, v170, v171
	v_add_f32_e32 v171, v178, v179
	v_mul_f32_e32 v189, v171, v187
	v_sub_f32_e32 v170, v171, v178
	v_mul_f32_e32 v178, v185, v189
	v_fma_f32 v180, v189, v185, -v178
	v_fmac_f32_e32 v180, v189, v186
	v_sub_f32_e32 v188, v179, v170
	v_add_f32_e32 v170, v178, v180
	v_sub_f32_e32 v179, v171, v170
	v_pk_add_f32 v[182:183], v[170:171], v[178:179] neg_lo:[0,1] neg_hi:[0,1]
	v_mov_b32_e32 v181, v170
	v_pk_add_f32 v[170:171], v[182:183], v[180:181] neg_lo:[0,1] neg_hi:[0,1]
	s_mov_b32 s31, 0x3f317218
	v_add_f32_e32 v171, v188, v171
	v_add_f32_e32 v170, v170, v171
	v_add_f32_e32 v171, v179, v170
	v_mul_f32_e32 v188, v187, v171
	v_mul_f32_e32 v178, v185, v188
	v_fma_f32 v180, v188, v185, -v178
	v_fmac_f32_e32 v180, v188, v186
	v_sub_f32_e32 v179, v179, v171
	v_add_f32_e32 v185, v170, v179
	v_add_f32_e32 v170, v178, v180
	v_sub_f32_e32 v179, v171, v170
	v_pk_add_f32 v[182:183], v[170:171], v[178:179] neg_lo:[0,1] neg_hi:[0,1]
	v_mov_b32_e32 v181, v170
	v_pk_add_f32 v[170:171], v[182:183], v[180:181] neg_lo:[0,1] neg_hi:[0,1]
	s_nop 0
	v_add_f32_e32 v171, v185, v171
	v_add_f32_e32 v170, v170, v171
	v_add_f32_e32 v171, v189, v188
	v_add_f32_e32 v170, v179, v170
	v_sub_f32_e32 v178, v171, v189
	v_mul_f32_e32 v170, v187, v170
	v_sub_f32_e32 v178, v188, v178
	v_add_f32_e32 v178, v178, v170
	v_add_f32_e32 v180, v171, v178
	v_mul_f32_e32 v181, v180, v180
	v_fmamk_f32 v170, v181, 0x3e9b6dac, v236
	v_fmaak_f32 v205, v181, v170, 0x3f2aaada
	v_cvt_f32_i32_e32 v170, v184
	v_sub_f32_e32 v171, v180, v171
	v_sub_f32_e32 v171, v178, v171
	v_ldexp_f32 v182, v171, 1
	v_mul_f32_e32 v171, v180, v181
	v_ldexp_f32 v179, v180, 1
	v_pk_mul_f32 v[180:181], v[170:171], v[204:205]
	s_nop 0
	v_fma_f32 v178, v170, s31, -v180
	v_fmac_f32_e32 v178, 0xb102e308, v170
	v_pk_add_f32 v[170:171], v[180:181], v[178:179]
	s_mov_b32 s31, 0x7f800000
	v_sub_f32_e32 v179, v171, v179
	v_sub_f32_e32 v179, v181, v179
	v_add_f32_e32 v183, v182, v179
	v_mov_b32_e32 v182, v180
	v_pk_add_f32 v[180:181], v[170:171], v[180:181] neg_lo:[0,1] neg_hi:[0,1]
	v_pk_add_f32 v[184:185], v[170:171], v[182:183]
	v_mov_b32_e32 v179, v170
	v_mov_b32_e32 v181, v185
	v_pk_add_f32 v[186:187], v[178:179], v[180:181] neg_lo:[0,1] neg_hi:[0,1]
	v_pk_add_f32 v[178:179], v[178:179], v[180:181]
	v_mov_b32_e32 v182, v183
	v_pk_add_f32 v[180:181], v[178:179], v[170:171] op_sel:[1,0] op_sel_hi:[0,1] neg_lo:[0,1] neg_hi:[0,1]
	v_pk_add_f32 v[188:189], v[184:185], v[180:181] op_sel_hi:[1,0] neg_lo:[0,1] neg_hi:[0,1]
	v_mov_b32_e32 v184, v185
	v_mov_b32_e32 v185, v179
	v_pk_mov_b32 v[180:181], v[170:171], v[180:181] op_sel:[1,0]
	v_mov_b32_e32 v183, v170
	v_pk_add_f32 v[180:181], v[184:185], v[180:181] neg_lo:[0,1] neg_hi:[0,1]
	v_mov_b32_e32 v188, v186
	v_pk_add_f32 v[170:171], v[182:183], v[180:181] neg_lo:[0,1] neg_hi:[0,1]
	v_mov_b32_e32 v187, v179
	v_pk_add_f32 v[180:181], v[188:189], v[170:171]
	v_cmp_neq_f32_e32 vcc, s31, v177
	v_pk_add_f32 v[182:183], v[180:181], v[180:181] op_sel:[0,1] op_sel_hi:[1,0]
	s_mov_b32 s31, 0x33800000
	v_pk_add_f32 v[178:179], v[178:179], v[182:183] op_sel:[1,0] op_sel_hi:[0,1]
	v_mov_b32_e32 v181, v178
	v_pk_add_f32 v[184:185], v[180:181], v[186:187] neg_lo:[0,1] neg_hi:[0,1]
	v_mov_b32_e32 v171, v182
	v_sub_f32_e32 v179, v180, v184
	v_pk_add_f32 v[170:171], v[170:171], v[184:185] neg_lo:[0,1] neg_hi:[0,1]
	v_sub_f32_e32 v179, v186, v179
	v_add_f32_e32 v170, v170, v179
	v_add_f32_e32 v170, v170, v171
	v_add_f32_e32 v170, v178, v170
	v_cndmask_b32_e32 v170, v237, v170, vcc
	v_cmp_ngt_f32_e32 vcc, -1.0, v177
	s_nop 1
	v_cndmask_b32_e32 v170, v238, v170, vcc
	v_cmp_neq_f32_e32 vcc, -1.0, v177
	s_nop 1
	v_cndmask_b32_e32 v170, v239, v170, vcc
	v_cmp_lt_f32_e64 vcc, |v177|, s31
	s_nop 1
	v_cndmask_b32_e32 v170, v170, v177, vcc
	v_sub_f32_e32 v170, v0, v170

.LBB0_645:
	s_or_b64 exec, exec, s[4:5]
	v_or_b32_e32 v178, 1, v176
	v_ashrrev_i32_e32 v179, 31, v178
	v_lshlrev_b64 v[178:179], 13, v[178:179]
	v_lshl_add_u64 v[178:179], v[174:175], 0, v[178:179]
	v_readlane_b32 s4, v254, 26
	global_store_dword v[178:179], v170, off
	v_readlane_b32 s5, v254, 27
	s_nop 4
	s_load_dword s4, s[4:5], 0x8
	s_waitcnt lgkmcnt(0)
	v_mov_b32_e32 v0, s4
	v_add_f32_e32 v0, v172, v0
	v_cmp_nlt_f32_e32 vcc, 0, v0
	s_and_saveexec_b64 s[4:5], vcc
	s_xor_b64 s[4:5], exec, s[4:5]
	s_cbranch_execz .LBB0_647
	v_mul_f32_e32 v170, 0x3fb8aa3b, v0
	v_exp_f32_e32 v172, v170
	s_mov_b32 s31, 0x3f2aaaab
	v_add_f32_e32 v177, 1.0, v172
	v_frexp_mant_f32_e32 v179, v177
	v_cvt_f64_f32_e32 v[170:171], v177
	v_frexp_exp_i32_f64_e32 v170, v[170:171]
	v_cmp_gt_f32_e32 vcc, s31, v179
	v_add_f32_e32 v178, -1.0, v177
	v_sub_f32_e32 v180, v178, v177
	v_subbrev_co_u32_e32 v184, vcc, 0, v170, vcc
	v_sub_u32_e32 v170, 0, v184
	v_sub_f32_e32 v178, v172, v178
	v_add_f32_e32 v180, 1.0, v180
	v_ldexp_f32 v171, v177, v170
	v_add_f32_e32 v178, v178, v180
	v_add_f32_e32 v177, -1.0, v171
	v_add_f32_e32 v179, 1.0, v171
	v_ldexp_f32 v170, v178, v170
	v_add_f32_e32 v178, 1.0, v177
	v_add_f32_e32 v180, -1.0, v179
	v_sub_f32_e32 v178, v171, v178
	v_sub_f32_e32 v171, v171, v180
	v_add_f32_e32 v178, v170, v178
	v_add_f32_e32 v170, v170, v171
	v_add_f32_e32 v185, v179, v170
	v_rcp_f32_e32 v187, v185
	v_sub_f32_e32 v171, v185, v179
	v_sub_f32_e32 v186, v170, v171
	v_add_f32_e32 v171, v177, v178
	v_sub_f32_e32 v170, v171, v177
	v_mul_f32_e32 v188, v171, v187
	v_sub_f32_e32 v177, v178, v170
	v_mul_f32_e32 v178, v185, v188
	v_fma_f32 v180, v188, v185, -v178
	v_fmac_f32_e32 v180, v188, v186
	v_add_f32_e32 v170, v178, v180
	v_sub_f32_e32 v179, v171, v170
	v_pk_add_f32 v[182:183], v[170:171], v[178:179] neg_lo:[0,1] neg_hi:[0,1]
	v_mov_b32_e32 v181, v170
	v_pk_add_f32 v[170:171], v[182:183], v[180:181] neg_lo:[0,1] neg_hi:[0,1]
	s_mov_b32 s31, 0x3f317218
	v_add_f32_e32 v171, v177, v171
	v_add_f32_e32 v170, v170, v171
	v_add_f32_e32 v171, v179, v170
	v_mul_f32_e32 v177, v187, v171
	v_mul_f32_e32 v178, v185, v177
	v_fma_f32 v180, v177, v185, -v178
	v_fmac_f32_e32 v180, v177, v186
	v_sub_f32_e32 v179, v179, v171
	v_add_f32_e32 v185, v170, v179
	v_add_f32_e32 v170, v178, v180
	v_sub_f32_e32 v179, v171, v170
	v_pk_add_f32 v[182:183], v[170:171], v[178:179] neg_lo:[0,1] neg_hi:[0,1]
	v_mov_b32_e32 v181, v170
	v_pk_add_f32 v[170:171], v[182:183], v[180:181] neg_lo:[0,1] neg_hi:[0,1]
	s_nop 0
	v_add_f32_e32 v171, v185, v171
	v_add_f32_e32 v170, v170, v171
	v_add_f32_e32 v171, v188, v177
	v_add_f32_e32 v170, v179, v170
	v_sub_f32_e32 v178, v171, v188
	v_mul_f32_e32 v170, v187, v170
	v_sub_f32_e32 v177, v177, v178
	v_add_f32_e32 v177, v177, v170
	v_add_f32_e32 v178, v171, v177
	v_mul_f32_e32 v180, v178, v178
	v_fmamk_f32 v170, v180, 0x3e9b6dac, v236
	v_fmaak_f32 v205, v180, v170, 0x3f2aaada
	v_cvt_f32_i32_e32 v170, v184
	v_sub_f32_e32 v171, v178, v171
	v_sub_f32_e32 v171, v177, v171
	v_ldexp_f32 v177, v171, 1
	v_mul_f32_e32 v171, v178, v180
	v_pk_mul_f32 v[180:181], v[170:171], v[204:205]
	v_ldexp_f32 v179, v178, 1
	v_fma_f32 v178, v170, s31, -v180
	v_fmac_f32_e32 v178, 0xb102e308, v170
	v_pk_add_f32 v[170:171], v[180:181], v[178:179]
	v_mov_b32_e32 v182, v180
	v_sub_f32_e32 v179, v171, v179
	v_sub_f32_e32 v179, v181, v179
	v_add_f32_e32 v183, v177, v179
	v_pk_add_f32 v[180:181], v[170:171], v[180:181] neg_lo:[0,1] neg_hi:[0,1]
	v_pk_add_f32 v[184:185], v[170:171], v[182:183]
	v_mov_b32_e32 v179, v170
	v_mov_b32_e32 v181, v185
	v_pk_add_f32 v[186:187], v[178:179], v[180:181] neg_lo:[0,1] neg_hi:[0,1]
	v_pk_add_f32 v[178:179], v[178:179], v[180:181]
	v_mov_b32_e32 v182, v183
	v_pk_add_f32 v[180:181], v[178:179], v[170:171] op_sel:[1,0] op_sel_hi:[0,1] neg_lo:[0,1] neg_hi:[0,1]
	v_pk_add_f32 v[188:189], v[184:185], v[180:181] op_sel_hi:[1,0] neg_lo:[0,1] neg_hi:[0,1]
	v_mov_b32_e32 v184, v185
	v_mov_b32_e32 v185, v179
	v_pk_mov_b32 v[180:181], v[170:171], v[180:181] op_sel:[1,0]
	v_mov_b32_e32 v183, v170
	v_pk_add_f32 v[180:181], v[184:185], v[180:181] neg_lo:[0,1] neg_hi:[0,1]
	v_mov_b32_e32 v188, v186
	v_pk_add_f32 v[170:171], v[182:183], v[180:181] neg_lo:[0,1] neg_hi:[0,1]
	v_mov_b32_e32 v187, v179
	v_pk_add_f32 v[180:181], v[188:189], v[170:171]
	s_mov_b32 s31, 0x7f800000
	v_pk_add_f32 v[182:183], v[180:181], v[180:181] op_sel:[0,1] op_sel_hi:[1,0]
	v_cmp_neq_f32_e32 vcc, s31, v172
	v_pk_add_f32 v[178:179], v[178:179], v[182:183] op_sel:[1,0] op_sel_hi:[0,1]
	v_mov_b32_e32 v181, v178
	v_pk_add_f32 v[184:185], v[180:181], v[186:187] neg_lo:[0,1] neg_hi:[0,1]
	v_mov_b32_e32 v171, v182
	v_sub_f32_e32 v177, v180, v184
	v_pk_add_f32 v[170:171], v[170:171], v[184:185] neg_lo:[0,1] neg_hi:[0,1]
	v_sub_f32_e32 v177, v186, v177
	v_add_f32_e32 v170, v170, v177
	v_add_f32_e32 v170, v170, v171
	v_add_f32_e32 v170, v178, v170
	v_cndmask_b32_e32 v170, v237, v170, vcc
	v_cmp_ngt_f32_e32 vcc, -1.0, v172
	s_mov_b32 s31, 0x33800000
	s_nop 0
	v_cndmask_b32_e32 v170, v238, v170, vcc
	v_cmp_neq_f32_e32 vcc, -1.0, v172
	s_nop 1
	v_cndmask_b32_e32 v170, v239, v170, vcc
	v_cmp_lt_f32_e64 vcc, |v172|, s31
	s_nop 1
	v_cndmask_b32_e32 v170, v170, v172, vcc
	v_sub_f32_e32 v170, v0, v170

.LBB0_649:
	s_or_b64 exec, exec, s[4:5]
	v_or_b32_e32 v178, 2, v176
	v_ashrrev_i32_e32 v179, 31, v178
	v_lshlrev_b64 v[178:179], 13, v[178:179]
	v_lshl_add_u64 v[178:179], v[174:175], 0, v[178:179]
	v_readlane_b32 s4, v254, 26
	global_store_dword v[178:179], v170, off
	v_readlane_b32 s5, v254, 27
	s_nop 4
	s_load_dword s4, s[4:5], 0xc
	s_waitcnt lgkmcnt(0)
	v_mov_b32_e32 v0, s4
	v_add_f32_e32 v0, v173, v0
	v_cmp_nlt_f32_e32 vcc, 0, v0
	s_and_saveexec_b64 s[4:5], vcc
	s_xor_b64 s[4:5], exec, s[4:5]
	s_cbranch_execz .LBB0_651
	v_mul_f32_e32 v170, 0x3fb8aa3b, v0
	v_exp_f32_e32 v177, v170
	s_mov_b32 s31, 0x3f2aaaab
	v_add_f32_e32 v172, 1.0, v177
	v_frexp_mant_f32_e32 v178, v172
	v_cvt_f64_f32_e32 v[170:171], v172
	v_frexp_exp_i32_f64_e32 v170, v[170:171]
	v_cmp_gt_f32_e32 vcc, s31, v178
	v_add_f32_e32 v173, -1.0, v172
	v_sub_f32_e32 v179, v173, v172
	v_subbrev_co_u32_e32 v182, vcc, 0, v170, vcc
	v_sub_u32_e32 v170, 0, v182
	v_sub_f32_e32 v173, v177, v173
	v_add_f32_e32 v179, 1.0, v179
	v_ldexp_f32 v171, v172, v170
	v_add_f32_e32 v173, v173, v179
	v_add_f32_e32 v172, -1.0, v171
	v_add_f32_e32 v178, 1.0, v171
	v_ldexp_f32 v170, v173, v170
	v_add_f32_e32 v173, 1.0, v172
	v_add_f32_e32 v179, -1.0, v178
	v_sub_f32_e32 v173, v171, v173
	v_sub_f32_e32 v171, v171, v179
	v_add_f32_e32 v173, v170, v173
	v_add_f32_e32 v170, v170, v171
	v_add_f32_e32 v183, v178, v170
	v_rcp_f32_e32 v185, v183
	v_sub_f32_e32 v171, v183, v178
	v_sub_f32_e32 v184, v170, v171
	v_add_f32_e32 v171, v172, v173
	v_mul_f32_e32 v187, v171, v185
	v_sub_f32_e32 v170, v171, v172
	v_mul_f32_e32 v172, v183, v187
	v_fma_f32 v178, v187, v183, -v172
	v_fmac_f32_e32 v178, v187, v184
	v_sub_f32_e32 v186, v173, v170
	v_add_f32_e32 v170, v172, v178
	v_sub_f32_e32 v173, v171, v170
	v_pk_add_f32 v[180:181], v[170:171], v[172:173] neg_lo:[0,1] neg_hi:[0,1]
	v_mov_b32_e32 v179, v170
	v_pk_add_f32 v[170:171], v[180:181], v[178:179] neg_lo:[0,1] neg_hi:[0,1]
	s_mov_b32 s31, 0x3f317218
	v_add_f32_e32 v171, v186, v171
	v_add_f32_e32 v170, v170, v171
	v_add_f32_e32 v171, v173, v170
	v_mul_f32_e32 v186, v185, v171
	v_mul_f32_e32 v172, v183, v186
	v_fma_f32 v178, v186, v183, -v172
	v_fmac_f32_e32 v178, v186, v184
	v_sub_f32_e32 v173, v173, v171
	v_add_f32_e32 v183, v170, v173
	v_add_f32_e32 v170, v172, v178
	v_sub_f32_e32 v173, v171, v170
	v_pk_add_f32 v[180:181], v[170:171], v[172:173] neg_lo:[0,1] neg_hi:[0,1]
	v_mov_b32_e32 v179, v170
	v_pk_add_f32 v[170:171], v[180:181], v[178:179] neg_lo:[0,1] neg_hi:[0,1]
	s_nop 0
	v_add_f32_e32 v171, v183, v171
	v_add_f32_e32 v170, v170, v171
	v_add_f32_e32 v171, v187, v186
	v_add_f32_e32 v170, v173, v170
	v_sub_f32_e32 v172, v171, v187
	v_mul_f32_e32 v170, v185, v170
	v_sub_f32_e32 v172, v186, v172
	v_add_f32_e32 v172, v172, v170
	v_add_f32_e32 v178, v171, v172
	v_mul_f32_e32 v179, v178, v178
	v_fmamk_f32 v170, v179, 0x3e9b6dac, v236
	v_fmaak_f32 v205, v179, v170, 0x3f2aaada
	v_cvt_f32_i32_e32 v170, v182
	v_sub_f32_e32 v171, v178, v171
	v_sub_f32_e32 v171, v172, v171
	v_ldexp_f32 v180, v171, 1
	v_mul_f32_e32 v171, v178, v179
	v_ldexp_f32 v173, v178, 1
	v_pk_mul_f32 v[178:179], v[170:171], v[204:205]
	s_nop 0
	v_fma_f32 v172, v170, s31, -v178
	v_fmac_f32_e32 v172, 0xb102e308, v170
	v_pk_add_f32 v[170:171], v[178:179], v[172:173]
	s_mov_b32 s31, 0x7f800000
	v_sub_f32_e32 v173, v171, v173
	v_sub_f32_e32 v173, v179, v173
	v_add_f32_e32 v181, v180, v173
	v_mov_b32_e32 v180, v178
	v_pk_add_f32 v[178:179], v[170:171], v[178:179] neg_lo:[0,1] neg_hi:[0,1]
	v_pk_add_f32 v[182:183], v[170:171], v[180:181]
	v_mov_b32_e32 v173, v170
	v_mov_b32_e32 v179, v183
	v_pk_add_f32 v[184:185], v[172:173], v[178:179] neg_lo:[0,1] neg_hi:[0,1]
	v_pk_add_f32 v[172:173], v[172:173], v[178:179]
	v_mov_b32_e32 v180, v181
	v_pk_add_f32 v[178:179], v[172:173], v[170:171] op_sel:[1,0] op_sel_hi:[0,1] neg_lo:[0,1] neg_hi:[0,1]
	v_pk_add_f32 v[186:187], v[182:183], v[178:179] op_sel_hi:[1,0] neg_lo:[0,1] neg_hi:[0,1]
	v_mov_b32_e32 v182, v183
	v_mov_b32_e32 v183, v173
	v_pk_mov_b32 v[178:179], v[170:171], v[178:179] op_sel:[1,0]
	v_mov_b32_e32 v181, v170
	v_pk_add_f32 v[178:179], v[182:183], v[178:179] neg_lo:[0,1] neg_hi:[0,1]
	v_mov_b32_e32 v186, v184
	v_pk_add_f32 v[170:171], v[180:181], v[178:179] neg_lo:[0,1] neg_hi:[0,1]
	v_mov_b32_e32 v185, v173
	v_pk_add_f32 v[178:179], v[186:187], v[170:171]
	v_cmp_neq_f32_e32 vcc, s31, v177
	v_pk_add_f32 v[180:181], v[178:179], v[178:179] op_sel:[0,1] op_sel_hi:[1,0]
	s_mov_b32 s31, 0x33800000
	v_pk_add_f32 v[172:173], v[172:173], v[180:181] op_sel:[1,0] op_sel_hi:[0,1]
	v_mov_b32_e32 v179, v172
	v_pk_add_f32 v[182:183], v[178:179], v[184:185] neg_lo:[0,1] neg_hi:[0,1]
	v_mov_b32_e32 v171, v180
	v_sub_f32_e32 v173, v178, v182
	v_pk_add_f32 v[170:171], v[170:171], v[182:183] neg_lo:[0,1] neg_hi:[0,1]
	v_sub_f32_e32 v173, v184, v173
	v_add_f32_e32 v170, v170, v173
	v_add_f32_e32 v170, v170, v171
	v_add_f32_e32 v170, v172, v170
	v_cndmask_b32_e32 v170, v237, v170, vcc
	v_cmp_ngt_f32_e32 vcc, -1.0, v177
	s_nop 1
	v_cndmask_b32_e32 v170, v238, v170, vcc
	v_cmp_neq_f32_e32 vcc, -1.0, v177
	s_nop 1
	v_cndmask_b32_e32 v170, v239, v170, vcc
	v_cmp_lt_f32_e64 vcc, |v177|, s31
	s_nop 1
	v_cndmask_b32_e32 v170, v170, v177, vcc
	v_sub_f32_e32 v170, v0, v170

.LBB0_677:
	s_and_saveexec_b64 s[4:5], s[10:11]
	s_xor_b64 s[72:73], exec, s[4:5]
	s_cbranch_execz .LBB0_695
	v_readlane_b32 s4, v254, 26
	v_readlane_b32 s5, v254, 27
	s_nop 4
	s_load_dword s4, s[4:5], 0x0
	s_waitcnt lgkmcnt(0)
	v_mov_b32_e32 v0, s4
	v_add_f32_e32 v0, v146, v0
	v_cmp_nlt_f32_e32 vcc, 0, v0
	s_and_saveexec_b64 s[4:5], vcc
	s_xor_b64 s[4:5], exec, s[4:5]
	s_cbranch_execz .LBB0_680
	v_mul_f32_e32 v146, 0x3fb8aa3b, v0
	v_exp_f32_e32 v146, v146
	s_mov_b32 s31, 0x3f2aaaab
	v_add_f32_e32 v168, 1.0, v146
	v_frexp_mant_f32_e32 v170, v168
	v_cvt_f64_f32_e32 v[166:167], v168
	v_frexp_exp_i32_f64_e32 v166, v[166:167]
	v_cmp_gt_f32_e32 vcc, s31, v170
	v_add_f32_e32 v169, -1.0, v168
	v_sub_f32_e32 v171, v169, v168
	v_subbrev_co_u32_e32 v174, vcc, 0, v166, vcc
	v_sub_u32_e32 v166, 0, v174
	v_sub_f32_e32 v169, v146, v169
	v_add_f32_e32 v171, 1.0, v171
	v_ldexp_f32 v167, v168, v166
	v_add_f32_e32 v169, v169, v171
	v_add_f32_e32 v168, -1.0, v167
	v_add_f32_e32 v170, 1.0, v167
	v_ldexp_f32 v166, v169, v166
	v_add_f32_e32 v169, 1.0, v168
	v_add_f32_e32 v171, -1.0, v170
	v_sub_f32_e32 v169, v167, v169
	v_sub_f32_e32 v167, v167, v171
	v_add_f32_e32 v169, v166, v169
	v_add_f32_e32 v166, v166, v167
	v_add_f32_e32 v175, v170, v166
	v_rcp_f32_e32 v177, v175
	v_sub_f32_e32 v167, v175, v170
	v_sub_f32_e32 v176, v166, v167
	v_add_f32_e32 v167, v168, v169
	v_mul_f32_e32 v179, v167, v177
	v_sub_f32_e32 v166, v167, v168
	v_mul_f32_e32 v168, v175, v179
	v_fma_f32 v170, v179, v175, -v168
	v_fmac_f32_e32 v170, v179, v176
	v_sub_f32_e32 v178, v169, v166
	v_add_f32_e32 v166, v168, v170
	v_sub_f32_e32 v169, v167, v166
	v_pk_add_f32 v[172:173], v[166:167], v[168:169] neg_lo:[0,1] neg_hi:[0,1]
	v_mov_b32_e32 v171, v166
	v_pk_add_f32 v[166:167], v[172:173], v[170:171] neg_lo:[0,1] neg_hi:[0,1]
	s_mov_b32 s31, 0x3f317218
	v_add_f32_e32 v167, v178, v167
	v_add_f32_e32 v166, v166, v167
	v_add_f32_e32 v167, v169, v166
	v_mul_f32_e32 v178, v177, v167
	v_mul_f32_e32 v168, v175, v178
	v_fma_f32 v170, v178, v175, -v168
	v_fmac_f32_e32 v170, v178, v176
	v_sub_f32_e32 v169, v169, v167
	v_add_f32_e32 v175, v166, v169
	v_add_f32_e32 v166, v168, v170
	v_sub_f32_e32 v169, v167, v166
	v_pk_add_f32 v[172:173], v[166:167], v[168:169] neg_lo:[0,1] neg_hi:[0,1]
	v_mov_b32_e32 v171, v166
	v_pk_add_f32 v[166:167], v[172:173], v[170:171] neg_lo:[0,1] neg_hi:[0,1]
	s_nop 0
	v_add_f32_e32 v167, v175, v167
	v_add_f32_e32 v166, v166, v167
	v_add_f32_e32 v167, v179, v178
	v_add_f32_e32 v166, v169, v166
	v_sub_f32_e32 v168, v167, v179
	v_mul_f32_e32 v166, v177, v166
	v_sub_f32_e32 v168, v178, v168
	v_add_f32_e32 v168, v168, v166
	v_add_f32_e32 v170, v167, v168
	v_mul_f32_e32 v171, v170, v170
	v_fmamk_f32 v166, v171, 0x3e9b6dac, v236
	v_fmaak_f32 v205, v171, v166, 0x3f2aaada
	v_cvt_f32_i32_e32 v166, v174
	v_sub_f32_e32 v167, v170, v167
	v_sub_f32_e32 v167, v168, v167
	v_ldexp_f32 v172, v167, 1
	v_mul_f32_e32 v167, v170, v171
	v_ldexp_f32 v169, v170, 1
	v_pk_mul_f32 v[170:171], v[166:167], v[204:205]
	s_nop 0
	v_fma_f32 v168, v166, s31, -v170
	v_fmac_f32_e32 v168, 0xb102e308, v166
	v_pk_add_f32 v[166:167], v[170:171], v[168:169]
	s_mov_b32 s31, 0x7f800000
	v_sub_f32_e32 v169, v167, v169
	v_sub_f32_e32 v169, v171, v169
	v_add_f32_e32 v173, v172, v169
	v_mov_b32_e32 v172, v170
	v_pk_add_f32 v[170:171], v[166:167], v[170:171] neg_lo:[0,1] neg_hi:[0,1]
	v_pk_add_f32 v[174:175], v[166:167], v[172:173]
	v_mov_b32_e32 v169, v166
	v_mov_b32_e32 v171, v175
	v_pk_add_f32 v[176:177], v[168:169], v[170:171] neg_lo:[0,1] neg_hi:[0,1]
	v_pk_add_f32 v[168:169], v[168:169], v[170:171]
	v_mov_b32_e32 v172, v173
	v_pk_add_f32 v[170:171], v[168:169], v[166:167] op_sel:[1,0] op_sel_hi:[0,1] neg_lo:[0,1] neg_hi:[0,1]
	v_pk_add_f32 v[178:179], v[174:175], v[170:171] op_sel_hi:[1,0] neg_lo:[0,1] neg_hi:[0,1]
	v_mov_b32_e32 v174, v175
	v_mov_b32_e32 v175, v169
	v_pk_mov_b32 v[170:171], v[166:167], v[170:171] op_sel:[1,0]
	v_mov_b32_e32 v173, v166
	v_pk_add_f32 v[170:171], v[174:175], v[170:171] neg_lo:[0,1] neg_hi:[0,1]
	v_mov_b32_e32 v178, v176
	v_pk_add_f32 v[166:167], v[172:173], v[170:171] neg_lo:[0,1] neg_hi:[0,1]
	v_mov_b32_e32 v177, v169
	v_pk_add_f32 v[170:171], v[178:179], v[166:167]
	v_cmp_neq_f32_e32 vcc, s31, v146
	v_pk_add_f32 v[172:173], v[170:171], v[170:171] op_sel:[0,1] op_sel_hi:[1,0]
	s_mov_b32 s31, 0x33800000
	v_pk_add_f32 v[168:169], v[168:169], v[172:173] op_sel:[1,0] op_sel_hi:[0,1]
	v_mov_b32_e32 v171, v168
	v_pk_add_f32 v[174:175], v[170:171], v[176:177] neg_lo:[0,1] neg_hi:[0,1]
	v_mov_b32_e32 v167, v172
	v_sub_f32_e32 v169, v170, v174
	v_pk_add_f32 v[166:167], v[166:167], v[174:175] neg_lo:[0,1] neg_hi:[0,1]
	v_sub_f32_e32 v169, v176, v169
	v_add_f32_e32 v166, v166, v169
	v_add_f32_e32 v166, v166, v167
	v_add_f32_e32 v166, v168, v166
	v_cndmask_b32_e32 v166, v237, v166, vcc
	v_cmp_ngt_f32_e32 vcc, -1.0, v146
	s_nop 1
	v_cndmask_b32_e32 v166, v238, v166, vcc
	v_cmp_neq_f32_e32 vcc, -1.0, v146
	s_nop 1
	v_cndmask_b32_e32 v166, v239, v166, vcc
	v_cmp_lt_f32_e64 vcc, |v146|, s31
	s_nop 1
	v_cndmask_b32_e32 v146, v166, v146, vcc
	v_sub_f32_e32 v146, v0, v146

.LBB0_682:
	s_or_b64 exec, exec, s[4:5]
	v_lshlrev_b32_e32 v168, 2, v181
	v_lshlrev_b32_e32 v0, 2, v182
	v_ashrrev_i32_e32 v169, 31, v168
	v_lshl_add_u64 v[166:167], s[84:85], 0, v[0:1]
	v_lshlrev_b64 v[170:171], 13, v[168:169]
	v_lshl_add_u64 v[170:171], v[166:167], 0, v[170:171]
	v_readlane_b32 s4, v254, 26
	global_store_dword v[170:171], v146, off
	v_readlane_b32 s5, v254, 27
	s_nop 4
	s_load_dword s4, s[4:5], 0x4
	s_waitcnt lgkmcnt(0)
	v_mov_b32_e32 v0, s4
	v_add_f32_e32 v0, v147, v0
	v_cmp_nlt_f32_e32 vcc, 0, v0
	s_and_saveexec_b64 s[4:5], vcc
	s_xor_b64 s[4:5], exec, s[4:5]
	s_cbranch_execz .LBB0_684
	v_mul_f32_e32 v146, 0x3fb8aa3b, v0
	v_exp_f32_e32 v169, v146
	s_mov_b32 s31, 0x3f2aaaab
	v_add_f32_e32 v170, 1.0, v169
	v_frexp_mant_f32_e32 v172, v170
	v_cvt_f64_f32_e32 v[146:147], v170
	v_frexp_exp_i32_f64_e32 v146, v[146:147]
	v_cmp_gt_f32_e32 vcc, s31, v172
	v_add_f32_e32 v171, -1.0, v170
	v_sub_f32_e32 v173, v171, v170
	v_subbrev_co_u32_e32 v176, vcc, 0, v146, vcc
	v_sub_u32_e32 v146, 0, v176
	v_sub_f32_e32 v171, v169, v171
	v_add_f32_e32 v173, 1.0, v173
	v_ldexp_f32 v147, v170, v146
	v_add_f32_e32 v171, v171, v173
	v_add_f32_e32 v170, -1.0, v147
	v_add_f32_e32 v172, 1.0, v147
	v_ldexp_f32 v146, v171, v146
	v_add_f32_e32 v171, 1.0, v170
	v_add_f32_e32 v173, -1.0, v172
	v_sub_f32_e32 v171, v147, v171
	v_sub_f32_e32 v147, v147, v173
	v_add_f32_e32 v171, v146, v171
	v_add_f32_e32 v146, v146, v147
	v_add_f32_e32 v177, v172, v146
	v_rcp_f32_e32 v179, v177
	v_sub_f32_e32 v147, v177, v172
	v_sub_f32_e32 v178, v146, v147
	v_add_f32_e32 v147, v170, v171
	v_mul_f32_e32 v181, v147, v179
	v_sub_f32_e32 v146, v147, v170
	v_mul_f32_e32 v170, v177, v181
	v_fma_f32 v172, v181, v177, -v170
	v_fmac_f32_e32 v172, v181, v178
	v_sub_f32_e32 v180, v171, v146
	v_add_f32_e32 v146, v170, v172
	v_sub_f32_e32 v171, v147, v146
	v_pk_add_f32 v[174:175], v[146:147], v[170:171] neg_lo:[0,1] neg_hi:[0,1]
	v_mov_b32_e32 v173, v146
	v_pk_add_f32 v[146:147], v[174:175], v[172:173] neg_lo:[0,1] neg_hi:[0,1]
	s_mov_b32 s31, 0x3f317218
	v_add_f32_e32 v147, v180, v147
	v_add_f32_e32 v146, v146, v147
	v_add_f32_e32 v147, v171, v146
	v_mul_f32_e32 v180, v179, v147
	v_mul_f32_e32 v170, v177, v180
	v_fma_f32 v172, v180, v177, -v170
	v_fmac_f32_e32 v172, v180, v178
	v_sub_f32_e32 v171, v171, v147
	v_add_f32_e32 v177, v146, v171
	v_add_f32_e32 v146, v170, v172
	v_sub_f32_e32 v171, v147, v146
	v_pk_add_f32 v[174:175], v[146:147], v[170:171] neg_lo:[0,1] neg_hi:[0,1]
	v_mov_b32_e32 v173, v146
	v_pk_add_f32 v[146:147], v[174:175], v[172:173] neg_lo:[0,1] neg_hi:[0,1]
	s_nop 0
	v_add_f32_e32 v147, v177, v147
	v_add_f32_e32 v146, v146, v147
	v_add_f32_e32 v147, v181, v180
	v_add_f32_e32 v146, v171, v146
	v_sub_f32_e32 v170, v147, v181
	v_mul_f32_e32 v146, v179, v146
	v_sub_f32_e32 v170, v180, v170
	v_add_f32_e32 v170, v170, v146
	v_add_f32_e32 v172, v147, v170
	v_mul_f32_e32 v173, v172, v172
	v_fmamk_f32 v146, v173, 0x3e9b6dac, v236
	v_fmaak_f32 v205, v173, v146, 0x3f2aaada
	v_cvt_f32_i32_e32 v146, v176
	v_sub_f32_e32 v147, v172, v147
	v_sub_f32_e32 v147, v170, v147
	v_ldexp_f32 v174, v147, 1
	v_mul_f32_e32 v147, v172, v173
	v_ldexp_f32 v171, v172, 1
	v_pk_mul_f32 v[172:173], v[146:147], v[204:205]
	s_nop 0
	v_fma_f32 v170, v146, s31, -v172
	v_fmac_f32_e32 v170, 0xb102e308, v146
	v_pk_add_f32 v[146:147], v[172:173], v[170:171]
	s_mov_b32 s31, 0x7f800000
	v_sub_f32_e32 v171, v147, v171
	v_sub_f32_e32 v171, v173, v171
	v_add_f32_e32 v175, v174, v171
	v_mov_b32_e32 v174, v172
	v_pk_add_f32 v[172:173], v[146:147], v[172:173] neg_lo:[0,1] neg_hi:[0,1]
	v_pk_add_f32 v[176:177], v[146:147], v[174:175]
	v_mov_b32_e32 v171, v146
	v_mov_b32_e32 v173, v177
	v_pk_add_f32 v[178:179], v[170:171], v[172:173] neg_lo:[0,1] neg_hi:[0,1]
	v_pk_add_f32 v[170:171], v[170:171], v[172:173]
	v_mov_b32_e32 v174, v175
	v_pk_add_f32 v[172:173], v[170:171], v[146:147] op_sel:[1,0] op_sel_hi:[0,1] neg_lo:[0,1] neg_hi:[0,1]
	v_pk_add_f32 v[180:181], v[176:177], v[172:173] op_sel_hi:[1,0] neg_lo:[0,1] neg_hi:[0,1]
	v_mov_b32_e32 v176, v177
	v_mov_b32_e32 v177, v171
	v_pk_mov_b32 v[172:173], v[146:147], v[172:173] op_sel:[1,0]
	v_mov_b32_e32 v175, v146
	v_pk_add_f32 v[172:173], v[176:177], v[172:173] neg_lo:[0,1] neg_hi:[0,1]
	v_mov_b32_e32 v180, v178
	v_pk_add_f32 v[146:147], v[174:175], v[172:173] neg_lo:[0,1] neg_hi:[0,1]
	v_mov_b32_e32 v179, v171
	v_pk_add_f32 v[172:173], v[180:181], v[146:147]
	v_cmp_neq_f32_e32 vcc, s31, v169
	v_pk_add_f32 v[174:175], v[172:173], v[172:173] op_sel:[0,1] op_sel_hi:[1,0]
	s_mov_b32 s31, 0x33800000
	v_pk_add_f32 v[170:171], v[170:171], v[174:175] op_sel:[1,0] op_sel_hi:[0,1]
	v_mov_b32_e32 v173, v170
	v_pk_add_f32 v[176:177], v[172:173], v[178:179] neg_lo:[0,1] neg_hi:[0,1]
	v_mov_b32_e32 v147, v174
	v_sub_f32_e32 v171, v172, v176
	v_pk_add_f32 v[146:147], v[146:147], v[176:177] neg_lo:[0,1] neg_hi:[0,1]
	v_sub_f32_e32 v171, v178, v171
	v_add_f32_e32 v146, v146, v171
	v_add_f32_e32 v146, v146, v147
	v_add_f32_e32 v146, v170, v146
	v_cndmask_b32_e32 v146, v237, v146, vcc
	v_cmp_ngt_f32_e32 vcc, -1.0, v169
	s_nop 1
	v_cndmask_b32_e32 v146, v238, v146, vcc
	v_cmp_neq_f32_e32 vcc, -1.0, v169
	s_nop 1
	v_cndmask_b32_e32 v146, v239, v146, vcc
	v_cmp_lt_f32_e64 vcc, |v169|, s31
	s_nop 1
	v_cndmask_b32_e32 v146, v146, v169, vcc
	v_sub_f32_e32 v146, v0, v146

.LBB0_686:
	s_or_b64 exec, exec, s[4:5]
	v_or_b32_e32 v170, 1, v168
	v_ashrrev_i32_e32 v171, 31, v170
	v_lshlrev_b64 v[170:171], 13, v[170:171]
	v_lshl_add_u64 v[170:171], v[166:167], 0, v[170:171]
	v_readlane_b32 s4, v254, 26
	global_store_dword v[170:171], v146, off
	v_readlane_b32 s5, v254, 27
	s_nop 4
	s_load_dword s4, s[4:5], 0x8
	s_waitcnt lgkmcnt(0)
	v_mov_b32_e32 v0, s4
	v_add_f32_e32 v0, v148, v0
	v_cmp_nlt_f32_e32 vcc, 0, v0
	s_and_saveexec_b64 s[4:5], vcc
	s_xor_b64 s[4:5], exec, s[4:5]
	s_cbranch_execz .LBB0_688
	v_mul_f32_e32 v146, 0x3fb8aa3b, v0
	v_exp_f32_e32 v148, v146
	s_mov_b32 s31, 0x3f2aaaab
	v_add_f32_e32 v169, 1.0, v148
	v_frexp_mant_f32_e32 v171, v169
	v_cvt_f64_f32_e32 v[146:147], v169
	v_frexp_exp_i32_f64_e32 v146, v[146:147]
	v_cmp_gt_f32_e32 vcc, s31, v171
	v_add_f32_e32 v170, -1.0, v169
	v_sub_f32_e32 v172, v170, v169
	v_subbrev_co_u32_e32 v176, vcc, 0, v146, vcc
	v_sub_u32_e32 v146, 0, v176
	v_sub_f32_e32 v170, v148, v170
	v_add_f32_e32 v172, 1.0, v172
	v_ldexp_f32 v147, v169, v146
	v_add_f32_e32 v170, v170, v172
	v_add_f32_e32 v169, -1.0, v147
	v_add_f32_e32 v171, 1.0, v147
	v_ldexp_f32 v146, v170, v146
	v_add_f32_e32 v170, 1.0, v169
	v_add_f32_e32 v172, -1.0, v171
	v_sub_f32_e32 v170, v147, v170
	v_sub_f32_e32 v147, v147, v172
	v_add_f32_e32 v170, v146, v170
	v_add_f32_e32 v146, v146, v147
	v_add_f32_e32 v177, v171, v146
	v_rcp_f32_e32 v179, v177
	v_sub_f32_e32 v147, v177, v171
	v_sub_f32_e32 v178, v146, v147
	v_add_f32_e32 v147, v169, v170
	v_sub_f32_e32 v146, v147, v169
	v_mul_f32_e32 v180, v147, v179
	v_sub_f32_e32 v169, v170, v146
	v_mul_f32_e32 v170, v177, v180
	v_fma_f32 v172, v180, v177, -v170
	v_fmac_f32_e32 v172, v180, v178
	v_add_f32_e32 v146, v170, v172
	v_sub_f32_e32 v171, v147, v146
	v_pk_add_f32 v[174:175], v[146:147], v[170:171] neg_lo:[0,1] neg_hi:[0,1]
	v_mov_b32_e32 v173, v146
	v_pk_add_f32 v[146:147], v[174:175], v[172:173] neg_lo:[0,1] neg_hi:[0,1]
	s_mov_b32 s31, 0x3f317218
	v_add_f32_e32 v147, v169, v147
	v_add_f32_e32 v146, v146, v147
	v_add_f32_e32 v147, v171, v146
	v_mul_f32_e32 v169, v179, v147
	v_mul_f32_e32 v170, v177, v169
	v_fma_f32 v172, v169, v177, -v170
	v_fmac_f32_e32 v172, v169, v178
	v_sub_f32_e32 v171, v171, v147
	v_add_f32_e32 v177, v146, v171
	v_add_f32_e32 v146, v170, v172
	v_sub_f32_e32 v171, v147, v146
	v_pk_add_f32 v[174:175], v[146:147], v[170:171] neg_lo:[0,1] neg_hi:[0,1]
	v_mov_b32_e32 v173, v146
	v_pk_add_f32 v[146:147], v[174:175], v[172:173] neg_lo:[0,1] neg_hi:[0,1]
	s_nop 0
	v_add_f32_e32 v147, v177, v147
	v_add_f32_e32 v146, v146, v147
	v_add_f32_e32 v147, v180, v169
	v_add_f32_e32 v146, v171, v146
	v_sub_f32_e32 v170, v147, v180
	v_mul_f32_e32 v146, v179, v146
	v_sub_f32_e32 v169, v169, v170
	v_add_f32_e32 v169, v169, v146
	v_add_f32_e32 v170, v147, v169
	v_mul_f32_e32 v172, v170, v170
	v_fmamk_f32 v146, v172, 0x3e9b6dac, v236
	v_fmaak_f32 v205, v172, v146, 0x3f2aaada
	v_cvt_f32_i32_e32 v146, v176
	v_sub_f32_e32 v147, v170, v147
	v_sub_f32_e32 v147, v169, v147
	v_ldexp_f32 v169, v147, 1
	v_mul_f32_e32 v147, v170, v172
	v_pk_mul_f32 v[172:173], v[146:147], v[204:205]
	v_ldexp_f32 v171, v170, 1
	v_fma_f32 v170, v146, s31, -v172
	v_fmac_f32_e32 v170, 0xb102e308, v146
	v_pk_add_f32 v[146:147], v[172:173], v[170:171]
	v_mov_b32_e32 v174, v172
	v_sub_f32_e32 v171, v147, v171
	v_sub_f32_e32 v171, v173, v171
	v_add_f32_e32 v175, v169, v171
	v_pk_add_f32 v[172:173], v[146:147], v[172:173] neg_lo:[0,1] neg_hi:[0,1]
	v_pk_add_f32 v[176:177], v[146:147], v[174:175]
	v_mov_b32_e32 v171, v146
	v_mov_b32_e32 v173, v177
	v_pk_add_f32 v[178:179], v[170:171], v[172:173] neg_lo:[0,1] neg_hi:[0,1]
	v_pk_add_f32 v[170:171], v[170:171], v[172:173]
	v_mov_b32_e32 v174, v175
	v_pk_add_f32 v[172:173], v[170:171], v[146:147] op_sel:[1,0] op_sel_hi:[0,1] neg_lo:[0,1] neg_hi:[0,1]
	v_pk_add_f32 v[180:181], v[176:177], v[172:173] op_sel_hi:[1,0] neg_lo:[0,1] neg_hi:[0,1]
	v_mov_b32_e32 v176, v177
	v_mov_b32_e32 v177, v171
	v_pk_mov_b32 v[172:173], v[146:147], v[172:173] op_sel:[1,0]
	v_mov_b32_e32 v175, v146
	v_pk_add_f32 v[172:173], v[176:177], v[172:173] neg_lo:[0,1] neg_hi:[0,1]
	v_mov_b32_e32 v180, v178
	v_pk_add_f32 v[146:147], v[174:175], v[172:173] neg_lo:[0,1] neg_hi:[0,1]
	v_mov_b32_e32 v179, v171
	v_pk_add_f32 v[172:173], v[180:181], v[146:147]
	s_mov_b32 s31, 0x7f800000
	v_pk_add_f32 v[174:175], v[172:173], v[172:173] op_sel:[0,1] op_sel_hi:[1,0]
	v_cmp_neq_f32_e32 vcc, s31, v148
	v_pk_add_f32 v[170:171], v[170:171], v[174:175] op_sel:[1,0] op_sel_hi:[0,1]
	v_mov_b32_e32 v173, v170
	v_pk_add_f32 v[176:177], v[172:173], v[178:179] neg_lo:[0,1] neg_hi:[0,1]
	v_mov_b32_e32 v147, v174
	v_sub_f32_e32 v169, v172, v176
	v_pk_add_f32 v[146:147], v[146:147], v[176:177] neg_lo:[0,1] neg_hi:[0,1]
	v_sub_f32_e32 v169, v178, v169
	v_add_f32_e32 v146, v146, v169
	v_add_f32_e32 v146, v146, v147
	v_add_f32_e32 v146, v170, v146
	v_cndmask_b32_e32 v146, v237, v146, vcc
	v_cmp_ngt_f32_e32 vcc, -1.0, v148
	s_mov_b32 s31, 0x33800000
	s_nop 0
	v_cndmask_b32_e32 v146, v238, v146, vcc
	v_cmp_neq_f32_e32 vcc, -1.0, v148
	s_nop 1
	v_cndmask_b32_e32 v146, v239, v146, vcc
	v_cmp_lt_f32_e64 vcc, |v148|, s31
	s_nop 1
	v_cndmask_b32_e32 v146, v146, v148, vcc
	v_sub_f32_e32 v146, v0, v146

.LBB0_690:
	s_or_b64 exec, exec, s[4:5]
	v_or_b32_e32 v170, 2, v168
	v_ashrrev_i32_e32 v171, 31, v170
	v_lshlrev_b64 v[170:171], 13, v[170:171]
	v_lshl_add_u64 v[170:171], v[166:167], 0, v[170:171]
	v_readlane_b32 s4, v254, 26
	global_store_dword v[170:171], v146, off
	v_readlane_b32 s5, v254, 27
	s_nop 4
	s_load_dword s4, s[4:5], 0xc
	s_waitcnt lgkmcnt(0)
	v_mov_b32_e32 v0, s4
	v_add_f32_e32 v0, v149, v0
	v_cmp_nlt_f32_e32 vcc, 0, v0
	s_and_saveexec_b64 s[4:5], vcc
	s_xor_b64 s[4:5], exec, s[4:5]
	s_cbranch_execz .LBB0_692
	v_mul_f32_e32 v146, 0x3fb8aa3b, v0
	v_exp_f32_e32 v169, v146
	s_mov_b32 s31, 0x3f2aaaab
	v_add_f32_e32 v148, 1.0, v169
	v_frexp_mant_f32_e32 v170, v148
	v_cvt_f64_f32_e32 v[146:147], v148
	v_frexp_exp_i32_f64_e32 v146, v[146:147]
	v_cmp_gt_f32_e32 vcc, s31, v170
	v_add_f32_e32 v149, -1.0, v148
	v_sub_f32_e32 v171, v149, v148
	v_subbrev_co_u32_e32 v174, vcc, 0, v146, vcc
	v_sub_u32_e32 v146, 0, v174
	v_sub_f32_e32 v149, v169, v149
	v_add_f32_e32 v171, 1.0, v171
	v_ldexp_f32 v147, v148, v146
	v_add_f32_e32 v149, v149, v171
	v_add_f32_e32 v148, -1.0, v147
	v_add_f32_e32 v170, 1.0, v147
	v_ldexp_f32 v146, v149, v146
	v_add_f32_e32 v149, 1.0, v148
	v_add_f32_e32 v171, -1.0, v170
	v_sub_f32_e32 v149, v147, v149
	v_sub_f32_e32 v147, v147, v171
	v_add_f32_e32 v149, v146, v149
	v_add_f32_e32 v146, v146, v147
	v_add_f32_e32 v175, v170, v146
	v_rcp_f32_e32 v177, v175
	v_sub_f32_e32 v147, v175, v170
	v_sub_f32_e32 v176, v146, v147
	v_add_f32_e32 v147, v148, v149
	v_mul_f32_e32 v179, v147, v177
	v_sub_f32_e32 v146, v147, v148
	v_mul_f32_e32 v148, v175, v179
	v_fma_f32 v170, v179, v175, -v148
	v_fmac_f32_e32 v170, v179, v176
	v_sub_f32_e32 v178, v149, v146
	v_add_f32_e32 v146, v148, v170
	v_sub_f32_e32 v149, v147, v146
	v_pk_add_f32 v[172:173], v[146:147], v[148:149] neg_lo:[0,1] neg_hi:[0,1]
	v_mov_b32_e32 v171, v146
	v_pk_add_f32 v[146:147], v[172:173], v[170:171] neg_lo:[0,1] neg_hi:[0,1]
	s_mov_b32 s31, 0x3f317218
	v_add_f32_e32 v147, v178, v147
	v_add_f32_e32 v146, v146, v147
	v_add_f32_e32 v147, v149, v146
	v_mul_f32_e32 v178, v177, v147
	v_mul_f32_e32 v148, v175, v178
	v_fma_f32 v170, v178, v175, -v148
	v_fmac_f32_e32 v170, v178, v176
	v_sub_f32_e32 v149, v149, v147
	v_add_f32_e32 v175, v146, v149
	v_add_f32_e32 v146, v148, v170
	v_sub_f32_e32 v149, v147, v146
	v_pk_add_f32 v[172:173], v[146:147], v[148:149] neg_lo:[0,1] neg_hi:[0,1]
	v_mov_b32_e32 v171, v146
	v_pk_add_f32 v[146:147], v[172:173], v[170:171] neg_lo:[0,1] neg_hi:[0,1]
	s_nop 0
	v_add_f32_e32 v147, v175, v147
	v_add_f32_e32 v146, v146, v147
	v_add_f32_e32 v147, v179, v178
	v_add_f32_e32 v146, v149, v146
	v_sub_f32_e32 v148, v147, v179
	v_mul_f32_e32 v146, v177, v146
	v_sub_f32_e32 v148, v178, v148
	v_add_f32_e32 v148, v148, v146
	v_add_f32_e32 v170, v147, v148
	v_mul_f32_e32 v171, v170, v170
	v_fmamk_f32 v146, v171, 0x3e9b6dac, v236
	v_fmaak_f32 v205, v171, v146, 0x3f2aaada
	v_cvt_f32_i32_e32 v146, v174
	v_sub_f32_e32 v147, v170, v147
	v_sub_f32_e32 v147, v148, v147
	v_ldexp_f32 v172, v147, 1
	v_mul_f32_e32 v147, v170, v171
	v_ldexp_f32 v149, v170, 1
	v_pk_mul_f32 v[170:171], v[146:147], v[204:205]
	s_nop 0
	v_fma_f32 v148, v146, s31, -v170
	v_fmac_f32_e32 v148, 0xb102e308, v146
	v_pk_add_f32 v[146:147], v[170:171], v[148:149]
	s_mov_b32 s31, 0x7f800000
	v_sub_f32_e32 v149, v147, v149
	v_sub_f32_e32 v149, v171, v149
	v_add_f32_e32 v173, v172, v149
	v_mov_b32_e32 v172, v170
	v_pk_add_f32 v[170:171], v[146:147], v[170:171] neg_lo:[0,1] neg_hi:[0,1]
	v_pk_add_f32 v[174:175], v[146:147], v[172:173]
	v_mov_b32_e32 v149, v146
	v_mov_b32_e32 v171, v175
	v_pk_add_f32 v[176:177], v[148:149], v[170:171] neg_lo:[0,1] neg_hi:[0,1]
	v_pk_add_f32 v[148:149], v[148:149], v[170:171]
	v_mov_b32_e32 v172, v173
	v_pk_add_f32 v[170:171], v[148:149], v[146:147] op_sel:[1,0] op_sel_hi:[0,1] neg_lo:[0,1] neg_hi:[0,1]
	v_pk_add_f32 v[178:179], v[174:175], v[170:171] op_sel_hi:[1,0] neg_lo:[0,1] neg_hi:[0,1]
	v_mov_b32_e32 v174, v175
	v_mov_b32_e32 v175, v149
	v_pk_mov_b32 v[170:171], v[146:147], v[170:171] op_sel:[1,0]
	v_mov_b32_e32 v173, v146
	v_pk_add_f32 v[170:171], v[174:175], v[170:171] neg_lo:[0,1] neg_hi:[0,1]
	v_mov_b32_e32 v178, v176
	v_pk_add_f32 v[146:147], v[172:173], v[170:171] neg_lo:[0,1] neg_hi:[0,1]
	v_mov_b32_e32 v177, v149
	v_pk_add_f32 v[170:171], v[178:179], v[146:147]
	v_cmp_neq_f32_e32 vcc, s31, v169
	v_pk_add_f32 v[172:173], v[170:171], v[170:171] op_sel:[0,1] op_sel_hi:[1,0]
	s_mov_b32 s31, 0x33800000
	v_pk_add_f32 v[148:149], v[148:149], v[172:173] op_sel:[1,0] op_sel_hi:[0,1]
	v_mov_b32_e32 v171, v148
	v_pk_add_f32 v[174:175], v[170:171], v[176:177] neg_lo:[0,1] neg_hi:[0,1]
	v_mov_b32_e32 v147, v172
	v_sub_f32_e32 v149, v170, v174
	v_pk_add_f32 v[146:147], v[146:147], v[174:175] neg_lo:[0,1] neg_hi:[0,1]
	v_sub_f32_e32 v149, v176, v149
	v_add_f32_e32 v146, v146, v149
	v_add_f32_e32 v146, v146, v147
	v_add_f32_e32 v146, v148, v146
	v_cndmask_b32_e32 v146, v237, v146, vcc
	v_cmp_ngt_f32_e32 vcc, -1.0, v169
	s_nop 1
	v_cndmask_b32_e32 v146, v238, v146, vcc
	v_cmp_neq_f32_e32 vcc, -1.0, v169
	s_nop 1
	v_cndmask_b32_e32 v146, v239, v146, vcc
	v_cmp_lt_f32_e64 vcc, |v169|, s31
	s_nop 1
	v_cndmask_b32_e32 v146, v146, v169, vcc
	v_sub_f32_e32 v146, v0, v146

.LBB0_718:
	s_and_saveexec_b64 s[4:5], s[10:11]
	s_xor_b64 s[18:19], exec, s[4:5]
	s_cbranch_execz .LBB0_736
	v_readlane_b32 s4, v254, 26
	v_readlane_b32 s5, v254, 27
	s_waitcnt lgkmcnt(0)
	s_nop 3
	s_load_dword s4, s[4:5], 0x0
	s_waitcnt lgkmcnt(0)
	v_mov_b32_e32 v0, s4
	v_add_f32_e32 v0, v122, v0
	v_cmp_nlt_f32_e32 vcc, 0, v0
	s_and_saveexec_b64 s[4:5], vcc
	s_xor_b64 s[4:5], exec, s[4:5]
	s_cbranch_execz .LBB0_721
	v_mul_f32_e32 v122, 0x3fb8aa3b, v0
	v_exp_f32_e32 v122, v122
	s_mov_b32 s31, 0x3f2aaaab
	v_add_f32_e32 v128, 1.0, v122
	v_frexp_mant_f32_e32 v146, v128
	v_cvt_f64_f32_e32 v[126:127], v128
	v_frexp_exp_i32_f64_e32 v126, v[126:127]
	v_cmp_gt_f32_e32 vcc, s31, v146
	v_add_f32_e32 v129, -1.0, v128
	v_sub_f32_e32 v147, v129, v128
	v_subbrev_co_u32_e32 v150, vcc, 0, v126, vcc
	v_sub_u32_e32 v126, 0, v150
	v_sub_f32_e32 v129, v122, v129
	v_add_f32_e32 v147, 1.0, v147
	v_ldexp_f32 v127, v128, v126
	v_add_f32_e32 v129, v129, v147
	v_add_f32_e32 v128, -1.0, v127
	v_add_f32_e32 v146, 1.0, v127
	v_ldexp_f32 v126, v129, v126
	v_add_f32_e32 v129, 1.0, v128
	v_add_f32_e32 v147, -1.0, v146
	v_sub_f32_e32 v129, v127, v129
	v_sub_f32_e32 v127, v127, v147
	v_add_f32_e32 v129, v126, v129
	v_add_f32_e32 v126, v126, v127
	v_add_f32_e32 v151, v146, v126
	v_rcp_f32_e32 v153, v151
	v_sub_f32_e32 v127, v151, v146
	v_sub_f32_e32 v152, v126, v127
	v_add_f32_e32 v127, v128, v129
	v_mul_f32_e32 v155, v127, v153
	v_sub_f32_e32 v126, v127, v128
	v_mul_f32_e32 v128, v151, v155
	v_fma_f32 v146, v155, v151, -v128
	v_fmac_f32_e32 v146, v155, v152
	v_sub_f32_e32 v154, v129, v126
	v_add_f32_e32 v126, v128, v146
	v_sub_f32_e32 v129, v127, v126
	v_pk_add_f32 v[148:149], v[126:127], v[128:129] neg_lo:[0,1] neg_hi:[0,1]
	v_mov_b32_e32 v147, v126
	v_pk_add_f32 v[126:127], v[148:149], v[146:147] neg_lo:[0,1] neg_hi:[0,1]
	s_mov_b32 s31, 0x3f317218
	v_add_f32_e32 v127, v154, v127
	v_add_f32_e32 v126, v126, v127
	v_add_f32_e32 v127, v129, v126
	v_mul_f32_e32 v154, v153, v127
	v_mul_f32_e32 v128, v151, v154
	v_fma_f32 v146, v154, v151, -v128
	v_fmac_f32_e32 v146, v154, v152
	v_sub_f32_e32 v129, v129, v127
	v_add_f32_e32 v151, v126, v129
	v_add_f32_e32 v126, v128, v146
	v_sub_f32_e32 v129, v127, v126
	v_pk_add_f32 v[148:149], v[126:127], v[128:129] neg_lo:[0,1] neg_hi:[0,1]
	v_mov_b32_e32 v147, v126
	v_pk_add_f32 v[126:127], v[148:149], v[146:147] neg_lo:[0,1] neg_hi:[0,1]
	s_nop 0
	v_add_f32_e32 v127, v151, v127
	v_add_f32_e32 v126, v126, v127
	v_add_f32_e32 v127, v155, v154
	v_add_f32_e32 v126, v129, v126
	v_sub_f32_e32 v128, v127, v155
	v_mul_f32_e32 v126, v153, v126
	v_sub_f32_e32 v128, v154, v128
	v_add_f32_e32 v128, v128, v126
	v_add_f32_e32 v146, v127, v128
	v_mul_f32_e32 v147, v146, v146
	v_fmamk_f32 v126, v147, 0x3e9b6dac, v236
	v_fmaak_f32 v205, v147, v126, 0x3f2aaada
	v_cvt_f32_i32_e32 v126, v150
	v_sub_f32_e32 v127, v146, v127
	v_sub_f32_e32 v127, v128, v127
	v_ldexp_f32 v148, v127, 1
	v_mul_f32_e32 v127, v146, v147
	v_ldexp_f32 v129, v146, 1
	v_pk_mul_f32 v[146:147], v[126:127], v[204:205]
	s_nop 0
	v_fma_f32 v128, v126, s31, -v146
	v_fmac_f32_e32 v128, 0xb102e308, v126
	v_pk_add_f32 v[126:127], v[146:147], v[128:129]
	s_mov_b32 s31, 0x7f800000
	v_sub_f32_e32 v129, v127, v129
	v_sub_f32_e32 v129, v147, v129
	v_add_f32_e32 v149, v148, v129
	v_mov_b32_e32 v148, v146
	v_pk_add_f32 v[146:147], v[126:127], v[146:147] neg_lo:[0,1] neg_hi:[0,1]
	v_pk_add_f32 v[150:151], v[126:127], v[148:149]
	v_mov_b32_e32 v129, v126
	v_mov_b32_e32 v147, v151
	v_pk_add_f32 v[152:153], v[128:129], v[146:147] neg_lo:[0,1] neg_hi:[0,1]
	v_pk_add_f32 v[128:129], v[128:129], v[146:147]
	v_mov_b32_e32 v148, v149
	v_pk_add_f32 v[146:147], v[128:129], v[126:127] op_sel:[1,0] op_sel_hi:[0,1] neg_lo:[0,1] neg_hi:[0,1]
	v_pk_add_f32 v[154:155], v[150:151], v[146:147] op_sel_hi:[1,0] neg_lo:[0,1] neg_hi:[0,1]
	v_mov_b32_e32 v150, v151
	v_mov_b32_e32 v151, v129
	v_pk_mov_b32 v[146:147], v[126:127], v[146:147] op_sel:[1,0]
	v_mov_b32_e32 v149, v126
	v_pk_add_f32 v[146:147], v[150:151], v[146:147] neg_lo:[0,1] neg_hi:[0,1]
	v_mov_b32_e32 v154, v152
	v_pk_add_f32 v[126:127], v[148:149], v[146:147] neg_lo:[0,1] neg_hi:[0,1]
	v_mov_b32_e32 v153, v129
	v_pk_add_f32 v[146:147], v[154:155], v[126:127]
	v_cmp_neq_f32_e32 vcc, s31, v122
	v_pk_add_f32 v[148:149], v[146:147], v[146:147] op_sel:[0,1] op_sel_hi:[1,0]
	s_mov_b32 s31, 0x33800000
	v_pk_add_f32 v[128:129], v[128:129], v[148:149] op_sel:[1,0] op_sel_hi:[0,1]
	v_mov_b32_e32 v147, v128
	v_pk_add_f32 v[150:151], v[146:147], v[152:153] neg_lo:[0,1] neg_hi:[0,1]
	v_mov_b32_e32 v127, v148
	v_sub_f32_e32 v129, v146, v150
	v_pk_add_f32 v[126:127], v[126:127], v[150:151] neg_lo:[0,1] neg_hi:[0,1]
	v_sub_f32_e32 v129, v152, v129
	v_add_f32_e32 v126, v126, v129
	v_add_f32_e32 v126, v126, v127
	v_add_f32_e32 v126, v128, v126
	v_cndmask_b32_e32 v126, v237, v126, vcc
	v_cmp_ngt_f32_e32 vcc, -1.0, v122
	s_nop 1
	v_cndmask_b32_e32 v126, v238, v126, vcc
	v_cmp_neq_f32_e32 vcc, -1.0, v122
	s_nop 1
	v_cndmask_b32_e32 v126, v239, v126, vcc
	v_cmp_lt_f32_e64 vcc, |v122|, s31
	s_nop 1
	v_cndmask_b32_e32 v122, v126, v122, vcc
	v_sub_f32_e32 v122, v0, v122

.LBB0_723:
	s_or_b64 exec, exec, s[4:5]
	v_lshlrev_b32_e32 v128, 2, v156
	v_lshlrev_b32_e32 v0, 2, v157
	v_ashrrev_i32_e32 v129, 31, v128
	v_lshl_add_u64 v[126:127], s[84:85], 0, v[0:1]
	v_lshlrev_b64 v[146:147], 13, v[128:129]
	v_lshl_add_u64 v[146:147], v[126:127], 0, v[146:147]
	v_readlane_b32 s4, v254, 26
	global_store_dword v[146:147], v122, off
	v_readlane_b32 s5, v254, 27
	s_nop 4
	s_load_dword s4, s[4:5], 0x4
	s_waitcnt lgkmcnt(0)
	v_mov_b32_e32 v0, s4
	v_add_f32_e32 v0, v123, v0
	v_cmp_nlt_f32_e32 vcc, 0, v0
	s_and_saveexec_b64 s[4:5], vcc
	s_xor_b64 s[4:5], exec, s[4:5]
	s_cbranch_execz .LBB0_725
	v_mul_f32_e32 v122, 0x3fb8aa3b, v0
	v_exp_f32_e32 v129, v122
	s_mov_b32 s31, 0x3f2aaaab
	v_add_f32_e32 v146, 1.0, v129
	v_frexp_mant_f32_e32 v148, v146
	v_cvt_f64_f32_e32 v[122:123], v146
	v_frexp_exp_i32_f64_e32 v122, v[122:123]
	v_cmp_gt_f32_e32 vcc, s31, v148
	v_add_f32_e32 v147, -1.0, v146
	v_sub_f32_e32 v149, v147, v146
	v_subbrev_co_u32_e32 v152, vcc, 0, v122, vcc
	v_sub_u32_e32 v122, 0, v152
	v_sub_f32_e32 v147, v129, v147
	v_add_f32_e32 v149, 1.0, v149
	v_ldexp_f32 v123, v146, v122
	v_add_f32_e32 v147, v147, v149
	v_add_f32_e32 v146, -1.0, v123
	v_add_f32_e32 v148, 1.0, v123
	v_ldexp_f32 v122, v147, v122
	v_add_f32_e32 v147, 1.0, v146
	v_add_f32_e32 v149, -1.0, v148
	v_sub_f32_e32 v147, v123, v147
	v_sub_f32_e32 v123, v123, v149
	v_add_f32_e32 v147, v122, v147
	v_add_f32_e32 v122, v122, v123
	v_add_f32_e32 v153, v148, v122
	v_rcp_f32_e32 v155, v153
	v_sub_f32_e32 v123, v153, v148
	v_sub_f32_e32 v154, v122, v123
	v_add_f32_e32 v123, v146, v147
	v_mul_f32_e32 v157, v123, v155
	v_sub_f32_e32 v122, v123, v146
	v_mul_f32_e32 v146, v153, v157
	v_fma_f32 v148, v157, v153, -v146
	v_fmac_f32_e32 v148, v157, v154
	v_sub_f32_e32 v156, v147, v122
	v_add_f32_e32 v122, v146, v148
	v_sub_f32_e32 v147, v123, v122
	v_pk_add_f32 v[150:151], v[122:123], v[146:147] neg_lo:[0,1] neg_hi:[0,1]
	v_mov_b32_e32 v149, v122
	v_pk_add_f32 v[122:123], v[150:151], v[148:149] neg_lo:[0,1] neg_hi:[0,1]
	s_mov_b32 s31, 0x3f317218
	v_add_f32_e32 v123, v156, v123
	v_add_f32_e32 v122, v122, v123
	v_add_f32_e32 v123, v147, v122
	v_mul_f32_e32 v156, v155, v123
	v_mul_f32_e32 v146, v153, v156
	v_fma_f32 v148, v156, v153, -v146
	v_fmac_f32_e32 v148, v156, v154
	v_sub_f32_e32 v147, v147, v123
	v_add_f32_e32 v153, v122, v147
	v_add_f32_e32 v122, v146, v148
	v_sub_f32_e32 v147, v123, v122
	v_pk_add_f32 v[150:151], v[122:123], v[146:147] neg_lo:[0,1] neg_hi:[0,1]
	v_mov_b32_e32 v149, v122
	v_pk_add_f32 v[122:123], v[150:151], v[148:149] neg_lo:[0,1] neg_hi:[0,1]
	s_nop 0
	v_add_f32_e32 v123, v153, v123
	v_add_f32_e32 v122, v122, v123
	v_add_f32_e32 v123, v157, v156
	v_add_f32_e32 v122, v147, v122
	v_sub_f32_e32 v146, v123, v157
	v_mul_f32_e32 v122, v155, v122
	v_sub_f32_e32 v146, v156, v146
	v_add_f32_e32 v146, v146, v122
	v_add_f32_e32 v148, v123, v146
	v_mul_f32_e32 v149, v148, v148
	v_fmamk_f32 v122, v149, 0x3e9b6dac, v236
	v_fmaak_f32 v205, v149, v122, 0x3f2aaada
	v_cvt_f32_i32_e32 v122, v152
	v_sub_f32_e32 v123, v148, v123
	v_sub_f32_e32 v123, v146, v123
	v_ldexp_f32 v150, v123, 1
	v_mul_f32_e32 v123, v148, v149
	v_ldexp_f32 v147, v148, 1
	v_pk_mul_f32 v[148:149], v[122:123], v[204:205]
	s_nop 0
	v_fma_f32 v146, v122, s31, -v148
	v_fmac_f32_e32 v146, 0xb102e308, v122
	v_pk_add_f32 v[122:123], v[148:149], v[146:147]
	s_mov_b32 s31, 0x7f800000
	v_sub_f32_e32 v147, v123, v147
	v_sub_f32_e32 v147, v149, v147
	v_add_f32_e32 v151, v150, v147
	v_mov_b32_e32 v150, v148
	v_pk_add_f32 v[148:149], v[122:123], v[148:149] neg_lo:[0,1] neg_hi:[0,1]
	v_pk_add_f32 v[152:153], v[122:123], v[150:151]
	v_mov_b32_e32 v147, v122
	v_mov_b32_e32 v149, v153
	v_pk_add_f32 v[154:155], v[146:147], v[148:149] neg_lo:[0,1] neg_hi:[0,1]
	v_pk_add_f32 v[146:147], v[146:147], v[148:149]
	v_mov_b32_e32 v150, v151
	v_pk_add_f32 v[148:149], v[146:147], v[122:123] op_sel:[1,0] op_sel_hi:[0,1] neg_lo:[0,1] neg_hi:[0,1]
	v_pk_add_f32 v[156:157], v[152:153], v[148:149] op_sel_hi:[1,0] neg_lo:[0,1] neg_hi:[0,1]
	v_mov_b32_e32 v152, v153
	v_mov_b32_e32 v153, v147
	v_pk_mov_b32 v[148:149], v[122:123], v[148:149] op_sel:[1,0]
	v_mov_b32_e32 v151, v122
	v_pk_add_f32 v[148:149], v[152:153], v[148:149] neg_lo:[0,1] neg_hi:[0,1]
	v_mov_b32_e32 v156, v154
	v_pk_add_f32 v[122:123], v[150:151], v[148:149] neg_lo:[0,1] neg_hi:[0,1]
	v_mov_b32_e32 v155, v147
	v_pk_add_f32 v[148:149], v[156:157], v[122:123]
	v_cmp_neq_f32_e32 vcc, s31, v129
	v_pk_add_f32 v[150:151], v[148:149], v[148:149] op_sel:[0,1] op_sel_hi:[1,0]
	s_mov_b32 s31, 0x33800000
	v_pk_add_f32 v[146:147], v[146:147], v[150:151] op_sel:[1,0] op_sel_hi:[0,1]
	v_mov_b32_e32 v149, v146
	v_pk_add_f32 v[152:153], v[148:149], v[154:155] neg_lo:[0,1] neg_hi:[0,1]
	v_mov_b32_e32 v123, v150
	v_sub_f32_e32 v147, v148, v152
	v_pk_add_f32 v[122:123], v[122:123], v[152:153] neg_lo:[0,1] neg_hi:[0,1]
	v_sub_f32_e32 v147, v154, v147
	v_add_f32_e32 v122, v122, v147
	v_add_f32_e32 v122, v122, v123
	v_add_f32_e32 v122, v146, v122
	v_cndmask_b32_e32 v122, v237, v122, vcc
	v_cmp_ngt_f32_e32 vcc, -1.0, v129
	s_nop 1
	v_cndmask_b32_e32 v122, v238, v122, vcc
	v_cmp_neq_f32_e32 vcc, -1.0, v129
	s_nop 1
	v_cndmask_b32_e32 v122, v239, v122, vcc
	v_cmp_lt_f32_e64 vcc, |v129|, s31
	s_nop 1
	v_cndmask_b32_e32 v122, v122, v129, vcc
	v_sub_f32_e32 v122, v0, v122

.LBB0_727:
	s_or_b64 exec, exec, s[4:5]
	v_or_b32_e32 v146, 1, v128
	v_ashrrev_i32_e32 v147, 31, v146
	v_lshlrev_b64 v[146:147], 13, v[146:147]
	v_lshl_add_u64 v[146:147], v[126:127], 0, v[146:147]
	v_readlane_b32 s4, v254, 26
	global_store_dword v[146:147], v122, off
	v_readlane_b32 s5, v254, 27
	s_nop 4
	s_load_dword s4, s[4:5], 0x8
	s_waitcnt lgkmcnt(0)
	v_mov_b32_e32 v0, s4
	v_add_f32_e32 v0, v124, v0
	v_cmp_nlt_f32_e32 vcc, 0, v0
	s_and_saveexec_b64 s[4:5], vcc
	s_xor_b64 s[4:5], exec, s[4:5]
	s_cbranch_execz .LBB0_729
	v_mul_f32_e32 v122, 0x3fb8aa3b, v0
	v_exp_f32_e32 v124, v122
	s_mov_b32 s31, 0x3f2aaaab
	v_add_f32_e32 v129, 1.0, v124
	v_frexp_mant_f32_e32 v147, v129
	v_cvt_f64_f32_e32 v[122:123], v129
	v_frexp_exp_i32_f64_e32 v122, v[122:123]
	v_cmp_gt_f32_e32 vcc, s31, v147
	v_add_f32_e32 v146, -1.0, v129
	v_sub_f32_e32 v148, v146, v129
	v_subbrev_co_u32_e32 v152, vcc, 0, v122, vcc
	v_sub_u32_e32 v122, 0, v152
	v_sub_f32_e32 v146, v124, v146
	v_add_f32_e32 v148, 1.0, v148
	v_ldexp_f32 v123, v129, v122
	v_add_f32_e32 v146, v146, v148
	v_add_f32_e32 v129, -1.0, v123
	v_add_f32_e32 v147, 1.0, v123
	v_ldexp_f32 v122, v146, v122
	v_add_f32_e32 v146, 1.0, v129
	v_add_f32_e32 v148, -1.0, v147
	v_sub_f32_e32 v146, v123, v146
	v_sub_f32_e32 v123, v123, v148
	v_add_f32_e32 v146, v122, v146
	v_add_f32_e32 v122, v122, v123
	v_add_f32_e32 v153, v147, v122
	v_rcp_f32_e32 v155, v153
	v_sub_f32_e32 v123, v153, v147
	v_sub_f32_e32 v154, v122, v123
	v_add_f32_e32 v123, v129, v146
	v_sub_f32_e32 v122, v123, v129
	v_mul_f32_e32 v156, v123, v155
	v_sub_f32_e32 v129, v146, v122
	v_mul_f32_e32 v146, v153, v156
	v_fma_f32 v148, v156, v153, -v146
	v_fmac_f32_e32 v148, v156, v154
	v_add_f32_e32 v122, v146, v148
	v_sub_f32_e32 v147, v123, v122
	v_pk_add_f32 v[150:151], v[122:123], v[146:147] neg_lo:[0,1] neg_hi:[0,1]
	v_mov_b32_e32 v149, v122
	v_pk_add_f32 v[122:123], v[150:151], v[148:149] neg_lo:[0,1] neg_hi:[0,1]
	s_mov_b32 s31, 0x3f317218
	v_add_f32_e32 v123, v129, v123
	v_add_f32_e32 v122, v122, v123
	v_add_f32_e32 v123, v147, v122
	v_mul_f32_e32 v129, v155, v123
	v_mul_f32_e32 v146, v153, v129
	v_fma_f32 v148, v129, v153, -v146
	v_fmac_f32_e32 v148, v129, v154
	v_sub_f32_e32 v147, v147, v123
	v_add_f32_e32 v153, v122, v147
	v_add_f32_e32 v122, v146, v148
	v_sub_f32_e32 v147, v123, v122
	v_pk_add_f32 v[150:151], v[122:123], v[146:147] neg_lo:[0,1] neg_hi:[0,1]
	v_mov_b32_e32 v149, v122
	v_pk_add_f32 v[122:123], v[150:151], v[148:149] neg_lo:[0,1] neg_hi:[0,1]
	s_nop 0
	v_add_f32_e32 v123, v153, v123
	v_add_f32_e32 v122, v122, v123
	v_add_f32_e32 v123, v156, v129
	v_add_f32_e32 v122, v147, v122
	v_sub_f32_e32 v146, v123, v156
	v_mul_f32_e32 v122, v155, v122
	v_sub_f32_e32 v129, v129, v146
	v_add_f32_e32 v129, v129, v122
	v_add_f32_e32 v146, v123, v129
	v_mul_f32_e32 v148, v146, v146
	v_fmamk_f32 v122, v148, 0x3e9b6dac, v236
	v_fmaak_f32 v205, v148, v122, 0x3f2aaada
	v_cvt_f32_i32_e32 v122, v152
	v_sub_f32_e32 v123, v146, v123
	v_sub_f32_e32 v123, v129, v123
	v_ldexp_f32 v129, v123, 1
	v_mul_f32_e32 v123, v146, v148
	v_pk_mul_f32 v[148:149], v[122:123], v[204:205]
	v_ldexp_f32 v147, v146, 1
	v_fma_f32 v146, v122, s31, -v148
	v_fmac_f32_e32 v146, 0xb102e308, v122
	v_pk_add_f32 v[122:123], v[148:149], v[146:147]
	v_mov_b32_e32 v150, v148
	v_sub_f32_e32 v147, v123, v147
	v_sub_f32_e32 v147, v149, v147
	v_add_f32_e32 v151, v129, v147
	v_pk_add_f32 v[148:149], v[122:123], v[148:149] neg_lo:[0,1] neg_hi:[0,1]
	v_pk_add_f32 v[152:153], v[122:123], v[150:151]
	v_mov_b32_e32 v147, v122
	v_mov_b32_e32 v149, v153
	v_pk_add_f32 v[154:155], v[146:147], v[148:149] neg_lo:[0,1] neg_hi:[0,1]
	v_pk_add_f32 v[146:147], v[146:147], v[148:149]
	v_mov_b32_e32 v150, v151
	v_pk_add_f32 v[148:149], v[146:147], v[122:123] op_sel:[1,0] op_sel_hi:[0,1] neg_lo:[0,1] neg_hi:[0,1]
	v_pk_add_f32 v[156:157], v[152:153], v[148:149] op_sel_hi:[1,0] neg_lo:[0,1] neg_hi:[0,1]
	v_mov_b32_e32 v152, v153
	v_mov_b32_e32 v153, v147
	v_pk_mov_b32 v[148:149], v[122:123], v[148:149] op_sel:[1,0]
	v_mov_b32_e32 v151, v122
	v_pk_add_f32 v[148:149], v[152:153], v[148:149] neg_lo:[0,1] neg_hi:[0,1]
	v_mov_b32_e32 v156, v154
	v_pk_add_f32 v[122:123], v[150:151], v[148:149] neg_lo:[0,1] neg_hi:[0,1]
	v_mov_b32_e32 v155, v147
	v_pk_add_f32 v[148:149], v[156:157], v[122:123]
	s_mov_b32 s31, 0x7f800000
	v_pk_add_f32 v[150:151], v[148:149], v[148:149] op_sel:[0,1] op_sel_hi:[1,0]
	v_cmp_neq_f32_e32 vcc, s31, v124
	v_pk_add_f32 v[146:147], v[146:147], v[150:151] op_sel:[1,0] op_sel_hi:[0,1]
	v_mov_b32_e32 v149, v146
	v_pk_add_f32 v[152:153], v[148:149], v[154:155] neg_lo:[0,1] neg_hi:[0,1]
	v_mov_b32_e32 v123, v150
	v_sub_f32_e32 v129, v148, v152
	v_pk_add_f32 v[122:123], v[122:123], v[152:153] neg_lo:[0,1] neg_hi:[0,1]
	v_sub_f32_e32 v129, v154, v129
	v_add_f32_e32 v122, v122, v129
	v_add_f32_e32 v122, v122, v123
	v_add_f32_e32 v122, v146, v122
	v_cndmask_b32_e32 v122, v237, v122, vcc
	v_cmp_ngt_f32_e32 vcc, -1.0, v124
	s_mov_b32 s31, 0x33800000
	s_nop 0
	v_cndmask_b32_e32 v122, v238, v122, vcc
	v_cmp_neq_f32_e32 vcc, -1.0, v124
	s_nop 1
	v_cndmask_b32_e32 v122, v239, v122, vcc
	v_cmp_lt_f32_e64 vcc, |v124|, s31
	s_nop 1
	v_cndmask_b32_e32 v122, v122, v124, vcc
	v_sub_f32_e32 v122, v0, v122

.LBB0_731:
	s_or_b64 exec, exec, s[4:5]
	v_or_b32_e32 v146, 2, v128
	v_ashrrev_i32_e32 v147, 31, v146
	v_lshlrev_b64 v[146:147], 13, v[146:147]
	v_lshl_add_u64 v[146:147], v[126:127], 0, v[146:147]
	v_readlane_b32 s4, v254, 26
	global_store_dword v[146:147], v122, off
	v_readlane_b32 s5, v254, 27
	s_nop 4
	s_load_dword s4, s[4:5], 0xc
	s_waitcnt lgkmcnt(0)
	v_mov_b32_e32 v0, s4
	v_add_f32_e32 v0, v125, v0
	v_cmp_nlt_f32_e32 vcc, 0, v0
	s_and_saveexec_b64 s[4:5], vcc
	s_xor_b64 s[4:5], exec, s[4:5]
	s_cbranch_execz .LBB0_733
	v_mul_f32_e32 v122, 0x3fb8aa3b, v0
	v_exp_f32_e32 v129, v122
	s_mov_b32 s31, 0x3f2aaaab
	v_add_f32_e32 v124, 1.0, v129
	v_frexp_mant_f32_e32 v146, v124
	v_cvt_f64_f32_e32 v[122:123], v124
	v_frexp_exp_i32_f64_e32 v122, v[122:123]
	v_cmp_gt_f32_e32 vcc, s31, v146
	v_add_f32_e32 v125, -1.0, v124
	v_sub_f32_e32 v147, v125, v124
	v_subbrev_co_u32_e32 v150, vcc, 0, v122, vcc
	v_sub_u32_e32 v122, 0, v150
	v_sub_f32_e32 v125, v129, v125
	v_add_f32_e32 v147, 1.0, v147
	v_ldexp_f32 v123, v124, v122
	v_add_f32_e32 v125, v125, v147
	v_add_f32_e32 v124, -1.0, v123
	v_add_f32_e32 v146, 1.0, v123
	v_ldexp_f32 v122, v125, v122
	v_add_f32_e32 v125, 1.0, v124
	v_add_f32_e32 v147, -1.0, v146
	v_sub_f32_e32 v125, v123, v125
	v_sub_f32_e32 v123, v123, v147
	v_add_f32_e32 v125, v122, v125
	v_add_f32_e32 v122, v122, v123
	v_add_f32_e32 v151, v146, v122
	v_rcp_f32_e32 v153, v151
	v_sub_f32_e32 v123, v151, v146
	v_sub_f32_e32 v152, v122, v123
	v_add_f32_e32 v123, v124, v125
	v_mul_f32_e32 v155, v123, v153
	v_sub_f32_e32 v122, v123, v124
	v_mul_f32_e32 v124, v151, v155
	v_fma_f32 v146, v155, v151, -v124
	v_fmac_f32_e32 v146, v155, v152
	v_sub_f32_e32 v154, v125, v122
	v_add_f32_e32 v122, v124, v146
	v_sub_f32_e32 v125, v123, v122
	v_pk_add_f32 v[148:149], v[122:123], v[124:125] neg_lo:[0,1] neg_hi:[0,1]
	v_mov_b32_e32 v147, v122
	v_pk_add_f32 v[122:123], v[148:149], v[146:147] neg_lo:[0,1] neg_hi:[0,1]
	s_mov_b32 s31, 0x3f317218
	v_add_f32_e32 v123, v154, v123
	v_add_f32_e32 v122, v122, v123
	v_add_f32_e32 v123, v125, v122
	v_mul_f32_e32 v154, v153, v123
	v_mul_f32_e32 v124, v151, v154
	v_fma_f32 v146, v154, v151, -v124
	v_fmac_f32_e32 v146, v154, v152
	v_sub_f32_e32 v125, v125, v123
	v_add_f32_e32 v151, v122, v125
	v_add_f32_e32 v122, v124, v146
	v_sub_f32_e32 v125, v123, v122
	v_pk_add_f32 v[148:149], v[122:123], v[124:125] neg_lo:[0,1] neg_hi:[0,1]
	v_mov_b32_e32 v147, v122
	v_pk_add_f32 v[122:123], v[148:149], v[146:147] neg_lo:[0,1] neg_hi:[0,1]
	s_nop 0
	v_add_f32_e32 v123, v151, v123
	v_add_f32_e32 v122, v122, v123
	v_add_f32_e32 v123, v155, v154
	v_add_f32_e32 v122, v125, v122
	v_sub_f32_e32 v124, v123, v155
	v_mul_f32_e32 v122, v153, v122
	v_sub_f32_e32 v124, v154, v124
	v_add_f32_e32 v124, v124, v122
	v_add_f32_e32 v146, v123, v124
	v_mul_f32_e32 v147, v146, v146
	v_fmamk_f32 v122, v147, 0x3e9b6dac, v236
	v_fmaak_f32 v205, v147, v122, 0x3f2aaada
	v_cvt_f32_i32_e32 v122, v150
	v_sub_f32_e32 v123, v146, v123
	v_sub_f32_e32 v123, v124, v123
	v_ldexp_f32 v148, v123, 1
	v_mul_f32_e32 v123, v146, v147
	v_ldexp_f32 v125, v146, 1
	v_pk_mul_f32 v[146:147], v[122:123], v[204:205]
	s_nop 0
	v_fma_f32 v124, v122, s31, -v146
	v_fmac_f32_e32 v124, 0xb102e308, v122
	v_pk_add_f32 v[122:123], v[146:147], v[124:125]
	s_mov_b32 s31, 0x7f800000
	v_sub_f32_e32 v125, v123, v125
	v_sub_f32_e32 v125, v147, v125
	v_add_f32_e32 v149, v148, v125
	v_mov_b32_e32 v148, v146
	v_pk_add_f32 v[146:147], v[122:123], v[146:147] neg_lo:[0,1] neg_hi:[0,1]
	v_pk_add_f32 v[150:151], v[122:123], v[148:149]
	v_mov_b32_e32 v125, v122
	v_mov_b32_e32 v147, v151
	v_pk_add_f32 v[152:153], v[124:125], v[146:147] neg_lo:[0,1] neg_hi:[0,1]
	v_pk_add_f32 v[124:125], v[124:125], v[146:147]
	v_mov_b32_e32 v148, v149
	v_pk_add_f32 v[146:147], v[124:125], v[122:123] op_sel:[1,0] op_sel_hi:[0,1] neg_lo:[0,1] neg_hi:[0,1]
	v_pk_add_f32 v[154:155], v[150:151], v[146:147] op_sel_hi:[1,0] neg_lo:[0,1] neg_hi:[0,1]
	v_mov_b32_e32 v150, v151
	v_mov_b32_e32 v151, v125
	v_pk_mov_b32 v[146:147], v[122:123], v[146:147] op_sel:[1,0]
	v_mov_b32_e32 v149, v122
	v_pk_add_f32 v[146:147], v[150:151], v[146:147] neg_lo:[0,1] neg_hi:[0,1]
	v_mov_b32_e32 v154, v152
	v_pk_add_f32 v[122:123], v[148:149], v[146:147] neg_lo:[0,1] neg_hi:[0,1]
	v_mov_b32_e32 v153, v125
	v_pk_add_f32 v[146:147], v[154:155], v[122:123]
	v_cmp_neq_f32_e32 vcc, s31, v129
	v_pk_add_f32 v[148:149], v[146:147], v[146:147] op_sel:[0,1] op_sel_hi:[1,0]
	s_mov_b32 s31, 0x33800000
	v_pk_add_f32 v[124:125], v[124:125], v[148:149] op_sel:[1,0] op_sel_hi:[0,1]
	v_mov_b32_e32 v147, v124
	v_pk_add_f32 v[150:151], v[146:147], v[152:153] neg_lo:[0,1] neg_hi:[0,1]
	v_mov_b32_e32 v123, v148
	v_sub_f32_e32 v125, v146, v150
	v_pk_add_f32 v[122:123], v[122:123], v[150:151] neg_lo:[0,1] neg_hi:[0,1]
	v_sub_f32_e32 v125, v152, v125
	v_add_f32_e32 v122, v122, v125
	v_add_f32_e32 v122, v122, v123
	v_add_f32_e32 v122, v124, v122
	v_cndmask_b32_e32 v122, v237, v122, vcc
	v_cmp_ngt_f32_e32 vcc, -1.0, v129
	s_nop 1
	v_cndmask_b32_e32 v122, v238, v122, vcc
	v_cmp_neq_f32_e32 vcc, -1.0, v129
	s_nop 1
	v_cndmask_b32_e32 v122, v239, v122, vcc
	v_cmp_lt_f32_e64 vcc, |v129|, s31
	s_nop 1
	v_cndmask_b32_e32 v122, v122, v129, vcc
	v_sub_f32_e32 v122, v0, v122

.LBB0_758:
	s_and_saveexec_b64 s[4:5], s[10:11]
	s_xor_b64 s[18:19], exec, s[4:5]
	s_cbranch_execz .LBB0_776
	v_readlane_b32 s4, v254, 26
	v_readlane_b32 s5, v254, 27
	s_waitcnt lgkmcnt(0)
	s_nop 3
	s_load_dword s4, s[4:5], 0x0
	s_waitcnt lgkmcnt(0)
	v_mov_b32_e32 v0, s4
	v_add_f32_e32 v0, v98, v0
	v_cmp_nlt_f32_e32 vcc, 0, v0
	s_and_saveexec_b64 s[4:5], vcc
	s_xor_b64 s[4:5], exec, s[4:5]
	s_cbranch_execz .LBB0_761
	v_mul_f32_e32 v98, 0x3fb8aa3b, v0
	v_exp_f32_e32 v98, v98
	s_mov_b32 s31, 0x3f2aaaab
	v_add_f32_e32 v104, 1.0, v98
	v_frexp_mant_f32_e32 v122, v104
	v_cvt_f64_f32_e32 v[102:103], v104
	v_frexp_exp_i32_f64_e32 v102, v[102:103]
	v_cmp_gt_f32_e32 vcc, s31, v122
	v_add_f32_e32 v105, -1.0, v104
	v_sub_f32_e32 v123, v105, v104
	v_subbrev_co_u32_e32 v126, vcc, 0, v102, vcc
	v_sub_u32_e32 v102, 0, v126
	v_sub_f32_e32 v105, v98, v105
	v_add_f32_e32 v123, 1.0, v123
	v_ldexp_f32 v103, v104, v102
	v_add_f32_e32 v105, v105, v123
	v_add_f32_e32 v104, -1.0, v103
	v_add_f32_e32 v122, 1.0, v103
	v_ldexp_f32 v102, v105, v102
	v_add_f32_e32 v105, 1.0, v104
	v_add_f32_e32 v123, -1.0, v122
	v_sub_f32_e32 v105, v103, v105
	v_sub_f32_e32 v103, v103, v123
	v_add_f32_e32 v105, v102, v105
	v_add_f32_e32 v102, v102, v103
	v_add_f32_e32 v127, v122, v102
	v_rcp_f32_e32 v129, v127
	v_sub_f32_e32 v103, v127, v122
	v_sub_f32_e32 v128, v102, v103
	v_add_f32_e32 v103, v104, v105
	v_mul_f32_e32 v131, v103, v129
	v_sub_f32_e32 v102, v103, v104
	v_mul_f32_e32 v104, v127, v131
	v_fma_f32 v122, v131, v127, -v104
	v_fmac_f32_e32 v122, v131, v128
	v_sub_f32_e32 v130, v105, v102
	v_add_f32_e32 v102, v104, v122
	v_sub_f32_e32 v105, v103, v102
	v_pk_add_f32 v[124:125], v[102:103], v[104:105] neg_lo:[0,1] neg_hi:[0,1]
	v_mov_b32_e32 v123, v102
	v_pk_add_f32 v[102:103], v[124:125], v[122:123] neg_lo:[0,1] neg_hi:[0,1]
	s_mov_b32 s31, 0x3f317218
	v_add_f32_e32 v103, v130, v103
	v_add_f32_e32 v102, v102, v103
	v_add_f32_e32 v103, v105, v102
	v_mul_f32_e32 v130, v129, v103
	v_mul_f32_e32 v104, v127, v130
	v_fma_f32 v122, v130, v127, -v104
	v_fmac_f32_e32 v122, v130, v128
	v_sub_f32_e32 v105, v105, v103
	v_add_f32_e32 v127, v102, v105
	v_add_f32_e32 v102, v104, v122
	v_sub_f32_e32 v105, v103, v102
	v_pk_add_f32 v[124:125], v[102:103], v[104:105] neg_lo:[0,1] neg_hi:[0,1]
	v_mov_b32_e32 v123, v102
	v_pk_add_f32 v[102:103], v[124:125], v[122:123] neg_lo:[0,1] neg_hi:[0,1]
	s_nop 0
	v_add_f32_e32 v103, v127, v103
	v_add_f32_e32 v102, v102, v103
	v_add_f32_e32 v103, v131, v130
	v_add_f32_e32 v102, v105, v102
	v_sub_f32_e32 v104, v103, v131
	v_mul_f32_e32 v102, v129, v102
	v_sub_f32_e32 v104, v130, v104
	v_add_f32_e32 v104, v104, v102
	v_add_f32_e32 v122, v103, v104
	v_mul_f32_e32 v123, v122, v122
	v_fmamk_f32 v102, v123, 0x3e9b6dac, v236
	v_fmaak_f32 v205, v123, v102, 0x3f2aaada
	v_cvt_f32_i32_e32 v102, v126
	v_sub_f32_e32 v103, v122, v103
	v_sub_f32_e32 v103, v104, v103
	v_ldexp_f32 v124, v103, 1
	v_mul_f32_e32 v103, v122, v123
	v_ldexp_f32 v105, v122, 1
	v_pk_mul_f32 v[122:123], v[102:103], v[204:205]
	s_nop 0
	v_fma_f32 v104, v102, s31, -v122
	v_fmac_f32_e32 v104, 0xb102e308, v102
	v_pk_add_f32 v[102:103], v[122:123], v[104:105]
	s_mov_b32 s31, 0x7f800000
	v_sub_f32_e32 v105, v103, v105
	v_sub_f32_e32 v105, v123, v105
	v_add_f32_e32 v125, v124, v105
	v_mov_b32_e32 v124, v122
	v_pk_add_f32 v[122:123], v[102:103], v[122:123] neg_lo:[0,1] neg_hi:[0,1]
	v_pk_add_f32 v[126:127], v[102:103], v[124:125]
	v_mov_b32_e32 v105, v102
	v_mov_b32_e32 v123, v127
	v_pk_add_f32 v[128:129], v[104:105], v[122:123] neg_lo:[0,1] neg_hi:[0,1]
	v_pk_add_f32 v[104:105], v[104:105], v[122:123]
	v_mov_b32_e32 v124, v125
	v_pk_add_f32 v[122:123], v[104:105], v[102:103] op_sel:[1,0] op_sel_hi:[0,1] neg_lo:[0,1] neg_hi:[0,1]
	v_pk_add_f32 v[130:131], v[126:127], v[122:123] op_sel_hi:[1,0] neg_lo:[0,1] neg_hi:[0,1]
	v_mov_b32_e32 v126, v127
	v_mov_b32_e32 v127, v105
	v_pk_mov_b32 v[122:123], v[102:103], v[122:123] op_sel:[1,0]
	v_mov_b32_e32 v125, v102
	v_pk_add_f32 v[122:123], v[126:127], v[122:123] neg_lo:[0,1] neg_hi:[0,1]
	v_mov_b32_e32 v130, v128
	v_pk_add_f32 v[102:103], v[124:125], v[122:123] neg_lo:[0,1] neg_hi:[0,1]
	v_mov_b32_e32 v129, v105
	v_pk_add_f32 v[122:123], v[130:131], v[102:103]
	v_cmp_neq_f32_e32 vcc, s31, v98
	v_pk_add_f32 v[124:125], v[122:123], v[122:123] op_sel:[0,1] op_sel_hi:[1,0]
	s_mov_b32 s31, 0x33800000
	v_pk_add_f32 v[104:105], v[104:105], v[124:125] op_sel:[1,0] op_sel_hi:[0,1]
	v_mov_b32_e32 v123, v104
	v_pk_add_f32 v[126:127], v[122:123], v[128:129] neg_lo:[0,1] neg_hi:[0,1]
	v_mov_b32_e32 v103, v124
	v_sub_f32_e32 v105, v122, v126
	v_pk_add_f32 v[102:103], v[102:103], v[126:127] neg_lo:[0,1] neg_hi:[0,1]
	v_sub_f32_e32 v105, v128, v105
	v_add_f32_e32 v102, v102, v105
	v_add_f32_e32 v102, v102, v103
	v_add_f32_e32 v102, v104, v102
	v_cndmask_b32_e32 v102, v237, v102, vcc
	v_cmp_ngt_f32_e32 vcc, -1.0, v98
	s_nop 1
	v_cndmask_b32_e32 v102, v238, v102, vcc
	v_cmp_neq_f32_e32 vcc, -1.0, v98
	s_nop 1
	v_cndmask_b32_e32 v102, v239, v102, vcc
	v_cmp_lt_f32_e64 vcc, |v98|, s31
	s_nop 1
	v_cndmask_b32_e32 v98, v102, v98, vcc
	v_sub_f32_e32 v98, v0, v98

.LBB0_763:
	s_or_b64 exec, exec, s[4:5]
	v_lshlrev_b32_e32 v104, 2, v133
	v_lshlrev_b32_e32 v0, 2, v134
	v_ashrrev_i32_e32 v105, 31, v104
	v_lshl_add_u64 v[102:103], s[84:85], 0, v[0:1]
	v_lshlrev_b64 v[122:123], 13, v[104:105]
	v_lshl_add_u64 v[122:123], v[102:103], 0, v[122:123]
	v_readlane_b32 s4, v254, 26
	global_store_dword v[122:123], v98, off
	v_readlane_b32 s5, v254, 27
	s_nop 4
	s_load_dword s4, s[4:5], 0x4
	s_waitcnt lgkmcnt(0)
	v_mov_b32_e32 v0, s4
	v_add_f32_e32 v0, v99, v0
	v_cmp_nlt_f32_e32 vcc, 0, v0
	s_and_saveexec_b64 s[4:5], vcc
	s_xor_b64 s[4:5], exec, s[4:5]
	s_cbranch_execz .LBB0_765
	v_mul_f32_e32 v98, 0x3fb8aa3b, v0
	v_exp_f32_e32 v105, v98
	s_mov_b32 s31, 0x3f2aaaab
	v_add_f32_e32 v122, 1.0, v105
	v_frexp_mant_f32_e32 v124, v122
	v_cvt_f64_f32_e32 v[98:99], v122
	v_frexp_exp_i32_f64_e32 v98, v[98:99]
	v_cmp_gt_f32_e32 vcc, s31, v124
	v_add_f32_e32 v123, -1.0, v122
	v_sub_f32_e32 v125, v123, v122
	v_subbrev_co_u32_e32 v128, vcc, 0, v98, vcc
	v_sub_u32_e32 v98, 0, v128
	v_sub_f32_e32 v123, v105, v123
	v_add_f32_e32 v125, 1.0, v125
	v_ldexp_f32 v99, v122, v98
	v_add_f32_e32 v123, v123, v125
	v_add_f32_e32 v122, -1.0, v99
	v_add_f32_e32 v124, 1.0, v99
	v_ldexp_f32 v98, v123, v98
	v_add_f32_e32 v123, 1.0, v122
	v_add_f32_e32 v125, -1.0, v124
	v_sub_f32_e32 v123, v99, v123
	v_sub_f32_e32 v99, v99, v125
	v_add_f32_e32 v123, v98, v123
	v_add_f32_e32 v98, v98, v99
	v_add_f32_e32 v129, v124, v98
	v_rcp_f32_e32 v131, v129
	v_sub_f32_e32 v99, v129, v124
	v_sub_f32_e32 v130, v98, v99
	v_add_f32_e32 v99, v122, v123
	v_mul_f32_e32 v133, v99, v131
	v_sub_f32_e32 v98, v99, v122
	v_mul_f32_e32 v122, v129, v133
	v_fma_f32 v124, v133, v129, -v122
	v_fmac_f32_e32 v124, v133, v130
	v_sub_f32_e32 v132, v123, v98
	v_add_f32_e32 v98, v122, v124
	v_sub_f32_e32 v123, v99, v98
	v_pk_add_f32 v[126:127], v[98:99], v[122:123] neg_lo:[0,1] neg_hi:[0,1]
	v_mov_b32_e32 v125, v98
	v_pk_add_f32 v[98:99], v[126:127], v[124:125] neg_lo:[0,1] neg_hi:[0,1]
	s_mov_b32 s31, 0x3f317218
	v_add_f32_e32 v99, v132, v99
	v_add_f32_e32 v98, v98, v99
	v_add_f32_e32 v99, v123, v98
	v_mul_f32_e32 v132, v131, v99
	v_mul_f32_e32 v122, v129, v132
	v_fma_f32 v124, v132, v129, -v122
	v_fmac_f32_e32 v124, v132, v130
	v_sub_f32_e32 v123, v123, v99
	v_add_f32_e32 v129, v98, v123
	v_add_f32_e32 v98, v122, v124
	v_sub_f32_e32 v123, v99, v98
	v_pk_add_f32 v[126:127], v[98:99], v[122:123] neg_lo:[0,1] neg_hi:[0,1]
	v_mov_b32_e32 v125, v98
	v_pk_add_f32 v[98:99], v[126:127], v[124:125] neg_lo:[0,1] neg_hi:[0,1]
	s_nop 0
	v_add_f32_e32 v99, v129, v99
	v_add_f32_e32 v98, v98, v99
	v_add_f32_e32 v99, v133, v132
	v_add_f32_e32 v98, v123, v98
	v_sub_f32_e32 v122, v99, v133
	v_mul_f32_e32 v98, v131, v98
	v_sub_f32_e32 v122, v132, v122
	v_add_f32_e32 v122, v122, v98
	v_add_f32_e32 v124, v99, v122
	v_mul_f32_e32 v125, v124, v124
	v_fmamk_f32 v98, v125, 0x3e9b6dac, v236
	v_fmaak_f32 v205, v125, v98, 0x3f2aaada
	v_cvt_f32_i32_e32 v98, v128
	v_sub_f32_e32 v99, v124, v99
	v_sub_f32_e32 v99, v122, v99
	v_ldexp_f32 v126, v99, 1
	v_mul_f32_e32 v99, v124, v125
	v_ldexp_f32 v123, v124, 1
	v_pk_mul_f32 v[124:125], v[98:99], v[204:205]
	s_nop 0
	v_fma_f32 v122, v98, s31, -v124
	v_fmac_f32_e32 v122, 0xb102e308, v98
	v_pk_add_f32 v[98:99], v[124:125], v[122:123]
	s_mov_b32 s31, 0x7f800000
	v_sub_f32_e32 v123, v99, v123
	v_sub_f32_e32 v123, v125, v123
	v_add_f32_e32 v127, v126, v123
	v_mov_b32_e32 v126, v124
	v_pk_add_f32 v[124:125], v[98:99], v[124:125] neg_lo:[0,1] neg_hi:[0,1]
	v_pk_add_f32 v[128:129], v[98:99], v[126:127]
	v_mov_b32_e32 v123, v98
	v_mov_b32_e32 v125, v129
	v_pk_add_f32 v[130:131], v[122:123], v[124:125] neg_lo:[0,1] neg_hi:[0,1]
	v_pk_add_f32 v[122:123], v[122:123], v[124:125]
	v_mov_b32_e32 v126, v127
	v_pk_add_f32 v[124:125], v[122:123], v[98:99] op_sel:[1,0] op_sel_hi:[0,1] neg_lo:[0,1] neg_hi:[0,1]
	v_pk_add_f32 v[132:133], v[128:129], v[124:125] op_sel_hi:[1,0] neg_lo:[0,1] neg_hi:[0,1]
	v_mov_b32_e32 v128, v129
	v_mov_b32_e32 v129, v123
	v_pk_mov_b32 v[124:125], v[98:99], v[124:125] op_sel:[1,0]
	v_mov_b32_e32 v127, v98
	v_pk_add_f32 v[124:125], v[128:129], v[124:125] neg_lo:[0,1] neg_hi:[0,1]
	v_mov_b32_e32 v132, v130
	v_pk_add_f32 v[98:99], v[126:127], v[124:125] neg_lo:[0,1] neg_hi:[0,1]
	v_mov_b32_e32 v131, v123
	v_pk_add_f32 v[124:125], v[132:133], v[98:99]
	v_cmp_neq_f32_e32 vcc, s31, v105
	v_pk_add_f32 v[126:127], v[124:125], v[124:125] op_sel:[0,1] op_sel_hi:[1,0]
	s_mov_b32 s31, 0x33800000
	v_pk_add_f32 v[122:123], v[122:123], v[126:127] op_sel:[1,0] op_sel_hi:[0,1]
	v_mov_b32_e32 v125, v122
	v_pk_add_f32 v[128:129], v[124:125], v[130:131] neg_lo:[0,1] neg_hi:[0,1]
	v_mov_b32_e32 v99, v126
	v_sub_f32_e32 v123, v124, v128
	v_pk_add_f32 v[98:99], v[98:99], v[128:129] neg_lo:[0,1] neg_hi:[0,1]
	v_sub_f32_e32 v123, v130, v123
	v_add_f32_e32 v98, v98, v123
	v_add_f32_e32 v98, v98, v99
	v_add_f32_e32 v98, v122, v98
	v_cndmask_b32_e32 v98, v237, v98, vcc
	v_cmp_ngt_f32_e32 vcc, -1.0, v105
	s_nop 1
	v_cndmask_b32_e32 v98, v238, v98, vcc
	v_cmp_neq_f32_e32 vcc, -1.0, v105
	s_nop 1
	v_cndmask_b32_e32 v98, v239, v98, vcc
	v_cmp_lt_f32_e64 vcc, |v105|, s31
	s_nop 1
	v_cndmask_b32_e32 v98, v98, v105, vcc
	v_sub_f32_e32 v98, v0, v98

.LBB0_767:
	s_or_b64 exec, exec, s[4:5]
	v_or_b32_e32 v122, 1, v104
	v_ashrrev_i32_e32 v123, 31, v122
	v_lshlrev_b64 v[122:123], 13, v[122:123]
	v_lshl_add_u64 v[122:123], v[102:103], 0, v[122:123]
	v_readlane_b32 s4, v254, 26
	global_store_dword v[122:123], v98, off
	v_readlane_b32 s5, v254, 27
	s_nop 4
	s_load_dword s4, s[4:5], 0x8
	s_waitcnt lgkmcnt(0)
	v_mov_b32_e32 v0, s4
	v_add_f32_e32 v0, v100, v0
	v_cmp_nlt_f32_e32 vcc, 0, v0
	s_and_saveexec_b64 s[4:5], vcc
	s_xor_b64 s[4:5], exec, s[4:5]
	s_cbranch_execz .LBB0_769
	v_mul_f32_e32 v98, 0x3fb8aa3b, v0
	v_exp_f32_e32 v100, v98
	s_mov_b32 s31, 0x3f2aaaab
	v_add_f32_e32 v105, 1.0, v100
	v_frexp_mant_f32_e32 v123, v105
	v_cvt_f64_f32_e32 v[98:99], v105
	v_frexp_exp_i32_f64_e32 v98, v[98:99]
	v_cmp_gt_f32_e32 vcc, s31, v123
	v_add_f32_e32 v122, -1.0, v105
	v_sub_f32_e32 v124, v122, v105
	v_subbrev_co_u32_e32 v128, vcc, 0, v98, vcc
	v_sub_u32_e32 v98, 0, v128
	v_sub_f32_e32 v122, v100, v122
	v_add_f32_e32 v124, 1.0, v124
	v_ldexp_f32 v99, v105, v98
	v_add_f32_e32 v122, v122, v124
	v_add_f32_e32 v105, -1.0, v99
	v_add_f32_e32 v123, 1.0, v99
	v_ldexp_f32 v98, v122, v98
	v_add_f32_e32 v122, 1.0, v105
	v_add_f32_e32 v124, -1.0, v123
	v_sub_f32_e32 v122, v99, v122
	v_sub_f32_e32 v99, v99, v124
	v_add_f32_e32 v122, v98, v122
	v_add_f32_e32 v98, v98, v99
	v_add_f32_e32 v129, v123, v98
	v_rcp_f32_e32 v131, v129
	v_sub_f32_e32 v99, v129, v123
	v_sub_f32_e32 v130, v98, v99
	v_add_f32_e32 v99, v105, v122
	v_sub_f32_e32 v98, v99, v105
	v_mul_f32_e32 v132, v99, v131
	v_sub_f32_e32 v105, v122, v98
	v_mul_f32_e32 v122, v129, v132
	v_fma_f32 v124, v132, v129, -v122
	v_fmac_f32_e32 v124, v132, v130
	v_add_f32_e32 v98, v122, v124
	v_sub_f32_e32 v123, v99, v98
	v_pk_add_f32 v[126:127], v[98:99], v[122:123] neg_lo:[0,1] neg_hi:[0,1]
	v_mov_b32_e32 v125, v98
	v_pk_add_f32 v[98:99], v[126:127], v[124:125] neg_lo:[0,1] neg_hi:[0,1]
	s_mov_b32 s31, 0x3f317218
	v_add_f32_e32 v99, v105, v99
	v_add_f32_e32 v98, v98, v99
	v_add_f32_e32 v99, v123, v98
	v_mul_f32_e32 v105, v131, v99
	v_mul_f32_e32 v122, v129, v105
	v_fma_f32 v124, v105, v129, -v122
	v_fmac_f32_e32 v124, v105, v130
	v_sub_f32_e32 v123, v123, v99
	v_add_f32_e32 v129, v98, v123
	v_add_f32_e32 v98, v122, v124
	v_sub_f32_e32 v123, v99, v98
	v_pk_add_f32 v[126:127], v[98:99], v[122:123] neg_lo:[0,1] neg_hi:[0,1]
	v_mov_b32_e32 v125, v98
	v_pk_add_f32 v[98:99], v[126:127], v[124:125] neg_lo:[0,1] neg_hi:[0,1]
	s_nop 0
	v_add_f32_e32 v99, v129, v99
	v_add_f32_e32 v98, v98, v99
	v_add_f32_e32 v99, v132, v105
	v_add_f32_e32 v98, v123, v98
	v_sub_f32_e32 v122, v99, v132
	v_mul_f32_e32 v98, v131, v98
	v_sub_f32_e32 v105, v105, v122
	v_add_f32_e32 v105, v105, v98
	v_add_f32_e32 v122, v99, v105
	v_mul_f32_e32 v124, v122, v122
	v_fmamk_f32 v98, v124, 0x3e9b6dac, v236
	v_fmaak_f32 v205, v124, v98, 0x3f2aaada
	v_cvt_f32_i32_e32 v98, v128
	v_sub_f32_e32 v99, v122, v99
	v_sub_f32_e32 v99, v105, v99
	v_ldexp_f32 v105, v99, 1
	v_mul_f32_e32 v99, v122, v124
	v_pk_mul_f32 v[124:125], v[98:99], v[204:205]
	v_ldexp_f32 v123, v122, 1
	v_fma_f32 v122, v98, s31, -v124
	v_fmac_f32_e32 v122, 0xb102e308, v98
	v_pk_add_f32 v[98:99], v[124:125], v[122:123]
	v_mov_b32_e32 v126, v124
	v_sub_f32_e32 v123, v99, v123
	v_sub_f32_e32 v123, v125, v123
	v_add_f32_e32 v127, v105, v123
	v_pk_add_f32 v[124:125], v[98:99], v[124:125] neg_lo:[0,1] neg_hi:[0,1]
	v_pk_add_f32 v[128:129], v[98:99], v[126:127]
	v_mov_b32_e32 v123, v98
	v_mov_b32_e32 v125, v129
	v_pk_add_f32 v[130:131], v[122:123], v[124:125] neg_lo:[0,1] neg_hi:[0,1]
	v_pk_add_f32 v[122:123], v[122:123], v[124:125]
	v_mov_b32_e32 v126, v127
	v_pk_add_f32 v[124:125], v[122:123], v[98:99] op_sel:[1,0] op_sel_hi:[0,1] neg_lo:[0,1] neg_hi:[0,1]
	v_pk_add_f32 v[132:133], v[128:129], v[124:125] op_sel_hi:[1,0] neg_lo:[0,1] neg_hi:[0,1]
	v_mov_b32_e32 v128, v129
	v_mov_b32_e32 v129, v123
	v_pk_mov_b32 v[124:125], v[98:99], v[124:125] op_sel:[1,0]
	v_mov_b32_e32 v127, v98
	v_pk_add_f32 v[124:125], v[128:129], v[124:125] neg_lo:[0,1] neg_hi:[0,1]
	v_mov_b32_e32 v132, v130
	v_pk_add_f32 v[98:99], v[126:127], v[124:125] neg_lo:[0,1] neg_hi:[0,1]
	v_mov_b32_e32 v131, v123
	v_pk_add_f32 v[124:125], v[132:133], v[98:99]
	s_mov_b32 s31, 0x7f800000
	v_pk_add_f32 v[126:127], v[124:125], v[124:125] op_sel:[0,1] op_sel_hi:[1,0]
	v_cmp_neq_f32_e32 vcc, s31, v100
	v_pk_add_f32 v[122:123], v[122:123], v[126:127] op_sel:[1,0] op_sel_hi:[0,1]
	v_mov_b32_e32 v125, v122
	v_pk_add_f32 v[128:129], v[124:125], v[130:131] neg_lo:[0,1] neg_hi:[0,1]
	v_mov_b32_e32 v99, v126
	v_sub_f32_e32 v105, v124, v128
	v_pk_add_f32 v[98:99], v[98:99], v[128:129] neg_lo:[0,1] neg_hi:[0,1]
	v_sub_f32_e32 v105, v130, v105
	v_add_f32_e32 v98, v98, v105
	v_add_f32_e32 v98, v98, v99
	v_add_f32_e32 v98, v122, v98
	v_cndmask_b32_e32 v98, v237, v98, vcc
	v_cmp_ngt_f32_e32 vcc, -1.0, v100
	s_mov_b32 s31, 0x33800000
	s_nop 0
	v_cndmask_b32_e32 v98, v238, v98, vcc
	v_cmp_neq_f32_e32 vcc, -1.0, v100
	s_nop 1
	v_cndmask_b32_e32 v98, v239, v98, vcc
	v_cmp_lt_f32_e64 vcc, |v100|, s31
	s_nop 1
	v_cndmask_b32_e32 v98, v98, v100, vcc
	v_sub_f32_e32 v98, v0, v98

.LBB0_771:
	s_or_b64 exec, exec, s[4:5]
	v_or_b32_e32 v122, 2, v104
	v_ashrrev_i32_e32 v123, 31, v122
	v_lshlrev_b64 v[122:123], 13, v[122:123]
	v_lshl_add_u64 v[122:123], v[102:103], 0, v[122:123]
	v_readlane_b32 s4, v254, 26
	global_store_dword v[122:123], v98, off
	v_readlane_b32 s5, v254, 27
	s_nop 4
	s_load_dword s4, s[4:5], 0xc
	s_waitcnt lgkmcnt(0)
	v_mov_b32_e32 v0, s4
	v_add_f32_e32 v0, v101, v0
	v_cmp_nlt_f32_e32 vcc, 0, v0
	s_and_saveexec_b64 s[4:5], vcc
	s_xor_b64 s[4:5], exec, s[4:5]
	s_cbranch_execz .LBB0_773
	v_mul_f32_e32 v98, 0x3fb8aa3b, v0
	v_exp_f32_e32 v105, v98
	s_mov_b32 s31, 0x3f2aaaab
	v_add_f32_e32 v100, 1.0, v105
	v_frexp_mant_f32_e32 v122, v100
	v_cvt_f64_f32_e32 v[98:99], v100
	v_frexp_exp_i32_f64_e32 v98, v[98:99]
	v_cmp_gt_f32_e32 vcc, s31, v122
	v_add_f32_e32 v101, -1.0, v100
	v_sub_f32_e32 v123, v101, v100
	v_subbrev_co_u32_e32 v126, vcc, 0, v98, vcc
	v_sub_u32_e32 v98, 0, v126
	v_sub_f32_e32 v101, v105, v101
	v_add_f32_e32 v123, 1.0, v123
	v_ldexp_f32 v99, v100, v98
	v_add_f32_e32 v101, v101, v123
	v_add_f32_e32 v100, -1.0, v99
	v_add_f32_e32 v122, 1.0, v99
	v_ldexp_f32 v98, v101, v98
	v_add_f32_e32 v101, 1.0, v100
	v_add_f32_e32 v123, -1.0, v122
	v_sub_f32_e32 v101, v99, v101
	v_sub_f32_e32 v99, v99, v123
	v_add_f32_e32 v101, v98, v101
	v_add_f32_e32 v98, v98, v99
	v_add_f32_e32 v127, v122, v98
	v_rcp_f32_e32 v129, v127
	v_sub_f32_e32 v99, v127, v122
	v_sub_f32_e32 v128, v98, v99
	v_add_f32_e32 v99, v100, v101
	v_mul_f32_e32 v131, v99, v129
	v_sub_f32_e32 v98, v99, v100
	v_mul_f32_e32 v100, v127, v131
	v_fma_f32 v122, v131, v127, -v100
	v_fmac_f32_e32 v122, v131, v128
	v_sub_f32_e32 v130, v101, v98
	v_add_f32_e32 v98, v100, v122
	v_sub_f32_e32 v101, v99, v98
	v_pk_add_f32 v[124:125], v[98:99], v[100:101] neg_lo:[0,1] neg_hi:[0,1]
	v_mov_b32_e32 v123, v98
	v_pk_add_f32 v[98:99], v[124:125], v[122:123] neg_lo:[0,1] neg_hi:[0,1]
	s_mov_b32 s31, 0x3f317218
	v_add_f32_e32 v99, v130, v99
	v_add_f32_e32 v98, v98, v99
	v_add_f32_e32 v99, v101, v98
	v_mul_f32_e32 v130, v129, v99
	v_mul_f32_e32 v100, v127, v130
	v_fma_f32 v122, v130, v127, -v100
	v_fmac_f32_e32 v122, v130, v128
	v_sub_f32_e32 v101, v101, v99
	v_add_f32_e32 v127, v98, v101
	v_add_f32_e32 v98, v100, v122
	v_sub_f32_e32 v101, v99, v98
	v_pk_add_f32 v[124:125], v[98:99], v[100:101] neg_lo:[0,1] neg_hi:[0,1]
	v_mov_b32_e32 v123, v98
	v_pk_add_f32 v[98:99], v[124:125], v[122:123] neg_lo:[0,1] neg_hi:[0,1]
	s_nop 0
	v_add_f32_e32 v99, v127, v99
	v_add_f32_e32 v98, v98, v99
	v_add_f32_e32 v99, v131, v130
	v_add_f32_e32 v98, v101, v98
	v_sub_f32_e32 v100, v99, v131
	v_mul_f32_e32 v98, v129, v98
	v_sub_f32_e32 v100, v130, v100
	v_add_f32_e32 v100, v100, v98
	v_add_f32_e32 v122, v99, v100
	v_mul_f32_e32 v123, v122, v122
	v_fmamk_f32 v98, v123, 0x3e9b6dac, v236
	v_fmaak_f32 v205, v123, v98, 0x3f2aaada
	v_cvt_f32_i32_e32 v98, v126
	v_sub_f32_e32 v99, v122, v99
	v_sub_f32_e32 v99, v100, v99
	v_ldexp_f32 v124, v99, 1
	v_mul_f32_e32 v99, v122, v123
	v_ldexp_f32 v101, v122, 1
	v_pk_mul_f32 v[122:123], v[98:99], v[204:205]
	s_nop 0
	v_fma_f32 v100, v98, s31, -v122
	v_fmac_f32_e32 v100, 0xb102e308, v98
	v_pk_add_f32 v[98:99], v[122:123], v[100:101]
	s_mov_b32 s31, 0x7f800000
	v_sub_f32_e32 v101, v99, v101
	v_sub_f32_e32 v101, v123, v101
	v_add_f32_e32 v125, v124, v101
	v_mov_b32_e32 v124, v122
	v_pk_add_f32 v[122:123], v[98:99], v[122:123] neg_lo:[0,1] neg_hi:[0,1]
	v_pk_add_f32 v[126:127], v[98:99], v[124:125]
	v_mov_b32_e32 v101, v98
	v_mov_b32_e32 v123, v127
	v_pk_add_f32 v[128:129], v[100:101], v[122:123] neg_lo:[0,1] neg_hi:[0,1]
	v_pk_add_f32 v[100:101], v[100:101], v[122:123]
	v_mov_b32_e32 v124, v125
	v_pk_add_f32 v[122:123], v[100:101], v[98:99] op_sel:[1,0] op_sel_hi:[0,1] neg_lo:[0,1] neg_hi:[0,1]
	v_pk_add_f32 v[130:131], v[126:127], v[122:123] op_sel_hi:[1,0] neg_lo:[0,1] neg_hi:[0,1]
	v_mov_b32_e32 v126, v127
	v_mov_b32_e32 v127, v101
	v_pk_mov_b32 v[122:123], v[98:99], v[122:123] op_sel:[1,0]
	v_mov_b32_e32 v125, v98
	v_pk_add_f32 v[122:123], v[126:127], v[122:123] neg_lo:[0,1] neg_hi:[0,1]
	v_mov_b32_e32 v130, v128
	v_pk_add_f32 v[98:99], v[124:125], v[122:123] neg_lo:[0,1] neg_hi:[0,1]
	v_mov_b32_e32 v129, v101
	v_pk_add_f32 v[122:123], v[130:131], v[98:99]
	v_cmp_neq_f32_e32 vcc, s31, v105
	v_pk_add_f32 v[124:125], v[122:123], v[122:123] op_sel:[0,1] op_sel_hi:[1,0]
	s_mov_b32 s31, 0x33800000
	v_pk_add_f32 v[100:101], v[100:101], v[124:125] op_sel:[1,0] op_sel_hi:[0,1]
	v_mov_b32_e32 v123, v100
	v_pk_add_f32 v[126:127], v[122:123], v[128:129] neg_lo:[0,1] neg_hi:[0,1]
	v_mov_b32_e32 v99, v124
	v_sub_f32_e32 v101, v122, v126
	v_pk_add_f32 v[98:99], v[98:99], v[126:127] neg_lo:[0,1] neg_hi:[0,1]
	v_sub_f32_e32 v101, v128, v101
	v_add_f32_e32 v98, v98, v101
	v_add_f32_e32 v98, v98, v99
	v_add_f32_e32 v98, v100, v98
	v_cndmask_b32_e32 v98, v237, v98, vcc
	v_cmp_ngt_f32_e32 vcc, -1.0, v105
	s_nop 1
	v_cndmask_b32_e32 v98, v238, v98, vcc
	v_cmp_neq_f32_e32 vcc, -1.0, v105
	s_nop 1
	v_cndmask_b32_e32 v98, v239, v98, vcc
	v_cmp_lt_f32_e64 vcc, |v105|, s31
	s_nop 1
	v_cndmask_b32_e32 v98, v98, v105, vcc
	v_sub_f32_e32 v98, v0, v98

.LBB0_798:
	s_and_saveexec_b64 s[4:5], s[10:11]
	s_xor_b64 s[18:19], exec, s[4:5]
	s_cbranch_execz .LBB0_816
	v_readlane_b32 s4, v254, 26
	v_readlane_b32 s5, v254, 27
	s_waitcnt lgkmcnt(0)
	s_nop 3
	s_load_dword s4, s[4:5], 0x0
	s_waitcnt lgkmcnt(0)
	v_mov_b32_e32 v0, s4
	v_add_f32_e32 v0, v74, v0
	v_cmp_nlt_f32_e32 vcc, 0, v0
	s_and_saveexec_b64 s[4:5], vcc
	s_xor_b64 s[4:5], exec, s[4:5]
	s_cbranch_execz .LBB0_801
	v_mul_f32_e32 v74, 0x3fb8aa3b, v0
	v_exp_f32_e32 v74, v74
	s_mov_b32 s31, 0x3f2aaaab
	v_add_f32_e32 v80, 1.0, v74
	v_frexp_mant_f32_e32 v98, v80
	v_cvt_f64_f32_e32 v[78:79], v80
	v_frexp_exp_i32_f64_e32 v78, v[78:79]
	v_cmp_gt_f32_e32 vcc, s31, v98
	v_add_f32_e32 v81, -1.0, v80
	v_sub_f32_e32 v99, v81, v80
	v_subbrev_co_u32_e32 v102, vcc, 0, v78, vcc
	v_sub_u32_e32 v78, 0, v102
	v_sub_f32_e32 v81, v74, v81
	v_add_f32_e32 v99, 1.0, v99
	v_ldexp_f32 v79, v80, v78
	v_add_f32_e32 v81, v81, v99
	v_add_f32_e32 v80, -1.0, v79
	v_add_f32_e32 v98, 1.0, v79
	v_ldexp_f32 v78, v81, v78
	v_add_f32_e32 v81, 1.0, v80
	v_add_f32_e32 v99, -1.0, v98
	v_sub_f32_e32 v81, v79, v81
	v_sub_f32_e32 v79, v79, v99
	v_add_f32_e32 v81, v78, v81
	v_add_f32_e32 v78, v78, v79
	v_add_f32_e32 v103, v98, v78
	v_rcp_f32_e32 v105, v103
	v_sub_f32_e32 v79, v103, v98
	v_sub_f32_e32 v104, v78, v79
	v_add_f32_e32 v79, v80, v81
	v_mul_f32_e32 v107, v79, v105
	v_sub_f32_e32 v78, v79, v80
	v_mul_f32_e32 v80, v103, v107
	v_fma_f32 v98, v107, v103, -v80
	v_fmac_f32_e32 v98, v107, v104
	v_sub_f32_e32 v106, v81, v78
	v_add_f32_e32 v78, v80, v98
	v_sub_f32_e32 v81, v79, v78
	v_pk_add_f32 v[100:101], v[78:79], v[80:81] neg_lo:[0,1] neg_hi:[0,1]
	v_mov_b32_e32 v99, v78
	v_pk_add_f32 v[78:79], v[100:101], v[98:99] neg_lo:[0,1] neg_hi:[0,1]
	s_mov_b32 s31, 0x3f317218
	v_add_f32_e32 v79, v106, v79
	v_add_f32_e32 v78, v78, v79
	v_add_f32_e32 v79, v81, v78
	v_mul_f32_e32 v106, v105, v79
	v_mul_f32_e32 v80, v103, v106
	v_fma_f32 v98, v106, v103, -v80
	v_fmac_f32_e32 v98, v106, v104
	v_sub_f32_e32 v81, v81, v79
	v_add_f32_e32 v103, v78, v81
	v_add_f32_e32 v78, v80, v98
	v_sub_f32_e32 v81, v79, v78
	v_pk_add_f32 v[100:101], v[78:79], v[80:81] neg_lo:[0,1] neg_hi:[0,1]
	v_mov_b32_e32 v99, v78
	v_pk_add_f32 v[78:79], v[100:101], v[98:99] neg_lo:[0,1] neg_hi:[0,1]
	s_nop 0
	v_add_f32_e32 v79, v103, v79
	v_add_f32_e32 v78, v78, v79
	v_add_f32_e32 v79, v107, v106
	v_add_f32_e32 v78, v81, v78
	v_sub_f32_e32 v80, v79, v107
	v_mul_f32_e32 v78, v105, v78
	v_sub_f32_e32 v80, v106, v80
	v_add_f32_e32 v80, v80, v78
	v_add_f32_e32 v98, v79, v80
	v_mul_f32_e32 v99, v98, v98
	v_fmamk_f32 v78, v99, 0x3e9b6dac, v236
	v_fmaak_f32 v205, v99, v78, 0x3f2aaada
	v_cvt_f32_i32_e32 v78, v102
	v_sub_f32_e32 v79, v98, v79
	v_sub_f32_e32 v79, v80, v79
	v_ldexp_f32 v100, v79, 1
	v_mul_f32_e32 v79, v98, v99
	v_ldexp_f32 v81, v98, 1
	v_pk_mul_f32 v[98:99], v[78:79], v[204:205]
	s_nop 0
	v_fma_f32 v80, v78, s31, -v98
	v_fmac_f32_e32 v80, 0xb102e308, v78
	v_pk_add_f32 v[78:79], v[98:99], v[80:81]
	s_mov_b32 s31, 0x7f800000
	v_sub_f32_e32 v81, v79, v81
	v_sub_f32_e32 v81, v99, v81
	v_add_f32_e32 v101, v100, v81
	v_mov_b32_e32 v100, v98
	v_pk_add_f32 v[98:99], v[78:79], v[98:99] neg_lo:[0,1] neg_hi:[0,1]
	v_pk_add_f32 v[102:103], v[78:79], v[100:101]
	v_mov_b32_e32 v81, v78
	v_mov_b32_e32 v99, v103
	v_pk_add_f32 v[104:105], v[80:81], v[98:99] neg_lo:[0,1] neg_hi:[0,1]
	v_pk_add_f32 v[80:81], v[80:81], v[98:99]
	v_mov_b32_e32 v100, v101
	v_pk_add_f32 v[98:99], v[80:81], v[78:79] op_sel:[1,0] op_sel_hi:[0,1] neg_lo:[0,1] neg_hi:[0,1]
	v_pk_add_f32 v[106:107], v[102:103], v[98:99] op_sel_hi:[1,0] neg_lo:[0,1] neg_hi:[0,1]
	v_mov_b32_e32 v102, v103
	v_mov_b32_e32 v103, v81
	v_pk_mov_b32 v[98:99], v[78:79], v[98:99] op_sel:[1,0]
	v_mov_b32_e32 v101, v78
	v_pk_add_f32 v[98:99], v[102:103], v[98:99] neg_lo:[0,1] neg_hi:[0,1]
	v_mov_b32_e32 v106, v104
	v_pk_add_f32 v[78:79], v[100:101], v[98:99] neg_lo:[0,1] neg_hi:[0,1]
	v_mov_b32_e32 v105, v81
	v_pk_add_f32 v[98:99], v[106:107], v[78:79]
	v_cmp_neq_f32_e32 vcc, s31, v74
	v_pk_add_f32 v[100:101], v[98:99], v[98:99] op_sel:[0,1] op_sel_hi:[1,0]
	s_mov_b32 s31, 0x33800000
	v_pk_add_f32 v[80:81], v[80:81], v[100:101] op_sel:[1,0] op_sel_hi:[0,1]
	v_mov_b32_e32 v99, v80
	v_pk_add_f32 v[102:103], v[98:99], v[104:105] neg_lo:[0,1] neg_hi:[0,1]
	v_mov_b32_e32 v79, v100
	v_sub_f32_e32 v81, v98, v102
	v_pk_add_f32 v[78:79], v[78:79], v[102:103] neg_lo:[0,1] neg_hi:[0,1]
	v_sub_f32_e32 v81, v104, v81
	v_add_f32_e32 v78, v78, v81
	v_add_f32_e32 v78, v78, v79
	v_add_f32_e32 v78, v80, v78
	v_cndmask_b32_e32 v78, v237, v78, vcc
	v_cmp_ngt_f32_e32 vcc, -1.0, v74
	s_nop 1
	v_cndmask_b32_e32 v78, v238, v78, vcc
	v_cmp_neq_f32_e32 vcc, -1.0, v74
	s_nop 1
	v_cndmask_b32_e32 v78, v239, v78, vcc
	v_cmp_lt_f32_e64 vcc, |v74|, s31
	s_nop 1
	v_cndmask_b32_e32 v74, v78, v74, vcc
	v_sub_f32_e32 v74, v0, v74

.LBB0_803:
	s_or_b64 exec, exec, s[4:5]
	v_lshlrev_b32_e32 v80, 2, v109
	v_lshlrev_b32_e32 v0, 2, v110
	v_ashrrev_i32_e32 v81, 31, v80
	v_lshl_add_u64 v[78:79], s[84:85], 0, v[0:1]
	v_lshlrev_b64 v[98:99], 13, v[80:81]
	v_lshl_add_u64 v[98:99], v[78:79], 0, v[98:99]
	v_readlane_b32 s4, v254, 26
	global_store_dword v[98:99], v74, off
	v_readlane_b32 s5, v254, 27
	s_nop 4
	s_load_dword s4, s[4:5], 0x4
	s_waitcnt lgkmcnt(0)
	v_mov_b32_e32 v0, s4
	v_add_f32_e32 v0, v75, v0
	v_cmp_nlt_f32_e32 vcc, 0, v0
	s_and_saveexec_b64 s[4:5], vcc
	s_xor_b64 s[4:5], exec, s[4:5]
	s_cbranch_execz .LBB0_805
	v_mul_f32_e32 v74, 0x3fb8aa3b, v0
	v_exp_f32_e32 v81, v74
	s_mov_b32 s31, 0x3f2aaaab
	v_add_f32_e32 v98, 1.0, v81
	v_frexp_mant_f32_e32 v100, v98
	v_cvt_f64_f32_e32 v[74:75], v98
	v_frexp_exp_i32_f64_e32 v74, v[74:75]
	v_cmp_gt_f32_e32 vcc, s31, v100
	v_add_f32_e32 v99, -1.0, v98
	v_sub_f32_e32 v101, v99, v98
	v_subbrev_co_u32_e32 v104, vcc, 0, v74, vcc
	v_sub_u32_e32 v74, 0, v104
	v_sub_f32_e32 v99, v81, v99
	v_add_f32_e32 v101, 1.0, v101
	v_ldexp_f32 v75, v98, v74
	v_add_f32_e32 v99, v99, v101
	v_add_f32_e32 v98, -1.0, v75
	v_add_f32_e32 v100, 1.0, v75
	v_ldexp_f32 v74, v99, v74
	v_add_f32_e32 v99, 1.0, v98
	v_add_f32_e32 v101, -1.0, v100
	v_sub_f32_e32 v99, v75, v99
	v_sub_f32_e32 v75, v75, v101
	v_add_f32_e32 v99, v74, v99
	v_add_f32_e32 v74, v74, v75
	v_add_f32_e32 v105, v100, v74
	v_rcp_f32_e32 v107, v105
	v_sub_f32_e32 v75, v105, v100
	v_sub_f32_e32 v106, v74, v75
	v_add_f32_e32 v75, v98, v99
	v_mul_f32_e32 v109, v75, v107
	v_sub_f32_e32 v74, v75, v98
	v_mul_f32_e32 v98, v105, v109
	v_fma_f32 v100, v109, v105, -v98
	v_fmac_f32_e32 v100, v109, v106
	v_sub_f32_e32 v108, v99, v74
	v_add_f32_e32 v74, v98, v100
	v_sub_f32_e32 v99, v75, v74
	v_pk_add_f32 v[102:103], v[74:75], v[98:99] neg_lo:[0,1] neg_hi:[0,1]
	v_mov_b32_e32 v101, v74
	v_pk_add_f32 v[74:75], v[102:103], v[100:101] neg_lo:[0,1] neg_hi:[0,1]
	s_mov_b32 s31, 0x3f317218
	v_add_f32_e32 v75, v108, v75
	v_add_f32_e32 v74, v74, v75
	v_add_f32_e32 v75, v99, v74
	v_mul_f32_e32 v108, v107, v75
	v_mul_f32_e32 v98, v105, v108
	v_fma_f32 v100, v108, v105, -v98
	v_fmac_f32_e32 v100, v108, v106
	v_sub_f32_e32 v99, v99, v75
	v_add_f32_e32 v105, v74, v99
	v_add_f32_e32 v74, v98, v100
	v_sub_f32_e32 v99, v75, v74
	v_pk_add_f32 v[102:103], v[74:75], v[98:99] neg_lo:[0,1] neg_hi:[0,1]
	v_mov_b32_e32 v101, v74
	v_pk_add_f32 v[74:75], v[102:103], v[100:101] neg_lo:[0,1] neg_hi:[0,1]
	s_nop 0
	v_add_f32_e32 v75, v105, v75
	v_add_f32_e32 v74, v74, v75
	v_add_f32_e32 v75, v109, v108
	v_add_f32_e32 v74, v99, v74
	v_sub_f32_e32 v98, v75, v109
	v_mul_f32_e32 v74, v107, v74
	v_sub_f32_e32 v98, v108, v98
	v_add_f32_e32 v98, v98, v74
	v_add_f32_e32 v100, v75, v98
	v_mul_f32_e32 v101, v100, v100
	v_fmamk_f32 v74, v101, 0x3e9b6dac, v236
	v_fmaak_f32 v205, v101, v74, 0x3f2aaada
	v_cvt_f32_i32_e32 v74, v104
	v_sub_f32_e32 v75, v100, v75
	v_sub_f32_e32 v75, v98, v75
	v_ldexp_f32 v102, v75, 1
	v_mul_f32_e32 v75, v100, v101
	v_ldexp_f32 v99, v100, 1
	v_pk_mul_f32 v[100:101], v[74:75], v[204:205]
	s_nop 0
	v_fma_f32 v98, v74, s31, -v100
	v_fmac_f32_e32 v98, 0xb102e308, v74
	v_pk_add_f32 v[74:75], v[100:101], v[98:99]
	s_mov_b32 s31, 0x7f800000
	v_sub_f32_e32 v99, v75, v99
	v_sub_f32_e32 v99, v101, v99
	v_add_f32_e32 v103, v102, v99
	v_mov_b32_e32 v102, v100
	v_pk_add_f32 v[100:101], v[74:75], v[100:101] neg_lo:[0,1] neg_hi:[0,1]
	v_pk_add_f32 v[104:105], v[74:75], v[102:103]
	v_mov_b32_e32 v99, v74
	v_mov_b32_e32 v101, v105
	v_pk_add_f32 v[106:107], v[98:99], v[100:101] neg_lo:[0,1] neg_hi:[0,1]
	v_pk_add_f32 v[98:99], v[98:99], v[100:101]
	v_mov_b32_e32 v102, v103
	v_pk_add_f32 v[100:101], v[98:99], v[74:75] op_sel:[1,0] op_sel_hi:[0,1] neg_lo:[0,1] neg_hi:[0,1]
	v_pk_add_f32 v[108:109], v[104:105], v[100:101] op_sel_hi:[1,0] neg_lo:[0,1] neg_hi:[0,1]
	v_mov_b32_e32 v104, v105
	v_mov_b32_e32 v105, v99
	v_pk_mov_b32 v[100:101], v[74:75], v[100:101] op_sel:[1,0]
	v_mov_b32_e32 v103, v74
	v_pk_add_f32 v[100:101], v[104:105], v[100:101] neg_lo:[0,1] neg_hi:[0,1]
	v_mov_b32_e32 v108, v106
	v_pk_add_f32 v[74:75], v[102:103], v[100:101] neg_lo:[0,1] neg_hi:[0,1]
	v_mov_b32_e32 v107, v99
	v_pk_add_f32 v[100:101], v[108:109], v[74:75]
	v_cmp_neq_f32_e32 vcc, s31, v81
	v_pk_add_f32 v[102:103], v[100:101], v[100:101] op_sel:[0,1] op_sel_hi:[1,0]
	s_mov_b32 s31, 0x33800000
	v_pk_add_f32 v[98:99], v[98:99], v[102:103] op_sel:[1,0] op_sel_hi:[0,1]
	v_mov_b32_e32 v101, v98
	v_pk_add_f32 v[104:105], v[100:101], v[106:107] neg_lo:[0,1] neg_hi:[0,1]
	v_mov_b32_e32 v75, v102
	v_sub_f32_e32 v99, v100, v104
	v_pk_add_f32 v[74:75], v[74:75], v[104:105] neg_lo:[0,1] neg_hi:[0,1]
	v_sub_f32_e32 v99, v106, v99
	v_add_f32_e32 v74, v74, v99
	v_add_f32_e32 v74, v74, v75
	v_add_f32_e32 v74, v98, v74
	v_cndmask_b32_e32 v74, v237, v74, vcc
	v_cmp_ngt_f32_e32 vcc, -1.0, v81
	s_nop 1
	v_cndmask_b32_e32 v74, v238, v74, vcc
	v_cmp_neq_f32_e32 vcc, -1.0, v81
	s_nop 1
	v_cndmask_b32_e32 v74, v239, v74, vcc
	v_cmp_lt_f32_e64 vcc, |v81|, s31
	s_nop 1
	v_cndmask_b32_e32 v74, v74, v81, vcc
	v_sub_f32_e32 v74, v0, v74

.LBB0_807:
	s_or_b64 exec, exec, s[4:5]
	v_or_b32_e32 v98, 1, v80
	v_ashrrev_i32_e32 v99, 31, v98
	v_lshlrev_b64 v[98:99], 13, v[98:99]
	v_lshl_add_u64 v[98:99], v[78:79], 0, v[98:99]
	v_readlane_b32 s4, v254, 26
	global_store_dword v[98:99], v74, off
	v_readlane_b32 s5, v254, 27
	s_nop 4
	s_load_dword s4, s[4:5], 0x8
	s_waitcnt lgkmcnt(0)
	v_mov_b32_e32 v0, s4
	v_add_f32_e32 v0, v76, v0
	v_cmp_nlt_f32_e32 vcc, 0, v0
	s_and_saveexec_b64 s[4:5], vcc
	s_xor_b64 s[4:5], exec, s[4:5]
	s_cbranch_execz .LBB0_809
	v_mul_f32_e32 v74, 0x3fb8aa3b, v0
	v_exp_f32_e32 v76, v74
	s_mov_b32 s31, 0x3f2aaaab
	v_add_f32_e32 v81, 1.0, v76
	v_frexp_mant_f32_e32 v99, v81
	v_cvt_f64_f32_e32 v[74:75], v81
	v_frexp_exp_i32_f64_e32 v74, v[74:75]
	v_cmp_gt_f32_e32 vcc, s31, v99
	v_add_f32_e32 v98, -1.0, v81
	v_sub_f32_e32 v100, v98, v81
	v_subbrev_co_u32_e32 v104, vcc, 0, v74, vcc
	v_sub_u32_e32 v74, 0, v104
	v_sub_f32_e32 v98, v76, v98
	v_add_f32_e32 v100, 1.0, v100
	v_ldexp_f32 v75, v81, v74
	v_add_f32_e32 v98, v98, v100
	v_add_f32_e32 v81, -1.0, v75
	v_add_f32_e32 v99, 1.0, v75
	v_ldexp_f32 v74, v98, v74
	v_add_f32_e32 v98, 1.0, v81
	v_add_f32_e32 v100, -1.0, v99
	v_sub_f32_e32 v98, v75, v98
	v_sub_f32_e32 v75, v75, v100
	v_add_f32_e32 v98, v74, v98
	v_add_f32_e32 v74, v74, v75
	v_add_f32_e32 v105, v99, v74
	v_rcp_f32_e32 v107, v105
	v_sub_f32_e32 v75, v105, v99
	v_sub_f32_e32 v106, v74, v75
	v_add_f32_e32 v75, v81, v98
	v_sub_f32_e32 v74, v75, v81
	v_mul_f32_e32 v108, v75, v107
	v_sub_f32_e32 v81, v98, v74
	v_mul_f32_e32 v98, v105, v108
	v_fma_f32 v100, v108, v105, -v98
	v_fmac_f32_e32 v100, v108, v106
	v_add_f32_e32 v74, v98, v100
	v_sub_f32_e32 v99, v75, v74
	v_pk_add_f32 v[102:103], v[74:75], v[98:99] neg_lo:[0,1] neg_hi:[0,1]
	v_mov_b32_e32 v101, v74
	v_pk_add_f32 v[74:75], v[102:103], v[100:101] neg_lo:[0,1] neg_hi:[0,1]
	s_mov_b32 s31, 0x3f317218
	v_add_f32_e32 v75, v81, v75
	v_add_f32_e32 v74, v74, v75
	v_add_f32_e32 v75, v99, v74
	v_mul_f32_e32 v81, v107, v75
	v_mul_f32_e32 v98, v105, v81
	v_fma_f32 v100, v81, v105, -v98
	v_fmac_f32_e32 v100, v81, v106
	v_sub_f32_e32 v99, v99, v75
	v_add_f32_e32 v105, v74, v99
	v_add_f32_e32 v74, v98, v100
	v_sub_f32_e32 v99, v75, v74
	v_pk_add_f32 v[102:103], v[74:75], v[98:99] neg_lo:[0,1] neg_hi:[0,1]
	v_mov_b32_e32 v101, v74
	v_pk_add_f32 v[74:75], v[102:103], v[100:101] neg_lo:[0,1] neg_hi:[0,1]
	s_nop 0
	v_add_f32_e32 v75, v105, v75
	v_add_f32_e32 v74, v74, v75
	v_add_f32_e32 v75, v108, v81
	v_add_f32_e32 v74, v99, v74
	v_sub_f32_e32 v98, v75, v108
	v_mul_f32_e32 v74, v107, v74
	v_sub_f32_e32 v81, v81, v98
	v_add_f32_e32 v81, v81, v74
	v_add_f32_e32 v98, v75, v81
	v_mul_f32_e32 v100, v98, v98
	v_fmamk_f32 v74, v100, 0x3e9b6dac, v236
	v_fmaak_f32 v205, v100, v74, 0x3f2aaada
	v_cvt_f32_i32_e32 v74, v104
	v_sub_f32_e32 v75, v98, v75
	v_sub_f32_e32 v75, v81, v75
	v_ldexp_f32 v81, v75, 1
	v_mul_f32_e32 v75, v98, v100
	v_pk_mul_f32 v[100:101], v[74:75], v[204:205]
	v_ldexp_f32 v99, v98, 1
	v_fma_f32 v98, v74, s31, -v100
	v_fmac_f32_e32 v98, 0xb102e308, v74
	v_pk_add_f32 v[74:75], v[100:101], v[98:99]
	v_mov_b32_e32 v102, v100
	v_sub_f32_e32 v99, v75, v99
	v_sub_f32_e32 v99, v101, v99
	v_add_f32_e32 v103, v81, v99
	v_pk_add_f32 v[100:101], v[74:75], v[100:101] neg_lo:[0,1] neg_hi:[0,1]
	v_pk_add_f32 v[104:105], v[74:75], v[102:103]
	v_mov_b32_e32 v99, v74
	v_mov_b32_e32 v101, v105
	v_pk_add_f32 v[106:107], v[98:99], v[100:101] neg_lo:[0,1] neg_hi:[0,1]
	v_pk_add_f32 v[98:99], v[98:99], v[100:101]
	v_mov_b32_e32 v102, v103
	v_pk_add_f32 v[100:101], v[98:99], v[74:75] op_sel:[1,0] op_sel_hi:[0,1] neg_lo:[0,1] neg_hi:[0,1]
	v_pk_add_f32 v[108:109], v[104:105], v[100:101] op_sel_hi:[1,0] neg_lo:[0,1] neg_hi:[0,1]
	v_mov_b32_e32 v104, v105
	v_mov_b32_e32 v105, v99
	v_pk_mov_b32 v[100:101], v[74:75], v[100:101] op_sel:[1,0]
	v_mov_b32_e32 v103, v74
	v_pk_add_f32 v[100:101], v[104:105], v[100:101] neg_lo:[0,1] neg_hi:[0,1]
	v_mov_b32_e32 v108, v106
	v_pk_add_f32 v[74:75], v[102:103], v[100:101] neg_lo:[0,1] neg_hi:[0,1]
	v_mov_b32_e32 v107, v99
	v_pk_add_f32 v[100:101], v[108:109], v[74:75]
	s_mov_b32 s31, 0x7f800000
	v_pk_add_f32 v[102:103], v[100:101], v[100:101] op_sel:[0,1] op_sel_hi:[1,0]
	v_cmp_neq_f32_e32 vcc, s31, v76
	v_pk_add_f32 v[98:99], v[98:99], v[102:103] op_sel:[1,0] op_sel_hi:[0,1]
	v_mov_b32_e32 v101, v98
	v_pk_add_f32 v[104:105], v[100:101], v[106:107] neg_lo:[0,1] neg_hi:[0,1]
	v_mov_b32_e32 v75, v102
	v_sub_f32_e32 v81, v100, v104
	v_pk_add_f32 v[74:75], v[74:75], v[104:105] neg_lo:[0,1] neg_hi:[0,1]
	v_sub_f32_e32 v81, v106, v81
	v_add_f32_e32 v74, v74, v81
	v_add_f32_e32 v74, v74, v75
	v_add_f32_e32 v74, v98, v74
	v_cndmask_b32_e32 v74, v237, v74, vcc
	v_cmp_ngt_f32_e32 vcc, -1.0, v76
	s_mov_b32 s31, 0x33800000
	s_nop 0
	v_cndmask_b32_e32 v74, v238, v74, vcc
	v_cmp_neq_f32_e32 vcc, -1.0, v76
	s_nop 1
	v_cndmask_b32_e32 v74, v239, v74, vcc
	v_cmp_lt_f32_e64 vcc, |v76|, s31
	s_nop 1
	v_cndmask_b32_e32 v74, v74, v76, vcc
	v_sub_f32_e32 v74, v0, v74

.LBB0_811:
	s_or_b64 exec, exec, s[4:5]
	v_or_b32_e32 v98, 2, v80
	v_ashrrev_i32_e32 v99, 31, v98
	v_lshlrev_b64 v[98:99], 13, v[98:99]
	v_lshl_add_u64 v[98:99], v[78:79], 0, v[98:99]
	v_readlane_b32 s4, v254, 26
	global_store_dword v[98:99], v74, off
	v_readlane_b32 s5, v254, 27
	s_nop 4
	s_load_dword s4, s[4:5], 0xc
	s_waitcnt lgkmcnt(0)
	v_mov_b32_e32 v0, s4
	v_add_f32_e32 v0, v77, v0
	v_cmp_nlt_f32_e32 vcc, 0, v0
	s_and_saveexec_b64 s[4:5], vcc
	s_xor_b64 s[4:5], exec, s[4:5]
	s_cbranch_execz .LBB0_813
	v_mul_f32_e32 v74, 0x3fb8aa3b, v0
	v_exp_f32_e32 v81, v74
	s_mov_b32 s31, 0x3f2aaaab
	v_add_f32_e32 v76, 1.0, v81
	v_frexp_mant_f32_e32 v98, v76
	v_cvt_f64_f32_e32 v[74:75], v76
	v_frexp_exp_i32_f64_e32 v74, v[74:75]
	v_cmp_gt_f32_e32 vcc, s31, v98
	v_add_f32_e32 v77, -1.0, v76
	v_sub_f32_e32 v99, v77, v76
	v_subbrev_co_u32_e32 v102, vcc, 0, v74, vcc
	v_sub_u32_e32 v74, 0, v102
	v_sub_f32_e32 v77, v81, v77
	v_add_f32_e32 v99, 1.0, v99
	v_ldexp_f32 v75, v76, v74
	v_add_f32_e32 v77, v77, v99
	v_add_f32_e32 v76, -1.0, v75
	v_add_f32_e32 v98, 1.0, v75
	v_ldexp_f32 v74, v77, v74
	v_add_f32_e32 v77, 1.0, v76
	v_add_f32_e32 v99, -1.0, v98
	v_sub_f32_e32 v77, v75, v77
	v_sub_f32_e32 v75, v75, v99
	v_add_f32_e32 v77, v74, v77
	v_add_f32_e32 v74, v74, v75
	v_add_f32_e32 v103, v98, v74
	v_rcp_f32_e32 v105, v103
	v_sub_f32_e32 v75, v103, v98
	v_sub_f32_e32 v104, v74, v75
	v_add_f32_e32 v75, v76, v77
	v_mul_f32_e32 v107, v75, v105
	v_sub_f32_e32 v74, v75, v76
	v_mul_f32_e32 v76, v103, v107
	v_fma_f32 v98, v107, v103, -v76
	v_fmac_f32_e32 v98, v107, v104
	v_sub_f32_e32 v106, v77, v74
	v_add_f32_e32 v74, v76, v98
	v_sub_f32_e32 v77, v75, v74
	v_pk_add_f32 v[100:101], v[74:75], v[76:77] neg_lo:[0,1] neg_hi:[0,1]
	v_mov_b32_e32 v99, v74
	v_pk_add_f32 v[74:75], v[100:101], v[98:99] neg_lo:[0,1] neg_hi:[0,1]
	s_mov_b32 s31, 0x3f317218
	v_add_f32_e32 v75, v106, v75
	v_add_f32_e32 v74, v74, v75
	v_add_f32_e32 v75, v77, v74
	v_mul_f32_e32 v106, v105, v75
	v_mul_f32_e32 v76, v103, v106
	v_fma_f32 v98, v106, v103, -v76
	v_fmac_f32_e32 v98, v106, v104
	v_sub_f32_e32 v77, v77, v75
	v_add_f32_e32 v103, v74, v77
	v_add_f32_e32 v74, v76, v98
	v_sub_f32_e32 v77, v75, v74
	v_pk_add_f32 v[100:101], v[74:75], v[76:77] neg_lo:[0,1] neg_hi:[0,1]
	v_mov_b32_e32 v99, v74
	v_pk_add_f32 v[74:75], v[100:101], v[98:99] neg_lo:[0,1] neg_hi:[0,1]
	s_nop 0
	v_add_f32_e32 v75, v103, v75
	v_add_f32_e32 v74, v74, v75
	v_add_f32_e32 v75, v107, v106
	v_add_f32_e32 v74, v77, v74
	v_sub_f32_e32 v76, v75, v107
	v_mul_f32_e32 v74, v105, v74
	v_sub_f32_e32 v76, v106, v76
	v_add_f32_e32 v76, v76, v74
	v_add_f32_e32 v98, v75, v76
	v_mul_f32_e32 v99, v98, v98
	v_fmamk_f32 v74, v99, 0x3e9b6dac, v236
	v_fmaak_f32 v205, v99, v74, 0x3f2aaada
	v_cvt_f32_i32_e32 v74, v102
	v_sub_f32_e32 v75, v98, v75
	v_sub_f32_e32 v75, v76, v75
	v_ldexp_f32 v100, v75, 1
	v_mul_f32_e32 v75, v98, v99
	v_ldexp_f32 v77, v98, 1
	v_pk_mul_f32 v[98:99], v[74:75], v[204:205]
	s_nop 0
	v_fma_f32 v76, v74, s31, -v98
	v_fmac_f32_e32 v76, 0xb102e308, v74
	v_pk_add_f32 v[74:75], v[98:99], v[76:77]
	s_mov_b32 s31, 0x7f800000
	v_sub_f32_e32 v77, v75, v77
	v_sub_f32_e32 v77, v99, v77
	v_add_f32_e32 v101, v100, v77
	v_mov_b32_e32 v100, v98
	v_pk_add_f32 v[98:99], v[74:75], v[98:99] neg_lo:[0,1] neg_hi:[0,1]
	v_pk_add_f32 v[102:103], v[74:75], v[100:101]
	v_mov_b32_e32 v77, v74
	v_mov_b32_e32 v99, v103
	v_pk_add_f32 v[104:105], v[76:77], v[98:99] neg_lo:[0,1] neg_hi:[0,1]
	v_pk_add_f32 v[76:77], v[76:77], v[98:99]
	v_mov_b32_e32 v100, v101
	v_pk_add_f32 v[98:99], v[76:77], v[74:75] op_sel:[1,0] op_sel_hi:[0,1] neg_lo:[0,1] neg_hi:[0,1]
	v_pk_add_f32 v[106:107], v[102:103], v[98:99] op_sel_hi:[1,0] neg_lo:[0,1] neg_hi:[0,1]
	v_mov_b32_e32 v102, v103
	v_mov_b32_e32 v103, v77
	v_pk_mov_b32 v[98:99], v[74:75], v[98:99] op_sel:[1,0]
	v_mov_b32_e32 v101, v74
	v_pk_add_f32 v[98:99], v[102:103], v[98:99] neg_lo:[0,1] neg_hi:[0,1]
	v_mov_b32_e32 v106, v104
	v_pk_add_f32 v[74:75], v[100:101], v[98:99] neg_lo:[0,1] neg_hi:[0,1]
	v_mov_b32_e32 v105, v77
	v_pk_add_f32 v[98:99], v[106:107], v[74:75]
	v_cmp_neq_f32_e32 vcc, s31, v81
	v_pk_add_f32 v[100:101], v[98:99], v[98:99] op_sel:[0,1] op_sel_hi:[1,0]
	s_mov_b32 s31, 0x33800000
	v_pk_add_f32 v[76:77], v[76:77], v[100:101] op_sel:[1,0] op_sel_hi:[0,1]
	v_mov_b32_e32 v99, v76
	v_pk_add_f32 v[102:103], v[98:99], v[104:105] neg_lo:[0,1] neg_hi:[0,1]
	v_mov_b32_e32 v75, v100
	v_sub_f32_e32 v77, v98, v102
	v_pk_add_f32 v[74:75], v[74:75], v[102:103] neg_lo:[0,1] neg_hi:[0,1]
	v_sub_f32_e32 v77, v104, v77
	v_add_f32_e32 v74, v74, v77
	v_add_f32_e32 v74, v74, v75
	v_add_f32_e32 v74, v76, v74
	v_cndmask_b32_e32 v74, v237, v74, vcc
	v_cmp_ngt_f32_e32 vcc, -1.0, v81
	s_nop 1
	v_cndmask_b32_e32 v74, v238, v74, vcc
	v_cmp_neq_f32_e32 vcc, -1.0, v81
	s_nop 1
	v_cndmask_b32_e32 v74, v239, v74, vcc
	v_cmp_lt_f32_e64 vcc, |v81|, s31
	s_nop 1
	v_cndmask_b32_e32 v74, v74, v81, vcc
	v_sub_f32_e32 v74, v0, v74

.LBB0_836:
	s_andn2_b64 vcc, exec, s[4:5]
	s_cbranch_vccnz .LBB0_858
	s_and_saveexec_b64 s[0:1], s[10:11]
	s_xor_b64 s[0:1], exec, s[0:1]
	s_cbranch_execz .LBB0_855
	v_readlane_b32 s4, v254, 26
	v_readlane_b32 s5, v254, 27
	s_waitcnt lgkmcnt(0)
	s_nop 3
	s_load_dword s4, s[4:5], 0x0
	s_waitcnt lgkmcnt(0)
	v_mov_b32_e32 v0, s4
	v_add_f32_e32 v0, v66, v0
	v_cmp_nlt_f32_e32 vcc, 0, v0
	s_and_saveexec_b64 s[4:5], vcc
	s_xor_b64 s[4:5], exec, s[4:5]
	s_cbranch_execz .LBB0_840
	v_mul_f32_e32 v66, 0x3fb8aa3b, v0
	v_exp_f32_e32 v66, v66
	s_mov_b32 s8, 0x3f2aaaab
	v_add_f32_e32 v72, 1.0, v66
	v_frexp_mant_f32_e32 v74, v72
	v_cvt_f64_f32_e32 v[70:71], v72
	v_frexp_exp_i32_f64_e32 v70, v[70:71]
	v_cmp_gt_f32_e32 vcc, s8, v74
	v_add_f32_e32 v73, -1.0, v72
	v_sub_f32_e32 v75, v73, v72
	v_subbrev_co_u32_e32 v78, vcc, 0, v70, vcc
	v_sub_u32_e32 v70, 0, v78
	v_sub_f32_e32 v73, v66, v73
	v_add_f32_e32 v75, 1.0, v75
	v_ldexp_f32 v71, v72, v70
	v_add_f32_e32 v73, v73, v75
	v_add_f32_e32 v72, -1.0, v71
	v_add_f32_e32 v74, 1.0, v71
	v_ldexp_f32 v70, v73, v70
	v_add_f32_e32 v73, 1.0, v72
	v_add_f32_e32 v75, -1.0, v74
	v_sub_f32_e32 v73, v71, v73
	v_sub_f32_e32 v71, v71, v75
	v_add_f32_e32 v73, v70, v73
	v_add_f32_e32 v70, v70, v71
	v_add_f32_e32 v79, v74, v70
	v_rcp_f32_e32 v81, v79
	v_sub_f32_e32 v71, v79, v74
	v_sub_f32_e32 v80, v70, v71
	v_add_f32_e32 v71, v72, v73
	v_mul_f32_e32 v83, v71, v81
	v_sub_f32_e32 v70, v71, v72
	v_mul_f32_e32 v72, v79, v83
	v_fma_f32 v74, v83, v79, -v72
	v_fmac_f32_e32 v74, v83, v80
	v_sub_f32_e32 v82, v73, v70
	v_add_f32_e32 v70, v72, v74
	v_sub_f32_e32 v73, v71, v70
	v_pk_add_f32 v[76:77], v[70:71], v[72:73] neg_lo:[0,1] neg_hi:[0,1]
	v_mov_b32_e32 v75, v70
	v_pk_add_f32 v[70:71], v[76:77], v[74:75] neg_lo:[0,1] neg_hi:[0,1]
	s_mov_b32 s8, 0x3f317218
	v_add_f32_e32 v71, v82, v71
	v_add_f32_e32 v70, v70, v71
	v_add_f32_e32 v71, v73, v70
	v_mul_f32_e32 v82, v81, v71
	v_mul_f32_e32 v72, v79, v82
	v_fma_f32 v74, v82, v79, -v72
	v_fmac_f32_e32 v74, v82, v80
	v_sub_f32_e32 v73, v73, v71
	v_add_f32_e32 v79, v70, v73
	v_add_f32_e32 v70, v72, v74
	v_sub_f32_e32 v73, v71, v70
	v_pk_add_f32 v[76:77], v[70:71], v[72:73] neg_lo:[0,1] neg_hi:[0,1]
	v_mov_b32_e32 v75, v70
	v_pk_add_f32 v[70:71], v[76:77], v[74:75] neg_lo:[0,1] neg_hi:[0,1]
	s_nop 0
	v_add_f32_e32 v71, v79, v71
	v_add_f32_e32 v70, v70, v71
	v_add_f32_e32 v71, v83, v82
	v_add_f32_e32 v70, v73, v70
	v_sub_f32_e32 v72, v71, v83
	v_mul_f32_e32 v70, v81, v70
	v_sub_f32_e32 v72, v82, v72
	v_add_f32_e32 v72, v72, v70
	v_add_f32_e32 v74, v71, v72
	v_mul_f32_e32 v75, v74, v74
	v_fmamk_f32 v70, v75, 0x3e9b6dac, v236
	v_fmaak_f32 v205, v75, v70, 0x3f2aaada
	v_cvt_f32_i32_e32 v70, v78
	v_sub_f32_e32 v71, v74, v71
	v_sub_f32_e32 v71, v72, v71
	v_ldexp_f32 v76, v71, 1
	v_mul_f32_e32 v71, v74, v75
	v_ldexp_f32 v73, v74, 1
	v_pk_mul_f32 v[74:75], v[70:71], v[204:205]
	s_nop 0
	v_fma_f32 v72, v70, s8, -v74
	v_fmac_f32_e32 v72, 0xb102e308, v70
	v_pk_add_f32 v[70:71], v[74:75], v[72:73]
	s_mov_b32 s8, 0x7f800000
	v_sub_f32_e32 v73, v71, v73
	v_sub_f32_e32 v73, v75, v73
	v_add_f32_e32 v77, v76, v73
	v_mov_b32_e32 v76, v74
	v_pk_add_f32 v[74:75], v[70:71], v[74:75] neg_lo:[0,1] neg_hi:[0,1]
	v_pk_add_f32 v[78:79], v[70:71], v[76:77]
	v_mov_b32_e32 v73, v70
	v_mov_b32_e32 v75, v79
	v_pk_add_f32 v[80:81], v[72:73], v[74:75] neg_lo:[0,1] neg_hi:[0,1]
	v_pk_add_f32 v[72:73], v[72:73], v[74:75]
	v_mov_b32_e32 v76, v77
	v_pk_add_f32 v[74:75], v[72:73], v[70:71] op_sel:[1,0] op_sel_hi:[0,1] neg_lo:[0,1] neg_hi:[0,1]
	v_pk_add_f32 v[82:83], v[78:79], v[74:75] op_sel_hi:[1,0] neg_lo:[0,1] neg_hi:[0,1]
	v_mov_b32_e32 v78, v79
	v_mov_b32_e32 v79, v73
	v_pk_mov_b32 v[74:75], v[70:71], v[74:75] op_sel:[1,0]
	v_mov_b32_e32 v77, v70
	v_pk_add_f32 v[74:75], v[78:79], v[74:75] neg_lo:[0,1] neg_hi:[0,1]
	v_mov_b32_e32 v82, v80
	v_pk_add_f32 v[70:71], v[76:77], v[74:75] neg_lo:[0,1] neg_hi:[0,1]
	v_mov_b32_e32 v81, v73
	v_pk_add_f32 v[74:75], v[82:83], v[70:71]
	v_cmp_neq_f32_e32 vcc, s8, v66
	v_pk_add_f32 v[76:77], v[74:75], v[74:75] op_sel:[0,1] op_sel_hi:[1,0]
	s_mov_b32 s8, 0x33800000
	v_pk_add_f32 v[72:73], v[72:73], v[76:77] op_sel:[1,0] op_sel_hi:[0,1]
	v_mov_b32_e32 v75, v72
	v_pk_add_f32 v[78:79], v[74:75], v[80:81] neg_lo:[0,1] neg_hi:[0,1]
	v_mov_b32_e32 v71, v76
	v_sub_f32_e32 v73, v74, v78
	v_pk_add_f32 v[70:71], v[70:71], v[78:79] neg_lo:[0,1] neg_hi:[0,1]
	v_sub_f32_e32 v73, v80, v73
	v_add_f32_e32 v70, v70, v73
	v_add_f32_e32 v70, v70, v71
	v_add_f32_e32 v70, v72, v70
	v_cndmask_b32_e32 v70, v237, v70, vcc
	v_cmp_ngt_f32_e32 vcc, -1.0, v66
	s_nop 1
	v_cndmask_b32_e32 v70, v238, v70, vcc
	v_cmp_neq_f32_e32 vcc, -1.0, v66
	s_nop 1
	v_cndmask_b32_e32 v70, v239, v70, vcc
	v_cmp_lt_f32_e64 vcc, |v66|, s8
	s_nop 1
	v_cndmask_b32_e32 v66, v70, v66, vcc
	v_sub_f32_e32 v66, v0, v66

.LBB0_842:
	s_or_b64 exec, exec, s[4:5]
	v_lshlrev_b32_e32 v72, 2, v85
	v_lshlrev_b32_e32 v0, 2, v86
	v_ashrrev_i32_e32 v73, 31, v72
	v_lshl_add_u64 v[70:71], s[84:85], 0, v[0:1]
	v_lshlrev_b64 v[74:75], 13, v[72:73]
	v_lshl_add_u64 v[74:75], v[70:71], 0, v[74:75]
	v_readlane_b32 s4, v254, 26
	global_store_dword v[74:75], v66, off
	v_readlane_b32 s5, v254, 27
	s_nop 4
	s_load_dword s4, s[4:5], 0x4
	s_waitcnt lgkmcnt(0)
	v_mov_b32_e32 v0, s4
	v_add_f32_e32 v0, v67, v0
	v_cmp_nlt_f32_e32 vcc, 0, v0
	s_and_saveexec_b64 s[4:5], vcc
	s_xor_b64 s[4:5], exec, s[4:5]
	s_cbranch_execz .LBB0_844
	v_mul_f32_e32 v66, 0x3fb8aa3b, v0
	v_exp_f32_e32 v73, v66
	s_mov_b32 s8, 0x3f2aaaab
	v_add_f32_e32 v74, 1.0, v73
	v_frexp_mant_f32_e32 v76, v74
	v_cvt_f64_f32_e32 v[66:67], v74
	v_frexp_exp_i32_f64_e32 v66, v[66:67]
	v_cmp_gt_f32_e32 vcc, s8, v76
	v_add_f32_e32 v75, -1.0, v74
	v_sub_f32_e32 v77, v75, v74
	v_subbrev_co_u32_e32 v80, vcc, 0, v66, vcc
	v_sub_u32_e32 v66, 0, v80
	v_sub_f32_e32 v75, v73, v75
	v_add_f32_e32 v77, 1.0, v77
	v_ldexp_f32 v67, v74, v66
	v_add_f32_e32 v75, v75, v77
	v_add_f32_e32 v74, -1.0, v67
	v_add_f32_e32 v76, 1.0, v67
	v_ldexp_f32 v66, v75, v66
	v_add_f32_e32 v75, 1.0, v74
	v_add_f32_e32 v77, -1.0, v76
	v_sub_f32_e32 v75, v67, v75
	v_sub_f32_e32 v67, v67, v77
	v_add_f32_e32 v75, v66, v75
	v_add_f32_e32 v66, v66, v67
	v_add_f32_e32 v81, v76, v66
	v_rcp_f32_e32 v83, v81
	v_sub_f32_e32 v67, v81, v76
	v_sub_f32_e32 v82, v66, v67
	v_add_f32_e32 v67, v74, v75
	v_mul_f32_e32 v85, v67, v83
	v_sub_f32_e32 v66, v67, v74
	v_mul_f32_e32 v74, v81, v85
	v_fma_f32 v76, v85, v81, -v74
	v_fmac_f32_e32 v76, v85, v82
	v_sub_f32_e32 v84, v75, v66
	v_add_f32_e32 v66, v74, v76
	v_sub_f32_e32 v75, v67, v66
	v_pk_add_f32 v[78:79], v[66:67], v[74:75] neg_lo:[0,1] neg_hi:[0,1]
	v_mov_b32_e32 v77, v66
	v_pk_add_f32 v[66:67], v[78:79], v[76:77] neg_lo:[0,1] neg_hi:[0,1]
	s_mov_b32 s8, 0x3f317218
	v_add_f32_e32 v67, v84, v67
	v_add_f32_e32 v66, v66, v67
	v_add_f32_e32 v67, v75, v66
	v_mul_f32_e32 v84, v83, v67
	v_mul_f32_e32 v74, v81, v84
	v_fma_f32 v76, v84, v81, -v74
	v_fmac_f32_e32 v76, v84, v82
	v_sub_f32_e32 v75, v75, v67
	v_add_f32_e32 v81, v66, v75
	v_add_f32_e32 v66, v74, v76
	v_sub_f32_e32 v75, v67, v66
	v_pk_add_f32 v[78:79], v[66:67], v[74:75] neg_lo:[0,1] neg_hi:[0,1]
	v_mov_b32_e32 v77, v66
	v_pk_add_f32 v[66:67], v[78:79], v[76:77] neg_lo:[0,1] neg_hi:[0,1]
	s_nop 0
	v_add_f32_e32 v67, v81, v67
	v_add_f32_e32 v66, v66, v67
	v_add_f32_e32 v67, v85, v84
	v_add_f32_e32 v66, v75, v66
	v_sub_f32_e32 v74, v67, v85
	v_mul_f32_e32 v66, v83, v66
	v_sub_f32_e32 v74, v84, v74
	v_add_f32_e32 v74, v74, v66
	v_add_f32_e32 v76, v67, v74
	v_mul_f32_e32 v77, v76, v76
	v_fmamk_f32 v66, v77, 0x3e9b6dac, v236
	v_fmaak_f32 v205, v77, v66, 0x3f2aaada
	v_cvt_f32_i32_e32 v66, v80
	v_sub_f32_e32 v67, v76, v67
	v_sub_f32_e32 v67, v74, v67
	v_ldexp_f32 v78, v67, 1
	v_mul_f32_e32 v67, v76, v77
	v_ldexp_f32 v75, v76, 1
	v_pk_mul_f32 v[76:77], v[66:67], v[204:205]
	s_nop 0
	v_fma_f32 v74, v66, s8, -v76
	v_fmac_f32_e32 v74, 0xb102e308, v66
	v_pk_add_f32 v[66:67], v[76:77], v[74:75]
	s_mov_b32 s8, 0x7f800000
	v_sub_f32_e32 v75, v67, v75
	v_sub_f32_e32 v75, v77, v75
	v_add_f32_e32 v79, v78, v75
	v_mov_b32_e32 v78, v76
	v_pk_add_f32 v[76:77], v[66:67], v[76:77] neg_lo:[0,1] neg_hi:[0,1]
	v_pk_add_f32 v[80:81], v[66:67], v[78:79]
	v_mov_b32_e32 v75, v66
	v_mov_b32_e32 v77, v81
	v_pk_add_f32 v[82:83], v[74:75], v[76:77] neg_lo:[0,1] neg_hi:[0,1]
	v_pk_add_f32 v[74:75], v[74:75], v[76:77]
	v_mov_b32_e32 v78, v79
	v_pk_add_f32 v[76:77], v[74:75], v[66:67] op_sel:[1,0] op_sel_hi:[0,1] neg_lo:[0,1] neg_hi:[0,1]
	v_pk_add_f32 v[84:85], v[80:81], v[76:77] op_sel_hi:[1,0] neg_lo:[0,1] neg_hi:[0,1]
	v_mov_b32_e32 v80, v81
	v_mov_b32_e32 v81, v75
	v_pk_mov_b32 v[76:77], v[66:67], v[76:77] op_sel:[1,0]
	v_mov_b32_e32 v79, v66
	v_pk_add_f32 v[76:77], v[80:81], v[76:77] neg_lo:[0,1] neg_hi:[0,1]
	v_mov_b32_e32 v84, v82
	v_pk_add_f32 v[66:67], v[78:79], v[76:77] neg_lo:[0,1] neg_hi:[0,1]
	v_mov_b32_e32 v83, v75
	v_pk_add_f32 v[76:77], v[84:85], v[66:67]
	v_cmp_neq_f32_e32 vcc, s8, v73
	v_pk_add_f32 v[78:79], v[76:77], v[76:77] op_sel:[0,1] op_sel_hi:[1,0]
	s_mov_b32 s8, 0x33800000
	v_pk_add_f32 v[74:75], v[74:75], v[78:79] op_sel:[1,0] op_sel_hi:[0,1]
	v_mov_b32_e32 v77, v74
	v_pk_add_f32 v[80:81], v[76:77], v[82:83] neg_lo:[0,1] neg_hi:[0,1]
	v_mov_b32_e32 v67, v78
	v_sub_f32_e32 v75, v76, v80
	v_pk_add_f32 v[66:67], v[66:67], v[80:81] neg_lo:[0,1] neg_hi:[0,1]
	v_sub_f32_e32 v75, v82, v75
	v_add_f32_e32 v66, v66, v75
	v_add_f32_e32 v66, v66, v67
	v_add_f32_e32 v66, v74, v66
	v_cndmask_b32_e32 v66, v237, v66, vcc
	v_cmp_ngt_f32_e32 vcc, -1.0, v73
	s_nop 1
	v_cndmask_b32_e32 v66, v238, v66, vcc
	v_cmp_neq_f32_e32 vcc, -1.0, v73
	s_nop 1
	v_cndmask_b32_e32 v66, v239, v66, vcc
	v_cmp_lt_f32_e64 vcc, |v73|, s8
	s_nop 1
	v_cndmask_b32_e32 v66, v66, v73, vcc
	v_sub_f32_e32 v66, v0, v66

.LBB0_846:
	s_or_b64 exec, exec, s[4:5]
	v_or_b32_e32 v74, 1, v72
	v_ashrrev_i32_e32 v75, 31, v74
	v_lshlrev_b64 v[74:75], 13, v[74:75]
	v_lshl_add_u64 v[74:75], v[70:71], 0, v[74:75]
	v_readlane_b32 s4, v254, 26
	global_store_dword v[74:75], v66, off
	v_readlane_b32 s5, v254, 27
	s_nop 4
	s_load_dword s4, s[4:5], 0x8
	s_waitcnt lgkmcnt(0)
	v_mov_b32_e32 v0, s4
	v_add_f32_e32 v0, v68, v0
	v_cmp_nlt_f32_e32 vcc, 0, v0
	s_and_saveexec_b64 s[4:5], vcc
	s_xor_b64 s[4:5], exec, s[4:5]
	s_cbranch_execz .LBB0_848
	v_mul_f32_e32 v66, 0x3fb8aa3b, v0
	v_exp_f32_e32 v68, v66
	s_mov_b32 s8, 0x3f2aaaab
	v_add_f32_e32 v73, 1.0, v68
	v_frexp_mant_f32_e32 v75, v73
	v_cvt_f64_f32_e32 v[66:67], v73
	v_frexp_exp_i32_f64_e32 v66, v[66:67]
	v_cmp_gt_f32_e32 vcc, s8, v75
	v_add_f32_e32 v74, -1.0, v73
	v_sub_f32_e32 v76, v74, v73
	v_subbrev_co_u32_e32 v80, vcc, 0, v66, vcc
	v_sub_u32_e32 v66, 0, v80
	v_sub_f32_e32 v74, v68, v74
	v_add_f32_e32 v76, 1.0, v76
	v_ldexp_f32 v67, v73, v66
	v_add_f32_e32 v74, v74, v76
	v_add_f32_e32 v73, -1.0, v67
	v_add_f32_e32 v75, 1.0, v67
	v_ldexp_f32 v66, v74, v66
	v_add_f32_e32 v74, 1.0, v73
	v_add_f32_e32 v76, -1.0, v75
	v_sub_f32_e32 v74, v67, v74
	v_sub_f32_e32 v67, v67, v76
	v_add_f32_e32 v74, v66, v74
	v_add_f32_e32 v66, v66, v67
	v_add_f32_e32 v81, v75, v66
	v_rcp_f32_e32 v83, v81
	v_sub_f32_e32 v67, v81, v75
	v_sub_f32_e32 v82, v66, v67
	v_add_f32_e32 v67, v73, v74
	v_sub_f32_e32 v66, v67, v73
	v_mul_f32_e32 v84, v67, v83
	v_sub_f32_e32 v73, v74, v66
	v_mul_f32_e32 v74, v81, v84
	v_fma_f32 v76, v84, v81, -v74
	v_fmac_f32_e32 v76, v84, v82
	v_add_f32_e32 v66, v74, v76
	v_sub_f32_e32 v75, v67, v66
	v_pk_add_f32 v[78:79], v[66:67], v[74:75] neg_lo:[0,1] neg_hi:[0,1]
	v_mov_b32_e32 v77, v66
	v_pk_add_f32 v[66:67], v[78:79], v[76:77] neg_lo:[0,1] neg_hi:[0,1]
	s_mov_b32 s8, 0x3f317218
	v_add_f32_e32 v67, v73, v67
	v_add_f32_e32 v66, v66, v67
	v_add_f32_e32 v67, v75, v66
	v_mul_f32_e32 v73, v83, v67
	v_mul_f32_e32 v74, v81, v73
	v_fma_f32 v76, v73, v81, -v74
	v_fmac_f32_e32 v76, v73, v82
	v_sub_f32_e32 v75, v75, v67
	v_add_f32_e32 v81, v66, v75
	v_add_f32_e32 v66, v74, v76
	v_sub_f32_e32 v75, v67, v66
	v_pk_add_f32 v[78:79], v[66:67], v[74:75] neg_lo:[0,1] neg_hi:[0,1]
	v_mov_b32_e32 v77, v66
	v_pk_add_f32 v[66:67], v[78:79], v[76:77] neg_lo:[0,1] neg_hi:[0,1]
	s_nop 0
	v_add_f32_e32 v67, v81, v67
	v_add_f32_e32 v66, v66, v67
	v_add_f32_e32 v67, v84, v73
	v_add_f32_e32 v66, v75, v66
	v_sub_f32_e32 v74, v67, v84
	v_mul_f32_e32 v66, v83, v66
	v_sub_f32_e32 v73, v73, v74
	v_add_f32_e32 v73, v73, v66
	v_add_f32_e32 v74, v67, v73
	v_mul_f32_e32 v76, v74, v74
	v_fmamk_f32 v66, v76, 0x3e9b6dac, v236
	v_fmaak_f32 v205, v76, v66, 0x3f2aaada
	v_cvt_f32_i32_e32 v66, v80
	v_sub_f32_e32 v67, v74, v67
	v_sub_f32_e32 v67, v73, v67
	v_ldexp_f32 v73, v67, 1
	v_mul_f32_e32 v67, v74, v76
	v_pk_mul_f32 v[76:77], v[66:67], v[204:205]
	v_ldexp_f32 v75, v74, 1
	v_fma_f32 v74, v66, s8, -v76
	v_fmac_f32_e32 v74, 0xb102e308, v66
	v_pk_add_f32 v[66:67], v[76:77], v[74:75]
	v_mov_b32_e32 v78, v76
	v_sub_f32_e32 v75, v67, v75
	v_sub_f32_e32 v75, v77, v75
	v_add_f32_e32 v79, v73, v75
	v_pk_add_f32 v[76:77], v[66:67], v[76:77] neg_lo:[0,1] neg_hi:[0,1]
	v_pk_add_f32 v[80:81], v[66:67], v[78:79]
	v_mov_b32_e32 v75, v66
	v_mov_b32_e32 v77, v81
	v_pk_add_f32 v[82:83], v[74:75], v[76:77] neg_lo:[0,1] neg_hi:[0,1]
	v_pk_add_f32 v[74:75], v[74:75], v[76:77]
	v_mov_b32_e32 v78, v79
	v_pk_add_f32 v[76:77], v[74:75], v[66:67] op_sel:[1,0] op_sel_hi:[0,1] neg_lo:[0,1] neg_hi:[0,1]
	v_pk_add_f32 v[84:85], v[80:81], v[76:77] op_sel_hi:[1,0] neg_lo:[0,1] neg_hi:[0,1]
	v_mov_b32_e32 v80, v81
	v_mov_b32_e32 v81, v75
	v_pk_mov_b32 v[76:77], v[66:67], v[76:77] op_sel:[1,0]
	v_mov_b32_e32 v79, v66
	v_pk_add_f32 v[76:77], v[80:81], v[76:77] neg_lo:[0,1] neg_hi:[0,1]
	v_mov_b32_e32 v84, v82
	v_pk_add_f32 v[66:67], v[78:79], v[76:77] neg_lo:[0,1] neg_hi:[0,1]
	v_mov_b32_e32 v83, v75
	v_pk_add_f32 v[76:77], v[84:85], v[66:67]
	s_mov_b32 s8, 0x7f800000
	v_pk_add_f32 v[78:79], v[76:77], v[76:77] op_sel:[0,1] op_sel_hi:[1,0]
	v_cmp_neq_f32_e32 vcc, s8, v68
	v_pk_add_f32 v[74:75], v[74:75], v[78:79] op_sel:[1,0] op_sel_hi:[0,1]
	v_mov_b32_e32 v77, v74
	v_pk_add_f32 v[80:81], v[76:77], v[82:83] neg_lo:[0,1] neg_hi:[0,1]
	v_mov_b32_e32 v67, v78
	v_sub_f32_e32 v73, v76, v80
	v_pk_add_f32 v[66:67], v[66:67], v[80:81] neg_lo:[0,1] neg_hi:[0,1]
	v_sub_f32_e32 v73, v82, v73
	v_add_f32_e32 v66, v66, v73
	v_add_f32_e32 v66, v66, v67
	v_add_f32_e32 v66, v74, v66
	v_cndmask_b32_e32 v66, v237, v66, vcc
	v_cmp_ngt_f32_e32 vcc, -1.0, v68
	s_mov_b32 s8, 0x33800000
	s_nop 0
	v_cndmask_b32_e32 v66, v238, v66, vcc
	v_cmp_neq_f32_e32 vcc, -1.0, v68
	s_nop 1
	v_cndmask_b32_e32 v66, v239, v66, vcc
	v_cmp_lt_f32_e64 vcc, |v68|, s8
	s_nop 1
	v_cndmask_b32_e32 v66, v66, v68, vcc
	v_sub_f32_e32 v66, v0, v66

.LBB0_850:
	s_or_b64 exec, exec, s[4:5]
	v_or_b32_e32 v74, 2, v72
	v_ashrrev_i32_e32 v75, 31, v74
	v_lshlrev_b64 v[74:75], 13, v[74:75]
	v_lshl_add_u64 v[74:75], v[70:71], 0, v[74:75]
	v_readlane_b32 s4, v254, 26
	global_store_dword v[74:75], v66, off
	v_readlane_b32 s5, v254, 27
	s_nop 4
	s_load_dword s4, s[4:5], 0xc
	s_waitcnt lgkmcnt(0)
	v_mov_b32_e32 v0, s4
	v_add_f32_e32 v0, v69, v0
	v_cmp_nlt_f32_e32 vcc, 0, v0
	s_and_saveexec_b64 s[4:5], vcc
	s_xor_b64 s[4:5], exec, s[4:5]
	s_cbranch_execz .LBB0_852
	v_mul_f32_e32 v66, 0x3fb8aa3b, v0
	v_exp_f32_e32 v73, v66
	s_mov_b32 s8, 0x3f2aaaab
	v_add_f32_e32 v68, 1.0, v73
	v_frexp_mant_f32_e32 v74, v68
	v_cvt_f64_f32_e32 v[66:67], v68
	v_frexp_exp_i32_f64_e32 v66, v[66:67]
	v_cmp_gt_f32_e32 vcc, s8, v74
	v_add_f32_e32 v69, -1.0, v68
	v_sub_f32_e32 v75, v69, v68
	v_subbrev_co_u32_e32 v78, vcc, 0, v66, vcc
	v_sub_u32_e32 v66, 0, v78
	v_sub_f32_e32 v69, v73, v69
	v_add_f32_e32 v75, 1.0, v75
	v_ldexp_f32 v67, v68, v66
	v_add_f32_e32 v69, v69, v75
	v_add_f32_e32 v68, -1.0, v67
	v_add_f32_e32 v74, 1.0, v67
	v_ldexp_f32 v66, v69, v66
	v_add_f32_e32 v69, 1.0, v68
	v_add_f32_e32 v75, -1.0, v74
	v_sub_f32_e32 v69, v67, v69
	v_sub_f32_e32 v67, v67, v75
	v_add_f32_e32 v69, v66, v69
	v_add_f32_e32 v66, v66, v67
	v_add_f32_e32 v79, v74, v66
	v_rcp_f32_e32 v81, v79
	v_sub_f32_e32 v67, v79, v74
	v_sub_f32_e32 v80, v66, v67
	v_add_f32_e32 v67, v68, v69
	v_mul_f32_e32 v83, v67, v81
	v_sub_f32_e32 v66, v67, v68
	v_mul_f32_e32 v68, v79, v83
	v_fma_f32 v74, v83, v79, -v68
	v_fmac_f32_e32 v74, v83, v80
	v_sub_f32_e32 v82, v69, v66
	v_add_f32_e32 v66, v68, v74
	v_sub_f32_e32 v69, v67, v66
	v_pk_add_f32 v[76:77], v[66:67], v[68:69] neg_lo:[0,1] neg_hi:[0,1]
	v_mov_b32_e32 v75, v66
	v_pk_add_f32 v[66:67], v[76:77], v[74:75] neg_lo:[0,1] neg_hi:[0,1]
	s_mov_b32 s8, 0x3f317218
	v_add_f32_e32 v67, v82, v67
	v_add_f32_e32 v66, v66, v67
	v_add_f32_e32 v67, v69, v66
	v_mul_f32_e32 v82, v81, v67
	v_mul_f32_e32 v68, v79, v82
	v_fma_f32 v74, v82, v79, -v68
	v_fmac_f32_e32 v74, v82, v80
	v_sub_f32_e32 v69, v69, v67
	v_add_f32_e32 v79, v66, v69
	v_add_f32_e32 v66, v68, v74
	v_sub_f32_e32 v69, v67, v66
	v_pk_add_f32 v[76:77], v[66:67], v[68:69] neg_lo:[0,1] neg_hi:[0,1]
	v_mov_b32_e32 v75, v66
	v_pk_add_f32 v[66:67], v[76:77], v[74:75] neg_lo:[0,1] neg_hi:[0,1]
	s_nop 0
	v_add_f32_e32 v67, v79, v67
	v_add_f32_e32 v66, v66, v67
	v_add_f32_e32 v67, v83, v82
	v_add_f32_e32 v66, v69, v66
	v_sub_f32_e32 v68, v67, v83
	v_mul_f32_e32 v66, v81, v66
	v_sub_f32_e32 v68, v82, v68
	v_add_f32_e32 v68, v68, v66
	v_add_f32_e32 v74, v67, v68
	v_mul_f32_e32 v75, v74, v74
	v_fmamk_f32 v66, v75, 0x3e9b6dac, v236
	v_fmaak_f32 v205, v75, v66, 0x3f2aaada
	v_cvt_f32_i32_e32 v66, v78
	v_sub_f32_e32 v67, v74, v67
	v_sub_f32_e32 v67, v68, v67
	v_ldexp_f32 v76, v67, 1
	v_mul_f32_e32 v67, v74, v75
	v_ldexp_f32 v69, v74, 1
	v_pk_mul_f32 v[74:75], v[66:67], v[204:205]
	s_nop 0
	v_fma_f32 v68, v66, s8, -v74
	v_fmac_f32_e32 v68, 0xb102e308, v66
	v_pk_add_f32 v[66:67], v[74:75], v[68:69]
	s_mov_b32 s8, 0x7f800000
	v_sub_f32_e32 v69, v67, v69
	v_sub_f32_e32 v69, v75, v69
	v_add_f32_e32 v77, v76, v69
	v_mov_b32_e32 v76, v74
	v_pk_add_f32 v[74:75], v[66:67], v[74:75] neg_lo:[0,1] neg_hi:[0,1]
	v_pk_add_f32 v[78:79], v[66:67], v[76:77]
	v_mov_b32_e32 v69, v66
	v_mov_b32_e32 v75, v79
	v_pk_add_f32 v[80:81], v[68:69], v[74:75] neg_lo:[0,1] neg_hi:[0,1]
	v_pk_add_f32 v[68:69], v[68:69], v[74:75]
	v_mov_b32_e32 v76, v77
	v_pk_add_f32 v[74:75], v[68:69], v[66:67] op_sel:[1,0] op_sel_hi:[0,1] neg_lo:[0,1] neg_hi:[0,1]
	v_pk_add_f32 v[82:83], v[78:79], v[74:75] op_sel_hi:[1,0] neg_lo:[0,1] neg_hi:[0,1]
	v_mov_b32_e32 v78, v79
	v_mov_b32_e32 v79, v69
	v_pk_mov_b32 v[74:75], v[66:67], v[74:75] op_sel:[1,0]
	v_mov_b32_e32 v77, v66
	v_pk_add_f32 v[74:75], v[78:79], v[74:75] neg_lo:[0,1] neg_hi:[0,1]
	v_mov_b32_e32 v82, v80
	v_pk_add_f32 v[66:67], v[76:77], v[74:75] neg_lo:[0,1] neg_hi:[0,1]
	v_mov_b32_e32 v81, v69
	v_pk_add_f32 v[74:75], v[82:83], v[66:67]
	v_cmp_neq_f32_e32 vcc, s8, v73
	v_pk_add_f32 v[76:77], v[74:75], v[74:75] op_sel:[0,1] op_sel_hi:[1,0]
	s_mov_b32 s8, 0x33800000
	v_pk_add_f32 v[68:69], v[68:69], v[76:77] op_sel:[1,0] op_sel_hi:[0,1]
	v_mov_b32_e32 v75, v68
	v_pk_add_f32 v[78:79], v[74:75], v[80:81] neg_lo:[0,1] neg_hi:[0,1]
	v_mov_b32_e32 v67, v76
	v_sub_f32_e32 v69, v74, v78
	v_pk_add_f32 v[66:67], v[66:67], v[78:79] neg_lo:[0,1] neg_hi:[0,1]
	v_sub_f32_e32 v69, v80, v69
	v_add_f32_e32 v66, v66, v69
	v_add_f32_e32 v66, v66, v67
	v_add_f32_e32 v66, v68, v66
	v_cndmask_b32_e32 v66, v237, v66, vcc
	v_cmp_ngt_f32_e32 vcc, -1.0, v73
	s_nop 1
	v_cndmask_b32_e32 v66, v238, v66, vcc
	v_cmp_neq_f32_e32 vcc, -1.0, v73
	s_nop 1
	v_cndmask_b32_e32 v66, v239, v66, vcc
	v_cmp_lt_f32_e64 vcc, |v73|, s8
	s_nop 1
	v_cndmask_b32_e32 v66, v66, v73, vcc
	v_sub_f32_e32 v66, v0, v66

.LBB0_933:
	s_and_saveexec_b64 s[4:5], s[10:11]
	s_xor_b64 s[16:17], exec, s[4:5]
	s_cbranch_execz .LBB0_951
	v_readlane_b32 s4, v254, 26
	v_readlane_b32 s5, v254, 27
	s_nop 4
	s_load_dword s4, s[4:5], 0x0
	s_waitcnt lgkmcnt(0)
	v_mov_b32_e32 v0, s4
	v_add_f32_e32 v0, v58, v0
	v_cmp_nlt_f32_e32 vcc, 0, v0
	s_and_saveexec_b64 s[4:5], vcc
	s_xor_b64 s[4:5], exec, s[4:5]
	s_cbranch_execz .LBB0_936
	v_mul_f32_e32 v58, 0x3fb8aa3b, v0
	v_exp_f32_e32 v58, v58
	s_mov_b32 s27, 0x3f2aaaab
	v_add_f32_e32 v64, 1.0, v58
	v_frexp_mant_f32_e32 v130, v64
	v_cvt_f64_f32_e32 v[62:63], v64
	v_frexp_exp_i32_f64_e32 v62, v[62:63]
	v_cmp_gt_f32_e32 vcc, s27, v130
	v_add_f32_e32 v65, -1.0, v64
	v_sub_f32_e32 v131, v65, v64
	v_subbrev_co_u32_e32 v144, vcc, 0, v62, vcc
	v_sub_u32_e32 v62, 0, v144
	v_sub_f32_e32 v65, v58, v65
	v_add_f32_e32 v131, 1.0, v131
	v_ldexp_f32 v63, v64, v62
	v_add_f32_e32 v65, v65, v131
	v_add_f32_e32 v64, -1.0, v63
	v_add_f32_e32 v130, 1.0, v63
	v_ldexp_f32 v62, v65, v62
	v_add_f32_e32 v65, 1.0, v64
	v_add_f32_e32 v131, -1.0, v130
	v_sub_f32_e32 v65, v63, v65
	v_sub_f32_e32 v63, v63, v131
	v_add_f32_e32 v65, v62, v65
	v_add_f32_e32 v62, v62, v63
	v_add_f32_e32 v145, v130, v62
	v_rcp_f32_e32 v147, v145
	v_sub_f32_e32 v63, v145, v130
	v_sub_f32_e32 v146, v62, v63
	v_add_f32_e32 v63, v64, v65
	v_mul_f32_e32 v149, v63, v147
	v_sub_f32_e32 v62, v63, v64
	v_mul_f32_e32 v64, v145, v149
	v_fma_f32 v130, v149, v145, -v64
	v_fmac_f32_e32 v130, v149, v146
	v_sub_f32_e32 v148, v65, v62
	v_add_f32_e32 v62, v64, v130
	v_sub_f32_e32 v65, v63, v62
	v_pk_add_f32 v[132:133], v[62:63], v[64:65] neg_lo:[0,1] neg_hi:[0,1]
	v_mov_b32_e32 v131, v62
	v_pk_add_f32 v[62:63], v[132:133], v[130:131] neg_lo:[0,1] neg_hi:[0,1]
	s_mov_b32 s27, 0x3f317218
	v_add_f32_e32 v63, v148, v63
	v_add_f32_e32 v62, v62, v63
	v_add_f32_e32 v63, v65, v62
	v_mul_f32_e32 v148, v147, v63
	v_mul_f32_e32 v64, v145, v148
	v_fma_f32 v130, v148, v145, -v64
	v_fmac_f32_e32 v130, v148, v146
	v_sub_f32_e32 v65, v65, v63
	v_add_f32_e32 v145, v62, v65
	v_add_f32_e32 v62, v64, v130
	v_sub_f32_e32 v65, v63, v62
	v_pk_add_f32 v[132:133], v[62:63], v[64:65] neg_lo:[0,1] neg_hi:[0,1]
	v_mov_b32_e32 v131, v62
	v_pk_add_f32 v[62:63], v[132:133], v[130:131] neg_lo:[0,1] neg_hi:[0,1]
	s_nop 0
	v_add_f32_e32 v63, v145, v63
	v_add_f32_e32 v62, v62, v63
	v_add_f32_e32 v63, v149, v148
	v_add_f32_e32 v62, v65, v62
	v_sub_f32_e32 v64, v63, v149
	v_mul_f32_e32 v62, v147, v62
	v_sub_f32_e32 v64, v148, v64
	v_add_f32_e32 v64, v64, v62
	v_add_f32_e32 v130, v63, v64
	v_mul_f32_e32 v131, v130, v130
	v_fmamk_f32 v62, v131, 0x3e9b6dac, v236
	v_fmaak_f32 v205, v131, v62, 0x3f2aaada
	v_cvt_f32_i32_e32 v62, v144
	v_sub_f32_e32 v63, v130, v63
	v_sub_f32_e32 v63, v64, v63
	v_ldexp_f32 v132, v63, 1
	v_mul_f32_e32 v63, v130, v131
	v_ldexp_f32 v65, v130, 1
	v_pk_mul_f32 v[130:131], v[62:63], v[204:205]
	s_nop 0
	v_fma_f32 v64, v62, s27, -v130
	v_fmac_f32_e32 v64, 0xb102e308, v62
	v_pk_add_f32 v[62:63], v[130:131], v[64:65]
	s_mov_b32 s27, 0x7f800000
	v_sub_f32_e32 v65, v63, v65
	v_sub_f32_e32 v65, v131, v65
	v_add_f32_e32 v133, v132, v65
	v_mov_b32_e32 v132, v130
	v_pk_add_f32 v[130:131], v[62:63], v[130:131] neg_lo:[0,1] neg_hi:[0,1]
	v_pk_add_f32 v[144:145], v[62:63], v[132:133]
	v_mov_b32_e32 v65, v62
	v_mov_b32_e32 v131, v145
	v_pk_add_f32 v[146:147], v[64:65], v[130:131] neg_lo:[0,1] neg_hi:[0,1]
	v_pk_add_f32 v[64:65], v[64:65], v[130:131]
	v_mov_b32_e32 v132, v133
	v_pk_add_f32 v[130:131], v[64:65], v[62:63] op_sel:[1,0] op_sel_hi:[0,1] neg_lo:[0,1] neg_hi:[0,1]
	v_pk_add_f32 v[148:149], v[144:145], v[130:131] op_sel_hi:[1,0] neg_lo:[0,1] neg_hi:[0,1]
	v_mov_b32_e32 v144, v145
	v_mov_b32_e32 v145, v65
	v_pk_mov_b32 v[130:131], v[62:63], v[130:131] op_sel:[1,0]
	v_mov_b32_e32 v133, v62
	v_pk_add_f32 v[130:131], v[144:145], v[130:131] neg_lo:[0,1] neg_hi:[0,1]
	v_mov_b32_e32 v148, v146
	v_pk_add_f32 v[62:63], v[132:133], v[130:131] neg_lo:[0,1] neg_hi:[0,1]
	v_mov_b32_e32 v147, v65
	v_pk_add_f32 v[130:131], v[148:149], v[62:63]
	v_cmp_neq_f32_e32 vcc, s27, v58
	v_pk_add_f32 v[132:133], v[130:131], v[130:131] op_sel:[0,1] op_sel_hi:[1,0]
	s_mov_b32 s27, 0x33800000
	v_pk_add_f32 v[64:65], v[64:65], v[132:133] op_sel:[1,0] op_sel_hi:[0,1]
	v_mov_b32_e32 v131, v64
	v_pk_add_f32 v[144:145], v[130:131], v[146:147] neg_lo:[0,1] neg_hi:[0,1]
	v_mov_b32_e32 v63, v132
	v_sub_f32_e32 v65, v130, v144
	v_pk_add_f32 v[62:63], v[62:63], v[144:145] neg_lo:[0,1] neg_hi:[0,1]
	v_sub_f32_e32 v65, v146, v65
	v_add_f32_e32 v62, v62, v65
	v_add_f32_e32 v62, v62, v63
	v_add_f32_e32 v62, v64, v62
	v_cndmask_b32_e32 v62, v237, v62, vcc
	v_cmp_ngt_f32_e32 vcc, -1.0, v58
	s_nop 1
	v_cndmask_b32_e32 v62, v238, v62, vcc
	v_cmp_neq_f32_e32 vcc, -1.0, v58
	s_nop 1
	v_cndmask_b32_e32 v62, v239, v62, vcc
	v_cmp_lt_f32_e64 vcc, |v58|, s27
	s_nop 1
	v_cndmask_b32_e32 v58, v62, v58, vcc
	v_sub_f32_e32 v58, v0, v58

.LBB0_938:
	s_or_b64 exec, exec, s[4:5]
	v_lshlrev_b32_e32 v64, 2, v154
	v_lshlrev_b32_e32 v0, 2, v155
	v_ashrrev_i32_e32 v65, 31, v64
	v_lshl_add_u64 v[62:63], s[84:85], 0, v[0:1]
	v_lshlrev_b64 v[130:131], 13, v[64:65]
	v_lshl_add_u64 v[130:131], v[62:63], 0, v[130:131]
	v_readlane_b32 s4, v254, 26
	global_store_dword v[130:131], v58, off
	v_readlane_b32 s5, v254, 27
	s_nop 4
	s_load_dword s4, s[4:5], 0x4
	s_waitcnt lgkmcnt(0)
	v_mov_b32_e32 v0, s4
	v_add_f32_e32 v0, v59, v0
	v_cmp_nlt_f32_e32 vcc, 0, v0
	s_and_saveexec_b64 s[4:5], vcc
	s_xor_b64 s[4:5], exec, s[4:5]
	s_cbranch_execz .LBB0_940
	v_mul_f32_e32 v58, 0x3fb8aa3b, v0
	v_exp_f32_e32 v65, v58
	s_mov_b32 s27, 0x3f2aaaab
	v_add_f32_e32 v130, 1.0, v65
	v_frexp_mant_f32_e32 v132, v130
	v_cvt_f64_f32_e32 v[58:59], v130
	v_frexp_exp_i32_f64_e32 v58, v[58:59]
	v_cmp_gt_f32_e32 vcc, s27, v132
	v_add_f32_e32 v131, -1.0, v130
	v_sub_f32_e32 v133, v131, v130
	v_subbrev_co_u32_e32 v146, vcc, 0, v58, vcc
	v_sub_u32_e32 v58, 0, v146
	v_sub_f32_e32 v131, v65, v131
	v_add_f32_e32 v133, 1.0, v133
	v_ldexp_f32 v59, v130, v58
	v_add_f32_e32 v131, v131, v133
	v_add_f32_e32 v130, -1.0, v59
	v_add_f32_e32 v132, 1.0, v59
	v_ldexp_f32 v58, v131, v58
	v_add_f32_e32 v131, 1.0, v130
	v_add_f32_e32 v133, -1.0, v132
	v_sub_f32_e32 v131, v59, v131
	v_sub_f32_e32 v59, v59, v133
	v_add_f32_e32 v131, v58, v131
	v_add_f32_e32 v58, v58, v59
	v_add_f32_e32 v147, v132, v58
	v_rcp_f32_e32 v149, v147
	v_sub_f32_e32 v59, v147, v132
	v_sub_f32_e32 v148, v58, v59
	v_add_f32_e32 v59, v130, v131
	v_mul_f32_e32 v155, v59, v149
	v_sub_f32_e32 v58, v59, v130
	v_mul_f32_e32 v130, v147, v155
	v_fma_f32 v132, v155, v147, -v130
	v_fmac_f32_e32 v132, v155, v148
	v_sub_f32_e32 v154, v131, v58
	v_add_f32_e32 v58, v130, v132
	v_sub_f32_e32 v131, v59, v58
	v_pk_add_f32 v[144:145], v[58:59], v[130:131] neg_lo:[0,1] neg_hi:[0,1]
	v_mov_b32_e32 v133, v58
	v_pk_add_f32 v[58:59], v[144:145], v[132:133] neg_lo:[0,1] neg_hi:[0,1]
	s_mov_b32 s27, 0x3f317218
	v_add_f32_e32 v59, v154, v59
	v_add_f32_e32 v58, v58, v59
	v_add_f32_e32 v59, v131, v58
	v_mul_f32_e32 v154, v149, v59
	v_mul_f32_e32 v130, v147, v154
	v_fma_f32 v132, v154, v147, -v130
	v_fmac_f32_e32 v132, v154, v148
	v_sub_f32_e32 v131, v131, v59
	v_add_f32_e32 v147, v58, v131
	v_add_f32_e32 v58, v130, v132
	v_sub_f32_e32 v131, v59, v58
	v_pk_add_f32 v[144:145], v[58:59], v[130:131] neg_lo:[0,1] neg_hi:[0,1]
	v_mov_b32_e32 v133, v58
	v_pk_add_f32 v[58:59], v[144:145], v[132:133] neg_lo:[0,1] neg_hi:[0,1]
	s_nop 0
	v_add_f32_e32 v59, v147, v59
	v_add_f32_e32 v58, v58, v59
	v_add_f32_e32 v59, v155, v154
	v_add_f32_e32 v58, v131, v58
	v_sub_f32_e32 v130, v59, v155
	v_mul_f32_e32 v58, v149, v58
	v_sub_f32_e32 v130, v154, v130
	v_add_f32_e32 v130, v130, v58
	v_add_f32_e32 v132, v59, v130
	v_mul_f32_e32 v133, v132, v132
	v_fmamk_f32 v58, v133, 0x3e9b6dac, v236
	v_fmaak_f32 v205, v133, v58, 0x3f2aaada
	v_cvt_f32_i32_e32 v58, v146
	v_sub_f32_e32 v59, v132, v59
	v_sub_f32_e32 v59, v130, v59
	v_ldexp_f32 v144, v59, 1
	v_mul_f32_e32 v59, v132, v133
	v_ldexp_f32 v131, v132, 1
	v_pk_mul_f32 v[132:133], v[58:59], v[204:205]
	s_nop 0
	v_fma_f32 v130, v58, s27, -v132
	v_fmac_f32_e32 v130, 0xb102e308, v58
	v_pk_add_f32 v[58:59], v[132:133], v[130:131]
	s_mov_b32 s27, 0x7f800000
	v_sub_f32_e32 v131, v59, v131
	v_sub_f32_e32 v131, v133, v131
	v_add_f32_e32 v145, v144, v131
	v_mov_b32_e32 v144, v132
	v_pk_add_f32 v[132:133], v[58:59], v[132:133] neg_lo:[0,1] neg_hi:[0,1]
	v_pk_add_f32 v[146:147], v[58:59], v[144:145]
	v_mov_b32_e32 v131, v58
	v_mov_b32_e32 v133, v147
	v_pk_add_f32 v[148:149], v[130:131], v[132:133] neg_lo:[0,1] neg_hi:[0,1]
	v_pk_add_f32 v[130:131], v[130:131], v[132:133]
	v_mov_b32_e32 v144, v145
	v_pk_add_f32 v[132:133], v[130:131], v[58:59] op_sel:[1,0] op_sel_hi:[0,1] neg_lo:[0,1] neg_hi:[0,1]
	v_pk_add_f32 v[154:155], v[146:147], v[132:133] op_sel_hi:[1,0] neg_lo:[0,1] neg_hi:[0,1]
	v_mov_b32_e32 v146, v147
	v_mov_b32_e32 v147, v131
	v_pk_mov_b32 v[132:133], v[58:59], v[132:133] op_sel:[1,0]
	v_mov_b32_e32 v145, v58
	v_pk_add_f32 v[132:133], v[146:147], v[132:133] neg_lo:[0,1] neg_hi:[0,1]
	v_mov_b32_e32 v154, v148
	v_pk_add_f32 v[58:59], v[144:145], v[132:133] neg_lo:[0,1] neg_hi:[0,1]
	v_mov_b32_e32 v149, v131
	v_pk_add_f32 v[132:133], v[154:155], v[58:59]
	v_cmp_neq_f32_e32 vcc, s27, v65
	v_pk_add_f32 v[144:145], v[132:133], v[132:133] op_sel:[0,1] op_sel_hi:[1,0]
	s_mov_b32 s27, 0x33800000
	v_pk_add_f32 v[130:131], v[130:131], v[144:145] op_sel:[1,0] op_sel_hi:[0,1]
	v_mov_b32_e32 v133, v130
	v_pk_add_f32 v[146:147], v[132:133], v[148:149] neg_lo:[0,1] neg_hi:[0,1]
	v_mov_b32_e32 v59, v144
	v_sub_f32_e32 v131, v132, v146
	v_pk_add_f32 v[58:59], v[58:59], v[146:147] neg_lo:[0,1] neg_hi:[0,1]
	v_sub_f32_e32 v131, v148, v131
	v_add_f32_e32 v58, v58, v131
	v_add_f32_e32 v58, v58, v59
	v_add_f32_e32 v58, v130, v58
	v_cndmask_b32_e32 v58, v237, v58, vcc
	v_cmp_ngt_f32_e32 vcc, -1.0, v65
	s_nop 1
	v_cndmask_b32_e32 v58, v238, v58, vcc
	v_cmp_neq_f32_e32 vcc, -1.0, v65
	s_nop 1
	v_cndmask_b32_e32 v58, v239, v58, vcc
	v_cmp_lt_f32_e64 vcc, |v65|, s27
	s_nop 1
	v_cndmask_b32_e32 v58, v58, v65, vcc
	v_sub_f32_e32 v58, v0, v58

.LBB0_942:
	s_or_b64 exec, exec, s[4:5]
	v_or_b32_e32 v130, 1, v64
	v_ashrrev_i32_e32 v131, 31, v130
	v_lshlrev_b64 v[130:131], 13, v[130:131]
	v_lshl_add_u64 v[130:131], v[62:63], 0, v[130:131]
	v_readlane_b32 s4, v254, 26
	global_store_dword v[130:131], v58, off
	v_readlane_b32 s5, v254, 27
	s_nop 4
	s_load_dword s4, s[4:5], 0x8
	s_waitcnt lgkmcnt(0)
	v_mov_b32_e32 v0, s4
	v_add_f32_e32 v0, v60, v0
	v_cmp_nlt_f32_e32 vcc, 0, v0
	s_and_saveexec_b64 s[4:5], vcc
	s_xor_b64 s[4:5], exec, s[4:5]
	s_cbranch_execz .LBB0_944
	v_mul_f32_e32 v58, 0x3fb8aa3b, v0
	v_exp_f32_e32 v60, v58
	s_mov_b32 s27, 0x3f2aaaab
	v_add_f32_e32 v65, 1.0, v60
	v_frexp_mant_f32_e32 v131, v65
	v_cvt_f64_f32_e32 v[58:59], v65
	v_frexp_exp_i32_f64_e32 v58, v[58:59]
	v_cmp_gt_f32_e32 vcc, s27, v131
	v_add_f32_e32 v130, -1.0, v65
	v_sub_f32_e32 v132, v130, v65
	v_subbrev_co_u32_e32 v146, vcc, 0, v58, vcc
	v_sub_u32_e32 v58, 0, v146
	v_sub_f32_e32 v130, v60, v130
	v_add_f32_e32 v132, 1.0, v132
	v_ldexp_f32 v59, v65, v58
	v_add_f32_e32 v130, v130, v132
	v_add_f32_e32 v65, -1.0, v59
	v_add_f32_e32 v131, 1.0, v59
	v_ldexp_f32 v58, v130, v58
	v_add_f32_e32 v130, 1.0, v65
	v_add_f32_e32 v132, -1.0, v131
	v_sub_f32_e32 v130, v59, v130
	v_sub_f32_e32 v59, v59, v132
	v_add_f32_e32 v130, v58, v130
	v_add_f32_e32 v58, v58, v59
	v_add_f32_e32 v147, v131, v58
	v_rcp_f32_e32 v149, v147
	v_sub_f32_e32 v59, v147, v131
	v_sub_f32_e32 v148, v58, v59
	v_add_f32_e32 v59, v65, v130
	v_sub_f32_e32 v58, v59, v65
	v_mul_f32_e32 v154, v59, v149
	v_sub_f32_e32 v65, v130, v58
	v_mul_f32_e32 v130, v147, v154
	v_fma_f32 v132, v154, v147, -v130
	v_fmac_f32_e32 v132, v154, v148
	v_add_f32_e32 v58, v130, v132
	v_sub_f32_e32 v131, v59, v58
	v_pk_add_f32 v[144:145], v[58:59], v[130:131] neg_lo:[0,1] neg_hi:[0,1]
	v_mov_b32_e32 v133, v58
	v_pk_add_f32 v[58:59], v[144:145], v[132:133] neg_lo:[0,1] neg_hi:[0,1]
	s_mov_b32 s27, 0x3f317218
	v_add_f32_e32 v59, v65, v59
	v_add_f32_e32 v58, v58, v59
	v_add_f32_e32 v59, v131, v58
	v_mul_f32_e32 v65, v149, v59
	v_mul_f32_e32 v130, v147, v65
	v_fma_f32 v132, v65, v147, -v130
	v_fmac_f32_e32 v132, v65, v148
	v_sub_f32_e32 v131, v131, v59
	v_add_f32_e32 v147, v58, v131
	v_add_f32_e32 v58, v130, v132
	v_sub_f32_e32 v131, v59, v58
	v_pk_add_f32 v[144:145], v[58:59], v[130:131] neg_lo:[0,1] neg_hi:[0,1]
	v_mov_b32_e32 v133, v58
	v_pk_add_f32 v[58:59], v[144:145], v[132:133] neg_lo:[0,1] neg_hi:[0,1]
	s_nop 0
	v_add_f32_e32 v59, v147, v59
	v_add_f32_e32 v58, v58, v59
	v_add_f32_e32 v59, v154, v65
	v_add_f32_e32 v58, v131, v58
	v_sub_f32_e32 v130, v59, v154
	v_mul_f32_e32 v58, v149, v58
	v_sub_f32_e32 v65, v65, v130
	v_add_f32_e32 v65, v65, v58
	v_add_f32_e32 v130, v59, v65
	v_mul_f32_e32 v132, v130, v130
	v_fmamk_f32 v58, v132, 0x3e9b6dac, v236
	v_fmaak_f32 v205, v132, v58, 0x3f2aaada
	v_cvt_f32_i32_e32 v58, v146
	v_sub_f32_e32 v59, v130, v59
	v_sub_f32_e32 v59, v65, v59
	v_ldexp_f32 v65, v59, 1
	v_mul_f32_e32 v59, v130, v132
	v_pk_mul_f32 v[132:133], v[58:59], v[204:205]
	v_ldexp_f32 v131, v130, 1
	v_fma_f32 v130, v58, s27, -v132
	v_fmac_f32_e32 v130, 0xb102e308, v58
	v_pk_add_f32 v[58:59], v[132:133], v[130:131]
	v_mov_b32_e32 v144, v132
	v_sub_f32_e32 v131, v59, v131
	v_sub_f32_e32 v131, v133, v131
	v_add_f32_e32 v145, v65, v131
	v_pk_add_f32 v[132:133], v[58:59], v[132:133] neg_lo:[0,1] neg_hi:[0,1]
	v_pk_add_f32 v[146:147], v[58:59], v[144:145]
	v_mov_b32_e32 v131, v58
	v_mov_b32_e32 v133, v147
	v_pk_add_f32 v[148:149], v[130:131], v[132:133] neg_lo:[0,1] neg_hi:[0,1]
	v_pk_add_f32 v[130:131], v[130:131], v[132:133]
	v_mov_b32_e32 v144, v145
	v_pk_add_f32 v[132:133], v[130:131], v[58:59] op_sel:[1,0] op_sel_hi:[0,1] neg_lo:[0,1] neg_hi:[0,1]
	v_pk_add_f32 v[154:155], v[146:147], v[132:133] op_sel_hi:[1,0] neg_lo:[0,1] neg_hi:[0,1]
	v_mov_b32_e32 v146, v147
	v_mov_b32_e32 v147, v131
	v_pk_mov_b32 v[132:133], v[58:59], v[132:133] op_sel:[1,0]
	v_mov_b32_e32 v145, v58
	v_pk_add_f32 v[132:133], v[146:147], v[132:133] neg_lo:[0,1] neg_hi:[0,1]
	v_mov_b32_e32 v154, v148
	v_pk_add_f32 v[58:59], v[144:145], v[132:133] neg_lo:[0,1] neg_hi:[0,1]
	v_mov_b32_e32 v149, v131
	v_pk_add_f32 v[132:133], v[154:155], v[58:59]
	s_mov_b32 s27, 0x7f800000
	v_pk_add_f32 v[144:145], v[132:133], v[132:133] op_sel:[0,1] op_sel_hi:[1,0]
	v_cmp_neq_f32_e32 vcc, s27, v60
	v_pk_add_f32 v[130:131], v[130:131], v[144:145] op_sel:[1,0] op_sel_hi:[0,1]
	v_mov_b32_e32 v133, v130
	v_pk_add_f32 v[146:147], v[132:133], v[148:149] neg_lo:[0,1] neg_hi:[0,1]
	v_mov_b32_e32 v59, v144
	v_sub_f32_e32 v65, v132, v146
	v_pk_add_f32 v[58:59], v[58:59], v[146:147] neg_lo:[0,1] neg_hi:[0,1]
	v_sub_f32_e32 v65, v148, v65
	v_add_f32_e32 v58, v58, v65
	v_add_f32_e32 v58, v58, v59
	v_add_f32_e32 v58, v130, v58
	v_cndmask_b32_e32 v58, v237, v58, vcc
	v_cmp_ngt_f32_e32 vcc, -1.0, v60
	s_mov_b32 s27, 0x33800000
	s_nop 0
	v_cndmask_b32_e32 v58, v238, v58, vcc
	v_cmp_neq_f32_e32 vcc, -1.0, v60
	s_nop 1
	v_cndmask_b32_e32 v58, v239, v58, vcc
	v_cmp_lt_f32_e64 vcc, |v60|, s27
	s_nop 1
	v_cndmask_b32_e32 v58, v58, v60, vcc
	v_sub_f32_e32 v58, v0, v58

.LBB0_946:
	s_or_b64 exec, exec, s[4:5]
	v_or_b32_e32 v130, 2, v64
	v_ashrrev_i32_e32 v131, 31, v130
	v_lshlrev_b64 v[130:131], 13, v[130:131]
	v_lshl_add_u64 v[130:131], v[62:63], 0, v[130:131]
	v_readlane_b32 s4, v254, 26
	global_store_dword v[130:131], v58, off
	v_readlane_b32 s5, v254, 27
	s_nop 4
	s_load_dword s4, s[4:5], 0xc
	s_waitcnt lgkmcnt(0)
	v_mov_b32_e32 v0, s4
	v_add_f32_e32 v0, v61, v0
	v_cmp_nlt_f32_e32 vcc, 0, v0
	s_and_saveexec_b64 s[4:5], vcc
	s_xor_b64 s[4:5], exec, s[4:5]
	s_cbranch_execz .LBB0_948
	v_mul_f32_e32 v58, 0x3fb8aa3b, v0
	v_exp_f32_e32 v65, v58
	s_mov_b32 s27, 0x3f2aaaab
	v_add_f32_e32 v60, 1.0, v65
	v_frexp_mant_f32_e32 v130, v60
	v_cvt_f64_f32_e32 v[58:59], v60
	v_frexp_exp_i32_f64_e32 v58, v[58:59]
	v_cmp_gt_f32_e32 vcc, s27, v130
	v_add_f32_e32 v61, -1.0, v60
	v_sub_f32_e32 v131, v61, v60
	v_subbrev_co_u32_e32 v144, vcc, 0, v58, vcc
	v_sub_u32_e32 v58, 0, v144
	v_sub_f32_e32 v61, v65, v61
	v_add_f32_e32 v131, 1.0, v131
	v_ldexp_f32 v59, v60, v58
	v_add_f32_e32 v61, v61, v131
	v_add_f32_e32 v60, -1.0, v59
	v_add_f32_e32 v130, 1.0, v59
	v_ldexp_f32 v58, v61, v58
	v_add_f32_e32 v61, 1.0, v60
	v_add_f32_e32 v131, -1.0, v130
	v_sub_f32_e32 v61, v59, v61
	v_sub_f32_e32 v59, v59, v131
	v_add_f32_e32 v61, v58, v61
	v_add_f32_e32 v58, v58, v59
	v_add_f32_e32 v145, v130, v58
	v_rcp_f32_e32 v147, v145
	v_sub_f32_e32 v59, v145, v130
	v_sub_f32_e32 v146, v58, v59
	v_add_f32_e32 v59, v60, v61
	v_mul_f32_e32 v149, v59, v147
	v_sub_f32_e32 v58, v59, v60
	v_mul_f32_e32 v60, v145, v149
	v_fma_f32 v130, v149, v145, -v60
	v_fmac_f32_e32 v130, v149, v146
	v_sub_f32_e32 v148, v61, v58
	v_add_f32_e32 v58, v60, v130
	v_sub_f32_e32 v61, v59, v58
	v_pk_add_f32 v[132:133], v[58:59], v[60:61] neg_lo:[0,1] neg_hi:[0,1]
	v_mov_b32_e32 v131, v58
	v_pk_add_f32 v[58:59], v[132:133], v[130:131] neg_lo:[0,1] neg_hi:[0,1]
	s_mov_b32 s27, 0x3f317218
	v_add_f32_e32 v59, v148, v59
	v_add_f32_e32 v58, v58, v59
	v_add_f32_e32 v59, v61, v58
	v_mul_f32_e32 v148, v147, v59
	v_mul_f32_e32 v60, v145, v148
	v_fma_f32 v130, v148, v145, -v60
	v_fmac_f32_e32 v130, v148, v146
	v_sub_f32_e32 v61, v61, v59
	v_add_f32_e32 v145, v58, v61
	v_add_f32_e32 v58, v60, v130
	v_sub_f32_e32 v61, v59, v58
	v_pk_add_f32 v[132:133], v[58:59], v[60:61] neg_lo:[0,1] neg_hi:[0,1]
	v_mov_b32_e32 v131, v58
	v_pk_add_f32 v[58:59], v[132:133], v[130:131] neg_lo:[0,1] neg_hi:[0,1]
	s_nop 0
	v_add_f32_e32 v59, v145, v59
	v_add_f32_e32 v58, v58, v59
	v_add_f32_e32 v59, v149, v148
	v_add_f32_e32 v58, v61, v58
	v_sub_f32_e32 v60, v59, v149
	v_mul_f32_e32 v58, v147, v58
	v_sub_f32_e32 v60, v148, v60
	v_add_f32_e32 v60, v60, v58
	v_add_f32_e32 v130, v59, v60
	v_mul_f32_e32 v131, v130, v130
	v_fmamk_f32 v58, v131, 0x3e9b6dac, v236
	v_fmaak_f32 v205, v131, v58, 0x3f2aaada
	v_cvt_f32_i32_e32 v58, v144
	v_sub_f32_e32 v59, v130, v59
	v_sub_f32_e32 v59, v60, v59
	v_ldexp_f32 v132, v59, 1
	v_mul_f32_e32 v59, v130, v131
	v_ldexp_f32 v61, v130, 1
	v_pk_mul_f32 v[130:131], v[58:59], v[204:205]
	s_nop 0
	v_fma_f32 v60, v58, s27, -v130
	v_fmac_f32_e32 v60, 0xb102e308, v58
	v_pk_add_f32 v[58:59], v[130:131], v[60:61]
	s_mov_b32 s27, 0x7f800000
	v_sub_f32_e32 v61, v59, v61
	v_sub_f32_e32 v61, v131, v61
	v_add_f32_e32 v133, v132, v61
	v_mov_b32_e32 v132, v130
	v_pk_add_f32 v[130:131], v[58:59], v[130:131] neg_lo:[0,1] neg_hi:[0,1]
	v_pk_add_f32 v[144:145], v[58:59], v[132:133]
	v_mov_b32_e32 v61, v58
	v_mov_b32_e32 v131, v145
	v_pk_add_f32 v[146:147], v[60:61], v[130:131] neg_lo:[0,1] neg_hi:[0,1]
	v_pk_add_f32 v[60:61], v[60:61], v[130:131]
	v_mov_b32_e32 v132, v133
	v_pk_add_f32 v[130:131], v[60:61], v[58:59] op_sel:[1,0] op_sel_hi:[0,1] neg_lo:[0,1] neg_hi:[0,1]
	v_pk_add_f32 v[148:149], v[144:145], v[130:131] op_sel_hi:[1,0] neg_lo:[0,1] neg_hi:[0,1]
	v_mov_b32_e32 v144, v145
	v_mov_b32_e32 v145, v61
	v_pk_mov_b32 v[130:131], v[58:59], v[130:131] op_sel:[1,0]
	v_mov_b32_e32 v133, v58
	v_pk_add_f32 v[130:131], v[144:145], v[130:131] neg_lo:[0,1] neg_hi:[0,1]
	v_mov_b32_e32 v148, v146
	v_pk_add_f32 v[58:59], v[132:133], v[130:131] neg_lo:[0,1] neg_hi:[0,1]
	v_mov_b32_e32 v147, v61
	v_pk_add_f32 v[130:131], v[148:149], v[58:59]
	v_cmp_neq_f32_e32 vcc, s27, v65
	v_pk_add_f32 v[132:133], v[130:131], v[130:131] op_sel:[0,1] op_sel_hi:[1,0]
	s_mov_b32 s27, 0x33800000
	v_pk_add_f32 v[60:61], v[60:61], v[132:133] op_sel:[1,0] op_sel_hi:[0,1]
	v_mov_b32_e32 v131, v60
	v_pk_add_f32 v[144:145], v[130:131], v[146:147] neg_lo:[0,1] neg_hi:[0,1]
	v_mov_b32_e32 v59, v132
	v_sub_f32_e32 v61, v130, v144
	v_pk_add_f32 v[58:59], v[58:59], v[144:145] neg_lo:[0,1] neg_hi:[0,1]
	v_sub_f32_e32 v61, v146, v61
	v_add_f32_e32 v58, v58, v61
	v_add_f32_e32 v58, v58, v59
	v_add_f32_e32 v58, v60, v58
	v_cndmask_b32_e32 v58, v237, v58, vcc
	v_cmp_ngt_f32_e32 vcc, -1.0, v65
	s_nop 1
	v_cndmask_b32_e32 v58, v238, v58, vcc
	v_cmp_neq_f32_e32 vcc, -1.0, v65
	s_nop 1
	v_cndmask_b32_e32 v58, v239, v58, vcc
	v_cmp_lt_f32_e64 vcc, |v65|, s27
	s_nop 1
	v_cndmask_b32_e32 v58, v58, v65, vcc
	v_sub_f32_e32 v58, v0, v58

.LBB0_973:
	s_and_saveexec_b64 s[4:5], s[10:11]
	s_xor_b64 s[42:43], exec, s[4:5]
	s_cbranch_execz .LBB0_991
	v_readlane_b32 s4, v254, 26
	v_readlane_b32 s5, v254, 27
	s_nop 4
	s_load_dword s4, s[4:5], 0x0
	s_waitcnt lgkmcnt(0)
	v_mov_b32_e32 v0, s4
	v_add_f32_e32 v0, v50, v0
	v_cmp_nlt_f32_e32 vcc, 0, v0
	s_and_saveexec_b64 s[4:5], vcc
	s_xor_b64 s[4:5], exec, s[4:5]
	s_cbranch_execz .LBB0_976
	v_mul_f32_e32 v50, 0x3fb8aa3b, v0
	v_exp_f32_e32 v50, v50
	s_mov_b32 s27, 0x3f2aaaab
	v_add_f32_e32 v56, 1.0, v50
	v_frexp_mant_f32_e32 v58, v56
	v_cvt_f64_f32_e32 v[54:55], v56
	v_frexp_exp_i32_f64_e32 v54, v[54:55]
	v_cmp_gt_f32_e32 vcc, s27, v58
	v_add_f32_e32 v57, -1.0, v56
	v_sub_f32_e32 v59, v57, v56
	v_subbrev_co_u32_e32 v62, vcc, 0, v54, vcc
	v_sub_u32_e32 v54, 0, v62
	v_sub_f32_e32 v57, v50, v57
	v_add_f32_e32 v59, 1.0, v59
	v_ldexp_f32 v55, v56, v54
	v_add_f32_e32 v57, v57, v59
	v_add_f32_e32 v56, -1.0, v55
	v_add_f32_e32 v58, 1.0, v55
	v_ldexp_f32 v54, v57, v54
	v_add_f32_e32 v57, 1.0, v56
	v_add_f32_e32 v59, -1.0, v58
	v_sub_f32_e32 v57, v55, v57
	v_sub_f32_e32 v55, v55, v59
	v_add_f32_e32 v57, v54, v57
	v_add_f32_e32 v54, v54, v55
	v_add_f32_e32 v63, v58, v54
	v_rcp_f32_e32 v65, v63
	v_sub_f32_e32 v55, v63, v58
	v_sub_f32_e32 v64, v54, v55
	v_add_f32_e32 v55, v56, v57
	v_mul_f32_e32 v131, v55, v65
	v_sub_f32_e32 v54, v55, v56
	v_mul_f32_e32 v56, v63, v131
	v_fma_f32 v58, v131, v63, -v56
	v_fmac_f32_e32 v58, v131, v64
	v_sub_f32_e32 v130, v57, v54
	v_add_f32_e32 v54, v56, v58
	v_sub_f32_e32 v57, v55, v54
	v_pk_add_f32 v[60:61], v[54:55], v[56:57] neg_lo:[0,1] neg_hi:[0,1]
	v_mov_b32_e32 v59, v54
	v_pk_add_f32 v[54:55], v[60:61], v[58:59] neg_lo:[0,1] neg_hi:[0,1]
	s_mov_b32 s27, 0x3f317218
	v_add_f32_e32 v55, v130, v55
	v_add_f32_e32 v54, v54, v55
	v_add_f32_e32 v55, v57, v54
	v_mul_f32_e32 v130, v65, v55
	v_mul_f32_e32 v56, v63, v130
	v_fma_f32 v58, v130, v63, -v56
	v_fmac_f32_e32 v58, v130, v64
	v_sub_f32_e32 v57, v57, v55
	v_add_f32_e32 v63, v54, v57
	v_add_f32_e32 v54, v56, v58
	v_sub_f32_e32 v57, v55, v54
	v_pk_add_f32 v[60:61], v[54:55], v[56:57] neg_lo:[0,1] neg_hi:[0,1]
	v_mov_b32_e32 v59, v54
	v_pk_add_f32 v[54:55], v[60:61], v[58:59] neg_lo:[0,1] neg_hi:[0,1]
	s_nop 0
	v_add_f32_e32 v55, v63, v55
	v_add_f32_e32 v54, v54, v55
	v_add_f32_e32 v55, v131, v130
	v_add_f32_e32 v54, v57, v54
	v_sub_f32_e32 v56, v55, v131
	v_mul_f32_e32 v54, v65, v54
	v_sub_f32_e32 v56, v130, v56
	v_add_f32_e32 v56, v56, v54
	v_add_f32_e32 v58, v55, v56
	v_mul_f32_e32 v59, v58, v58
	v_fmamk_f32 v54, v59, 0x3e9b6dac, v236
	v_fmaak_f32 v205, v59, v54, 0x3f2aaada
	v_cvt_f32_i32_e32 v54, v62
	v_sub_f32_e32 v55, v58, v55
	v_sub_f32_e32 v55, v56, v55
	v_ldexp_f32 v60, v55, 1
	v_mul_f32_e32 v55, v58, v59
	v_ldexp_f32 v57, v58, 1
	v_pk_mul_f32 v[58:59], v[54:55], v[204:205]
	s_nop 0
	v_fma_f32 v56, v54, s27, -v58
	v_fmac_f32_e32 v56, 0xb102e308, v54
	v_pk_add_f32 v[54:55], v[58:59], v[56:57]
	s_mov_b32 s27, 0x7f800000
	v_sub_f32_e32 v57, v55, v57
	v_sub_f32_e32 v57, v59, v57
	v_add_f32_e32 v61, v60, v57
	v_mov_b32_e32 v60, v58
	v_pk_add_f32 v[58:59], v[54:55], v[58:59] neg_lo:[0,1] neg_hi:[0,1]
	v_pk_add_f32 v[62:63], v[54:55], v[60:61]
	v_mov_b32_e32 v57, v54
	v_mov_b32_e32 v59, v63
	v_pk_add_f32 v[64:65], v[56:57], v[58:59] neg_lo:[0,1] neg_hi:[0,1]
	v_pk_add_f32 v[56:57], v[56:57], v[58:59]
	v_mov_b32_e32 v60, v61
	v_pk_add_f32 v[58:59], v[56:57], v[54:55] op_sel:[1,0] op_sel_hi:[0,1] neg_lo:[0,1] neg_hi:[0,1]
	v_pk_add_f32 v[130:131], v[62:63], v[58:59] op_sel_hi:[1,0] neg_lo:[0,1] neg_hi:[0,1]
	v_mov_b32_e32 v62, v63
	v_mov_b32_e32 v63, v57
	v_pk_mov_b32 v[58:59], v[54:55], v[58:59] op_sel:[1,0]
	v_mov_b32_e32 v61, v54
	v_pk_add_f32 v[58:59], v[62:63], v[58:59] neg_lo:[0,1] neg_hi:[0,1]
	v_mov_b32_e32 v130, v64
	v_pk_add_f32 v[54:55], v[60:61], v[58:59] neg_lo:[0,1] neg_hi:[0,1]
	v_mov_b32_e32 v65, v57
	v_pk_add_f32 v[58:59], v[130:131], v[54:55]
	v_cmp_neq_f32_e32 vcc, s27, v50
	v_pk_add_f32 v[60:61], v[58:59], v[58:59] op_sel:[0,1] op_sel_hi:[1,0]
	s_mov_b32 s27, 0x33800000
	v_pk_add_f32 v[56:57], v[56:57], v[60:61] op_sel:[1,0] op_sel_hi:[0,1]
	v_mov_b32_e32 v59, v56
	v_pk_add_f32 v[62:63], v[58:59], v[64:65] neg_lo:[0,1] neg_hi:[0,1]
	v_mov_b32_e32 v55, v60
	v_sub_f32_e32 v57, v58, v62
	v_pk_add_f32 v[54:55], v[54:55], v[62:63] neg_lo:[0,1] neg_hi:[0,1]
	v_sub_f32_e32 v57, v64, v57
	v_add_f32_e32 v54, v54, v57
	v_add_f32_e32 v54, v54, v55
	v_add_f32_e32 v54, v56, v54
	v_cndmask_b32_e32 v54, v237, v54, vcc
	v_cmp_ngt_f32_e32 vcc, -1.0, v50
	s_nop 1
	v_cndmask_b32_e32 v54, v238, v54, vcc
	v_cmp_neq_f32_e32 vcc, -1.0, v50
	s_nop 1
	v_cndmask_b32_e32 v54, v239, v54, vcc
	v_cmp_lt_f32_e64 vcc, |v50|, s27
	s_nop 1
	v_cndmask_b32_e32 v50, v54, v50, vcc
	v_sub_f32_e32 v50, v0, v50

.LBB0_978:
	s_or_b64 exec, exec, s[4:5]
	v_lshlrev_b32_e32 v56, 2, v144
	v_lshlrev_b32_e32 v0, 2, v145
	v_ashrrev_i32_e32 v57, 31, v56
	v_lshl_add_u64 v[54:55], s[84:85], 0, v[0:1]
	v_lshlrev_b64 v[58:59], 13, v[56:57]
	v_lshl_add_u64 v[58:59], v[54:55], 0, v[58:59]
	v_readlane_b32 s4, v254, 26
	global_store_dword v[58:59], v50, off
	v_readlane_b32 s5, v254, 27
	s_nop 4
	s_load_dword s4, s[4:5], 0x4
	s_waitcnt lgkmcnt(0)
	v_mov_b32_e32 v0, s4
	v_add_f32_e32 v0, v51, v0
	v_cmp_nlt_f32_e32 vcc, 0, v0
	s_and_saveexec_b64 s[4:5], vcc
	s_xor_b64 s[4:5], exec, s[4:5]
	s_cbranch_execz .LBB0_980
	v_mul_f32_e32 v50, 0x3fb8aa3b, v0
	v_exp_f32_e32 v57, v50
	s_mov_b32 s27, 0x3f2aaaab
	v_add_f32_e32 v58, 1.0, v57
	v_frexp_mant_f32_e32 v60, v58
	v_cvt_f64_f32_e32 v[50:51], v58
	v_frexp_exp_i32_f64_e32 v50, v[50:51]
	v_cmp_gt_f32_e32 vcc, s27, v60
	v_add_f32_e32 v59, -1.0, v58
	v_sub_f32_e32 v61, v59, v58
	v_subbrev_co_u32_e32 v64, vcc, 0, v50, vcc
	v_sub_u32_e32 v50, 0, v64
	v_sub_f32_e32 v59, v57, v59
	v_add_f32_e32 v61, 1.0, v61
	v_ldexp_f32 v51, v58, v50
	v_add_f32_e32 v59, v59, v61
	v_add_f32_e32 v58, -1.0, v51
	v_add_f32_e32 v60, 1.0, v51
	v_ldexp_f32 v50, v59, v50
	v_add_f32_e32 v59, 1.0, v58
	v_add_f32_e32 v61, -1.0, v60
	v_sub_f32_e32 v59, v51, v59
	v_sub_f32_e32 v51, v51, v61
	v_add_f32_e32 v59, v50, v59
	v_add_f32_e32 v50, v50, v51
	v_add_f32_e32 v65, v60, v50
	v_rcp_f32_e32 v131, v65
	v_sub_f32_e32 v51, v65, v60
	v_sub_f32_e32 v130, v50, v51
	v_add_f32_e32 v51, v58, v59
	v_mul_f32_e32 v144, v51, v131
	v_sub_f32_e32 v50, v51, v58
	v_mul_f32_e32 v58, v65, v144
	v_fma_f32 v60, v144, v65, -v58
	v_fmac_f32_e32 v60, v144, v130
	v_sub_f32_e32 v133, v59, v50
	v_add_f32_e32 v50, v58, v60
	v_sub_f32_e32 v59, v51, v50
	v_pk_add_f32 v[62:63], v[50:51], v[58:59] neg_lo:[0,1] neg_hi:[0,1]
	v_mov_b32_e32 v61, v50
	v_pk_add_f32 v[50:51], v[62:63], v[60:61] neg_lo:[0,1] neg_hi:[0,1]
	s_mov_b32 s27, 0x3f317218
	v_add_f32_e32 v51, v133, v51
	v_add_f32_e32 v50, v50, v51
	v_add_f32_e32 v51, v59, v50
	v_mul_f32_e32 v133, v131, v51
	v_mul_f32_e32 v58, v65, v133
	v_fma_f32 v60, v133, v65, -v58
	v_fmac_f32_e32 v60, v133, v130
	v_sub_f32_e32 v59, v59, v51
	v_add_f32_e32 v65, v50, v59
	v_add_f32_e32 v50, v58, v60
	v_sub_f32_e32 v59, v51, v50
	v_pk_add_f32 v[62:63], v[50:51], v[58:59] neg_lo:[0,1] neg_hi:[0,1]
	v_mov_b32_e32 v61, v50
	v_pk_add_f32 v[50:51], v[62:63], v[60:61] neg_lo:[0,1] neg_hi:[0,1]
	s_nop 0
	v_add_f32_e32 v51, v65, v51
	v_add_f32_e32 v50, v50, v51
	v_add_f32_e32 v51, v144, v133
	v_add_f32_e32 v50, v59, v50
	v_sub_f32_e32 v58, v51, v144
	v_mul_f32_e32 v50, v131, v50
	v_sub_f32_e32 v58, v133, v58
	v_add_f32_e32 v58, v58, v50
	v_add_f32_e32 v60, v51, v58
	v_mul_f32_e32 v61, v60, v60
	v_fmamk_f32 v50, v61, 0x3e9b6dac, v236
	v_fmaak_f32 v205, v61, v50, 0x3f2aaada
	v_cvt_f32_i32_e32 v50, v64
	v_sub_f32_e32 v51, v60, v51
	v_sub_f32_e32 v51, v58, v51
	v_ldexp_f32 v62, v51, 1
	v_mul_f32_e32 v51, v60, v61
	v_ldexp_f32 v59, v60, 1
	v_pk_mul_f32 v[60:61], v[50:51], v[204:205]
	s_nop 0
	v_fma_f32 v58, v50, s27, -v60
	v_fmac_f32_e32 v58, 0xb102e308, v50
	v_pk_add_f32 v[50:51], v[60:61], v[58:59]
	s_mov_b32 s27, 0x7f800000
	v_sub_f32_e32 v59, v51, v59
	v_sub_f32_e32 v59, v61, v59
	v_add_f32_e32 v63, v62, v59
	v_mov_b32_e32 v62, v60
	v_pk_add_f32 v[60:61], v[50:51], v[60:61] neg_lo:[0,1] neg_hi:[0,1]
	v_pk_add_f32 v[64:65], v[50:51], v[62:63]
	v_mov_b32_e32 v59, v50
	v_mov_b32_e32 v61, v65
	v_pk_add_f32 v[130:131], v[58:59], v[60:61] neg_lo:[0,1] neg_hi:[0,1]
	v_pk_add_f32 v[58:59], v[58:59], v[60:61]
	v_mov_b32_e32 v62, v63
	v_pk_add_f32 v[60:61], v[58:59], v[50:51] op_sel:[1,0] op_sel_hi:[0,1] neg_lo:[0,1] neg_hi:[0,1]
	v_pk_add_f32 v[144:145], v[64:65], v[60:61] op_sel_hi:[1,0] neg_lo:[0,1] neg_hi:[0,1]
	v_mov_b32_e32 v64, v65
	v_mov_b32_e32 v65, v59
	v_pk_mov_b32 v[60:61], v[50:51], v[60:61] op_sel:[1,0]
	v_mov_b32_e32 v63, v50
	v_pk_add_f32 v[60:61], v[64:65], v[60:61] neg_lo:[0,1] neg_hi:[0,1]
	v_mov_b32_e32 v144, v130
	v_pk_add_f32 v[50:51], v[62:63], v[60:61] neg_lo:[0,1] neg_hi:[0,1]
	v_mov_b32_e32 v131, v59
	v_pk_add_f32 v[60:61], v[144:145], v[50:51]
	v_cmp_neq_f32_e32 vcc, s27, v57
	v_pk_add_f32 v[62:63], v[60:61], v[60:61] op_sel:[0,1] op_sel_hi:[1,0]
	s_mov_b32 s27, 0x33800000
	v_pk_add_f32 v[58:59], v[58:59], v[62:63] op_sel:[1,0] op_sel_hi:[0,1]
	v_mov_b32_e32 v61, v58
	v_pk_add_f32 v[64:65], v[60:61], v[130:131] neg_lo:[0,1] neg_hi:[0,1]
	v_mov_b32_e32 v51, v62
	v_sub_f32_e32 v59, v60, v64
	v_pk_add_f32 v[50:51], v[50:51], v[64:65] neg_lo:[0,1] neg_hi:[0,1]
	v_sub_f32_e32 v59, v130, v59
	v_add_f32_e32 v50, v50, v59
	v_add_f32_e32 v50, v50, v51
	v_add_f32_e32 v50, v58, v50
	v_cndmask_b32_e32 v50, v237, v50, vcc
	v_cmp_ngt_f32_e32 vcc, -1.0, v57
	s_nop 1
	v_cndmask_b32_e32 v50, v238, v50, vcc
	v_cmp_neq_f32_e32 vcc, -1.0, v57
	s_nop 1
	v_cndmask_b32_e32 v50, v239, v50, vcc
	v_cmp_lt_f32_e64 vcc, |v57|, s27
	s_nop 1
	v_cndmask_b32_e32 v50, v50, v57, vcc
	v_sub_f32_e32 v50, v0, v50

.LBB0_982:
	s_or_b64 exec, exec, s[4:5]
	v_or_b32_e32 v58, 1, v56
	v_ashrrev_i32_e32 v59, 31, v58
	v_lshlrev_b64 v[58:59], 13, v[58:59]
	v_lshl_add_u64 v[58:59], v[54:55], 0, v[58:59]
	v_readlane_b32 s4, v254, 26
	global_store_dword v[58:59], v50, off
	v_readlane_b32 s5, v254, 27
	s_nop 4
	s_load_dword s4, s[4:5], 0x8
	s_waitcnt lgkmcnt(0)
	v_mov_b32_e32 v0, s4
	v_add_f32_e32 v0, v52, v0
	v_cmp_nlt_f32_e32 vcc, 0, v0
	s_and_saveexec_b64 s[4:5], vcc
	s_xor_b64 s[4:5], exec, s[4:5]
	s_cbranch_execz .LBB0_984
	v_mul_f32_e32 v50, 0x3fb8aa3b, v0
	v_exp_f32_e32 v52, v50
	s_mov_b32 s27, 0x3f2aaaab
	v_add_f32_e32 v57, 1.0, v52
	v_frexp_mant_f32_e32 v59, v57
	v_cvt_f64_f32_e32 v[50:51], v57
	v_frexp_exp_i32_f64_e32 v50, v[50:51]
	v_cmp_gt_f32_e32 vcc, s27, v59
	v_add_f32_e32 v58, -1.0, v57
	v_sub_f32_e32 v60, v58, v57
	v_subbrev_co_u32_e32 v64, vcc, 0, v50, vcc
	v_sub_u32_e32 v50, 0, v64
	v_sub_f32_e32 v58, v52, v58
	v_add_f32_e32 v60, 1.0, v60
	v_ldexp_f32 v51, v57, v50
	v_add_f32_e32 v58, v58, v60
	v_add_f32_e32 v57, -1.0, v51
	v_add_f32_e32 v59, 1.0, v51
	v_ldexp_f32 v50, v58, v50
	v_add_f32_e32 v58, 1.0, v57
	v_add_f32_e32 v60, -1.0, v59
	v_sub_f32_e32 v58, v51, v58
	v_sub_f32_e32 v51, v51, v60
	v_add_f32_e32 v58, v50, v58
	v_add_f32_e32 v50, v50, v51
	v_add_f32_e32 v65, v59, v50
	v_rcp_f32_e32 v131, v65
	v_sub_f32_e32 v51, v65, v59
	v_sub_f32_e32 v130, v50, v51
	v_add_f32_e32 v51, v57, v58
	v_sub_f32_e32 v50, v51, v57
	v_mul_f32_e32 v133, v51, v131
	v_sub_f32_e32 v57, v58, v50
	v_mul_f32_e32 v58, v65, v133
	v_fma_f32 v60, v133, v65, -v58
	v_fmac_f32_e32 v60, v133, v130
	v_add_f32_e32 v50, v58, v60
	v_sub_f32_e32 v59, v51, v50
	v_pk_add_f32 v[62:63], v[50:51], v[58:59] neg_lo:[0,1] neg_hi:[0,1]
	v_mov_b32_e32 v61, v50
	v_pk_add_f32 v[50:51], v[62:63], v[60:61] neg_lo:[0,1] neg_hi:[0,1]
	s_mov_b32 s27, 0x3f317218
	v_add_f32_e32 v51, v57, v51
	v_add_f32_e32 v50, v50, v51
	v_add_f32_e32 v51, v59, v50
	v_mul_f32_e32 v57, v131, v51
	v_mul_f32_e32 v58, v65, v57
	v_fma_f32 v60, v57, v65, -v58
	v_fmac_f32_e32 v60, v57, v130
	v_sub_f32_e32 v59, v59, v51
	v_add_f32_e32 v65, v50, v59
	v_add_f32_e32 v50, v58, v60
	v_sub_f32_e32 v59, v51, v50
	v_pk_add_f32 v[62:63], v[50:51], v[58:59] neg_lo:[0,1] neg_hi:[0,1]
	v_mov_b32_e32 v61, v50
	v_pk_add_f32 v[50:51], v[62:63], v[60:61] neg_lo:[0,1] neg_hi:[0,1]
	s_nop 0
	v_add_f32_e32 v51, v65, v51
	v_add_f32_e32 v50, v50, v51
	v_add_f32_e32 v51, v133, v57
	v_add_f32_e32 v50, v59, v50
	v_sub_f32_e32 v58, v51, v133
	v_mul_f32_e32 v50, v131, v50
	v_sub_f32_e32 v57, v57, v58
	v_add_f32_e32 v57, v57, v50
	v_add_f32_e32 v58, v51, v57
	v_mul_f32_e32 v60, v58, v58
	v_fmamk_f32 v50, v60, 0x3e9b6dac, v236
	v_fmaak_f32 v205, v60, v50, 0x3f2aaada
	v_cvt_f32_i32_e32 v50, v64
	v_sub_f32_e32 v51, v58, v51
	v_sub_f32_e32 v51, v57, v51
	v_ldexp_f32 v57, v51, 1
	v_mul_f32_e32 v51, v58, v60
	v_pk_mul_f32 v[60:61], v[50:51], v[204:205]
	v_ldexp_f32 v59, v58, 1
	v_fma_f32 v58, v50, s27, -v60
	v_fmac_f32_e32 v58, 0xb102e308, v50
	v_pk_add_f32 v[50:51], v[60:61], v[58:59]
	v_mov_b32_e32 v62, v60
	v_sub_f32_e32 v59, v51, v59
	v_sub_f32_e32 v59, v61, v59
	v_add_f32_e32 v63, v57, v59
	v_pk_add_f32 v[60:61], v[50:51], v[60:61] neg_lo:[0,1] neg_hi:[0,1]
	v_pk_add_f32 v[64:65], v[50:51], v[62:63]
	v_mov_b32_e32 v59, v50
	v_mov_b32_e32 v61, v65
	v_pk_add_f32 v[130:131], v[58:59], v[60:61] neg_lo:[0,1] neg_hi:[0,1]
	v_pk_add_f32 v[58:59], v[58:59], v[60:61]
	v_mov_b32_e32 v62, v63
	v_pk_add_f32 v[60:61], v[58:59], v[50:51] op_sel:[1,0] op_sel_hi:[0,1] neg_lo:[0,1] neg_hi:[0,1]
	v_pk_add_f32 v[144:145], v[64:65], v[60:61] op_sel_hi:[1,0] neg_lo:[0,1] neg_hi:[0,1]
	v_mov_b32_e32 v64, v65
	v_mov_b32_e32 v65, v59
	v_pk_mov_b32 v[60:61], v[50:51], v[60:61] op_sel:[1,0]
	v_mov_b32_e32 v63, v50
	v_pk_add_f32 v[60:61], v[64:65], v[60:61] neg_lo:[0,1] neg_hi:[0,1]
	v_mov_b32_e32 v144, v130
	v_pk_add_f32 v[50:51], v[62:63], v[60:61] neg_lo:[0,1] neg_hi:[0,1]
	v_mov_b32_e32 v131, v59
	v_pk_add_f32 v[60:61], v[144:145], v[50:51]
	s_mov_b32 s27, 0x7f800000
	v_pk_add_f32 v[62:63], v[60:61], v[60:61] op_sel:[0,1] op_sel_hi:[1,0]
	v_cmp_neq_f32_e32 vcc, s27, v52
	v_pk_add_f32 v[58:59], v[58:59], v[62:63] op_sel:[1,0] op_sel_hi:[0,1]
	v_mov_b32_e32 v61, v58
	v_pk_add_f32 v[64:65], v[60:61], v[130:131] neg_lo:[0,1] neg_hi:[0,1]
	v_mov_b32_e32 v51, v62
	v_sub_f32_e32 v57, v60, v64
	v_pk_add_f32 v[50:51], v[50:51], v[64:65] neg_lo:[0,1] neg_hi:[0,1]
	v_sub_f32_e32 v57, v130, v57
	v_add_f32_e32 v50, v50, v57
	v_add_f32_e32 v50, v50, v51
	v_add_f32_e32 v50, v58, v50
	v_cndmask_b32_e32 v50, v237, v50, vcc
	v_cmp_ngt_f32_e32 vcc, -1.0, v52
	s_mov_b32 s27, 0x33800000
	s_nop 0
	v_cndmask_b32_e32 v50, v238, v50, vcc
	v_cmp_neq_f32_e32 vcc, -1.0, v52
	s_nop 1
	v_cndmask_b32_e32 v50, v239, v50, vcc
	v_cmp_lt_f32_e64 vcc, |v52|, s27
	s_nop 1
	v_cndmask_b32_e32 v50, v50, v52, vcc
	v_sub_f32_e32 v50, v0, v50

.LBB0_986:
	s_or_b64 exec, exec, s[4:5]
	v_or_b32_e32 v58, 2, v56
	v_ashrrev_i32_e32 v59, 31, v58
	v_lshlrev_b64 v[58:59], 13, v[58:59]
	v_lshl_add_u64 v[58:59], v[54:55], 0, v[58:59]
	v_readlane_b32 s4, v254, 26
	global_store_dword v[58:59], v50, off
	v_readlane_b32 s5, v254, 27
	s_nop 4
	s_load_dword s4, s[4:5], 0xc
	s_waitcnt lgkmcnt(0)
	v_mov_b32_e32 v0, s4
	v_add_f32_e32 v0, v53, v0
	v_cmp_nlt_f32_e32 vcc, 0, v0
	s_and_saveexec_b64 s[4:5], vcc
	s_xor_b64 s[4:5], exec, s[4:5]
	s_cbranch_execz .LBB0_988
	v_mul_f32_e32 v50, 0x3fb8aa3b, v0
	v_exp_f32_e32 v57, v50
	s_mov_b32 s27, 0x3f2aaaab
	v_add_f32_e32 v52, 1.0, v57
	v_frexp_mant_f32_e32 v58, v52
	v_cvt_f64_f32_e32 v[50:51], v52
	v_frexp_exp_i32_f64_e32 v50, v[50:51]
	v_cmp_gt_f32_e32 vcc, s27, v58
	v_add_f32_e32 v53, -1.0, v52
	v_sub_f32_e32 v59, v53, v52
	v_subbrev_co_u32_e32 v62, vcc, 0, v50, vcc
	v_sub_u32_e32 v50, 0, v62
	v_sub_f32_e32 v53, v57, v53
	v_add_f32_e32 v59, 1.0, v59
	v_ldexp_f32 v51, v52, v50
	v_add_f32_e32 v53, v53, v59
	v_add_f32_e32 v52, -1.0, v51
	v_add_f32_e32 v58, 1.0, v51
	v_ldexp_f32 v50, v53, v50
	v_add_f32_e32 v53, 1.0, v52
	v_add_f32_e32 v59, -1.0, v58
	v_sub_f32_e32 v53, v51, v53
	v_sub_f32_e32 v51, v51, v59
	v_add_f32_e32 v53, v50, v53
	v_add_f32_e32 v50, v50, v51
	v_add_f32_e32 v63, v58, v50
	v_rcp_f32_e32 v65, v63
	v_sub_f32_e32 v51, v63, v58
	v_sub_f32_e32 v64, v50, v51
	v_add_f32_e32 v51, v52, v53
	v_mul_f32_e32 v131, v51, v65
	v_sub_f32_e32 v50, v51, v52
	v_mul_f32_e32 v52, v63, v131
	v_fma_f32 v58, v131, v63, -v52
	v_fmac_f32_e32 v58, v131, v64
	v_sub_f32_e32 v130, v53, v50
	v_add_f32_e32 v50, v52, v58
	v_sub_f32_e32 v53, v51, v50
	v_pk_add_f32 v[60:61], v[50:51], v[52:53] neg_lo:[0,1] neg_hi:[0,1]
	v_mov_b32_e32 v59, v50
	v_pk_add_f32 v[50:51], v[60:61], v[58:59] neg_lo:[0,1] neg_hi:[0,1]
	s_mov_b32 s27, 0x3f317218
	v_add_f32_e32 v51, v130, v51
	v_add_f32_e32 v50, v50, v51
	v_add_f32_e32 v51, v53, v50
	v_mul_f32_e32 v130, v65, v51
	v_mul_f32_e32 v52, v63, v130
	v_fma_f32 v58, v130, v63, -v52
	v_fmac_f32_e32 v58, v130, v64
	v_sub_f32_e32 v53, v53, v51
	v_add_f32_e32 v63, v50, v53
	v_add_f32_e32 v50, v52, v58
	v_sub_f32_e32 v53, v51, v50
	v_pk_add_f32 v[60:61], v[50:51], v[52:53] neg_lo:[0,1] neg_hi:[0,1]
	v_mov_b32_e32 v59, v50
	v_pk_add_f32 v[50:51], v[60:61], v[58:59] neg_lo:[0,1] neg_hi:[0,1]
	s_nop 0
	v_add_f32_e32 v51, v63, v51
	v_add_f32_e32 v50, v50, v51
	v_add_f32_e32 v51, v131, v130
	v_add_f32_e32 v50, v53, v50
	v_sub_f32_e32 v52, v51, v131
	v_mul_f32_e32 v50, v65, v50
	v_sub_f32_e32 v52, v130, v52
	v_add_f32_e32 v52, v52, v50
	v_add_f32_e32 v58, v51, v52
	v_mul_f32_e32 v59, v58, v58
	v_fmamk_f32 v50, v59, 0x3e9b6dac, v236
	v_fmaak_f32 v205, v59, v50, 0x3f2aaada
	v_cvt_f32_i32_e32 v50, v62
	v_sub_f32_e32 v51, v58, v51
	v_sub_f32_e32 v51, v52, v51
	v_ldexp_f32 v60, v51, 1
	v_mul_f32_e32 v51, v58, v59
	v_ldexp_f32 v53, v58, 1
	v_pk_mul_f32 v[58:59], v[50:51], v[204:205]
	s_nop 0
	v_fma_f32 v52, v50, s27, -v58
	v_fmac_f32_e32 v52, 0xb102e308, v50
	v_pk_add_f32 v[50:51], v[58:59], v[52:53]
	s_mov_b32 s27, 0x7f800000
	v_sub_f32_e32 v53, v51, v53
	v_sub_f32_e32 v53, v59, v53
	v_add_f32_e32 v61, v60, v53
	v_mov_b32_e32 v60, v58
	v_pk_add_f32 v[58:59], v[50:51], v[58:59] neg_lo:[0,1] neg_hi:[0,1]
	v_pk_add_f32 v[62:63], v[50:51], v[60:61]
	v_mov_b32_e32 v53, v50
	v_mov_b32_e32 v59, v63
	v_pk_add_f32 v[64:65], v[52:53], v[58:59] neg_lo:[0,1] neg_hi:[0,1]
	v_pk_add_f32 v[52:53], v[52:53], v[58:59]
	v_mov_b32_e32 v60, v61
	v_pk_add_f32 v[58:59], v[52:53], v[50:51] op_sel:[1,0] op_sel_hi:[0,1] neg_lo:[0,1] neg_hi:[0,1]
	v_pk_add_f32 v[130:131], v[62:63], v[58:59] op_sel_hi:[1,0] neg_lo:[0,1] neg_hi:[0,1]
	v_mov_b32_e32 v62, v63
	v_mov_b32_e32 v63, v53
	v_pk_mov_b32 v[58:59], v[50:51], v[58:59] op_sel:[1,0]
	v_mov_b32_e32 v61, v50
	v_pk_add_f32 v[58:59], v[62:63], v[58:59] neg_lo:[0,1] neg_hi:[0,1]
	v_mov_b32_e32 v130, v64
	v_pk_add_f32 v[50:51], v[60:61], v[58:59] neg_lo:[0,1] neg_hi:[0,1]
	v_mov_b32_e32 v65, v53
	v_pk_add_f32 v[58:59], v[130:131], v[50:51]
	v_cmp_neq_f32_e32 vcc, s27, v57
	v_pk_add_f32 v[60:61], v[58:59], v[58:59] op_sel:[0,1] op_sel_hi:[1,0]
	s_mov_b32 s27, 0x33800000
	v_pk_add_f32 v[52:53], v[52:53], v[60:61] op_sel:[1,0] op_sel_hi:[0,1]
	v_mov_b32_e32 v59, v52
	v_pk_add_f32 v[62:63], v[58:59], v[64:65] neg_lo:[0,1] neg_hi:[0,1]
	v_mov_b32_e32 v51, v60
	v_sub_f32_e32 v53, v58, v62
	v_pk_add_f32 v[50:51], v[50:51], v[62:63] neg_lo:[0,1] neg_hi:[0,1]
	v_sub_f32_e32 v53, v64, v53
	v_add_f32_e32 v50, v50, v53
	v_add_f32_e32 v50, v50, v51
	v_add_f32_e32 v50, v52, v50
	v_cndmask_b32_e32 v50, v237, v50, vcc
	v_cmp_ngt_f32_e32 vcc, -1.0, v57
	s_nop 1
	v_cndmask_b32_e32 v50, v238, v50, vcc
	v_cmp_neq_f32_e32 vcc, -1.0, v57
	s_nop 1
	v_cndmask_b32_e32 v50, v239, v50, vcc
	v_cmp_lt_f32_e64 vcc, |v57|, s27
	s_nop 1
	v_cndmask_b32_e32 v50, v50, v57, vcc
	v_sub_f32_e32 v50, v0, v50

.LBB0_1013:
	s_and_saveexec_b64 s[4:5], s[10:11]
	s_xor_b64 s[42:43], exec, s[4:5]
	s_cbranch_execz .LBB0_1031
	v_readlane_b32 s4, v254, 26
	v_readlane_b32 s5, v254, 27
	s_nop 4
	s_load_dword s4, s[4:5], 0x0
	s_waitcnt lgkmcnt(0)
	v_mov_b32_e32 v0, s4
	v_add_f32_e32 v0, v42, v0
	v_cmp_nlt_f32_e32 vcc, 0, v0
	s_and_saveexec_b64 s[4:5], vcc
	s_xor_b64 s[4:5], exec, s[4:5]
	s_cbranch_execz .LBB0_1016
	v_mul_f32_e32 v42, 0x3fb8aa3b, v0
	v_exp_f32_e32 v42, v42
	s_mov_b32 s27, 0x3f2aaaab
	v_add_f32_e32 v48, 1.0, v42
	v_frexp_mant_f32_e32 v50, v48
	v_cvt_f64_f32_e32 v[46:47], v48
	v_frexp_exp_i32_f64_e32 v46, v[46:47]
	v_cmp_gt_f32_e32 vcc, s27, v50
	v_add_f32_e32 v49, -1.0, v48
	v_sub_f32_e32 v51, v49, v48
	v_subbrev_co_u32_e32 v54, vcc, 0, v46, vcc
	v_sub_u32_e32 v46, 0, v54
	v_sub_f32_e32 v49, v42, v49
	v_add_f32_e32 v51, 1.0, v51
	v_ldexp_f32 v47, v48, v46
	v_add_f32_e32 v49, v49, v51
	v_add_f32_e32 v48, -1.0, v47
	v_add_f32_e32 v50, 1.0, v47
	v_ldexp_f32 v46, v49, v46
	v_add_f32_e32 v49, 1.0, v48
	v_add_f32_e32 v51, -1.0, v50
	v_sub_f32_e32 v49, v47, v49
	v_sub_f32_e32 v47, v47, v51
	v_add_f32_e32 v49, v46, v49
	v_add_f32_e32 v46, v46, v47
	v_add_f32_e32 v55, v50, v46
	v_rcp_f32_e32 v57, v55
	v_sub_f32_e32 v47, v55, v50
	v_sub_f32_e32 v56, v46, v47
	v_add_f32_e32 v47, v48, v49
	v_mul_f32_e32 v59, v47, v57
	v_sub_f32_e32 v46, v47, v48
	v_mul_f32_e32 v48, v55, v59
	v_fma_f32 v50, v59, v55, -v48
	v_fmac_f32_e32 v50, v59, v56
	v_sub_f32_e32 v58, v49, v46
	v_add_f32_e32 v46, v48, v50
	v_sub_f32_e32 v49, v47, v46
	v_pk_add_f32 v[52:53], v[46:47], v[48:49] neg_lo:[0,1] neg_hi:[0,1]
	v_mov_b32_e32 v51, v46
	v_pk_add_f32 v[46:47], v[52:53], v[50:51] neg_lo:[0,1] neg_hi:[0,1]
	s_mov_b32 s27, 0x3f317218
	v_add_f32_e32 v47, v58, v47
	v_add_f32_e32 v46, v46, v47
	v_add_f32_e32 v47, v49, v46
	v_mul_f32_e32 v58, v57, v47
	v_mul_f32_e32 v48, v55, v58
	v_fma_f32 v50, v58, v55, -v48
	v_fmac_f32_e32 v50, v58, v56
	v_sub_f32_e32 v49, v49, v47
	v_add_f32_e32 v55, v46, v49
	v_add_f32_e32 v46, v48, v50
	v_sub_f32_e32 v49, v47, v46
	v_pk_add_f32 v[52:53], v[46:47], v[48:49] neg_lo:[0,1] neg_hi:[0,1]
	v_mov_b32_e32 v51, v46
	v_pk_add_f32 v[46:47], v[52:53], v[50:51] neg_lo:[0,1] neg_hi:[0,1]
	s_nop 0
	v_add_f32_e32 v47, v55, v47
	v_add_f32_e32 v46, v46, v47
	v_add_f32_e32 v47, v59, v58
	v_add_f32_e32 v46, v49, v46
	v_sub_f32_e32 v48, v47, v59
	v_mul_f32_e32 v46, v57, v46
	v_sub_f32_e32 v48, v58, v48
	v_add_f32_e32 v48, v48, v46
	v_add_f32_e32 v50, v47, v48
	v_mul_f32_e32 v51, v50, v50
	v_fmamk_f32 v46, v51, 0x3e9b6dac, v236
	v_fmaak_f32 v205, v51, v46, 0x3f2aaada
	v_cvt_f32_i32_e32 v46, v54
	v_sub_f32_e32 v47, v50, v47
	v_sub_f32_e32 v47, v48, v47
	v_ldexp_f32 v52, v47, 1
	v_mul_f32_e32 v47, v50, v51
	v_ldexp_f32 v49, v50, 1
	v_pk_mul_f32 v[50:51], v[46:47], v[204:205]
	s_nop 0
	v_fma_f32 v48, v46, s27, -v50
	v_fmac_f32_e32 v48, 0xb102e308, v46
	v_pk_add_f32 v[46:47], v[50:51], v[48:49]
	s_mov_b32 s27, 0x7f800000
	v_sub_f32_e32 v49, v47, v49
	v_sub_f32_e32 v49, v51, v49
	v_add_f32_e32 v53, v52, v49
	v_mov_b32_e32 v52, v50
	v_pk_add_f32 v[50:51], v[46:47], v[50:51] neg_lo:[0,1] neg_hi:[0,1]
	v_pk_add_f32 v[54:55], v[46:47], v[52:53]
	v_mov_b32_e32 v49, v46
	v_mov_b32_e32 v51, v55
	v_pk_add_f32 v[56:57], v[48:49], v[50:51] neg_lo:[0,1] neg_hi:[0,1]
	v_pk_add_f32 v[48:49], v[48:49], v[50:51]
	v_mov_b32_e32 v52, v53
	v_pk_add_f32 v[50:51], v[48:49], v[46:47] op_sel:[1,0] op_sel_hi:[0,1] neg_lo:[0,1] neg_hi:[0,1]
	v_pk_add_f32 v[58:59], v[54:55], v[50:51] op_sel_hi:[1,0] neg_lo:[0,1] neg_hi:[0,1]
	v_mov_b32_e32 v54, v55
	v_mov_b32_e32 v55, v49
	v_pk_mov_b32 v[50:51], v[46:47], v[50:51] op_sel:[1,0]
	v_mov_b32_e32 v53, v46
	v_pk_add_f32 v[50:51], v[54:55], v[50:51] neg_lo:[0,1] neg_hi:[0,1]
	v_mov_b32_e32 v58, v56
	v_pk_add_f32 v[46:47], v[52:53], v[50:51] neg_lo:[0,1] neg_hi:[0,1]
	v_mov_b32_e32 v57, v49
	v_pk_add_f32 v[50:51], v[58:59], v[46:47]
	v_cmp_neq_f32_e32 vcc, s27, v42
	v_pk_add_f32 v[52:53], v[50:51], v[50:51] op_sel:[0,1] op_sel_hi:[1,0]
	s_mov_b32 s27, 0x33800000
	v_pk_add_f32 v[48:49], v[48:49], v[52:53] op_sel:[1,0] op_sel_hi:[0,1]
	v_mov_b32_e32 v51, v48
	v_pk_add_f32 v[54:55], v[50:51], v[56:57] neg_lo:[0,1] neg_hi:[0,1]
	v_mov_b32_e32 v47, v52
	v_sub_f32_e32 v49, v50, v54
	v_pk_add_f32 v[46:47], v[46:47], v[54:55] neg_lo:[0,1] neg_hi:[0,1]
	v_sub_f32_e32 v49, v56, v49
	v_add_f32_e32 v46, v46, v49
	v_add_f32_e32 v46, v46, v47
	v_add_f32_e32 v46, v48, v46
	v_cndmask_b32_e32 v46, v237, v46, vcc
	v_cmp_ngt_f32_e32 vcc, -1.0, v42
	s_nop 1
	v_cndmask_b32_e32 v46, v238, v46, vcc
	v_cmp_neq_f32_e32 vcc, -1.0, v42
	s_nop 1
	v_cndmask_b32_e32 v46, v239, v46, vcc
	v_cmp_lt_f32_e64 vcc, |v42|, s27
	s_nop 1
	v_cndmask_b32_e32 v42, v46, v42, vcc
	v_sub_f32_e32 v42, v0, v42

.LBB0_1018:
	s_or_b64 exec, exec, s[4:5]
	v_lshlrev_b32_e32 v48, 2, v61
	v_lshlrev_b32_e32 v0, 2, v62
	v_ashrrev_i32_e32 v49, 31, v48
	v_lshl_add_u64 v[46:47], s[84:85], 0, v[0:1]
	v_lshlrev_b64 v[50:51], 13, v[48:49]
	v_lshl_add_u64 v[50:51], v[46:47], 0, v[50:51]
	v_readlane_b32 s4, v254, 26
	global_store_dword v[50:51], v42, off
	v_readlane_b32 s5, v254, 27
	s_nop 4
	s_load_dword s4, s[4:5], 0x4
	s_waitcnt lgkmcnt(0)
	v_mov_b32_e32 v0, s4
	v_add_f32_e32 v0, v43, v0
	v_cmp_nlt_f32_e32 vcc, 0, v0
	s_and_saveexec_b64 s[4:5], vcc
	s_xor_b64 s[4:5], exec, s[4:5]
	s_cbranch_execz .LBB0_1020
	v_mul_f32_e32 v42, 0x3fb8aa3b, v0
	v_exp_f32_e32 v49, v42
	s_mov_b32 s27, 0x3f2aaaab
	v_add_f32_e32 v50, 1.0, v49
	v_frexp_mant_f32_e32 v52, v50
	v_cvt_f64_f32_e32 v[42:43], v50
	v_frexp_exp_i32_f64_e32 v42, v[42:43]
	v_cmp_gt_f32_e32 vcc, s27, v52
	v_add_f32_e32 v51, -1.0, v50
	v_sub_f32_e32 v53, v51, v50
	v_subbrev_co_u32_e32 v56, vcc, 0, v42, vcc
	v_sub_u32_e32 v42, 0, v56
	v_sub_f32_e32 v51, v49, v51
	v_add_f32_e32 v53, 1.0, v53
	v_ldexp_f32 v43, v50, v42
	v_add_f32_e32 v51, v51, v53
	v_add_f32_e32 v50, -1.0, v43
	v_add_f32_e32 v52, 1.0, v43
	v_ldexp_f32 v42, v51, v42
	v_add_f32_e32 v51, 1.0, v50
	v_add_f32_e32 v53, -1.0, v52
	v_sub_f32_e32 v51, v43, v51
	v_sub_f32_e32 v43, v43, v53
	v_add_f32_e32 v51, v42, v51
	v_add_f32_e32 v42, v42, v43
	v_add_f32_e32 v57, v52, v42
	v_rcp_f32_e32 v59, v57
	v_sub_f32_e32 v43, v57, v52
	v_sub_f32_e32 v58, v42, v43
	v_add_f32_e32 v43, v50, v51
	v_mul_f32_e32 v61, v43, v59
	v_sub_f32_e32 v42, v43, v50
	v_mul_f32_e32 v50, v57, v61
	v_fma_f32 v52, v61, v57, -v50
	v_fmac_f32_e32 v52, v61, v58
	v_sub_f32_e32 v60, v51, v42
	v_add_f32_e32 v42, v50, v52
	v_sub_f32_e32 v51, v43, v42
	v_pk_add_f32 v[54:55], v[42:43], v[50:51] neg_lo:[0,1] neg_hi:[0,1]
	v_mov_b32_e32 v53, v42
	v_pk_add_f32 v[42:43], v[54:55], v[52:53] neg_lo:[0,1] neg_hi:[0,1]
	s_mov_b32 s27, 0x3f317218
	v_add_f32_e32 v43, v60, v43
	v_add_f32_e32 v42, v42, v43
	v_add_f32_e32 v43, v51, v42
	v_mul_f32_e32 v60, v59, v43
	v_mul_f32_e32 v50, v57, v60
	v_fma_f32 v52, v60, v57, -v50
	v_fmac_f32_e32 v52, v60, v58
	v_sub_f32_e32 v51, v51, v43
	v_add_f32_e32 v57, v42, v51
	v_add_f32_e32 v42, v50, v52
	v_sub_f32_e32 v51, v43, v42
	v_pk_add_f32 v[54:55], v[42:43], v[50:51] neg_lo:[0,1] neg_hi:[0,1]
	v_mov_b32_e32 v53, v42
	v_pk_add_f32 v[42:43], v[54:55], v[52:53] neg_lo:[0,1] neg_hi:[0,1]
	s_nop 0
	v_add_f32_e32 v43, v57, v43
	v_add_f32_e32 v42, v42, v43
	v_add_f32_e32 v43, v61, v60
	v_add_f32_e32 v42, v51, v42
	v_sub_f32_e32 v50, v43, v61
	v_mul_f32_e32 v42, v59, v42
	v_sub_f32_e32 v50, v60, v50
	v_add_f32_e32 v50, v50, v42
	v_add_f32_e32 v52, v43, v50
	v_mul_f32_e32 v53, v52, v52
	v_fmamk_f32 v42, v53, 0x3e9b6dac, v236
	v_fmaak_f32 v205, v53, v42, 0x3f2aaada
	v_cvt_f32_i32_e32 v42, v56
	v_sub_f32_e32 v43, v52, v43
	v_sub_f32_e32 v43, v50, v43
	v_ldexp_f32 v54, v43, 1
	v_mul_f32_e32 v43, v52, v53
	v_ldexp_f32 v51, v52, 1
	v_pk_mul_f32 v[52:53], v[42:43], v[204:205]
	s_nop 0
	v_fma_f32 v50, v42, s27, -v52
	v_fmac_f32_e32 v50, 0xb102e308, v42
	v_pk_add_f32 v[42:43], v[52:53], v[50:51]
	s_mov_b32 s27, 0x7f800000
	v_sub_f32_e32 v51, v43, v51
	v_sub_f32_e32 v51, v53, v51
	v_add_f32_e32 v55, v54, v51
	v_mov_b32_e32 v54, v52
	v_pk_add_f32 v[52:53], v[42:43], v[52:53] neg_lo:[0,1] neg_hi:[0,1]
	v_pk_add_f32 v[56:57], v[42:43], v[54:55]
	v_mov_b32_e32 v51, v42
	v_mov_b32_e32 v53, v57
	v_pk_add_f32 v[58:59], v[50:51], v[52:53] neg_lo:[0,1] neg_hi:[0,1]
	v_pk_add_f32 v[50:51], v[50:51], v[52:53]
	v_mov_b32_e32 v54, v55
	v_pk_add_f32 v[52:53], v[50:51], v[42:43] op_sel:[1,0] op_sel_hi:[0,1] neg_lo:[0,1] neg_hi:[0,1]
	v_pk_add_f32 v[60:61], v[56:57], v[52:53] op_sel_hi:[1,0] neg_lo:[0,1] neg_hi:[0,1]
	v_mov_b32_e32 v56, v57
	v_mov_b32_e32 v57, v51
	v_pk_mov_b32 v[52:53], v[42:43], v[52:53] op_sel:[1,0]
	v_mov_b32_e32 v55, v42
	v_pk_add_f32 v[52:53], v[56:57], v[52:53] neg_lo:[0,1] neg_hi:[0,1]
	v_mov_b32_e32 v60, v58
	v_pk_add_f32 v[42:43], v[54:55], v[52:53] neg_lo:[0,1] neg_hi:[0,1]
	v_mov_b32_e32 v59, v51
	v_pk_add_f32 v[52:53], v[60:61], v[42:43]
	v_cmp_neq_f32_e32 vcc, s27, v49
	v_pk_add_f32 v[54:55], v[52:53], v[52:53] op_sel:[0,1] op_sel_hi:[1,0]
	s_mov_b32 s27, 0x33800000
	v_pk_add_f32 v[50:51], v[50:51], v[54:55] op_sel:[1,0] op_sel_hi:[0,1]
	v_mov_b32_e32 v53, v50
	v_pk_add_f32 v[56:57], v[52:53], v[58:59] neg_lo:[0,1] neg_hi:[0,1]
	v_mov_b32_e32 v43, v54
	v_sub_f32_e32 v51, v52, v56
	v_pk_add_f32 v[42:43], v[42:43], v[56:57] neg_lo:[0,1] neg_hi:[0,1]
	v_sub_f32_e32 v51, v58, v51
	v_add_f32_e32 v42, v42, v51
	v_add_f32_e32 v42, v42, v43
	v_add_f32_e32 v42, v50, v42
	v_cndmask_b32_e32 v42, v237, v42, vcc
	v_cmp_ngt_f32_e32 vcc, -1.0, v49
	s_nop 1
	v_cndmask_b32_e32 v42, v238, v42, vcc
	v_cmp_neq_f32_e32 vcc, -1.0, v49
	s_nop 1
	v_cndmask_b32_e32 v42, v239, v42, vcc
	v_cmp_lt_f32_e64 vcc, |v49|, s27
	s_nop 1
	v_cndmask_b32_e32 v42, v42, v49, vcc
	v_sub_f32_e32 v42, v0, v42

.LBB0_1022:
	s_or_b64 exec, exec, s[4:5]
	v_or_b32_e32 v50, 1, v48
	v_ashrrev_i32_e32 v51, 31, v50
	v_lshlrev_b64 v[50:51], 13, v[50:51]
	v_lshl_add_u64 v[50:51], v[46:47], 0, v[50:51]
	v_readlane_b32 s4, v254, 26
	global_store_dword v[50:51], v42, off
	v_readlane_b32 s5, v254, 27
	s_nop 4
	s_load_dword s4, s[4:5], 0x8
	s_waitcnt lgkmcnt(0)
	v_mov_b32_e32 v0, s4
	v_add_f32_e32 v0, v44, v0
	v_cmp_nlt_f32_e32 vcc, 0, v0
	s_and_saveexec_b64 s[4:5], vcc
	s_xor_b64 s[4:5], exec, s[4:5]
	s_cbranch_execz .LBB0_1024
	v_mul_f32_e32 v42, 0x3fb8aa3b, v0
	v_exp_f32_e32 v44, v42
	s_mov_b32 s27, 0x3f2aaaab
	v_add_f32_e32 v49, 1.0, v44
	v_frexp_mant_f32_e32 v51, v49
	v_cvt_f64_f32_e32 v[42:43], v49
	v_frexp_exp_i32_f64_e32 v42, v[42:43]
	v_cmp_gt_f32_e32 vcc, s27, v51
	v_add_f32_e32 v50, -1.0, v49
	v_sub_f32_e32 v52, v50, v49
	v_subbrev_co_u32_e32 v56, vcc, 0, v42, vcc
	v_sub_u32_e32 v42, 0, v56
	v_sub_f32_e32 v50, v44, v50
	v_add_f32_e32 v52, 1.0, v52
	v_ldexp_f32 v43, v49, v42
	v_add_f32_e32 v50, v50, v52
	v_add_f32_e32 v49, -1.0, v43
	v_add_f32_e32 v51, 1.0, v43
	v_ldexp_f32 v42, v50, v42
	v_add_f32_e32 v50, 1.0, v49
	v_add_f32_e32 v52, -1.0, v51
	v_sub_f32_e32 v50, v43, v50
	v_sub_f32_e32 v43, v43, v52
	v_add_f32_e32 v50, v42, v50
	v_add_f32_e32 v42, v42, v43
	v_add_f32_e32 v57, v51, v42
	v_rcp_f32_e32 v59, v57
	v_sub_f32_e32 v43, v57, v51
	v_sub_f32_e32 v58, v42, v43
	v_add_f32_e32 v43, v49, v50
	v_sub_f32_e32 v42, v43, v49
	v_mul_f32_e32 v60, v43, v59
	v_sub_f32_e32 v49, v50, v42
	v_mul_f32_e32 v50, v57, v60
	v_fma_f32 v52, v60, v57, -v50
	v_fmac_f32_e32 v52, v60, v58
	v_add_f32_e32 v42, v50, v52
	v_sub_f32_e32 v51, v43, v42
	v_pk_add_f32 v[54:55], v[42:43], v[50:51] neg_lo:[0,1] neg_hi:[0,1]
	v_mov_b32_e32 v53, v42
	v_pk_add_f32 v[42:43], v[54:55], v[52:53] neg_lo:[0,1] neg_hi:[0,1]
	s_mov_b32 s27, 0x3f317218
	v_add_f32_e32 v43, v49, v43
	v_add_f32_e32 v42, v42, v43
	v_add_f32_e32 v43, v51, v42
	v_mul_f32_e32 v49, v59, v43
	v_mul_f32_e32 v50, v57, v49
	v_fma_f32 v52, v49, v57, -v50
	v_fmac_f32_e32 v52, v49, v58
	v_sub_f32_e32 v51, v51, v43
	v_add_f32_e32 v57, v42, v51
	v_add_f32_e32 v42, v50, v52
	v_sub_f32_e32 v51, v43, v42
	v_pk_add_f32 v[54:55], v[42:43], v[50:51] neg_lo:[0,1] neg_hi:[0,1]
	v_mov_b32_e32 v53, v42
	v_pk_add_f32 v[42:43], v[54:55], v[52:53] neg_lo:[0,1] neg_hi:[0,1]
	s_nop 0
	v_add_f32_e32 v43, v57, v43
	v_add_f32_e32 v42, v42, v43
	v_add_f32_e32 v43, v60, v49
	v_add_f32_e32 v42, v51, v42
	v_sub_f32_e32 v50, v43, v60
	v_mul_f32_e32 v42, v59, v42
	v_sub_f32_e32 v49, v49, v50
	v_add_f32_e32 v49, v49, v42
	v_add_f32_e32 v50, v43, v49
	v_mul_f32_e32 v52, v50, v50
	v_fmamk_f32 v42, v52, 0x3e9b6dac, v236
	v_fmaak_f32 v205, v52, v42, 0x3f2aaada
	v_cvt_f32_i32_e32 v42, v56
	v_sub_f32_e32 v43, v50, v43
	v_sub_f32_e32 v43, v49, v43
	v_ldexp_f32 v49, v43, 1
	v_mul_f32_e32 v43, v50, v52
	v_pk_mul_f32 v[52:53], v[42:43], v[204:205]
	v_ldexp_f32 v51, v50, 1
	v_fma_f32 v50, v42, s27, -v52
	v_fmac_f32_e32 v50, 0xb102e308, v42
	v_pk_add_f32 v[42:43], v[52:53], v[50:51]
	v_mov_b32_e32 v54, v52
	v_sub_f32_e32 v51, v43, v51
	v_sub_f32_e32 v51, v53, v51
	v_add_f32_e32 v55, v49, v51
	v_pk_add_f32 v[52:53], v[42:43], v[52:53] neg_lo:[0,1] neg_hi:[0,1]
	v_pk_add_f32 v[56:57], v[42:43], v[54:55]
	v_mov_b32_e32 v51, v42
	v_mov_b32_e32 v53, v57
	v_pk_add_f32 v[58:59], v[50:51], v[52:53] neg_lo:[0,1] neg_hi:[0,1]
	v_pk_add_f32 v[50:51], v[50:51], v[52:53]
	v_mov_b32_e32 v54, v55
	v_pk_add_f32 v[52:53], v[50:51], v[42:43] op_sel:[1,0] op_sel_hi:[0,1] neg_lo:[0,1] neg_hi:[0,1]
	v_pk_add_f32 v[60:61], v[56:57], v[52:53] op_sel_hi:[1,0] neg_lo:[0,1] neg_hi:[0,1]
	v_mov_b32_e32 v56, v57
	v_mov_b32_e32 v57, v51
	v_pk_mov_b32 v[52:53], v[42:43], v[52:53] op_sel:[1,0]
	v_mov_b32_e32 v55, v42
	v_pk_add_f32 v[52:53], v[56:57], v[52:53] neg_lo:[0,1] neg_hi:[0,1]
	v_mov_b32_e32 v60, v58
	v_pk_add_f32 v[42:43], v[54:55], v[52:53] neg_lo:[0,1] neg_hi:[0,1]
	v_mov_b32_e32 v59, v51
	v_pk_add_f32 v[52:53], v[60:61], v[42:43]
	s_mov_b32 s27, 0x7f800000
	v_pk_add_f32 v[54:55], v[52:53], v[52:53] op_sel:[0,1] op_sel_hi:[1,0]
	v_cmp_neq_f32_e32 vcc, s27, v44
	v_pk_add_f32 v[50:51], v[50:51], v[54:55] op_sel:[1,0] op_sel_hi:[0,1]
	v_mov_b32_e32 v53, v50
	v_pk_add_f32 v[56:57], v[52:53], v[58:59] neg_lo:[0,1] neg_hi:[0,1]
	v_mov_b32_e32 v43, v54
	v_sub_f32_e32 v49, v52, v56
	v_pk_add_f32 v[42:43], v[42:43], v[56:57] neg_lo:[0,1] neg_hi:[0,1]
	v_sub_f32_e32 v49, v58, v49
	v_add_f32_e32 v42, v42, v49
	v_add_f32_e32 v42, v42, v43
	v_add_f32_e32 v42, v50, v42
	v_cndmask_b32_e32 v42, v237, v42, vcc
	v_cmp_ngt_f32_e32 vcc, -1.0, v44
	s_mov_b32 s27, 0x33800000
	s_nop 0
	v_cndmask_b32_e32 v42, v238, v42, vcc
	v_cmp_neq_f32_e32 vcc, -1.0, v44
	s_nop 1
	v_cndmask_b32_e32 v42, v239, v42, vcc
	v_cmp_lt_f32_e64 vcc, |v44|, s27
	s_nop 1
	v_cndmask_b32_e32 v42, v42, v44, vcc
	v_sub_f32_e32 v42, v0, v42

.LBB0_1026:
	s_or_b64 exec, exec, s[4:5]
	v_or_b32_e32 v50, 2, v48
	v_ashrrev_i32_e32 v51, 31, v50
	v_lshlrev_b64 v[50:51], 13, v[50:51]
	v_lshl_add_u64 v[50:51], v[46:47], 0, v[50:51]
	v_readlane_b32 s4, v254, 26
	global_store_dword v[50:51], v42, off
	v_readlane_b32 s5, v254, 27
	s_nop 4
	s_load_dword s4, s[4:5], 0xc
	s_waitcnt lgkmcnt(0)
	v_mov_b32_e32 v0, s4
	v_add_f32_e32 v0, v45, v0
	v_cmp_nlt_f32_e32 vcc, 0, v0
	s_and_saveexec_b64 s[4:5], vcc
	s_xor_b64 s[4:5], exec, s[4:5]
	s_cbranch_execz .LBB0_1028
	v_mul_f32_e32 v42, 0x3fb8aa3b, v0
	v_exp_f32_e32 v49, v42
	s_mov_b32 s27, 0x3f2aaaab
	v_add_f32_e32 v44, 1.0, v49
	v_frexp_mant_f32_e32 v50, v44
	v_cvt_f64_f32_e32 v[42:43], v44
	v_frexp_exp_i32_f64_e32 v42, v[42:43]
	v_cmp_gt_f32_e32 vcc, s27, v50
	v_add_f32_e32 v45, -1.0, v44
	v_sub_f32_e32 v51, v45, v44
	v_subbrev_co_u32_e32 v54, vcc, 0, v42, vcc
	v_sub_u32_e32 v42, 0, v54
	v_sub_f32_e32 v45, v49, v45
	v_add_f32_e32 v51, 1.0, v51
	v_ldexp_f32 v43, v44, v42
	v_add_f32_e32 v45, v45, v51
	v_add_f32_e32 v44, -1.0, v43
	v_add_f32_e32 v50, 1.0, v43
	v_ldexp_f32 v42, v45, v42
	v_add_f32_e32 v45, 1.0, v44
	v_add_f32_e32 v51, -1.0, v50
	v_sub_f32_e32 v45, v43, v45
	v_sub_f32_e32 v43, v43, v51
	v_add_f32_e32 v45, v42, v45
	v_add_f32_e32 v42, v42, v43
	v_add_f32_e32 v55, v50, v42
	v_rcp_f32_e32 v57, v55
	v_sub_f32_e32 v43, v55, v50
	v_sub_f32_e32 v56, v42, v43
	v_add_f32_e32 v43, v44, v45
	v_mul_f32_e32 v59, v43, v57
	v_sub_f32_e32 v42, v43, v44
	v_mul_f32_e32 v44, v55, v59
	v_fma_f32 v50, v59, v55, -v44
	v_fmac_f32_e32 v50, v59, v56
	v_sub_f32_e32 v58, v45, v42
	v_add_f32_e32 v42, v44, v50
	v_sub_f32_e32 v45, v43, v42
	v_pk_add_f32 v[52:53], v[42:43], v[44:45] neg_lo:[0,1] neg_hi:[0,1]
	v_mov_b32_e32 v51, v42
	v_pk_add_f32 v[42:43], v[52:53], v[50:51] neg_lo:[0,1] neg_hi:[0,1]
	s_mov_b32 s27, 0x3f317218
	v_add_f32_e32 v43, v58, v43
	v_add_f32_e32 v42, v42, v43
	v_add_f32_e32 v43, v45, v42
	v_mul_f32_e32 v58, v57, v43
	v_mul_f32_e32 v44, v55, v58
	v_fma_f32 v50, v58, v55, -v44
	v_fmac_f32_e32 v50, v58, v56
	v_sub_f32_e32 v45, v45, v43
	v_add_f32_e32 v55, v42, v45
	v_add_f32_e32 v42, v44, v50
	v_sub_f32_e32 v45, v43, v42
	v_pk_add_f32 v[52:53], v[42:43], v[44:45] neg_lo:[0,1] neg_hi:[0,1]
	v_mov_b32_e32 v51, v42
	v_pk_add_f32 v[42:43], v[52:53], v[50:51] neg_lo:[0,1] neg_hi:[0,1]
	s_nop 0
	v_add_f32_e32 v43, v55, v43
	v_add_f32_e32 v42, v42, v43
	v_add_f32_e32 v43, v59, v58
	v_add_f32_e32 v42, v45, v42
	v_sub_f32_e32 v44, v43, v59
	v_mul_f32_e32 v42, v57, v42
	v_sub_f32_e32 v44, v58, v44
	v_add_f32_e32 v44, v44, v42
	v_add_f32_e32 v50, v43, v44
	v_mul_f32_e32 v51, v50, v50
	v_fmamk_f32 v42, v51, 0x3e9b6dac, v236
	v_fmaak_f32 v205, v51, v42, 0x3f2aaada
	v_cvt_f32_i32_e32 v42, v54
	v_sub_f32_e32 v43, v50, v43
	v_sub_f32_e32 v43, v44, v43
	v_ldexp_f32 v52, v43, 1
	v_mul_f32_e32 v43, v50, v51
	v_ldexp_f32 v45, v50, 1
	v_pk_mul_f32 v[50:51], v[42:43], v[204:205]
	s_nop 0
	v_fma_f32 v44, v42, s27, -v50
	v_fmac_f32_e32 v44, 0xb102e308, v42
	v_pk_add_f32 v[42:43], v[50:51], v[44:45]
	s_mov_b32 s27, 0x7f800000
	v_sub_f32_e32 v45, v43, v45
	v_sub_f32_e32 v45, v51, v45
	v_add_f32_e32 v53, v52, v45
	v_mov_b32_e32 v52, v50
	v_pk_add_f32 v[50:51], v[42:43], v[50:51] neg_lo:[0,1] neg_hi:[0,1]
	v_pk_add_f32 v[54:55], v[42:43], v[52:53]
	v_mov_b32_e32 v45, v42
	v_mov_b32_e32 v51, v55
	v_pk_add_f32 v[56:57], v[44:45], v[50:51] neg_lo:[0,1] neg_hi:[0,1]
	v_pk_add_f32 v[44:45], v[44:45], v[50:51]
	v_mov_b32_e32 v52, v53
	v_pk_add_f32 v[50:51], v[44:45], v[42:43] op_sel:[1,0] op_sel_hi:[0,1] neg_lo:[0,1] neg_hi:[0,1]
	v_pk_add_f32 v[58:59], v[54:55], v[50:51] op_sel_hi:[1,0] neg_lo:[0,1] neg_hi:[0,1]
	v_mov_b32_e32 v54, v55
	v_mov_b32_e32 v55, v45
	v_pk_mov_b32 v[50:51], v[42:43], v[50:51] op_sel:[1,0]
	v_mov_b32_e32 v53, v42
	v_pk_add_f32 v[50:51], v[54:55], v[50:51] neg_lo:[0,1] neg_hi:[0,1]
	v_mov_b32_e32 v58, v56
	v_pk_add_f32 v[42:43], v[52:53], v[50:51] neg_lo:[0,1] neg_hi:[0,1]
	v_mov_b32_e32 v57, v45
	v_pk_add_f32 v[50:51], v[58:59], v[42:43]
	v_cmp_neq_f32_e32 vcc, s27, v49
	v_pk_add_f32 v[52:53], v[50:51], v[50:51] op_sel:[0,1] op_sel_hi:[1,0]
	s_mov_b32 s27, 0x33800000
	v_pk_add_f32 v[44:45], v[44:45], v[52:53] op_sel:[1,0] op_sel_hi:[0,1]
	v_mov_b32_e32 v51, v44
	v_pk_add_f32 v[54:55], v[50:51], v[56:57] neg_lo:[0,1] neg_hi:[0,1]
	v_mov_b32_e32 v43, v52
	v_sub_f32_e32 v45, v50, v54
	v_pk_add_f32 v[42:43], v[42:43], v[54:55] neg_lo:[0,1] neg_hi:[0,1]
	v_sub_f32_e32 v45, v56, v45
	v_add_f32_e32 v42, v42, v45
	v_add_f32_e32 v42, v42, v43
	v_add_f32_e32 v42, v44, v42
	v_cndmask_b32_e32 v42, v237, v42, vcc
	v_cmp_ngt_f32_e32 vcc, -1.0, v49
	s_nop 1
	v_cndmask_b32_e32 v42, v238, v42, vcc
	v_cmp_neq_f32_e32 vcc, -1.0, v49
	s_nop 1
	v_cndmask_b32_e32 v42, v239, v42, vcc
	v_cmp_lt_f32_e64 vcc, |v49|, s27
	s_nop 1
	v_cndmask_b32_e32 v42, v42, v49, vcc
	v_sub_f32_e32 v42, v0, v42

.LBB0_1054:
	s_and_saveexec_b64 s[4:5], s[10:11]
	s_xor_b64 s[42:43], exec, s[4:5]
	s_cbranch_execz .LBB0_1072
	v_readlane_b32 s4, v254, 26
	v_readlane_b32 s5, v254, 27
	s_nop 4
	s_load_dword s4, s[4:5], 0x0
	s_waitcnt lgkmcnt(0)
	v_mov_b32_e32 v0, s4
	v_add_f32_e32 v0, v34, v0
	v_cmp_nlt_f32_e32 vcc, 0, v0
	s_and_saveexec_b64 s[4:5], vcc
	s_xor_b64 s[4:5], exec, s[4:5]
	s_cbranch_execz .LBB0_1057
	v_mul_f32_e32 v34, 0x3fb8aa3b, v0
	v_exp_f32_e32 v34, v34
	s_mov_b32 s27, 0x3f2aaaab
	v_add_f32_e32 v40, 1.0, v34
	v_frexp_mant_f32_e32 v42, v40
	v_cvt_f64_f32_e32 v[38:39], v40
	v_frexp_exp_i32_f64_e32 v38, v[38:39]
	v_cmp_gt_f32_e32 vcc, s27, v42
	v_add_f32_e32 v41, -1.0, v40
	v_sub_f32_e32 v43, v41, v40
	v_subbrev_co_u32_e32 v46, vcc, 0, v38, vcc
	v_sub_u32_e32 v38, 0, v46
	v_sub_f32_e32 v41, v34, v41
	v_add_f32_e32 v43, 1.0, v43
	v_ldexp_f32 v39, v40, v38
	v_add_f32_e32 v41, v41, v43
	v_add_f32_e32 v40, -1.0, v39
	v_add_f32_e32 v42, 1.0, v39
	v_ldexp_f32 v38, v41, v38
	v_add_f32_e32 v41, 1.0, v40
	v_add_f32_e32 v43, -1.0, v42
	v_sub_f32_e32 v41, v39, v41
	v_sub_f32_e32 v39, v39, v43
	v_add_f32_e32 v41, v38, v41
	v_add_f32_e32 v38, v38, v39
	v_add_f32_e32 v47, v42, v38
	v_rcp_f32_e32 v49, v47
	v_sub_f32_e32 v39, v47, v42
	v_sub_f32_e32 v48, v38, v39
	v_add_f32_e32 v39, v40, v41
	v_mul_f32_e32 v51, v39, v49
	v_sub_f32_e32 v38, v39, v40
	v_mul_f32_e32 v40, v47, v51
	v_fma_f32 v42, v51, v47, -v40
	v_fmac_f32_e32 v42, v51, v48
	v_sub_f32_e32 v50, v41, v38
	v_add_f32_e32 v38, v40, v42
	v_sub_f32_e32 v41, v39, v38
	v_pk_add_f32 v[44:45], v[38:39], v[40:41] neg_lo:[0,1] neg_hi:[0,1]
	v_mov_b32_e32 v43, v38
	v_pk_add_f32 v[38:39], v[44:45], v[42:43] neg_lo:[0,1] neg_hi:[0,1]
	s_mov_b32 s27, 0x3f317218
	v_add_f32_e32 v39, v50, v39
	v_add_f32_e32 v38, v38, v39
	v_add_f32_e32 v39, v41, v38
	v_mul_f32_e32 v50, v49, v39
	v_mul_f32_e32 v40, v47, v50
	v_fma_f32 v42, v50, v47, -v40
	v_fmac_f32_e32 v42, v50, v48
	v_sub_f32_e32 v41, v41, v39
	v_add_f32_e32 v47, v38, v41
	v_add_f32_e32 v38, v40, v42
	v_sub_f32_e32 v41, v39, v38
	v_pk_add_f32 v[44:45], v[38:39], v[40:41] neg_lo:[0,1] neg_hi:[0,1]
	v_mov_b32_e32 v43, v38
	v_pk_add_f32 v[38:39], v[44:45], v[42:43] neg_lo:[0,1] neg_hi:[0,1]
	s_nop 0
	v_add_f32_e32 v39, v47, v39
	v_add_f32_e32 v38, v38, v39
	v_add_f32_e32 v39, v51, v50
	v_add_f32_e32 v38, v41, v38
	v_sub_f32_e32 v40, v39, v51
	v_mul_f32_e32 v38, v49, v38
	v_sub_f32_e32 v40, v50, v40
	v_add_f32_e32 v40, v40, v38
	v_add_f32_e32 v42, v39, v40
	v_mul_f32_e32 v43, v42, v42
	v_fmamk_f32 v38, v43, 0x3e9b6dac, v236
	v_fmaak_f32 v205, v43, v38, 0x3f2aaada
	v_cvt_f32_i32_e32 v38, v46
	v_sub_f32_e32 v39, v42, v39
	v_sub_f32_e32 v39, v40, v39
	v_ldexp_f32 v44, v39, 1
	v_mul_f32_e32 v39, v42, v43
	v_ldexp_f32 v41, v42, 1
	v_pk_mul_f32 v[42:43], v[38:39], v[204:205]
	s_nop 0
	v_fma_f32 v40, v38, s27, -v42
	v_fmac_f32_e32 v40, 0xb102e308, v38
	v_pk_add_f32 v[38:39], v[42:43], v[40:41]
	s_mov_b32 s27, 0x7f800000
	v_sub_f32_e32 v41, v39, v41
	v_sub_f32_e32 v41, v43, v41
	v_add_f32_e32 v45, v44, v41
	v_mov_b32_e32 v44, v42
	v_pk_add_f32 v[42:43], v[38:39], v[42:43] neg_lo:[0,1] neg_hi:[0,1]
	v_pk_add_f32 v[46:47], v[38:39], v[44:45]
	v_mov_b32_e32 v41, v38
	v_mov_b32_e32 v43, v47
	v_pk_add_f32 v[48:49], v[40:41], v[42:43] neg_lo:[0,1] neg_hi:[0,1]
	v_pk_add_f32 v[40:41], v[40:41], v[42:43]
	v_mov_b32_e32 v44, v45
	v_pk_add_f32 v[42:43], v[40:41], v[38:39] op_sel:[1,0] op_sel_hi:[0,1] neg_lo:[0,1] neg_hi:[0,1]
	v_pk_add_f32 v[50:51], v[46:47], v[42:43] op_sel_hi:[1,0] neg_lo:[0,1] neg_hi:[0,1]
	v_mov_b32_e32 v46, v47
	v_mov_b32_e32 v47, v41
	v_pk_mov_b32 v[42:43], v[38:39], v[42:43] op_sel:[1,0]
	v_mov_b32_e32 v45, v38
	v_pk_add_f32 v[42:43], v[46:47], v[42:43] neg_lo:[0,1] neg_hi:[0,1]
	v_mov_b32_e32 v50, v48
	v_pk_add_f32 v[38:39], v[44:45], v[42:43] neg_lo:[0,1] neg_hi:[0,1]
	v_mov_b32_e32 v49, v41
	v_pk_add_f32 v[42:43], v[50:51], v[38:39]
	v_cmp_neq_f32_e32 vcc, s27, v34
	v_pk_add_f32 v[44:45], v[42:43], v[42:43] op_sel:[0,1] op_sel_hi:[1,0]
	s_mov_b32 s27, 0x33800000
	v_pk_add_f32 v[40:41], v[40:41], v[44:45] op_sel:[1,0] op_sel_hi:[0,1]
	v_mov_b32_e32 v43, v40
	v_pk_add_f32 v[46:47], v[42:43], v[48:49] neg_lo:[0,1] neg_hi:[0,1]
	v_mov_b32_e32 v39, v44
	v_sub_f32_e32 v41, v42, v46
	v_pk_add_f32 v[38:39], v[38:39], v[46:47] neg_lo:[0,1] neg_hi:[0,1]
	v_sub_f32_e32 v41, v48, v41
	v_add_f32_e32 v38, v38, v41
	v_add_f32_e32 v38, v38, v39
	v_add_f32_e32 v38, v40, v38
	v_cndmask_b32_e32 v38, v237, v38, vcc
	v_cmp_ngt_f32_e32 vcc, -1.0, v34
	s_nop 1
	v_cndmask_b32_e32 v38, v238, v38, vcc
	v_cmp_neq_f32_e32 vcc, -1.0, v34
	s_nop 1
	v_cndmask_b32_e32 v38, v239, v38, vcc
	v_cmp_lt_f32_e64 vcc, |v34|, s27
	s_nop 1
	v_cndmask_b32_e32 v34, v38, v34, vcc
	v_sub_f32_e32 v34, v0, v34

.LBB0_1059:
	s_or_b64 exec, exec, s[4:5]
	v_lshlrev_b32_e32 v40, 2, v53
	v_lshlrev_b32_e32 v0, 2, v54
	v_ashrrev_i32_e32 v41, 31, v40
	v_lshl_add_u64 v[38:39], s[84:85], 0, v[0:1]
	v_lshlrev_b64 v[42:43], 13, v[40:41]
	v_lshl_add_u64 v[42:43], v[38:39], 0, v[42:43]
	v_readlane_b32 s4, v254, 26
	global_store_dword v[42:43], v34, off
	v_readlane_b32 s5, v254, 27
	s_nop 4
	s_load_dword s4, s[4:5], 0x4
	s_waitcnt lgkmcnt(0)
	v_mov_b32_e32 v0, s4
	v_add_f32_e32 v0, v35, v0
	v_cmp_nlt_f32_e32 vcc, 0, v0
	s_and_saveexec_b64 s[4:5], vcc
	s_xor_b64 s[4:5], exec, s[4:5]
	s_cbranch_execz .LBB0_1061
	v_mul_f32_e32 v34, 0x3fb8aa3b, v0
	v_exp_f32_e32 v41, v34
	s_mov_b32 s27, 0x3f2aaaab
	v_add_f32_e32 v42, 1.0, v41
	v_frexp_mant_f32_e32 v44, v42
	v_cvt_f64_f32_e32 v[34:35], v42
	v_frexp_exp_i32_f64_e32 v34, v[34:35]
	v_cmp_gt_f32_e32 vcc, s27, v44
	v_add_f32_e32 v43, -1.0, v42
	v_sub_f32_e32 v45, v43, v42
	v_subbrev_co_u32_e32 v48, vcc, 0, v34, vcc
	v_sub_u32_e32 v34, 0, v48
	v_sub_f32_e32 v43, v41, v43
	v_add_f32_e32 v45, 1.0, v45
	v_ldexp_f32 v35, v42, v34
	v_add_f32_e32 v43, v43, v45
	v_add_f32_e32 v42, -1.0, v35
	v_add_f32_e32 v44, 1.0, v35
	v_ldexp_f32 v34, v43, v34
	v_add_f32_e32 v43, 1.0, v42
	v_add_f32_e32 v45, -1.0, v44
	v_sub_f32_e32 v43, v35, v43
	v_sub_f32_e32 v35, v35, v45
	v_add_f32_e32 v43, v34, v43
	v_add_f32_e32 v34, v34, v35
	v_add_f32_e32 v49, v44, v34
	v_rcp_f32_e32 v51, v49
	v_sub_f32_e32 v35, v49, v44
	v_sub_f32_e32 v50, v34, v35
	v_add_f32_e32 v35, v42, v43
	v_mul_f32_e32 v53, v35, v51
	v_sub_f32_e32 v34, v35, v42
	v_mul_f32_e32 v42, v49, v53
	v_fma_f32 v44, v53, v49, -v42
	v_fmac_f32_e32 v44, v53, v50
	v_sub_f32_e32 v52, v43, v34
	v_add_f32_e32 v34, v42, v44
	v_sub_f32_e32 v43, v35, v34
	v_pk_add_f32 v[46:47], v[34:35], v[42:43] neg_lo:[0,1] neg_hi:[0,1]
	v_mov_b32_e32 v45, v34
	v_pk_add_f32 v[34:35], v[46:47], v[44:45] neg_lo:[0,1] neg_hi:[0,1]
	s_mov_b32 s27, 0x3f317218
	v_add_f32_e32 v35, v52, v35
	v_add_f32_e32 v34, v34, v35
	v_add_f32_e32 v35, v43, v34
	v_mul_f32_e32 v52, v51, v35
	v_mul_f32_e32 v42, v49, v52
	v_fma_f32 v44, v52, v49, -v42
	v_fmac_f32_e32 v44, v52, v50
	v_sub_f32_e32 v43, v43, v35
	v_add_f32_e32 v49, v34, v43
	v_add_f32_e32 v34, v42, v44
	v_sub_f32_e32 v43, v35, v34
	v_pk_add_f32 v[46:47], v[34:35], v[42:43] neg_lo:[0,1] neg_hi:[0,1]
	v_mov_b32_e32 v45, v34
	v_pk_add_f32 v[34:35], v[46:47], v[44:45] neg_lo:[0,1] neg_hi:[0,1]
	s_nop 0
	v_add_f32_e32 v35, v49, v35
	v_add_f32_e32 v34, v34, v35
	v_add_f32_e32 v35, v53, v52
	v_add_f32_e32 v34, v43, v34
	v_sub_f32_e32 v42, v35, v53
	v_mul_f32_e32 v34, v51, v34
	v_sub_f32_e32 v42, v52, v42
	v_add_f32_e32 v42, v42, v34
	v_add_f32_e32 v44, v35, v42
	v_mul_f32_e32 v45, v44, v44
	v_fmamk_f32 v34, v45, 0x3e9b6dac, v236
	v_fmaak_f32 v205, v45, v34, 0x3f2aaada
	v_cvt_f32_i32_e32 v34, v48
	v_sub_f32_e32 v35, v44, v35
	v_sub_f32_e32 v35, v42, v35
	v_ldexp_f32 v46, v35, 1
	v_mul_f32_e32 v35, v44, v45
	v_ldexp_f32 v43, v44, 1
	v_pk_mul_f32 v[44:45], v[34:35], v[204:205]
	s_nop 0
	v_fma_f32 v42, v34, s27, -v44
	v_fmac_f32_e32 v42, 0xb102e308, v34
	v_pk_add_f32 v[34:35], v[44:45], v[42:43]
	s_mov_b32 s27, 0x7f800000
	v_sub_f32_e32 v43, v35, v43
	v_sub_f32_e32 v43, v45, v43
	v_add_f32_e32 v47, v46, v43
	v_mov_b32_e32 v46, v44
	v_pk_add_f32 v[44:45], v[34:35], v[44:45] neg_lo:[0,1] neg_hi:[0,1]
	v_pk_add_f32 v[48:49], v[34:35], v[46:47]
	v_mov_b32_e32 v43, v34
	v_mov_b32_e32 v45, v49
	v_pk_add_f32 v[50:51], v[42:43], v[44:45] neg_lo:[0,1] neg_hi:[0,1]
	v_pk_add_f32 v[42:43], v[42:43], v[44:45]
	v_mov_b32_e32 v46, v47
	v_pk_add_f32 v[44:45], v[42:43], v[34:35] op_sel:[1,0] op_sel_hi:[0,1] neg_lo:[0,1] neg_hi:[0,1]
	v_pk_add_f32 v[52:53], v[48:49], v[44:45] op_sel_hi:[1,0] neg_lo:[0,1] neg_hi:[0,1]
	v_mov_b32_e32 v48, v49
	v_mov_b32_e32 v49, v43
	v_pk_mov_b32 v[44:45], v[34:35], v[44:45] op_sel:[1,0]
	v_mov_b32_e32 v47, v34
	v_pk_add_f32 v[44:45], v[48:49], v[44:45] neg_lo:[0,1] neg_hi:[0,1]
	v_mov_b32_e32 v52, v50
	v_pk_add_f32 v[34:35], v[46:47], v[44:45] neg_lo:[0,1] neg_hi:[0,1]
	v_mov_b32_e32 v51, v43
	v_pk_add_f32 v[44:45], v[52:53], v[34:35]
	v_cmp_neq_f32_e32 vcc, s27, v41
	v_pk_add_f32 v[46:47], v[44:45], v[44:45] op_sel:[0,1] op_sel_hi:[1,0]
	s_mov_b32 s27, 0x33800000
	v_pk_add_f32 v[42:43], v[42:43], v[46:47] op_sel:[1,0] op_sel_hi:[0,1]
	v_mov_b32_e32 v45, v42
	v_pk_add_f32 v[48:49], v[44:45], v[50:51] neg_lo:[0,1] neg_hi:[0,1]
	v_mov_b32_e32 v35, v46
	v_sub_f32_e32 v43, v44, v48
	v_pk_add_f32 v[34:35], v[34:35], v[48:49] neg_lo:[0,1] neg_hi:[0,1]
	v_sub_f32_e32 v43, v50, v43
	v_add_f32_e32 v34, v34, v43
	v_add_f32_e32 v34, v34, v35
	v_add_f32_e32 v34, v42, v34
	v_cndmask_b32_e32 v34, v237, v34, vcc
	v_cmp_ngt_f32_e32 vcc, -1.0, v41
	s_nop 1
	v_cndmask_b32_e32 v34, v238, v34, vcc
	v_cmp_neq_f32_e32 vcc, -1.0, v41
	s_nop 1
	v_cndmask_b32_e32 v34, v239, v34, vcc
	v_cmp_lt_f32_e64 vcc, |v41|, s27
	s_nop 1
	v_cndmask_b32_e32 v34, v34, v41, vcc
	v_sub_f32_e32 v34, v0, v34

.LBB0_1063:
	s_or_b64 exec, exec, s[4:5]
	v_or_b32_e32 v42, 1, v40
	v_ashrrev_i32_e32 v43, 31, v42
	v_lshlrev_b64 v[42:43], 13, v[42:43]
	v_lshl_add_u64 v[42:43], v[38:39], 0, v[42:43]
	v_readlane_b32 s4, v254, 26
	global_store_dword v[42:43], v34, off
	v_readlane_b32 s5, v254, 27
	s_nop 4
	s_load_dword s4, s[4:5], 0x8
	s_waitcnt lgkmcnt(0)
	v_mov_b32_e32 v0, s4
	v_add_f32_e32 v0, v36, v0
	v_cmp_nlt_f32_e32 vcc, 0, v0
	s_and_saveexec_b64 s[4:5], vcc
	s_xor_b64 s[4:5], exec, s[4:5]
	s_cbranch_execz .LBB0_1065
	v_mul_f32_e32 v34, 0x3fb8aa3b, v0
	v_exp_f32_e32 v36, v34
	s_mov_b32 s27, 0x3f2aaaab
	v_add_f32_e32 v41, 1.0, v36
	v_frexp_mant_f32_e32 v43, v41
	v_cvt_f64_f32_e32 v[34:35], v41
	v_frexp_exp_i32_f64_e32 v34, v[34:35]
	v_cmp_gt_f32_e32 vcc, s27, v43
	v_add_f32_e32 v42, -1.0, v41
	v_sub_f32_e32 v44, v42, v41
	v_subbrev_co_u32_e32 v48, vcc, 0, v34, vcc
	v_sub_u32_e32 v34, 0, v48
	v_sub_f32_e32 v42, v36, v42
	v_add_f32_e32 v44, 1.0, v44
	v_ldexp_f32 v35, v41, v34
	v_add_f32_e32 v42, v42, v44
	v_add_f32_e32 v41, -1.0, v35
	v_add_f32_e32 v43, 1.0, v35
	v_ldexp_f32 v34, v42, v34
	v_add_f32_e32 v42, 1.0, v41
	v_add_f32_e32 v44, -1.0, v43
	v_sub_f32_e32 v42, v35, v42
	v_sub_f32_e32 v35, v35, v44
	v_add_f32_e32 v42, v34, v42
	v_add_f32_e32 v34, v34, v35
	v_add_f32_e32 v49, v43, v34
	v_rcp_f32_e32 v51, v49
	v_sub_f32_e32 v35, v49, v43
	v_sub_f32_e32 v50, v34, v35
	v_add_f32_e32 v35, v41, v42
	v_sub_f32_e32 v34, v35, v41
	v_mul_f32_e32 v52, v35, v51
	v_sub_f32_e32 v41, v42, v34
	v_mul_f32_e32 v42, v49, v52
	v_fma_f32 v44, v52, v49, -v42
	v_fmac_f32_e32 v44, v52, v50
	v_add_f32_e32 v34, v42, v44
	v_sub_f32_e32 v43, v35, v34
	v_pk_add_f32 v[46:47], v[34:35], v[42:43] neg_lo:[0,1] neg_hi:[0,1]
	v_mov_b32_e32 v45, v34
	v_pk_add_f32 v[34:35], v[46:47], v[44:45] neg_lo:[0,1] neg_hi:[0,1]
	s_mov_b32 s27, 0x3f317218
	v_add_f32_e32 v35, v41, v35
	v_add_f32_e32 v34, v34, v35
	v_add_f32_e32 v35, v43, v34
	v_mul_f32_e32 v41, v51, v35
	v_mul_f32_e32 v42, v49, v41
	v_fma_f32 v44, v41, v49, -v42
	v_fmac_f32_e32 v44, v41, v50
	v_sub_f32_e32 v43, v43, v35
	v_add_f32_e32 v49, v34, v43
	v_add_f32_e32 v34, v42, v44
	v_sub_f32_e32 v43, v35, v34
	v_pk_add_f32 v[46:47], v[34:35], v[42:43] neg_lo:[0,1] neg_hi:[0,1]
	v_mov_b32_e32 v45, v34
	v_pk_add_f32 v[34:35], v[46:47], v[44:45] neg_lo:[0,1] neg_hi:[0,1]
	s_nop 0
	v_add_f32_e32 v35, v49, v35
	v_add_f32_e32 v34, v34, v35
	v_add_f32_e32 v35, v52, v41
	v_add_f32_e32 v34, v43, v34
	v_sub_f32_e32 v42, v35, v52
	v_mul_f32_e32 v34, v51, v34
	v_sub_f32_e32 v41, v41, v42
	v_add_f32_e32 v41, v41, v34
	v_add_f32_e32 v42, v35, v41
	v_mul_f32_e32 v44, v42, v42
	v_fmamk_f32 v34, v44, 0x3e9b6dac, v236
	v_fmaak_f32 v205, v44, v34, 0x3f2aaada
	v_cvt_f32_i32_e32 v34, v48
	v_sub_f32_e32 v35, v42, v35
	v_sub_f32_e32 v35, v41, v35
	v_ldexp_f32 v41, v35, 1
	v_mul_f32_e32 v35, v42, v44
	v_pk_mul_f32 v[44:45], v[34:35], v[204:205]
	v_ldexp_f32 v43, v42, 1
	v_fma_f32 v42, v34, s27, -v44
	v_fmac_f32_e32 v42, 0xb102e308, v34
	v_pk_add_f32 v[34:35], v[44:45], v[42:43]
	v_mov_b32_e32 v46, v44
	v_sub_f32_e32 v43, v35, v43
	v_sub_f32_e32 v43, v45, v43
	v_add_f32_e32 v47, v41, v43
	v_pk_add_f32 v[44:45], v[34:35], v[44:45] neg_lo:[0,1] neg_hi:[0,1]
	v_pk_add_f32 v[48:49], v[34:35], v[46:47]
	v_mov_b32_e32 v43, v34
	v_mov_b32_e32 v45, v49
	v_pk_add_f32 v[50:51], v[42:43], v[44:45] neg_lo:[0,1] neg_hi:[0,1]
	v_pk_add_f32 v[42:43], v[42:43], v[44:45]
	v_mov_b32_e32 v46, v47
	v_pk_add_f32 v[44:45], v[42:43], v[34:35] op_sel:[1,0] op_sel_hi:[0,1] neg_lo:[0,1] neg_hi:[0,1]
	v_pk_add_f32 v[52:53], v[48:49], v[44:45] op_sel_hi:[1,0] neg_lo:[0,1] neg_hi:[0,1]
	v_mov_b32_e32 v48, v49
	v_mov_b32_e32 v49, v43
	v_pk_mov_b32 v[44:45], v[34:35], v[44:45] op_sel:[1,0]
	v_mov_b32_e32 v47, v34
	v_pk_add_f32 v[44:45], v[48:49], v[44:45] neg_lo:[0,1] neg_hi:[0,1]
	v_mov_b32_e32 v52, v50
	v_pk_add_f32 v[34:35], v[46:47], v[44:45] neg_lo:[0,1] neg_hi:[0,1]
	v_mov_b32_e32 v51, v43
	v_pk_add_f32 v[44:45], v[52:53], v[34:35]
	s_mov_b32 s27, 0x7f800000
	v_pk_add_f32 v[46:47], v[44:45], v[44:45] op_sel:[0,1] op_sel_hi:[1,0]
	v_cmp_neq_f32_e32 vcc, s27, v36
	v_pk_add_f32 v[42:43], v[42:43], v[46:47] op_sel:[1,0] op_sel_hi:[0,1]
	v_mov_b32_e32 v45, v42
	v_pk_add_f32 v[48:49], v[44:45], v[50:51] neg_lo:[0,1] neg_hi:[0,1]
	v_mov_b32_e32 v35, v46
	v_sub_f32_e32 v41, v44, v48
	v_pk_add_f32 v[34:35], v[34:35], v[48:49] neg_lo:[0,1] neg_hi:[0,1]
	v_sub_f32_e32 v41, v50, v41
	v_add_f32_e32 v34, v34, v41
	v_add_f32_e32 v34, v34, v35
	v_add_f32_e32 v34, v42, v34
	v_cndmask_b32_e32 v34, v237, v34, vcc
	v_cmp_ngt_f32_e32 vcc, -1.0, v36
	s_mov_b32 s27, 0x33800000
	s_nop 0
	v_cndmask_b32_e32 v34, v238, v34, vcc
	v_cmp_neq_f32_e32 vcc, -1.0, v36
	s_nop 1
	v_cndmask_b32_e32 v34, v239, v34, vcc
	v_cmp_lt_f32_e64 vcc, |v36|, s27
	s_nop 1
	v_cndmask_b32_e32 v34, v34, v36, vcc
	v_sub_f32_e32 v34, v0, v34

.LBB0_1067:
	s_or_b64 exec, exec, s[4:5]
	v_or_b32_e32 v42, 2, v40
	v_ashrrev_i32_e32 v43, 31, v42
	v_lshlrev_b64 v[42:43], 13, v[42:43]
	v_lshl_add_u64 v[42:43], v[38:39], 0, v[42:43]
	v_readlane_b32 s4, v254, 26
	global_store_dword v[42:43], v34, off
	v_readlane_b32 s5, v254, 27
	s_nop 4
	s_load_dword s4, s[4:5], 0xc
	s_waitcnt lgkmcnt(0)
	v_mov_b32_e32 v0, s4
	v_add_f32_e32 v0, v37, v0
	v_cmp_nlt_f32_e32 vcc, 0, v0
	s_and_saveexec_b64 s[4:5], vcc
	s_xor_b64 s[4:5], exec, s[4:5]
	s_cbranch_execz .LBB0_1069
	v_mul_f32_e32 v34, 0x3fb8aa3b, v0
	v_exp_f32_e32 v41, v34
	s_mov_b32 s27, 0x3f2aaaab
	v_add_f32_e32 v36, 1.0, v41
	v_frexp_mant_f32_e32 v42, v36
	v_cvt_f64_f32_e32 v[34:35], v36
	v_frexp_exp_i32_f64_e32 v34, v[34:35]
	v_cmp_gt_f32_e32 vcc, s27, v42
	v_add_f32_e32 v37, -1.0, v36
	v_sub_f32_e32 v43, v37, v36
	v_subbrev_co_u32_e32 v46, vcc, 0, v34, vcc
	v_sub_u32_e32 v34, 0, v46
	v_sub_f32_e32 v37, v41, v37
	v_add_f32_e32 v43, 1.0, v43
	v_ldexp_f32 v35, v36, v34
	v_add_f32_e32 v37, v37, v43
	v_add_f32_e32 v36, -1.0, v35
	v_add_f32_e32 v42, 1.0, v35
	v_ldexp_f32 v34, v37, v34
	v_add_f32_e32 v37, 1.0, v36
	v_add_f32_e32 v43, -1.0, v42
	v_sub_f32_e32 v37, v35, v37
	v_sub_f32_e32 v35, v35, v43
	v_add_f32_e32 v37, v34, v37
	v_add_f32_e32 v34, v34, v35
	v_add_f32_e32 v47, v42, v34
	v_rcp_f32_e32 v49, v47
	v_sub_f32_e32 v35, v47, v42
	v_sub_f32_e32 v48, v34, v35
	v_add_f32_e32 v35, v36, v37
	v_mul_f32_e32 v51, v35, v49
	v_sub_f32_e32 v34, v35, v36
	v_mul_f32_e32 v36, v47, v51
	v_fma_f32 v42, v51, v47, -v36
	v_fmac_f32_e32 v42, v51, v48
	v_sub_f32_e32 v50, v37, v34
	v_add_f32_e32 v34, v36, v42
	v_sub_f32_e32 v37, v35, v34
	v_pk_add_f32 v[44:45], v[34:35], v[36:37] neg_lo:[0,1] neg_hi:[0,1]
	v_mov_b32_e32 v43, v34
	v_pk_add_f32 v[34:35], v[44:45], v[42:43] neg_lo:[0,1] neg_hi:[0,1]
	s_mov_b32 s27, 0x3f317218
	v_add_f32_e32 v35, v50, v35
	v_add_f32_e32 v34, v34, v35
	v_add_f32_e32 v35, v37, v34
	v_mul_f32_e32 v50, v49, v35
	v_mul_f32_e32 v36, v47, v50
	v_fma_f32 v42, v50, v47, -v36
	v_fmac_f32_e32 v42, v50, v48
	v_sub_f32_e32 v37, v37, v35
	v_add_f32_e32 v47, v34, v37
	v_add_f32_e32 v34, v36, v42
	v_sub_f32_e32 v37, v35, v34
	v_pk_add_f32 v[44:45], v[34:35], v[36:37] neg_lo:[0,1] neg_hi:[0,1]
	v_mov_b32_e32 v43, v34
	v_pk_add_f32 v[34:35], v[44:45], v[42:43] neg_lo:[0,1] neg_hi:[0,1]
	s_nop 0
	v_add_f32_e32 v35, v47, v35
	v_add_f32_e32 v34, v34, v35
	v_add_f32_e32 v35, v51, v50
	v_add_f32_e32 v34, v37, v34
	v_sub_f32_e32 v36, v35, v51
	v_mul_f32_e32 v34, v49, v34
	v_sub_f32_e32 v36, v50, v36
	v_add_f32_e32 v36, v36, v34
	v_add_f32_e32 v42, v35, v36
	v_mul_f32_e32 v43, v42, v42
	v_fmamk_f32 v34, v43, 0x3e9b6dac, v236
	v_fmaak_f32 v205, v43, v34, 0x3f2aaada
	v_cvt_f32_i32_e32 v34, v46
	v_sub_f32_e32 v35, v42, v35
	v_sub_f32_e32 v35, v36, v35
	v_ldexp_f32 v44, v35, 1
	v_mul_f32_e32 v35, v42, v43
	v_ldexp_f32 v37, v42, 1
	v_pk_mul_f32 v[42:43], v[34:35], v[204:205]
	s_nop 0
	v_fma_f32 v36, v34, s27, -v42
	v_fmac_f32_e32 v36, 0xb102e308, v34
	v_pk_add_f32 v[34:35], v[42:43], v[36:37]
	s_mov_b32 s27, 0x7f800000
	v_sub_f32_e32 v37, v35, v37
	v_sub_f32_e32 v37, v43, v37
	v_add_f32_e32 v45, v44, v37
	v_mov_b32_e32 v44, v42
	v_pk_add_f32 v[42:43], v[34:35], v[42:43] neg_lo:[0,1] neg_hi:[0,1]
	v_pk_add_f32 v[46:47], v[34:35], v[44:45]
	v_mov_b32_e32 v37, v34
	v_mov_b32_e32 v43, v47
	v_pk_add_f32 v[48:49], v[36:37], v[42:43] neg_lo:[0,1] neg_hi:[0,1]
	v_pk_add_f32 v[36:37], v[36:37], v[42:43]
	v_mov_b32_e32 v44, v45
	v_pk_add_f32 v[42:43], v[36:37], v[34:35] op_sel:[1,0] op_sel_hi:[0,1] neg_lo:[0,1] neg_hi:[0,1]
	v_pk_add_f32 v[50:51], v[46:47], v[42:43] op_sel_hi:[1,0] neg_lo:[0,1] neg_hi:[0,1]
	v_mov_b32_e32 v46, v47
	v_mov_b32_e32 v47, v37
	v_pk_mov_b32 v[42:43], v[34:35], v[42:43] op_sel:[1,0]
	v_mov_b32_e32 v45, v34
	v_pk_add_f32 v[42:43], v[46:47], v[42:43] neg_lo:[0,1] neg_hi:[0,1]
	v_mov_b32_e32 v50, v48
	v_pk_add_f32 v[34:35], v[44:45], v[42:43] neg_lo:[0,1] neg_hi:[0,1]
	v_mov_b32_e32 v49, v37
	v_pk_add_f32 v[42:43], v[50:51], v[34:35]
	v_cmp_neq_f32_e32 vcc, s27, v41
	v_pk_add_f32 v[44:45], v[42:43], v[42:43] op_sel:[0,1] op_sel_hi:[1,0]
	s_mov_b32 s27, 0x33800000
	v_pk_add_f32 v[36:37], v[36:37], v[44:45] op_sel:[1,0] op_sel_hi:[0,1]
	v_mov_b32_e32 v43, v36
	v_pk_add_f32 v[46:47], v[42:43], v[48:49] neg_lo:[0,1] neg_hi:[0,1]
	v_mov_b32_e32 v35, v44
	v_sub_f32_e32 v37, v42, v46
	v_pk_add_f32 v[34:35], v[34:35], v[46:47] neg_lo:[0,1] neg_hi:[0,1]
	v_sub_f32_e32 v37, v48, v37
	v_add_f32_e32 v34, v34, v37
	v_add_f32_e32 v34, v34, v35
	v_add_f32_e32 v34, v36, v34
	v_cndmask_b32_e32 v34, v237, v34, vcc
	v_cmp_ngt_f32_e32 vcc, -1.0, v41
	s_nop 1
	v_cndmask_b32_e32 v34, v238, v34, vcc
	v_cmp_neq_f32_e32 vcc, -1.0, v41
	s_nop 1
	v_cndmask_b32_e32 v34, v239, v34, vcc
	v_cmp_lt_f32_e64 vcc, |v41|, s27
	s_nop 1
	v_cndmask_b32_e32 v34, v34, v41, vcc
	v_sub_f32_e32 v34, v0, v34

.LBB0_1095:
	s_and_saveexec_b64 s[4:5], s[10:11]
	s_xor_b64 s[18:19], exec, s[4:5]
	s_cbranch_execz .LBB0_1113
	v_readlane_b32 s4, v254, 26
	v_readlane_b32 s5, v254, 27
	s_nop 4
	s_load_dword s4, s[4:5], 0x0
	s_waitcnt lgkmcnt(0)
	v_mov_b32_e32 v0, s4
	v_add_f32_e32 v0, v26, v0
	v_cmp_nlt_f32_e32 vcc, 0, v0
	s_and_saveexec_b64 s[4:5], vcc
	s_xor_b64 s[4:5], exec, s[4:5]
	s_cbranch_execz .LBB0_1098
	v_mul_f32_e32 v26, 0x3fb8aa3b, v0
	v_exp_f32_e32 v26, v26
	s_mov_b32 s27, 0x3f2aaaab
	v_add_f32_e32 v32, 1.0, v26
	v_frexp_mant_f32_e32 v34, v32
	v_cvt_f64_f32_e32 v[30:31], v32
	v_frexp_exp_i32_f64_e32 v30, v[30:31]
	v_cmp_gt_f32_e32 vcc, s27, v34
	v_add_f32_e32 v33, -1.0, v32
	v_sub_f32_e32 v35, v33, v32
	v_subbrev_co_u32_e32 v38, vcc, 0, v30, vcc
	v_sub_u32_e32 v30, 0, v38
	v_sub_f32_e32 v33, v26, v33
	v_add_f32_e32 v35, 1.0, v35
	v_ldexp_f32 v31, v32, v30
	v_add_f32_e32 v33, v33, v35
	v_add_f32_e32 v32, -1.0, v31
	v_add_f32_e32 v34, 1.0, v31
	v_ldexp_f32 v30, v33, v30
	v_add_f32_e32 v33, 1.0, v32
	v_add_f32_e32 v35, -1.0, v34
	v_sub_f32_e32 v33, v31, v33
	v_sub_f32_e32 v31, v31, v35
	v_add_f32_e32 v33, v30, v33
	v_add_f32_e32 v30, v30, v31
	v_add_f32_e32 v40, v34, v30
	v_rcp_f32_e32 v42, v40
	v_sub_f32_e32 v31, v40, v34
	v_sub_f32_e32 v41, v30, v31
	v_add_f32_e32 v31, v32, v33
	v_mul_f32_e32 v44, v31, v42
	v_sub_f32_e32 v30, v31, v32
	v_mul_f32_e32 v32, v40, v44
	v_fma_f32 v34, v44, v40, -v32
	v_fmac_f32_e32 v34, v44, v41
	v_sub_f32_e32 v43, v33, v30
	v_add_f32_e32 v30, v32, v34
	v_sub_f32_e32 v33, v31, v30
	v_pk_add_f32 v[36:37], v[30:31], v[32:33] neg_lo:[0,1] neg_hi:[0,1]
	v_mov_b32_e32 v35, v30
	v_pk_add_f32 v[30:31], v[36:37], v[34:35] neg_lo:[0,1] neg_hi:[0,1]
	s_mov_b32 s27, 0x3f317218
	v_add_f32_e32 v31, v43, v31
	v_add_f32_e32 v30, v30, v31
	v_add_f32_e32 v31, v33, v30
	v_mul_f32_e32 v43, v42, v31
	v_mul_f32_e32 v32, v40, v43
	v_fma_f32 v34, v43, v40, -v32
	v_fmac_f32_e32 v34, v43, v41
	v_sub_f32_e32 v33, v33, v31
	v_add_f32_e32 v40, v30, v33
	v_add_f32_e32 v30, v32, v34
	v_sub_f32_e32 v33, v31, v30
	v_pk_add_f32 v[36:37], v[30:31], v[32:33] neg_lo:[0,1] neg_hi:[0,1]
	v_mov_b32_e32 v35, v30
	v_pk_add_f32 v[30:31], v[36:37], v[34:35] neg_lo:[0,1] neg_hi:[0,1]
	s_nop 0
	v_add_f32_e32 v31, v40, v31
	v_add_f32_e32 v30, v30, v31
	v_add_f32_e32 v31, v44, v43
	v_add_f32_e32 v30, v33, v30
	v_sub_f32_e32 v32, v31, v44
	v_mul_f32_e32 v30, v42, v30
	v_sub_f32_e32 v32, v43, v32
	v_add_f32_e32 v32, v32, v30
	v_add_f32_e32 v34, v31, v32
	v_mul_f32_e32 v35, v34, v34
	v_fmamk_f32 v30, v35, 0x3e9b6dac, v236
	v_fmaak_f32 v205, v35, v30, 0x3f2aaada
	v_cvt_f32_i32_e32 v30, v38
	v_sub_f32_e32 v31, v34, v31
	v_sub_f32_e32 v31, v32, v31
	v_ldexp_f32 v36, v31, 1
	v_mul_f32_e32 v31, v34, v35
	v_ldexp_f32 v33, v34, 1
	v_pk_mul_f32 v[34:35], v[30:31], v[204:205]
	s_nop 0
	v_fma_f32 v32, v30, s27, -v34
	v_fmac_f32_e32 v32, 0xb102e308, v30
	v_pk_add_f32 v[30:31], v[34:35], v[32:33]
	s_mov_b32 s27, 0x7f800000
	v_sub_f32_e32 v33, v31, v33
	v_sub_f32_e32 v33, v35, v33
	v_add_f32_e32 v37, v36, v33
	v_mov_b32_e32 v36, v34
	v_pk_add_f32 v[34:35], v[30:31], v[34:35] neg_lo:[0,1] neg_hi:[0,1]
	v_pk_add_f32 v[40:41], v[30:31], v[36:37]
	v_mov_b32_e32 v33, v30
	v_mov_b32_e32 v35, v41
	v_pk_add_f32 v[42:43], v[32:33], v[34:35] neg_lo:[0,1] neg_hi:[0,1]
	v_pk_add_f32 v[32:33], v[32:33], v[34:35]
	v_mov_b32_e32 v36, v37
	v_pk_add_f32 v[34:35], v[32:33], v[30:31] op_sel:[1,0] op_sel_hi:[0,1] neg_lo:[0,1] neg_hi:[0,1]
	v_pk_add_f32 v[44:45], v[40:41], v[34:35] op_sel_hi:[1,0] neg_lo:[0,1] neg_hi:[0,1]
	v_mov_b32_e32 v40, v41
	v_mov_b32_e32 v41, v33
	v_pk_mov_b32 v[34:35], v[30:31], v[34:35] op_sel:[1,0]
	v_mov_b32_e32 v37, v30
	v_pk_add_f32 v[34:35], v[40:41], v[34:35] neg_lo:[0,1] neg_hi:[0,1]
	v_mov_b32_e32 v44, v42
	v_pk_add_f32 v[30:31], v[36:37], v[34:35] neg_lo:[0,1] neg_hi:[0,1]
	v_mov_b32_e32 v43, v33
	v_pk_add_f32 v[34:35], v[44:45], v[30:31]
	v_cmp_neq_f32_e32 vcc, s27, v26
	v_pk_add_f32 v[36:37], v[34:35], v[34:35] op_sel:[0,1] op_sel_hi:[1,0]
	s_mov_b32 s27, 0x33800000
	v_pk_add_f32 v[32:33], v[32:33], v[36:37] op_sel:[1,0] op_sel_hi:[0,1]
	v_mov_b32_e32 v35, v32
	v_pk_add_f32 v[40:41], v[34:35], v[42:43] neg_lo:[0,1] neg_hi:[0,1]
	v_mov_b32_e32 v31, v36
	v_sub_f32_e32 v33, v34, v40
	v_pk_add_f32 v[30:31], v[30:31], v[40:41] neg_lo:[0,1] neg_hi:[0,1]
	v_sub_f32_e32 v33, v42, v33
	v_add_f32_e32 v30, v30, v33
	v_add_f32_e32 v30, v30, v31
	v_add_f32_e32 v30, v32, v30
	v_cndmask_b32_e32 v30, v237, v30, vcc
	v_cmp_ngt_f32_e32 vcc, -1.0, v26
	s_nop 1
	v_cndmask_b32_e32 v30, v238, v30, vcc
	v_cmp_neq_f32_e32 vcc, -1.0, v26
	s_nop 1
	v_cndmask_b32_e32 v30, v239, v30, vcc
	v_cmp_lt_f32_e64 vcc, |v26|, s27
	s_nop 1
	v_cndmask_b32_e32 v26, v30, v26, vcc
	v_sub_f32_e32 v26, v0, v26

.LBB0_1100:
	s_or_b64 exec, exec, s[4:5]
	v_lshlrev_b32_e32 v32, 2, v39
	v_lshlrev_b32_e32 v0, 2, v46
	v_ashrrev_i32_e32 v33, 31, v32
	v_lshl_add_u64 v[30:31], s[84:85], 0, v[0:1]
	v_lshlrev_b64 v[34:35], 13, v[32:33]
	v_lshl_add_u64 v[34:35], v[30:31], 0, v[34:35]
	v_readlane_b32 s4, v254, 26
	global_store_dword v[34:35], v26, off
	v_readlane_b32 s5, v254, 27
	s_nop 4
	s_load_dword s4, s[4:5], 0x4
	s_waitcnt lgkmcnt(0)
	v_mov_b32_e32 v0, s4
	v_add_f32_e32 v0, v27, v0
	v_cmp_nlt_f32_e32 vcc, 0, v0
	s_and_saveexec_b64 s[4:5], vcc
	s_xor_b64 s[4:5], exec, s[4:5]
	s_cbranch_execz .LBB0_1102
	v_mul_f32_e32 v26, 0x3fb8aa3b, v0
	v_exp_f32_e32 v33, v26
	s_mov_b32 s27, 0x3f2aaaab
	v_add_f32_e32 v34, 1.0, v33
	v_frexp_mant_f32_e32 v36, v34
	v_cvt_f64_f32_e32 v[26:27], v34
	v_frexp_exp_i32_f64_e32 v26, v[26:27]
	v_cmp_gt_f32_e32 vcc, s27, v36
	v_add_f32_e32 v35, -1.0, v34
	v_sub_f32_e32 v37, v35, v34
	v_subbrev_co_u32_e32 v40, vcc, 0, v26, vcc
	v_sub_u32_e32 v26, 0, v40
	v_sub_f32_e32 v35, v33, v35
	v_add_f32_e32 v37, 1.0, v37
	v_ldexp_f32 v27, v34, v26
	v_add_f32_e32 v35, v35, v37
	v_add_f32_e32 v34, -1.0, v27
	v_add_f32_e32 v36, 1.0, v27
	v_ldexp_f32 v26, v35, v26
	v_add_f32_e32 v35, 1.0, v34
	v_add_f32_e32 v37, -1.0, v36
	v_sub_f32_e32 v35, v27, v35
	v_sub_f32_e32 v27, v27, v37
	v_add_f32_e32 v35, v26, v35
	v_add_f32_e32 v26, v26, v27
	v_add_f32_e32 v41, v36, v26
	v_rcp_f32_e32 v43, v41
	v_sub_f32_e32 v27, v41, v36
	v_sub_f32_e32 v42, v26, v27
	v_add_f32_e32 v27, v34, v35
	v_mul_f32_e32 v45, v27, v43
	v_sub_f32_e32 v26, v27, v34
	v_mul_f32_e32 v34, v41, v45
	v_fma_f32 v36, v45, v41, -v34
	v_fmac_f32_e32 v36, v45, v42
	v_sub_f32_e32 v44, v35, v26
	v_add_f32_e32 v26, v34, v36
	v_sub_f32_e32 v35, v27, v26
	v_pk_add_f32 v[38:39], v[26:27], v[34:35] neg_lo:[0,1] neg_hi:[0,1]
	v_mov_b32_e32 v37, v26
	v_pk_add_f32 v[26:27], v[38:39], v[36:37] neg_lo:[0,1] neg_hi:[0,1]
	s_mov_b32 s27, 0x3f317218
	v_add_f32_e32 v27, v44, v27
	v_add_f32_e32 v26, v26, v27
	v_add_f32_e32 v27, v35, v26
	v_mul_f32_e32 v44, v43, v27
	v_mul_f32_e32 v34, v41, v44
	v_fma_f32 v36, v44, v41, -v34
	v_fmac_f32_e32 v36, v44, v42
	v_sub_f32_e32 v35, v35, v27
	v_add_f32_e32 v41, v26, v35
	v_add_f32_e32 v26, v34, v36
	v_sub_f32_e32 v35, v27, v26
	v_pk_add_f32 v[38:39], v[26:27], v[34:35] neg_lo:[0,1] neg_hi:[0,1]
	v_mov_b32_e32 v37, v26
	v_pk_add_f32 v[26:27], v[38:39], v[36:37] neg_lo:[0,1] neg_hi:[0,1]
	s_nop 0
	v_add_f32_e32 v27, v41, v27
	v_add_f32_e32 v26, v26, v27
	v_add_f32_e32 v27, v45, v44
	v_add_f32_e32 v26, v35, v26
	v_sub_f32_e32 v34, v27, v45
	v_mul_f32_e32 v26, v43, v26
	v_sub_f32_e32 v34, v44, v34
	v_add_f32_e32 v34, v34, v26
	v_add_f32_e32 v36, v27, v34
	v_mul_f32_e32 v37, v36, v36
	v_fmamk_f32 v26, v37, 0x3e9b6dac, v236
	v_fmaak_f32 v205, v37, v26, 0x3f2aaada
	v_cvt_f32_i32_e32 v26, v40
	v_sub_f32_e32 v27, v36, v27
	v_sub_f32_e32 v27, v34, v27
	v_ldexp_f32 v38, v27, 1
	v_mul_f32_e32 v27, v36, v37
	v_ldexp_f32 v35, v36, 1
	v_pk_mul_f32 v[36:37], v[26:27], v[204:205]
	s_nop 0
	v_fma_f32 v34, v26, s27, -v36
	v_fmac_f32_e32 v34, 0xb102e308, v26
	v_pk_add_f32 v[26:27], v[36:37], v[34:35]
	s_mov_b32 s27, 0x7f800000
	v_sub_f32_e32 v35, v27, v35
	v_sub_f32_e32 v35, v37, v35
	v_add_f32_e32 v39, v38, v35
	v_mov_b32_e32 v38, v36
	v_pk_add_f32 v[36:37], v[26:27], v[36:37] neg_lo:[0,1] neg_hi:[0,1]
	v_pk_add_f32 v[40:41], v[26:27], v[38:39]
	v_mov_b32_e32 v35, v26
	v_mov_b32_e32 v37, v41
	v_pk_add_f32 v[42:43], v[34:35], v[36:37] neg_lo:[0,1] neg_hi:[0,1]
	v_pk_add_f32 v[34:35], v[34:35], v[36:37]
	v_mov_b32_e32 v38, v39
	v_pk_add_f32 v[36:37], v[34:35], v[26:27] op_sel:[1,0] op_sel_hi:[0,1] neg_lo:[0,1] neg_hi:[0,1]
	v_pk_add_f32 v[44:45], v[40:41], v[36:37] op_sel_hi:[1,0] neg_lo:[0,1] neg_hi:[0,1]
	v_mov_b32_e32 v40, v41
	v_mov_b32_e32 v41, v35
	v_pk_mov_b32 v[36:37], v[26:27], v[36:37] op_sel:[1,0]
	v_mov_b32_e32 v39, v26
	v_pk_add_f32 v[36:37], v[40:41], v[36:37] neg_lo:[0,1] neg_hi:[0,1]
	v_mov_b32_e32 v44, v42
	v_pk_add_f32 v[26:27], v[38:39], v[36:37] neg_lo:[0,1] neg_hi:[0,1]
	v_mov_b32_e32 v43, v35
	v_pk_add_f32 v[36:37], v[44:45], v[26:27]
	v_cmp_neq_f32_e32 vcc, s27, v33
	v_pk_add_f32 v[38:39], v[36:37], v[36:37] op_sel:[0,1] op_sel_hi:[1,0]
	s_mov_b32 s27, 0x33800000
	v_pk_add_f32 v[34:35], v[34:35], v[38:39] op_sel:[1,0] op_sel_hi:[0,1]
	v_mov_b32_e32 v37, v34
	v_pk_add_f32 v[40:41], v[36:37], v[42:43] neg_lo:[0,1] neg_hi:[0,1]
	v_mov_b32_e32 v27, v38
	v_sub_f32_e32 v35, v36, v40
	v_pk_add_f32 v[26:27], v[26:27], v[40:41] neg_lo:[0,1] neg_hi:[0,1]
	v_sub_f32_e32 v35, v42, v35
	v_add_f32_e32 v26, v26, v35
	v_add_f32_e32 v26, v26, v27
	v_add_f32_e32 v26, v34, v26
	v_cndmask_b32_e32 v26, v237, v26, vcc
	v_cmp_ngt_f32_e32 vcc, -1.0, v33
	s_nop 1
	v_cndmask_b32_e32 v26, v238, v26, vcc
	v_cmp_neq_f32_e32 vcc, -1.0, v33
	s_nop 1
	v_cndmask_b32_e32 v26, v239, v26, vcc
	v_cmp_lt_f32_e64 vcc, |v33|, s27
	s_nop 1
	v_cndmask_b32_e32 v26, v26, v33, vcc
	v_sub_f32_e32 v26, v0, v26

.LBB0_1104:
	s_or_b64 exec, exec, s[4:5]
	v_or_b32_e32 v34, 1, v32
	v_ashrrev_i32_e32 v35, 31, v34
	v_lshlrev_b64 v[34:35], 13, v[34:35]
	v_lshl_add_u64 v[34:35], v[30:31], 0, v[34:35]
	v_readlane_b32 s4, v254, 26
	global_store_dword v[34:35], v26, off
	v_readlane_b32 s5, v254, 27
	s_nop 4
	s_load_dword s4, s[4:5], 0x8
	s_waitcnt lgkmcnt(0)
	v_mov_b32_e32 v0, s4
	v_add_f32_e32 v0, v28, v0
	v_cmp_nlt_f32_e32 vcc, 0, v0
	s_and_saveexec_b64 s[4:5], vcc
	s_xor_b64 s[4:5], exec, s[4:5]
	s_cbranch_execz .LBB0_1106
	v_mul_f32_e32 v26, 0x3fb8aa3b, v0
	v_exp_f32_e32 v28, v26
	s_mov_b32 s27, 0x3f2aaaab
	v_add_f32_e32 v33, 1.0, v28
	v_frexp_mant_f32_e32 v35, v33
	v_cvt_f64_f32_e32 v[26:27], v33
	v_frexp_exp_i32_f64_e32 v26, v[26:27]
	v_cmp_gt_f32_e32 vcc, s27, v35
	v_add_f32_e32 v34, -1.0, v33
	v_sub_f32_e32 v36, v34, v33
	v_subbrev_co_u32_e32 v40, vcc, 0, v26, vcc
	v_sub_u32_e32 v26, 0, v40
	v_sub_f32_e32 v34, v28, v34
	v_add_f32_e32 v36, 1.0, v36
	v_ldexp_f32 v27, v33, v26
	v_add_f32_e32 v34, v34, v36
	v_add_f32_e32 v33, -1.0, v27
	v_add_f32_e32 v35, 1.0, v27
	v_ldexp_f32 v26, v34, v26
	v_add_f32_e32 v34, 1.0, v33
	v_add_f32_e32 v36, -1.0, v35
	v_sub_f32_e32 v34, v27, v34
	v_sub_f32_e32 v27, v27, v36
	v_add_f32_e32 v34, v26, v34
	v_add_f32_e32 v26, v26, v27
	v_add_f32_e32 v41, v35, v26
	v_rcp_f32_e32 v43, v41
	v_sub_f32_e32 v27, v41, v35
	v_sub_f32_e32 v42, v26, v27
	v_add_f32_e32 v27, v33, v34
	v_sub_f32_e32 v26, v27, v33
	v_mul_f32_e32 v44, v27, v43
	v_sub_f32_e32 v33, v34, v26
	v_mul_f32_e32 v34, v41, v44
	v_fma_f32 v36, v44, v41, -v34
	v_fmac_f32_e32 v36, v44, v42
	v_add_f32_e32 v26, v34, v36
	v_sub_f32_e32 v35, v27, v26
	v_pk_add_f32 v[38:39], v[26:27], v[34:35] neg_lo:[0,1] neg_hi:[0,1]
	v_mov_b32_e32 v37, v26
	v_pk_add_f32 v[26:27], v[38:39], v[36:37] neg_lo:[0,1] neg_hi:[0,1]
	s_mov_b32 s27, 0x3f317218
	v_add_f32_e32 v27, v33, v27
	v_add_f32_e32 v26, v26, v27
	v_add_f32_e32 v27, v35, v26
	v_mul_f32_e32 v33, v43, v27
	v_mul_f32_e32 v34, v41, v33
	v_fma_f32 v36, v33, v41, -v34
	v_fmac_f32_e32 v36, v33, v42
	v_sub_f32_e32 v35, v35, v27
	v_add_f32_e32 v41, v26, v35
	v_add_f32_e32 v26, v34, v36
	v_sub_f32_e32 v35, v27, v26
	v_pk_add_f32 v[38:39], v[26:27], v[34:35] neg_lo:[0,1] neg_hi:[0,1]
	v_mov_b32_e32 v37, v26
	v_pk_add_f32 v[26:27], v[38:39], v[36:37] neg_lo:[0,1] neg_hi:[0,1]
	s_nop 0
	v_add_f32_e32 v27, v41, v27
	v_add_f32_e32 v26, v26, v27
	v_add_f32_e32 v27, v44, v33
	v_add_f32_e32 v26, v35, v26
	v_sub_f32_e32 v34, v27, v44
	v_mul_f32_e32 v26, v43, v26
	v_sub_f32_e32 v33, v33, v34
	v_add_f32_e32 v33, v33, v26
	v_add_f32_e32 v34, v27, v33
	v_mul_f32_e32 v36, v34, v34
	v_fmamk_f32 v26, v36, 0x3e9b6dac, v236
	v_fmaak_f32 v205, v36, v26, 0x3f2aaada
	v_cvt_f32_i32_e32 v26, v40
	v_sub_f32_e32 v27, v34, v27
	v_sub_f32_e32 v27, v33, v27
	v_ldexp_f32 v33, v27, 1
	v_mul_f32_e32 v27, v34, v36
	v_pk_mul_f32 v[36:37], v[26:27], v[204:205]
	v_ldexp_f32 v35, v34, 1
	v_fma_f32 v34, v26, s27, -v36
	v_fmac_f32_e32 v34, 0xb102e308, v26
	v_pk_add_f32 v[26:27], v[36:37], v[34:35]
	v_mov_b32_e32 v38, v36
	v_sub_f32_e32 v35, v27, v35
	v_sub_f32_e32 v35, v37, v35
	v_add_f32_e32 v39, v33, v35
	v_pk_add_f32 v[36:37], v[26:27], v[36:37] neg_lo:[0,1] neg_hi:[0,1]
	v_pk_add_f32 v[40:41], v[26:27], v[38:39]
	v_mov_b32_e32 v35, v26
	v_mov_b32_e32 v37, v41
	v_pk_add_f32 v[42:43], v[34:35], v[36:37] neg_lo:[0,1] neg_hi:[0,1]
	v_pk_add_f32 v[34:35], v[34:35], v[36:37]
	v_mov_b32_e32 v38, v39
	v_pk_add_f32 v[36:37], v[34:35], v[26:27] op_sel:[1,0] op_sel_hi:[0,1] neg_lo:[0,1] neg_hi:[0,1]
	v_pk_add_f32 v[44:45], v[40:41], v[36:37] op_sel_hi:[1,0] neg_lo:[0,1] neg_hi:[0,1]
	v_mov_b32_e32 v40, v41
	v_mov_b32_e32 v41, v35
	v_pk_mov_b32 v[36:37], v[26:27], v[36:37] op_sel:[1,0]
	v_mov_b32_e32 v39, v26
	v_pk_add_f32 v[36:37], v[40:41], v[36:37] neg_lo:[0,1] neg_hi:[0,1]
	v_mov_b32_e32 v44, v42
	v_pk_add_f32 v[26:27], v[38:39], v[36:37] neg_lo:[0,1] neg_hi:[0,1]
	v_mov_b32_e32 v43, v35
	v_pk_add_f32 v[36:37], v[44:45], v[26:27]
	s_mov_b32 s27, 0x7f800000
	v_pk_add_f32 v[38:39], v[36:37], v[36:37] op_sel:[0,1] op_sel_hi:[1,0]
	v_cmp_neq_f32_e32 vcc, s27, v28
	v_pk_add_f32 v[34:35], v[34:35], v[38:39] op_sel:[1,0] op_sel_hi:[0,1]
	v_mov_b32_e32 v37, v34
	v_pk_add_f32 v[40:41], v[36:37], v[42:43] neg_lo:[0,1] neg_hi:[0,1]
	v_mov_b32_e32 v27, v38
	v_sub_f32_e32 v33, v36, v40
	v_pk_add_f32 v[26:27], v[26:27], v[40:41] neg_lo:[0,1] neg_hi:[0,1]
	v_sub_f32_e32 v33, v42, v33
	v_add_f32_e32 v26, v26, v33
	v_add_f32_e32 v26, v26, v27
	v_add_f32_e32 v26, v34, v26
	v_cndmask_b32_e32 v26, v237, v26, vcc
	v_cmp_ngt_f32_e32 vcc, -1.0, v28
	s_mov_b32 s27, 0x33800000
	s_nop 0
	v_cndmask_b32_e32 v26, v238, v26, vcc
	v_cmp_neq_f32_e32 vcc, -1.0, v28
	s_nop 1
	v_cndmask_b32_e32 v26, v239, v26, vcc
	v_cmp_lt_f32_e64 vcc, |v28|, s27
	s_nop 1
	v_cndmask_b32_e32 v26, v26, v28, vcc
	v_sub_f32_e32 v26, v0, v26

.LBB0_1108:
	s_or_b64 exec, exec, s[4:5]
	v_or_b32_e32 v34, 2, v32
	v_ashrrev_i32_e32 v35, 31, v34
	v_lshlrev_b64 v[34:35], 13, v[34:35]
	v_lshl_add_u64 v[34:35], v[30:31], 0, v[34:35]
	v_readlane_b32 s4, v254, 26
	global_store_dword v[34:35], v26, off
	v_readlane_b32 s5, v254, 27
	s_nop 4
	s_load_dword s4, s[4:5], 0xc
	s_waitcnt lgkmcnt(0)
	v_mov_b32_e32 v0, s4
	v_add_f32_e32 v0, v29, v0
	v_cmp_nlt_f32_e32 vcc, 0, v0
	s_and_saveexec_b64 s[4:5], vcc
	s_xor_b64 s[4:5], exec, s[4:5]
	s_cbranch_execz .LBB0_1110
	v_mul_f32_e32 v26, 0x3fb8aa3b, v0
	v_exp_f32_e32 v33, v26
	s_mov_b32 s27, 0x3f2aaaab
	v_add_f32_e32 v28, 1.0, v33
	v_frexp_mant_f32_e32 v34, v28
	v_cvt_f64_f32_e32 v[26:27], v28
	v_frexp_exp_i32_f64_e32 v26, v[26:27]
	v_cmp_gt_f32_e32 vcc, s27, v34
	v_add_f32_e32 v29, -1.0, v28
	v_sub_f32_e32 v35, v29, v28
	v_subbrev_co_u32_e32 v38, vcc, 0, v26, vcc
	v_sub_u32_e32 v26, 0, v38
	v_sub_f32_e32 v29, v33, v29
	v_add_f32_e32 v35, 1.0, v35
	v_ldexp_f32 v27, v28, v26
	v_add_f32_e32 v29, v29, v35
	v_add_f32_e32 v28, -1.0, v27
	v_add_f32_e32 v34, 1.0, v27
	v_ldexp_f32 v26, v29, v26
	v_add_f32_e32 v29, 1.0, v28
	v_add_f32_e32 v35, -1.0, v34
	v_sub_f32_e32 v29, v27, v29
	v_sub_f32_e32 v27, v27, v35
	v_add_f32_e32 v29, v26, v29
	v_add_f32_e32 v26, v26, v27
	v_add_f32_e32 v39, v34, v26
	v_rcp_f32_e32 v41, v39
	v_sub_f32_e32 v27, v39, v34
	v_sub_f32_e32 v40, v26, v27
	v_add_f32_e32 v27, v28, v29
	v_mul_f32_e32 v43, v27, v41
	v_sub_f32_e32 v26, v27, v28
	v_mul_f32_e32 v28, v39, v43
	v_fma_f32 v34, v43, v39, -v28
	v_fmac_f32_e32 v34, v43, v40
	v_sub_f32_e32 v42, v29, v26
	v_add_f32_e32 v26, v28, v34
	v_sub_f32_e32 v29, v27, v26
	v_pk_add_f32 v[36:37], v[26:27], v[28:29] neg_lo:[0,1] neg_hi:[0,1]
	v_mov_b32_e32 v35, v26
	v_pk_add_f32 v[26:27], v[36:37], v[34:35] neg_lo:[0,1] neg_hi:[0,1]
	s_mov_b32 s27, 0x3f317218
	v_add_f32_e32 v27, v42, v27
	v_add_f32_e32 v26, v26, v27
	v_add_f32_e32 v27, v29, v26
	v_mul_f32_e32 v42, v41, v27
	v_mul_f32_e32 v28, v39, v42
	v_fma_f32 v34, v42, v39, -v28
	v_fmac_f32_e32 v34, v42, v40
	v_sub_f32_e32 v29, v29, v27
	v_add_f32_e32 v39, v26, v29
	v_add_f32_e32 v26, v28, v34
	v_sub_f32_e32 v29, v27, v26
	v_pk_add_f32 v[36:37], v[26:27], v[28:29] neg_lo:[0,1] neg_hi:[0,1]
	v_mov_b32_e32 v35, v26
	v_pk_add_f32 v[26:27], v[36:37], v[34:35] neg_lo:[0,1] neg_hi:[0,1]
	s_nop 0
	v_add_f32_e32 v27, v39, v27
	v_add_f32_e32 v26, v26, v27
	v_add_f32_e32 v27, v43, v42
	v_add_f32_e32 v26, v29, v26
	v_sub_f32_e32 v28, v27, v43
	v_mul_f32_e32 v26, v41, v26
	v_sub_f32_e32 v28, v42, v28
	v_add_f32_e32 v28, v28, v26
	v_add_f32_e32 v34, v27, v28
	v_mul_f32_e32 v35, v34, v34
	v_fmamk_f32 v26, v35, 0x3e9b6dac, v236
	v_fmaak_f32 v205, v35, v26, 0x3f2aaada
	v_cvt_f32_i32_e32 v26, v38
	v_sub_f32_e32 v27, v34, v27
	v_sub_f32_e32 v27, v28, v27
	v_ldexp_f32 v36, v27, 1
	v_mul_f32_e32 v27, v34, v35
	v_ldexp_f32 v29, v34, 1
	v_pk_mul_f32 v[34:35], v[26:27], v[204:205]
	s_nop 0
	v_fma_f32 v28, v26, s27, -v34
	v_fmac_f32_e32 v28, 0xb102e308, v26
	v_pk_add_f32 v[26:27], v[34:35], v[28:29]
	s_mov_b32 s27, 0x7f800000
	v_sub_f32_e32 v29, v27, v29
	v_sub_f32_e32 v29, v35, v29
	v_add_f32_e32 v37, v36, v29
	v_mov_b32_e32 v36, v34
	v_pk_add_f32 v[34:35], v[26:27], v[34:35] neg_lo:[0,1] neg_hi:[0,1]
	v_pk_add_f32 v[38:39], v[26:27], v[36:37]
	v_mov_b32_e32 v29, v26
	v_mov_b32_e32 v35, v39
	v_pk_add_f32 v[40:41], v[28:29], v[34:35] neg_lo:[0,1] neg_hi:[0,1]
	v_pk_add_f32 v[28:29], v[28:29], v[34:35]
	v_mov_b32_e32 v36, v37
	v_pk_add_f32 v[34:35], v[28:29], v[26:27] op_sel:[1,0] op_sel_hi:[0,1] neg_lo:[0,1] neg_hi:[0,1]
	v_pk_add_f32 v[42:43], v[38:39], v[34:35] op_sel_hi:[1,0] neg_lo:[0,1] neg_hi:[0,1]
	v_mov_b32_e32 v38, v39
	v_mov_b32_e32 v39, v29
	v_pk_mov_b32 v[34:35], v[26:27], v[34:35] op_sel:[1,0]
	v_mov_b32_e32 v37, v26
	v_pk_add_f32 v[34:35], v[38:39], v[34:35] neg_lo:[0,1] neg_hi:[0,1]
	v_mov_b32_e32 v42, v40
	v_pk_add_f32 v[26:27], v[36:37], v[34:35] neg_lo:[0,1] neg_hi:[0,1]
	v_mov_b32_e32 v41, v29
	v_pk_add_f32 v[34:35], v[42:43], v[26:27]
	v_cmp_neq_f32_e32 vcc, s27, v33
	v_pk_add_f32 v[36:37], v[34:35], v[34:35] op_sel:[0,1] op_sel_hi:[1,0]
	s_mov_b32 s27, 0x33800000
	v_pk_add_f32 v[28:29], v[28:29], v[36:37] op_sel:[1,0] op_sel_hi:[0,1]
	v_mov_b32_e32 v35, v28
	v_pk_add_f32 v[38:39], v[34:35], v[40:41] neg_lo:[0,1] neg_hi:[0,1]
	v_mov_b32_e32 v27, v36
	v_sub_f32_e32 v29, v34, v38
	v_pk_add_f32 v[26:27], v[26:27], v[38:39] neg_lo:[0,1] neg_hi:[0,1]
	v_sub_f32_e32 v29, v40, v29
	v_add_f32_e32 v26, v26, v29
	v_add_f32_e32 v26, v26, v27
	v_add_f32_e32 v26, v28, v26
	v_cndmask_b32_e32 v26, v237, v26, vcc
	v_cmp_ngt_f32_e32 vcc, -1.0, v33
	s_nop 1
	v_cndmask_b32_e32 v26, v238, v26, vcc
	v_cmp_neq_f32_e32 vcc, -1.0, v33
	s_nop 1
	v_cndmask_b32_e32 v26, v239, v26, vcc
	v_cmp_lt_f32_e64 vcc, |v33|, s27
	s_nop 1
	v_cndmask_b32_e32 v26, v26, v33, vcc
	v_sub_f32_e32 v26, v0, v26

.LBB0_1135:
	s_and_saveexec_b64 s[4:5], s[10:11]
	s_xor_b64 s[18:19], exec, s[4:5]
	s_cbranch_execz .LBB0_1153
	v_readlane_b32 s4, v254, 26
	v_readlane_b32 s5, v254, 27
	s_nop 4
	s_load_dword s4, s[4:5], 0x0
	s_waitcnt lgkmcnt(0)
	v_mov_b32_e32 v0, s4
	v_add_f32_e32 v0, v18, v0
	v_cmp_nlt_f32_e32 vcc, 0, v0
	s_and_saveexec_b64 s[4:5], vcc
	s_xor_b64 s[4:5], exec, s[4:5]
	s_cbranch_execz .LBB0_1138
	v_mul_f32_e32 v18, 0x3fb8aa3b, v0
	v_exp_f32_e32 v18, v18
	s_mov_b32 s27, 0x3f2aaaab
	v_add_f32_e32 v24, 1.0, v18
	v_frexp_mant_f32_e32 v26, v24
	v_cvt_f64_f32_e32 v[22:23], v24
	v_frexp_exp_i32_f64_e32 v22, v[22:23]
	v_cmp_gt_f32_e32 vcc, s27, v26
	v_add_f32_e32 v25, -1.0, v24
	v_sub_f32_e32 v27, v25, v24
	v_subbrev_co_u32_e32 v30, vcc, 0, v22, vcc
	v_sub_u32_e32 v22, 0, v30
	v_sub_f32_e32 v25, v18, v25
	v_add_f32_e32 v27, 1.0, v27
	v_ldexp_f32 v23, v24, v22
	v_add_f32_e32 v25, v25, v27
	v_add_f32_e32 v24, -1.0, v23
	v_add_f32_e32 v26, 1.0, v23
	v_ldexp_f32 v22, v25, v22
	v_add_f32_e32 v25, 1.0, v24
	v_add_f32_e32 v27, -1.0, v26
	v_sub_f32_e32 v25, v23, v25
	v_sub_f32_e32 v23, v23, v27
	v_add_f32_e32 v25, v22, v25
	v_add_f32_e32 v22, v22, v23
	v_add_f32_e32 v31, v26, v22
	v_rcp_f32_e32 v33, v31
	v_sub_f32_e32 v23, v31, v26
	v_sub_f32_e32 v32, v22, v23
	v_add_f32_e32 v23, v24, v25
	v_mul_f32_e32 v35, v23, v33
	v_sub_f32_e32 v22, v23, v24
	v_mul_f32_e32 v24, v31, v35
	v_fma_f32 v26, v35, v31, -v24
	v_fmac_f32_e32 v26, v35, v32
	v_sub_f32_e32 v34, v25, v22
	v_add_f32_e32 v22, v24, v26
	v_sub_f32_e32 v25, v23, v22
	v_pk_add_f32 v[28:29], v[22:23], v[24:25] neg_lo:[0,1] neg_hi:[0,1]
	v_mov_b32_e32 v27, v22
	v_pk_add_f32 v[22:23], v[28:29], v[26:27] neg_lo:[0,1] neg_hi:[0,1]
	s_mov_b32 s27, 0x3f317218
	v_add_f32_e32 v23, v34, v23
	v_add_f32_e32 v22, v22, v23
	v_add_f32_e32 v23, v25, v22
	v_mul_f32_e32 v34, v33, v23
	v_mul_f32_e32 v24, v31, v34
	v_fma_f32 v26, v34, v31, -v24
	v_fmac_f32_e32 v26, v34, v32
	v_sub_f32_e32 v25, v25, v23
	v_add_f32_e32 v31, v22, v25
	v_add_f32_e32 v22, v24, v26
	v_sub_f32_e32 v25, v23, v22
	v_pk_add_f32 v[28:29], v[22:23], v[24:25] neg_lo:[0,1] neg_hi:[0,1]
	v_mov_b32_e32 v27, v22
	v_pk_add_f32 v[22:23], v[28:29], v[26:27] neg_lo:[0,1] neg_hi:[0,1]
	s_nop 0
	v_add_f32_e32 v23, v31, v23
	v_add_f32_e32 v22, v22, v23
	v_add_f32_e32 v23, v35, v34
	v_add_f32_e32 v22, v25, v22
	v_sub_f32_e32 v24, v23, v35
	v_mul_f32_e32 v22, v33, v22
	v_sub_f32_e32 v24, v34, v24
	v_add_f32_e32 v24, v24, v22
	v_add_f32_e32 v26, v23, v24
	v_mul_f32_e32 v27, v26, v26
	v_fmamk_f32 v22, v27, 0x3e9b6dac, v236
	v_fmaak_f32 v205, v27, v22, 0x3f2aaada
	v_cvt_f32_i32_e32 v22, v30
	v_sub_f32_e32 v23, v26, v23
	v_sub_f32_e32 v23, v24, v23
	v_ldexp_f32 v28, v23, 1
	v_mul_f32_e32 v23, v26, v27
	v_ldexp_f32 v25, v26, 1
	v_pk_mul_f32 v[26:27], v[22:23], v[204:205]
	s_nop 0
	v_fma_f32 v24, v22, s27, -v26
	v_fmac_f32_e32 v24, 0xb102e308, v22
	v_pk_add_f32 v[22:23], v[26:27], v[24:25]
	s_mov_b32 s27, 0x7f800000
	v_sub_f32_e32 v25, v23, v25
	v_sub_f32_e32 v25, v27, v25
	v_add_f32_e32 v29, v28, v25
	v_mov_b32_e32 v28, v26
	v_pk_add_f32 v[26:27], v[22:23], v[26:27] neg_lo:[0,1] neg_hi:[0,1]
	v_pk_add_f32 v[30:31], v[22:23], v[28:29]
	v_mov_b32_e32 v25, v22
	v_mov_b32_e32 v27, v31
	v_pk_add_f32 v[32:33], v[24:25], v[26:27] neg_lo:[0,1] neg_hi:[0,1]
	v_pk_add_f32 v[24:25], v[24:25], v[26:27]
	v_mov_b32_e32 v28, v29
	v_pk_add_f32 v[26:27], v[24:25], v[22:23] op_sel:[1,0] op_sel_hi:[0,1] neg_lo:[0,1] neg_hi:[0,1]
	v_pk_add_f32 v[34:35], v[30:31], v[26:27] op_sel_hi:[1,0] neg_lo:[0,1] neg_hi:[0,1]
	v_mov_b32_e32 v30, v31
	v_mov_b32_e32 v31, v25
	v_pk_mov_b32 v[26:27], v[22:23], v[26:27] op_sel:[1,0]
	v_mov_b32_e32 v29, v22
	v_pk_add_f32 v[26:27], v[30:31], v[26:27] neg_lo:[0,1] neg_hi:[0,1]
	v_mov_b32_e32 v34, v32
	v_pk_add_f32 v[22:23], v[28:29], v[26:27] neg_lo:[0,1] neg_hi:[0,1]
	v_mov_b32_e32 v33, v25
	v_pk_add_f32 v[26:27], v[34:35], v[22:23]
	v_cmp_neq_f32_e32 vcc, s27, v18
	v_pk_add_f32 v[28:29], v[26:27], v[26:27] op_sel:[0,1] op_sel_hi:[1,0]
	s_mov_b32 s27, 0x33800000
	v_pk_add_f32 v[24:25], v[24:25], v[28:29] op_sel:[1,0] op_sel_hi:[0,1]
	v_mov_b32_e32 v27, v24
	v_pk_add_f32 v[30:31], v[26:27], v[32:33] neg_lo:[0,1] neg_hi:[0,1]
	v_mov_b32_e32 v23, v28
	v_sub_f32_e32 v25, v26, v30
	v_pk_add_f32 v[22:23], v[22:23], v[30:31] neg_lo:[0,1] neg_hi:[0,1]
	v_sub_f32_e32 v25, v32, v25
	v_add_f32_e32 v22, v22, v25
	v_add_f32_e32 v22, v22, v23
	v_add_f32_e32 v22, v24, v22
	v_cndmask_b32_e32 v22, v237, v22, vcc
	v_cmp_ngt_f32_e32 vcc, -1.0, v18
	s_nop 1
	v_cndmask_b32_e32 v22, v238, v22, vcc
	v_cmp_neq_f32_e32 vcc, -1.0, v18
	s_nop 1
	v_cndmask_b32_e32 v22, v239, v22, vcc
	v_cmp_lt_f32_e64 vcc, |v18|, s27
	s_nop 1
	v_cndmask_b32_e32 v18, v22, v18, vcc
	v_sub_f32_e32 v18, v0, v18

.LBB0_1140:
	s_or_b64 exec, exec, s[4:5]
	v_lshlrev_b32_e32 v24, 2, v37
	v_lshlrev_b32_e32 v0, 2, v38
	v_ashrrev_i32_e32 v25, 31, v24
	v_lshl_add_u64 v[22:23], s[84:85], 0, v[0:1]
	v_lshlrev_b64 v[26:27], 13, v[24:25]
	v_lshl_add_u64 v[26:27], v[22:23], 0, v[26:27]
	v_readlane_b32 s4, v254, 26
	global_store_dword v[26:27], v18, off
	v_readlane_b32 s5, v254, 27
	s_nop 4
	s_load_dword s4, s[4:5], 0x4
	s_waitcnt lgkmcnt(0)
	v_mov_b32_e32 v0, s4
	v_add_f32_e32 v0, v19, v0
	v_cmp_nlt_f32_e32 vcc, 0, v0
	s_and_saveexec_b64 s[4:5], vcc
	s_xor_b64 s[4:5], exec, s[4:5]
	s_cbranch_execz .LBB0_1142
	v_mul_f32_e32 v18, 0x3fb8aa3b, v0
	v_exp_f32_e32 v25, v18
	s_mov_b32 s27, 0x3f2aaaab
	v_add_f32_e32 v26, 1.0, v25
	v_frexp_mant_f32_e32 v28, v26
	v_cvt_f64_f32_e32 v[18:19], v26
	v_frexp_exp_i32_f64_e32 v18, v[18:19]
	v_cmp_gt_f32_e32 vcc, s27, v28
	v_add_f32_e32 v27, -1.0, v26
	v_sub_f32_e32 v29, v27, v26
	v_subbrev_co_u32_e32 v32, vcc, 0, v18, vcc
	v_sub_u32_e32 v18, 0, v32
	v_sub_f32_e32 v27, v25, v27
	v_add_f32_e32 v29, 1.0, v29
	v_ldexp_f32 v19, v26, v18
	v_add_f32_e32 v27, v27, v29
	v_add_f32_e32 v26, -1.0, v19
	v_add_f32_e32 v28, 1.0, v19
	v_ldexp_f32 v18, v27, v18
	v_add_f32_e32 v27, 1.0, v26
	v_add_f32_e32 v29, -1.0, v28
	v_sub_f32_e32 v27, v19, v27
	v_sub_f32_e32 v19, v19, v29
	v_add_f32_e32 v27, v18, v27
	v_add_f32_e32 v18, v18, v19
	v_add_f32_e32 v33, v28, v18
	v_rcp_f32_e32 v35, v33
	v_sub_f32_e32 v19, v33, v28
	v_sub_f32_e32 v34, v18, v19
	v_add_f32_e32 v19, v26, v27
	v_mul_f32_e32 v37, v19, v35
	v_sub_f32_e32 v18, v19, v26
	v_mul_f32_e32 v26, v33, v37
	v_fma_f32 v28, v37, v33, -v26
	v_fmac_f32_e32 v28, v37, v34
	v_sub_f32_e32 v36, v27, v18
	v_add_f32_e32 v18, v26, v28
	v_sub_f32_e32 v27, v19, v18
	v_pk_add_f32 v[30:31], v[18:19], v[26:27] neg_lo:[0,1] neg_hi:[0,1]
	v_mov_b32_e32 v29, v18
	v_pk_add_f32 v[18:19], v[30:31], v[28:29] neg_lo:[0,1] neg_hi:[0,1]
	s_mov_b32 s27, 0x3f317218
	v_add_f32_e32 v19, v36, v19
	v_add_f32_e32 v18, v18, v19
	v_add_f32_e32 v19, v27, v18
	v_mul_f32_e32 v36, v35, v19
	v_mul_f32_e32 v26, v33, v36
	v_fma_f32 v28, v36, v33, -v26
	v_fmac_f32_e32 v28, v36, v34
	v_sub_f32_e32 v27, v27, v19
	v_add_f32_e32 v33, v18, v27
	v_add_f32_e32 v18, v26, v28
	v_sub_f32_e32 v27, v19, v18
	v_pk_add_f32 v[30:31], v[18:19], v[26:27] neg_lo:[0,1] neg_hi:[0,1]
	v_mov_b32_e32 v29, v18
	v_pk_add_f32 v[18:19], v[30:31], v[28:29] neg_lo:[0,1] neg_hi:[0,1]
	s_nop 0
	v_add_f32_e32 v19, v33, v19
	v_add_f32_e32 v18, v18, v19
	v_add_f32_e32 v19, v37, v36
	v_add_f32_e32 v18, v27, v18
	v_sub_f32_e32 v26, v19, v37
	v_mul_f32_e32 v18, v35, v18
	v_sub_f32_e32 v26, v36, v26
	v_add_f32_e32 v26, v26, v18
	v_add_f32_e32 v28, v19, v26
	v_mul_f32_e32 v29, v28, v28
	v_fmamk_f32 v18, v29, 0x3e9b6dac, v236
	v_fmaak_f32 v205, v29, v18, 0x3f2aaada
	v_cvt_f32_i32_e32 v18, v32
	v_sub_f32_e32 v19, v28, v19
	v_sub_f32_e32 v19, v26, v19
	v_ldexp_f32 v30, v19, 1
	v_mul_f32_e32 v19, v28, v29
	v_ldexp_f32 v27, v28, 1
	v_pk_mul_f32 v[28:29], v[18:19], v[204:205]
	s_nop 0
	v_fma_f32 v26, v18, s27, -v28
	v_fmac_f32_e32 v26, 0xb102e308, v18
	v_pk_add_f32 v[18:19], v[28:29], v[26:27]
	s_mov_b32 s27, 0x7f800000
	v_sub_f32_e32 v27, v19, v27
	v_sub_f32_e32 v27, v29, v27
	v_add_f32_e32 v31, v30, v27
	v_mov_b32_e32 v30, v28
	v_pk_add_f32 v[28:29], v[18:19], v[28:29] neg_lo:[0,1] neg_hi:[0,1]
	v_pk_add_f32 v[32:33], v[18:19], v[30:31]
	v_mov_b32_e32 v27, v18
	v_mov_b32_e32 v29, v33
	v_pk_add_f32 v[34:35], v[26:27], v[28:29] neg_lo:[0,1] neg_hi:[0,1]
	v_pk_add_f32 v[26:27], v[26:27], v[28:29]
	v_mov_b32_e32 v30, v31
	v_pk_add_f32 v[28:29], v[26:27], v[18:19] op_sel:[1,0] op_sel_hi:[0,1] neg_lo:[0,1] neg_hi:[0,1]
	v_pk_add_f32 v[36:37], v[32:33], v[28:29] op_sel_hi:[1,0] neg_lo:[0,1] neg_hi:[0,1]
	v_mov_b32_e32 v32, v33
	v_mov_b32_e32 v33, v27
	v_pk_mov_b32 v[28:29], v[18:19], v[28:29] op_sel:[1,0]
	v_mov_b32_e32 v31, v18
	v_pk_add_f32 v[28:29], v[32:33], v[28:29] neg_lo:[0,1] neg_hi:[0,1]
	v_mov_b32_e32 v36, v34
	v_pk_add_f32 v[18:19], v[30:31], v[28:29] neg_lo:[0,1] neg_hi:[0,1]
	v_mov_b32_e32 v35, v27
	v_pk_add_f32 v[28:29], v[36:37], v[18:19]
	v_cmp_neq_f32_e32 vcc, s27, v25
	v_pk_add_f32 v[30:31], v[28:29], v[28:29] op_sel:[0,1] op_sel_hi:[1,0]
	s_mov_b32 s27, 0x33800000
	v_pk_add_f32 v[26:27], v[26:27], v[30:31] op_sel:[1,0] op_sel_hi:[0,1]
	v_mov_b32_e32 v29, v26
	v_pk_add_f32 v[32:33], v[28:29], v[34:35] neg_lo:[0,1] neg_hi:[0,1]
	v_mov_b32_e32 v19, v30
	v_sub_f32_e32 v27, v28, v32
	v_pk_add_f32 v[18:19], v[18:19], v[32:33] neg_lo:[0,1] neg_hi:[0,1]
	v_sub_f32_e32 v27, v34, v27
	v_add_f32_e32 v18, v18, v27
	v_add_f32_e32 v18, v18, v19
	v_add_f32_e32 v18, v26, v18
	v_cndmask_b32_e32 v18, v237, v18, vcc
	v_cmp_ngt_f32_e32 vcc, -1.0, v25
	s_nop 1
	v_cndmask_b32_e32 v18, v238, v18, vcc
	v_cmp_neq_f32_e32 vcc, -1.0, v25
	s_nop 1
	v_cndmask_b32_e32 v18, v239, v18, vcc
	v_cmp_lt_f32_e64 vcc, |v25|, s27
	s_nop 1
	v_cndmask_b32_e32 v18, v18, v25, vcc
	v_sub_f32_e32 v18, v0, v18

.LBB0_1144:
	s_or_b64 exec, exec, s[4:5]
	v_or_b32_e32 v26, 1, v24
	v_ashrrev_i32_e32 v27, 31, v26
	v_lshlrev_b64 v[26:27], 13, v[26:27]
	v_lshl_add_u64 v[26:27], v[22:23], 0, v[26:27]
	v_readlane_b32 s4, v254, 26
	global_store_dword v[26:27], v18, off
	v_readlane_b32 s5, v254, 27
	s_nop 4
	s_load_dword s4, s[4:5], 0x8
	s_waitcnt lgkmcnt(0)
	v_mov_b32_e32 v0, s4
	v_add_f32_e32 v0, v20, v0
	v_cmp_nlt_f32_e32 vcc, 0, v0
	s_and_saveexec_b64 s[4:5], vcc
	s_xor_b64 s[4:5], exec, s[4:5]
	s_cbranch_execz .LBB0_1146
	v_mul_f32_e32 v18, 0x3fb8aa3b, v0
	v_exp_f32_e32 v20, v18
	s_mov_b32 s27, 0x3f2aaaab
	v_add_f32_e32 v25, 1.0, v20
	v_frexp_mant_f32_e32 v27, v25
	v_cvt_f64_f32_e32 v[18:19], v25
	v_frexp_exp_i32_f64_e32 v18, v[18:19]
	v_cmp_gt_f32_e32 vcc, s27, v27
	v_add_f32_e32 v26, -1.0, v25
	v_sub_f32_e32 v28, v26, v25
	v_subbrev_co_u32_e32 v32, vcc, 0, v18, vcc
	v_sub_u32_e32 v18, 0, v32
	v_sub_f32_e32 v26, v20, v26
	v_add_f32_e32 v28, 1.0, v28
	v_ldexp_f32 v19, v25, v18
	v_add_f32_e32 v26, v26, v28
	v_add_f32_e32 v25, -1.0, v19
	v_add_f32_e32 v27, 1.0, v19
	v_ldexp_f32 v18, v26, v18
	v_add_f32_e32 v26, 1.0, v25
	v_add_f32_e32 v28, -1.0, v27
	v_sub_f32_e32 v26, v19, v26
	v_sub_f32_e32 v19, v19, v28
	v_add_f32_e32 v26, v18, v26
	v_add_f32_e32 v18, v18, v19
	v_add_f32_e32 v33, v27, v18
	v_rcp_f32_e32 v35, v33
	v_sub_f32_e32 v19, v33, v27
	v_sub_f32_e32 v34, v18, v19
	v_add_f32_e32 v19, v25, v26
	v_sub_f32_e32 v18, v19, v25
	v_mul_f32_e32 v36, v19, v35
	v_sub_f32_e32 v25, v26, v18
	v_mul_f32_e32 v26, v33, v36
	v_fma_f32 v28, v36, v33, -v26
	v_fmac_f32_e32 v28, v36, v34
	v_add_f32_e32 v18, v26, v28
	v_sub_f32_e32 v27, v19, v18
	v_pk_add_f32 v[30:31], v[18:19], v[26:27] neg_lo:[0,1] neg_hi:[0,1]
	v_mov_b32_e32 v29, v18
	v_pk_add_f32 v[18:19], v[30:31], v[28:29] neg_lo:[0,1] neg_hi:[0,1]
	s_mov_b32 s27, 0x3f317218
	v_add_f32_e32 v19, v25, v19
	v_add_f32_e32 v18, v18, v19
	v_add_f32_e32 v19, v27, v18
	v_mul_f32_e32 v25, v35, v19
	v_mul_f32_e32 v26, v33, v25
	v_fma_f32 v28, v25, v33, -v26
	v_fmac_f32_e32 v28, v25, v34
	v_sub_f32_e32 v27, v27, v19
	v_add_f32_e32 v33, v18, v27
	v_add_f32_e32 v18, v26, v28
	v_sub_f32_e32 v27, v19, v18
	v_pk_add_f32 v[30:31], v[18:19], v[26:27] neg_lo:[0,1] neg_hi:[0,1]
	v_mov_b32_e32 v29, v18
	v_pk_add_f32 v[18:19], v[30:31], v[28:29] neg_lo:[0,1] neg_hi:[0,1]
	s_nop 0
	v_add_f32_e32 v19, v33, v19
	v_add_f32_e32 v18, v18, v19
	v_add_f32_e32 v19, v36, v25
	v_add_f32_e32 v18, v27, v18
	v_sub_f32_e32 v26, v19, v36
	v_mul_f32_e32 v18, v35, v18
	v_sub_f32_e32 v25, v25, v26
	v_add_f32_e32 v25, v25, v18
	v_add_f32_e32 v26, v19, v25
	v_mul_f32_e32 v28, v26, v26
	v_fmamk_f32 v18, v28, 0x3e9b6dac, v236
	v_fmaak_f32 v205, v28, v18, 0x3f2aaada
	v_cvt_f32_i32_e32 v18, v32
	v_sub_f32_e32 v19, v26, v19
	v_sub_f32_e32 v19, v25, v19
	v_ldexp_f32 v25, v19, 1
	v_mul_f32_e32 v19, v26, v28
	v_pk_mul_f32 v[28:29], v[18:19], v[204:205]
	v_ldexp_f32 v27, v26, 1
	v_fma_f32 v26, v18, s27, -v28
	v_fmac_f32_e32 v26, 0xb102e308, v18
	v_pk_add_f32 v[18:19], v[28:29], v[26:27]
	v_mov_b32_e32 v30, v28
	v_sub_f32_e32 v27, v19, v27
	v_sub_f32_e32 v27, v29, v27
	v_add_f32_e32 v31, v25, v27
	v_pk_add_f32 v[28:29], v[18:19], v[28:29] neg_lo:[0,1] neg_hi:[0,1]
	v_pk_add_f32 v[32:33], v[18:19], v[30:31]
	v_mov_b32_e32 v27, v18
	v_mov_b32_e32 v29, v33
	v_pk_add_f32 v[34:35], v[26:27], v[28:29] neg_lo:[0,1] neg_hi:[0,1]
	v_pk_add_f32 v[26:27], v[26:27], v[28:29]
	v_mov_b32_e32 v30, v31
	v_pk_add_f32 v[28:29], v[26:27], v[18:19] op_sel:[1,0] op_sel_hi:[0,1] neg_lo:[0,1] neg_hi:[0,1]
	v_pk_add_f32 v[36:37], v[32:33], v[28:29] op_sel_hi:[1,0] neg_lo:[0,1] neg_hi:[0,1]
	v_mov_b32_e32 v32, v33
	v_mov_b32_e32 v33, v27
	v_pk_mov_b32 v[28:29], v[18:19], v[28:29] op_sel:[1,0]
	v_mov_b32_e32 v31, v18
	v_pk_add_f32 v[28:29], v[32:33], v[28:29] neg_lo:[0,1] neg_hi:[0,1]
	v_mov_b32_e32 v36, v34
	v_pk_add_f32 v[18:19], v[30:31], v[28:29] neg_lo:[0,1] neg_hi:[0,1]
	v_mov_b32_e32 v35, v27
	v_pk_add_f32 v[28:29], v[36:37], v[18:19]
	s_mov_b32 s27, 0x7f800000
	v_pk_add_f32 v[30:31], v[28:29], v[28:29] op_sel:[0,1] op_sel_hi:[1,0]
	v_cmp_neq_f32_e32 vcc, s27, v20
	v_pk_add_f32 v[26:27], v[26:27], v[30:31] op_sel:[1,0] op_sel_hi:[0,1]
	v_mov_b32_e32 v29, v26
	v_pk_add_f32 v[32:33], v[28:29], v[34:35] neg_lo:[0,1] neg_hi:[0,1]
	v_mov_b32_e32 v19, v30
	v_sub_f32_e32 v25, v28, v32
	v_pk_add_f32 v[18:19], v[18:19], v[32:33] neg_lo:[0,1] neg_hi:[0,1]
	v_sub_f32_e32 v25, v34, v25
	v_add_f32_e32 v18, v18, v25
	v_add_f32_e32 v18, v18, v19
	v_add_f32_e32 v18, v26, v18
	v_cndmask_b32_e32 v18, v237, v18, vcc
	v_cmp_ngt_f32_e32 vcc, -1.0, v20
	s_mov_b32 s27, 0x33800000
	s_nop 0
	v_cndmask_b32_e32 v18, v238, v18, vcc
	v_cmp_neq_f32_e32 vcc, -1.0, v20
	s_nop 1
	v_cndmask_b32_e32 v18, v239, v18, vcc
	v_cmp_lt_f32_e64 vcc, |v20|, s27
	s_nop 1
	v_cndmask_b32_e32 v18, v18, v20, vcc
	v_sub_f32_e32 v18, v0, v18

.LBB0_1148:
	s_or_b64 exec, exec, s[4:5]
	v_or_b32_e32 v26, 2, v24
	v_ashrrev_i32_e32 v27, 31, v26
	v_lshlrev_b64 v[26:27], 13, v[26:27]
	v_lshl_add_u64 v[26:27], v[22:23], 0, v[26:27]
	v_readlane_b32 s4, v254, 26
	global_store_dword v[26:27], v18, off
	v_readlane_b32 s5, v254, 27
	s_nop 4
	s_load_dword s4, s[4:5], 0xc
	s_waitcnt lgkmcnt(0)
	v_mov_b32_e32 v0, s4
	v_add_f32_e32 v0, v21, v0
	v_cmp_nlt_f32_e32 vcc, 0, v0
	s_and_saveexec_b64 s[4:5], vcc
	s_xor_b64 s[4:5], exec, s[4:5]
	s_cbranch_execz .LBB0_1150
	v_mul_f32_e32 v18, 0x3fb8aa3b, v0
	v_exp_f32_e32 v25, v18
	s_mov_b32 s27, 0x3f2aaaab
	v_add_f32_e32 v20, 1.0, v25
	v_frexp_mant_f32_e32 v26, v20
	v_cvt_f64_f32_e32 v[18:19], v20
	v_frexp_exp_i32_f64_e32 v18, v[18:19]
	v_cmp_gt_f32_e32 vcc, s27, v26
	v_add_f32_e32 v21, -1.0, v20
	v_sub_f32_e32 v27, v21, v20
	v_subbrev_co_u32_e32 v30, vcc, 0, v18, vcc
	v_sub_u32_e32 v18, 0, v30
	v_sub_f32_e32 v21, v25, v21
	v_add_f32_e32 v27, 1.0, v27
	v_ldexp_f32 v19, v20, v18
	v_add_f32_e32 v21, v21, v27
	v_add_f32_e32 v20, -1.0, v19
	v_add_f32_e32 v26, 1.0, v19
	v_ldexp_f32 v18, v21, v18
	v_add_f32_e32 v21, 1.0, v20
	v_add_f32_e32 v27, -1.0, v26
	v_sub_f32_e32 v21, v19, v21
	v_sub_f32_e32 v19, v19, v27
	v_add_f32_e32 v21, v18, v21
	v_add_f32_e32 v18, v18, v19
	v_add_f32_e32 v31, v26, v18
	v_rcp_f32_e32 v33, v31
	v_sub_f32_e32 v19, v31, v26
	v_sub_f32_e32 v32, v18, v19
	v_add_f32_e32 v19, v20, v21
	v_mul_f32_e32 v35, v19, v33
	v_sub_f32_e32 v18, v19, v20
	v_mul_f32_e32 v20, v31, v35
	v_fma_f32 v26, v35, v31, -v20
	v_fmac_f32_e32 v26, v35, v32
	v_sub_f32_e32 v34, v21, v18
	v_add_f32_e32 v18, v20, v26
	v_sub_f32_e32 v21, v19, v18
	v_pk_add_f32 v[28:29], v[18:19], v[20:21] neg_lo:[0,1] neg_hi:[0,1]
	v_mov_b32_e32 v27, v18
	v_pk_add_f32 v[18:19], v[28:29], v[26:27] neg_lo:[0,1] neg_hi:[0,1]
	s_mov_b32 s27, 0x3f317218
	v_add_f32_e32 v19, v34, v19
	v_add_f32_e32 v18, v18, v19
	v_add_f32_e32 v19, v21, v18
	v_mul_f32_e32 v34, v33, v19
	v_mul_f32_e32 v20, v31, v34
	v_fma_f32 v26, v34, v31, -v20
	v_fmac_f32_e32 v26, v34, v32
	v_sub_f32_e32 v21, v21, v19
	v_add_f32_e32 v31, v18, v21
	v_add_f32_e32 v18, v20, v26
	v_sub_f32_e32 v21, v19, v18
	v_pk_add_f32 v[28:29], v[18:19], v[20:21] neg_lo:[0,1] neg_hi:[0,1]
	v_mov_b32_e32 v27, v18
	v_pk_add_f32 v[18:19], v[28:29], v[26:27] neg_lo:[0,1] neg_hi:[0,1]
	s_nop 0
	v_add_f32_e32 v19, v31, v19
	v_add_f32_e32 v18, v18, v19
	v_add_f32_e32 v19, v35, v34
	v_add_f32_e32 v18, v21, v18
	v_sub_f32_e32 v20, v19, v35
	v_mul_f32_e32 v18, v33, v18
	v_sub_f32_e32 v20, v34, v20
	v_add_f32_e32 v20, v20, v18
	v_add_f32_e32 v26, v19, v20
	v_mul_f32_e32 v27, v26, v26
	v_fmamk_f32 v18, v27, 0x3e9b6dac, v236
	v_fmaak_f32 v205, v27, v18, 0x3f2aaada
	v_cvt_f32_i32_e32 v18, v30
	v_sub_f32_e32 v19, v26, v19
	v_sub_f32_e32 v19, v20, v19
	v_ldexp_f32 v28, v19, 1
	v_mul_f32_e32 v19, v26, v27
	v_ldexp_f32 v21, v26, 1
	v_pk_mul_f32 v[26:27], v[18:19], v[204:205]
	s_nop 0
	v_fma_f32 v20, v18, s27, -v26
	v_fmac_f32_e32 v20, 0xb102e308, v18
	v_pk_add_f32 v[18:19], v[26:27], v[20:21]
	s_mov_b32 s27, 0x7f800000
	v_sub_f32_e32 v21, v19, v21
	v_sub_f32_e32 v21, v27, v21
	v_add_f32_e32 v29, v28, v21
	v_mov_b32_e32 v28, v26
	v_pk_add_f32 v[26:27], v[18:19], v[26:27] neg_lo:[0,1] neg_hi:[0,1]
	v_pk_add_f32 v[30:31], v[18:19], v[28:29]
	v_mov_b32_e32 v21, v18
	v_mov_b32_e32 v27, v31
	v_pk_add_f32 v[32:33], v[20:21], v[26:27] neg_lo:[0,1] neg_hi:[0,1]
	v_pk_add_f32 v[20:21], v[20:21], v[26:27]
	v_mov_b32_e32 v28, v29
	v_pk_add_f32 v[26:27], v[20:21], v[18:19] op_sel:[1,0] op_sel_hi:[0,1] neg_lo:[0,1] neg_hi:[0,1]
	v_pk_add_f32 v[34:35], v[30:31], v[26:27] op_sel_hi:[1,0] neg_lo:[0,1] neg_hi:[0,1]
	v_mov_b32_e32 v30, v31
	v_mov_b32_e32 v31, v21
	v_pk_mov_b32 v[26:27], v[18:19], v[26:27] op_sel:[1,0]
	v_mov_b32_e32 v29, v18
	v_pk_add_f32 v[26:27], v[30:31], v[26:27] neg_lo:[0,1] neg_hi:[0,1]
	v_mov_b32_e32 v34, v32
	v_pk_add_f32 v[18:19], v[28:29], v[26:27] neg_lo:[0,1] neg_hi:[0,1]
	v_mov_b32_e32 v33, v21
	v_pk_add_f32 v[26:27], v[34:35], v[18:19]
	v_cmp_neq_f32_e32 vcc, s27, v25
	v_pk_add_f32 v[28:29], v[26:27], v[26:27] op_sel:[0,1] op_sel_hi:[1,0]
	s_mov_b32 s27, 0x33800000
	v_pk_add_f32 v[20:21], v[20:21], v[28:29] op_sel:[1,0] op_sel_hi:[0,1]
	v_mov_b32_e32 v27, v20
	v_pk_add_f32 v[30:31], v[26:27], v[32:33] neg_lo:[0,1] neg_hi:[0,1]
	v_mov_b32_e32 v19, v28
	v_sub_f32_e32 v21, v26, v30
	v_pk_add_f32 v[18:19], v[18:19], v[30:31] neg_lo:[0,1] neg_hi:[0,1]
	v_sub_f32_e32 v21, v32, v21
	v_add_f32_e32 v18, v18, v21
	v_add_f32_e32 v18, v18, v19
	v_add_f32_e32 v18, v20, v18
	v_cndmask_b32_e32 v18, v237, v18, vcc
	v_cmp_ngt_f32_e32 vcc, -1.0, v25
	s_nop 1
	v_cndmask_b32_e32 v18, v238, v18, vcc
	v_cmp_neq_f32_e32 vcc, -1.0, v25
	s_nop 1
	v_cndmask_b32_e32 v18, v239, v18, vcc
	v_cmp_lt_f32_e64 vcc, |v25|, s27
	s_nop 1
	v_cndmask_b32_e32 v18, v18, v25, vcc
	v_sub_f32_e32 v18, v0, v18

.LBB0_1175:
	s_and_saveexec_b64 s[4:5], s[10:11]
	s_xor_b64 s[18:19], exec, s[4:5]
	s_cbranch_execz .LBB0_1193
	v_readlane_b32 s4, v254, 26
	v_readlane_b32 s5, v254, 27
	s_nop 4
	s_load_dword s4, s[4:5], 0x0
	s_waitcnt lgkmcnt(0)
	v_mov_b32_e32 v0, s4
	v_add_f32_e32 v0, v10, v0
	v_cmp_nlt_f32_e32 vcc, 0, v0
	s_and_saveexec_b64 s[4:5], vcc
	s_xor_b64 s[4:5], exec, s[4:5]
	s_cbranch_execz .LBB0_1178
	v_mul_f32_e32 v10, 0x3fb8aa3b, v0
	v_exp_f32_e32 v10, v10
	s_mov_b32 s27, 0x3f2aaaab
	v_add_f32_e32 v16, 1.0, v10
	v_frexp_mant_f32_e32 v18, v16
	v_cvt_f64_f32_e32 v[14:15], v16
	v_frexp_exp_i32_f64_e32 v14, v[14:15]
	v_cmp_gt_f32_e32 vcc, s27, v18
	v_add_f32_e32 v17, -1.0, v16
	v_sub_f32_e32 v19, v17, v16
	v_subbrev_co_u32_e32 v22, vcc, 0, v14, vcc
	v_sub_u32_e32 v14, 0, v22
	v_sub_f32_e32 v17, v10, v17
	v_add_f32_e32 v19, 1.0, v19
	v_ldexp_f32 v15, v16, v14
	v_add_f32_e32 v17, v17, v19
	v_add_f32_e32 v16, -1.0, v15
	v_add_f32_e32 v18, 1.0, v15
	v_ldexp_f32 v14, v17, v14
	v_add_f32_e32 v17, 1.0, v16
	v_add_f32_e32 v19, -1.0, v18
	v_sub_f32_e32 v17, v15, v17
	v_sub_f32_e32 v15, v15, v19
	v_add_f32_e32 v17, v14, v17
	v_add_f32_e32 v14, v14, v15
	v_add_f32_e32 v23, v18, v14
	v_rcp_f32_e32 v25, v23
	v_sub_f32_e32 v15, v23, v18
	v_sub_f32_e32 v24, v14, v15
	v_add_f32_e32 v15, v16, v17
	v_mul_f32_e32 v27, v15, v25
	v_sub_f32_e32 v14, v15, v16
	v_mul_f32_e32 v16, v23, v27
	v_fma_f32 v18, v27, v23, -v16
	v_fmac_f32_e32 v18, v27, v24
	v_sub_f32_e32 v26, v17, v14
	v_add_f32_e32 v14, v16, v18
	v_sub_f32_e32 v17, v15, v14
	v_pk_add_f32 v[20:21], v[14:15], v[16:17] neg_lo:[0,1] neg_hi:[0,1]
	v_mov_b32_e32 v19, v14
	v_pk_add_f32 v[14:15], v[20:21], v[18:19] neg_lo:[0,1] neg_hi:[0,1]
	s_mov_b32 s27, 0x3f317218
	v_add_f32_e32 v15, v26, v15
	v_add_f32_e32 v14, v14, v15
	v_add_f32_e32 v15, v17, v14
	v_mul_f32_e32 v26, v25, v15
	v_mul_f32_e32 v16, v23, v26
	v_fma_f32 v18, v26, v23, -v16
	v_fmac_f32_e32 v18, v26, v24
	v_sub_f32_e32 v17, v17, v15
	v_add_f32_e32 v23, v14, v17
	v_add_f32_e32 v14, v16, v18
	v_sub_f32_e32 v17, v15, v14
	v_pk_add_f32 v[20:21], v[14:15], v[16:17] neg_lo:[0,1] neg_hi:[0,1]
	v_mov_b32_e32 v19, v14
	v_pk_add_f32 v[14:15], v[20:21], v[18:19] neg_lo:[0,1] neg_hi:[0,1]
	s_nop 0
	v_add_f32_e32 v15, v23, v15
	v_add_f32_e32 v14, v14, v15
	v_add_f32_e32 v15, v27, v26
	v_add_f32_e32 v14, v17, v14
	v_sub_f32_e32 v16, v15, v27
	v_mul_f32_e32 v14, v25, v14
	v_sub_f32_e32 v16, v26, v16
	v_add_f32_e32 v16, v16, v14
	v_add_f32_e32 v18, v15, v16
	v_mul_f32_e32 v19, v18, v18
	v_fmamk_f32 v14, v19, 0x3e9b6dac, v236
	v_fmaak_f32 v205, v19, v14, 0x3f2aaada
	v_cvt_f32_i32_e32 v14, v22
	v_sub_f32_e32 v15, v18, v15
	v_sub_f32_e32 v15, v16, v15
	v_ldexp_f32 v20, v15, 1
	v_mul_f32_e32 v15, v18, v19
	v_ldexp_f32 v17, v18, 1
	v_pk_mul_f32 v[18:19], v[14:15], v[204:205]
	s_nop 0
	v_fma_f32 v16, v14, s27, -v18
	v_fmac_f32_e32 v16, 0xb102e308, v14
	v_pk_add_f32 v[14:15], v[18:19], v[16:17]
	s_mov_b32 s27, 0x7f800000
	v_sub_f32_e32 v17, v15, v17
	v_sub_f32_e32 v17, v19, v17
	v_add_f32_e32 v21, v20, v17
	v_mov_b32_e32 v20, v18
	v_pk_add_f32 v[18:19], v[14:15], v[18:19] neg_lo:[0,1] neg_hi:[0,1]
	v_pk_add_f32 v[22:23], v[14:15], v[20:21]
	v_mov_b32_e32 v17, v14
	v_mov_b32_e32 v19, v23
	v_pk_add_f32 v[24:25], v[16:17], v[18:19] neg_lo:[0,1] neg_hi:[0,1]
	v_pk_add_f32 v[16:17], v[16:17], v[18:19]
	v_mov_b32_e32 v20, v21
	v_pk_add_f32 v[18:19], v[16:17], v[14:15] op_sel:[1,0] op_sel_hi:[0,1] neg_lo:[0,1] neg_hi:[0,1]
	v_pk_add_f32 v[26:27], v[22:23], v[18:19] op_sel_hi:[1,0] neg_lo:[0,1] neg_hi:[0,1]
	v_mov_b32_e32 v22, v23
	v_mov_b32_e32 v23, v17
	v_pk_mov_b32 v[18:19], v[14:15], v[18:19] op_sel:[1,0]
	v_mov_b32_e32 v21, v14
	v_pk_add_f32 v[18:19], v[22:23], v[18:19] neg_lo:[0,1] neg_hi:[0,1]
	v_mov_b32_e32 v26, v24
	v_pk_add_f32 v[14:15], v[20:21], v[18:19] neg_lo:[0,1] neg_hi:[0,1]
	v_mov_b32_e32 v25, v17
	v_pk_add_f32 v[18:19], v[26:27], v[14:15]
	v_cmp_neq_f32_e32 vcc, s27, v10
	v_pk_add_f32 v[20:21], v[18:19], v[18:19] op_sel:[0,1] op_sel_hi:[1,0]
	s_mov_b32 s27, 0x33800000
	v_pk_add_f32 v[16:17], v[16:17], v[20:21] op_sel:[1,0] op_sel_hi:[0,1]
	v_mov_b32_e32 v19, v16
	v_pk_add_f32 v[22:23], v[18:19], v[24:25] neg_lo:[0,1] neg_hi:[0,1]
	v_mov_b32_e32 v15, v20
	v_sub_f32_e32 v17, v18, v22
	v_pk_add_f32 v[14:15], v[14:15], v[22:23] neg_lo:[0,1] neg_hi:[0,1]
	v_sub_f32_e32 v17, v24, v17
	v_add_f32_e32 v14, v14, v17
	v_add_f32_e32 v14, v14, v15
	v_add_f32_e32 v14, v16, v14
	v_cndmask_b32_e32 v14, v237, v14, vcc
	v_cmp_ngt_f32_e32 vcc, -1.0, v10
	s_nop 1
	v_cndmask_b32_e32 v14, v238, v14, vcc
	v_cmp_neq_f32_e32 vcc, -1.0, v10
	s_nop 1
	v_cndmask_b32_e32 v14, v239, v14, vcc
	v_cmp_lt_f32_e64 vcc, |v10|, s27
	s_nop 1
	v_cndmask_b32_e32 v10, v14, v10, vcc
	v_sub_f32_e32 v10, v0, v10

.LBB0_1180:
	s_or_b64 exec, exec, s[4:5]
	v_lshlrev_b32_e32 v16, 2, v29
	v_lshlrev_b32_e32 v0, 2, v30
	v_ashrrev_i32_e32 v17, 31, v16
	v_lshl_add_u64 v[14:15], s[84:85], 0, v[0:1]
	v_lshlrev_b64 v[18:19], 13, v[16:17]
	v_lshl_add_u64 v[18:19], v[14:15], 0, v[18:19]
	v_readlane_b32 s4, v254, 26
	global_store_dword v[18:19], v10, off
	v_readlane_b32 s5, v254, 27
	s_nop 4
	s_load_dword s4, s[4:5], 0x4
	s_waitcnt lgkmcnt(0)
	v_mov_b32_e32 v0, s4
	v_add_f32_e32 v0, v11, v0
	v_cmp_nlt_f32_e32 vcc, 0, v0
	s_and_saveexec_b64 s[4:5], vcc
	s_xor_b64 s[4:5], exec, s[4:5]
	s_cbranch_execz .LBB0_1182
	v_mul_f32_e32 v10, 0x3fb8aa3b, v0
	v_exp_f32_e32 v17, v10
	s_mov_b32 s27, 0x3f2aaaab
	v_add_f32_e32 v18, 1.0, v17
	v_frexp_mant_f32_e32 v20, v18
	v_cvt_f64_f32_e32 v[10:11], v18
	v_frexp_exp_i32_f64_e32 v10, v[10:11]
	v_cmp_gt_f32_e32 vcc, s27, v20
	v_add_f32_e32 v19, -1.0, v18
	v_sub_f32_e32 v21, v19, v18
	v_subbrev_co_u32_e32 v24, vcc, 0, v10, vcc
	v_sub_u32_e32 v10, 0, v24
	v_sub_f32_e32 v19, v17, v19
	v_add_f32_e32 v21, 1.0, v21
	v_ldexp_f32 v11, v18, v10
	v_add_f32_e32 v19, v19, v21
	v_add_f32_e32 v18, -1.0, v11
	v_add_f32_e32 v20, 1.0, v11
	v_ldexp_f32 v10, v19, v10
	v_add_f32_e32 v19, 1.0, v18
	v_add_f32_e32 v21, -1.0, v20
	v_sub_f32_e32 v19, v11, v19
	v_sub_f32_e32 v11, v11, v21
	v_add_f32_e32 v19, v10, v19
	v_add_f32_e32 v10, v10, v11
	v_add_f32_e32 v25, v20, v10
	v_rcp_f32_e32 v27, v25
	v_sub_f32_e32 v11, v25, v20
	v_sub_f32_e32 v26, v10, v11
	v_add_f32_e32 v11, v18, v19
	v_mul_f32_e32 v29, v11, v27
	v_sub_f32_e32 v10, v11, v18
	v_mul_f32_e32 v18, v25, v29
	v_fma_f32 v20, v29, v25, -v18
	v_fmac_f32_e32 v20, v29, v26
	v_sub_f32_e32 v28, v19, v10
	v_add_f32_e32 v10, v18, v20
	v_sub_f32_e32 v19, v11, v10
	v_pk_add_f32 v[22:23], v[10:11], v[18:19] neg_lo:[0,1] neg_hi:[0,1]
	v_mov_b32_e32 v21, v10
	v_pk_add_f32 v[10:11], v[22:23], v[20:21] neg_lo:[0,1] neg_hi:[0,1]
	s_mov_b32 s27, 0x3f317218
	v_add_f32_e32 v11, v28, v11
	v_add_f32_e32 v10, v10, v11
	v_add_f32_e32 v11, v19, v10
	v_mul_f32_e32 v28, v27, v11
	v_mul_f32_e32 v18, v25, v28
	v_fma_f32 v20, v28, v25, -v18
	v_fmac_f32_e32 v20, v28, v26
	v_sub_f32_e32 v19, v19, v11
	v_add_f32_e32 v25, v10, v19
	v_add_f32_e32 v10, v18, v20
	v_sub_f32_e32 v19, v11, v10
	v_pk_add_f32 v[22:23], v[10:11], v[18:19] neg_lo:[0,1] neg_hi:[0,1]
	v_mov_b32_e32 v21, v10
	v_pk_add_f32 v[10:11], v[22:23], v[20:21] neg_lo:[0,1] neg_hi:[0,1]
	s_nop 0
	v_add_f32_e32 v11, v25, v11
	v_add_f32_e32 v10, v10, v11
	v_add_f32_e32 v11, v29, v28
	v_add_f32_e32 v10, v19, v10
	v_sub_f32_e32 v18, v11, v29
	v_mul_f32_e32 v10, v27, v10
	v_sub_f32_e32 v18, v28, v18
	v_add_f32_e32 v18, v18, v10
	v_add_f32_e32 v20, v11, v18
	v_mul_f32_e32 v21, v20, v20
	v_fmamk_f32 v10, v21, 0x3e9b6dac, v236
	v_fmaak_f32 v205, v21, v10, 0x3f2aaada
	v_cvt_f32_i32_e32 v10, v24
	v_sub_f32_e32 v11, v20, v11
	v_sub_f32_e32 v11, v18, v11
	v_ldexp_f32 v22, v11, 1
	v_mul_f32_e32 v11, v20, v21
	v_ldexp_f32 v19, v20, 1
	v_pk_mul_f32 v[20:21], v[10:11], v[204:205]
	s_nop 0
	v_fma_f32 v18, v10, s27, -v20
	v_fmac_f32_e32 v18, 0xb102e308, v10
	v_pk_add_f32 v[10:11], v[20:21], v[18:19]
	s_mov_b32 s27, 0x7f800000
	v_sub_f32_e32 v19, v11, v19
	v_sub_f32_e32 v19, v21, v19
	v_add_f32_e32 v23, v22, v19
	v_mov_b32_e32 v22, v20
	v_pk_add_f32 v[20:21], v[10:11], v[20:21] neg_lo:[0,1] neg_hi:[0,1]
	v_pk_add_f32 v[24:25], v[10:11], v[22:23]
	v_mov_b32_e32 v19, v10
	v_mov_b32_e32 v21, v25
	v_pk_add_f32 v[26:27], v[18:19], v[20:21] neg_lo:[0,1] neg_hi:[0,1]
	v_pk_add_f32 v[18:19], v[18:19], v[20:21]
	v_mov_b32_e32 v22, v23
	v_pk_add_f32 v[20:21], v[18:19], v[10:11] op_sel:[1,0] op_sel_hi:[0,1] neg_lo:[0,1] neg_hi:[0,1]
	v_pk_add_f32 v[28:29], v[24:25], v[20:21] op_sel_hi:[1,0] neg_lo:[0,1] neg_hi:[0,1]
	v_mov_b32_e32 v24, v25
	v_mov_b32_e32 v25, v19
	v_pk_mov_b32 v[20:21], v[10:11], v[20:21] op_sel:[1,0]
	v_mov_b32_e32 v23, v10
	v_pk_add_f32 v[20:21], v[24:25], v[20:21] neg_lo:[0,1] neg_hi:[0,1]
	v_mov_b32_e32 v28, v26
	v_pk_add_f32 v[10:11], v[22:23], v[20:21] neg_lo:[0,1] neg_hi:[0,1]
	v_mov_b32_e32 v27, v19
	v_pk_add_f32 v[20:21], v[28:29], v[10:11]
	v_cmp_neq_f32_e32 vcc, s27, v17
	v_pk_add_f32 v[22:23], v[20:21], v[20:21] op_sel:[0,1] op_sel_hi:[1,0]
	s_mov_b32 s27, 0x33800000
	v_pk_add_f32 v[18:19], v[18:19], v[22:23] op_sel:[1,0] op_sel_hi:[0,1]
	v_mov_b32_e32 v21, v18
	v_pk_add_f32 v[24:25], v[20:21], v[26:27] neg_lo:[0,1] neg_hi:[0,1]
	v_mov_b32_e32 v11, v22
	v_sub_f32_e32 v19, v20, v24
	v_pk_add_f32 v[10:11], v[10:11], v[24:25] neg_lo:[0,1] neg_hi:[0,1]
	v_sub_f32_e32 v19, v26, v19
	v_add_f32_e32 v10, v10, v19
	v_add_f32_e32 v10, v10, v11
	v_add_f32_e32 v10, v18, v10
	v_cndmask_b32_e32 v10, v237, v10, vcc
	v_cmp_ngt_f32_e32 vcc, -1.0, v17
	s_nop 1
	v_cndmask_b32_e32 v10, v238, v10, vcc
	v_cmp_neq_f32_e32 vcc, -1.0, v17
	s_nop 1
	v_cndmask_b32_e32 v10, v239, v10, vcc
	v_cmp_lt_f32_e64 vcc, |v17|, s27
	s_nop 1
	v_cndmask_b32_e32 v10, v10, v17, vcc
	v_sub_f32_e32 v10, v0, v10

.LBB0_1184:
	s_or_b64 exec, exec, s[4:5]
	v_or_b32_e32 v18, 1, v16
	v_ashrrev_i32_e32 v19, 31, v18
	v_lshlrev_b64 v[18:19], 13, v[18:19]
	v_lshl_add_u64 v[18:19], v[14:15], 0, v[18:19]
	v_readlane_b32 s4, v254, 26
	global_store_dword v[18:19], v10, off
	v_readlane_b32 s5, v254, 27
	s_nop 4
	s_load_dword s4, s[4:5], 0x8
	s_waitcnt lgkmcnt(0)
	v_mov_b32_e32 v0, s4
	v_add_f32_e32 v0, v12, v0
	v_cmp_nlt_f32_e32 vcc, 0, v0
	s_and_saveexec_b64 s[4:5], vcc
	s_xor_b64 s[4:5], exec, s[4:5]
	s_cbranch_execz .LBB0_1186
	v_mul_f32_e32 v10, 0x3fb8aa3b, v0
	v_exp_f32_e32 v12, v10
	s_mov_b32 s27, 0x3f2aaaab
	v_add_f32_e32 v17, 1.0, v12
	v_frexp_mant_f32_e32 v19, v17
	v_cvt_f64_f32_e32 v[10:11], v17
	v_frexp_exp_i32_f64_e32 v10, v[10:11]
	v_cmp_gt_f32_e32 vcc, s27, v19
	v_add_f32_e32 v18, -1.0, v17
	v_sub_f32_e32 v20, v18, v17
	v_subbrev_co_u32_e32 v24, vcc, 0, v10, vcc
	v_sub_u32_e32 v10, 0, v24
	v_sub_f32_e32 v18, v12, v18
	v_add_f32_e32 v20, 1.0, v20
	v_ldexp_f32 v11, v17, v10
	v_add_f32_e32 v18, v18, v20
	v_add_f32_e32 v17, -1.0, v11
	v_add_f32_e32 v19, 1.0, v11
	v_ldexp_f32 v10, v18, v10
	v_add_f32_e32 v18, 1.0, v17
	v_add_f32_e32 v20, -1.0, v19
	v_sub_f32_e32 v18, v11, v18
	v_sub_f32_e32 v11, v11, v20
	v_add_f32_e32 v18, v10, v18
	v_add_f32_e32 v10, v10, v11
	v_add_f32_e32 v25, v19, v10
	v_rcp_f32_e32 v27, v25
	v_sub_f32_e32 v11, v25, v19
	v_sub_f32_e32 v26, v10, v11
	v_add_f32_e32 v11, v17, v18
	v_sub_f32_e32 v10, v11, v17
	v_mul_f32_e32 v28, v11, v27
	v_sub_f32_e32 v17, v18, v10
	v_mul_f32_e32 v18, v25, v28
	v_fma_f32 v20, v28, v25, -v18
	v_fmac_f32_e32 v20, v28, v26
	v_add_f32_e32 v10, v18, v20
	v_sub_f32_e32 v19, v11, v10
	v_pk_add_f32 v[22:23], v[10:11], v[18:19] neg_lo:[0,1] neg_hi:[0,1]
	v_mov_b32_e32 v21, v10
	v_pk_add_f32 v[10:11], v[22:23], v[20:21] neg_lo:[0,1] neg_hi:[0,1]
	s_mov_b32 s27, 0x3f317218
	v_add_f32_e32 v11, v17, v11
	v_add_f32_e32 v10, v10, v11
	v_add_f32_e32 v11, v19, v10
	v_mul_f32_e32 v17, v27, v11
	v_mul_f32_e32 v18, v25, v17
	v_fma_f32 v20, v17, v25, -v18
	v_fmac_f32_e32 v20, v17, v26
	v_sub_f32_e32 v19, v19, v11
	v_add_f32_e32 v25, v10, v19
	v_add_f32_e32 v10, v18, v20
	v_sub_f32_e32 v19, v11, v10
	v_pk_add_f32 v[22:23], v[10:11], v[18:19] neg_lo:[0,1] neg_hi:[0,1]
	v_mov_b32_e32 v21, v10
	v_pk_add_f32 v[10:11], v[22:23], v[20:21] neg_lo:[0,1] neg_hi:[0,1]
	s_nop 0
	v_add_f32_e32 v11, v25, v11
	v_add_f32_e32 v10, v10, v11
	v_add_f32_e32 v11, v28, v17
	v_add_f32_e32 v10, v19, v10
	v_sub_f32_e32 v18, v11, v28
	v_mul_f32_e32 v10, v27, v10
	v_sub_f32_e32 v17, v17, v18
	v_add_f32_e32 v17, v17, v10
	v_add_f32_e32 v18, v11, v17
	v_mul_f32_e32 v20, v18, v18
	v_fmamk_f32 v10, v20, 0x3e9b6dac, v236
	v_fmaak_f32 v205, v20, v10, 0x3f2aaada
	v_cvt_f32_i32_e32 v10, v24
	v_sub_f32_e32 v11, v18, v11
	v_sub_f32_e32 v11, v17, v11
	v_ldexp_f32 v17, v11, 1
	v_mul_f32_e32 v11, v18, v20
	v_pk_mul_f32 v[20:21], v[10:11], v[204:205]
	v_ldexp_f32 v19, v18, 1
	v_fma_f32 v18, v10, s27, -v20
	v_fmac_f32_e32 v18, 0xb102e308, v10
	v_pk_add_f32 v[10:11], v[20:21], v[18:19]
	v_mov_b32_e32 v22, v20
	v_sub_f32_e32 v19, v11, v19
	v_sub_f32_e32 v19, v21, v19
	v_add_f32_e32 v23, v17, v19
	v_pk_add_f32 v[20:21], v[10:11], v[20:21] neg_lo:[0,1] neg_hi:[0,1]
	v_pk_add_f32 v[24:25], v[10:11], v[22:23]
	v_mov_b32_e32 v19, v10
	v_mov_b32_e32 v21, v25
	v_pk_add_f32 v[26:27], v[18:19], v[20:21] neg_lo:[0,1] neg_hi:[0,1]
	v_pk_add_f32 v[18:19], v[18:19], v[20:21]
	v_mov_b32_e32 v22, v23
	v_pk_add_f32 v[20:21], v[18:19], v[10:11] op_sel:[1,0] op_sel_hi:[0,1] neg_lo:[0,1] neg_hi:[0,1]
	v_pk_add_f32 v[28:29], v[24:25], v[20:21] op_sel_hi:[1,0] neg_lo:[0,1] neg_hi:[0,1]
	v_mov_b32_e32 v24, v25
	v_mov_b32_e32 v25, v19
	v_pk_mov_b32 v[20:21], v[10:11], v[20:21] op_sel:[1,0]
	v_mov_b32_e32 v23, v10
	v_pk_add_f32 v[20:21], v[24:25], v[20:21] neg_lo:[0,1] neg_hi:[0,1]
	v_mov_b32_e32 v28, v26
	v_pk_add_f32 v[10:11], v[22:23], v[20:21] neg_lo:[0,1] neg_hi:[0,1]
	v_mov_b32_e32 v27, v19
	v_pk_add_f32 v[20:21], v[28:29], v[10:11]
	s_mov_b32 s27, 0x7f800000
	v_pk_add_f32 v[22:23], v[20:21], v[20:21] op_sel:[0,1] op_sel_hi:[1,0]
	v_cmp_neq_f32_e32 vcc, s27, v12
	v_pk_add_f32 v[18:19], v[18:19], v[22:23] op_sel:[1,0] op_sel_hi:[0,1]
	v_mov_b32_e32 v21, v18
	v_pk_add_f32 v[24:25], v[20:21], v[26:27] neg_lo:[0,1] neg_hi:[0,1]
	v_mov_b32_e32 v11, v22
	v_sub_f32_e32 v17, v20, v24
	v_pk_add_f32 v[10:11], v[10:11], v[24:25] neg_lo:[0,1] neg_hi:[0,1]
	v_sub_f32_e32 v17, v26, v17
	v_add_f32_e32 v10, v10, v17
	v_add_f32_e32 v10, v10, v11
	v_add_f32_e32 v10, v18, v10
	v_cndmask_b32_e32 v10, v237, v10, vcc
	v_cmp_ngt_f32_e32 vcc, -1.0, v12
	s_mov_b32 s27, 0x33800000
	s_nop 0
	v_cndmask_b32_e32 v10, v238, v10, vcc
	v_cmp_neq_f32_e32 vcc, -1.0, v12
	s_nop 1
	v_cndmask_b32_e32 v10, v239, v10, vcc
	v_cmp_lt_f32_e64 vcc, |v12|, s27
	s_nop 1
	v_cndmask_b32_e32 v10, v10, v12, vcc
	v_sub_f32_e32 v10, v0, v10

.LBB0_1188:
	s_or_b64 exec, exec, s[4:5]
	v_or_b32_e32 v18, 2, v16
	v_ashrrev_i32_e32 v19, 31, v18
	v_lshlrev_b64 v[18:19], 13, v[18:19]
	v_lshl_add_u64 v[18:19], v[14:15], 0, v[18:19]
	v_readlane_b32 s4, v254, 26
	global_store_dword v[18:19], v10, off
	v_readlane_b32 s5, v254, 27
	s_nop 4
	s_load_dword s4, s[4:5], 0xc
	s_waitcnt lgkmcnt(0)
	v_mov_b32_e32 v0, s4
	v_add_f32_e32 v0, v13, v0
	v_cmp_nlt_f32_e32 vcc, 0, v0
	s_and_saveexec_b64 s[4:5], vcc
	s_xor_b64 s[4:5], exec, s[4:5]
	s_cbranch_execz .LBB0_1190
	v_mul_f32_e32 v10, 0x3fb8aa3b, v0
	v_exp_f32_e32 v17, v10
	s_mov_b32 s27, 0x3f2aaaab
	v_add_f32_e32 v12, 1.0, v17
	v_frexp_mant_f32_e32 v18, v12
	v_cvt_f64_f32_e32 v[10:11], v12
	v_frexp_exp_i32_f64_e32 v10, v[10:11]
	v_cmp_gt_f32_e32 vcc, s27, v18
	v_add_f32_e32 v13, -1.0, v12
	v_sub_f32_e32 v19, v13, v12
	v_subbrev_co_u32_e32 v22, vcc, 0, v10, vcc
	v_sub_u32_e32 v10, 0, v22
	v_sub_f32_e32 v13, v17, v13
	v_add_f32_e32 v19, 1.0, v19
	v_ldexp_f32 v11, v12, v10
	v_add_f32_e32 v13, v13, v19
	v_add_f32_e32 v12, -1.0, v11
	v_add_f32_e32 v18, 1.0, v11
	v_ldexp_f32 v10, v13, v10
	v_add_f32_e32 v13, 1.0, v12
	v_add_f32_e32 v19, -1.0, v18
	v_sub_f32_e32 v13, v11, v13
	v_sub_f32_e32 v11, v11, v19
	v_add_f32_e32 v13, v10, v13
	v_add_f32_e32 v10, v10, v11
	v_add_f32_e32 v23, v18, v10
	v_rcp_f32_e32 v25, v23
	v_sub_f32_e32 v11, v23, v18
	v_sub_f32_e32 v24, v10, v11
	v_add_f32_e32 v11, v12, v13
	v_mul_f32_e32 v27, v11, v25
	v_sub_f32_e32 v10, v11, v12
	v_mul_f32_e32 v12, v23, v27
	v_fma_f32 v18, v27, v23, -v12
	v_fmac_f32_e32 v18, v27, v24
	v_sub_f32_e32 v26, v13, v10
	v_add_f32_e32 v10, v12, v18
	v_sub_f32_e32 v13, v11, v10
	v_pk_add_f32 v[20:21], v[10:11], v[12:13] neg_lo:[0,1] neg_hi:[0,1]
	v_mov_b32_e32 v19, v10
	v_pk_add_f32 v[10:11], v[20:21], v[18:19] neg_lo:[0,1] neg_hi:[0,1]
	s_mov_b32 s27, 0x3f317218
	v_add_f32_e32 v11, v26, v11
	v_add_f32_e32 v10, v10, v11
	v_add_f32_e32 v11, v13, v10
	v_mul_f32_e32 v26, v25, v11
	v_mul_f32_e32 v12, v23, v26
	v_fma_f32 v18, v26, v23, -v12
	v_fmac_f32_e32 v18, v26, v24
	v_sub_f32_e32 v13, v13, v11
	v_add_f32_e32 v23, v10, v13
	v_add_f32_e32 v10, v12, v18
	v_sub_f32_e32 v13, v11, v10
	v_pk_add_f32 v[20:21], v[10:11], v[12:13] neg_lo:[0,1] neg_hi:[0,1]
	v_mov_b32_e32 v19, v10
	v_pk_add_f32 v[10:11], v[20:21], v[18:19] neg_lo:[0,1] neg_hi:[0,1]
	s_nop 0
	v_add_f32_e32 v11, v23, v11
	v_add_f32_e32 v10, v10, v11
	v_add_f32_e32 v11, v27, v26
	v_add_f32_e32 v10, v13, v10
	v_sub_f32_e32 v12, v11, v27
	v_mul_f32_e32 v10, v25, v10
	v_sub_f32_e32 v12, v26, v12
	v_add_f32_e32 v12, v12, v10
	v_add_f32_e32 v18, v11, v12
	v_mul_f32_e32 v19, v18, v18
	v_fmamk_f32 v10, v19, 0x3e9b6dac, v236
	v_fmaak_f32 v205, v19, v10, 0x3f2aaada
	v_cvt_f32_i32_e32 v10, v22
	v_sub_f32_e32 v11, v18, v11
	v_sub_f32_e32 v11, v12, v11
	v_ldexp_f32 v20, v11, 1
	v_mul_f32_e32 v11, v18, v19
	v_ldexp_f32 v13, v18, 1
	v_pk_mul_f32 v[18:19], v[10:11], v[204:205]
	s_nop 0
	v_fma_f32 v12, v10, s27, -v18
	v_fmac_f32_e32 v12, 0xb102e308, v10
	v_pk_add_f32 v[10:11], v[18:19], v[12:13]
	s_mov_b32 s27, 0x7f800000
	v_sub_f32_e32 v13, v11, v13
	v_sub_f32_e32 v13, v19, v13
	v_add_f32_e32 v21, v20, v13
	v_mov_b32_e32 v20, v18
	v_pk_add_f32 v[18:19], v[10:11], v[18:19] neg_lo:[0,1] neg_hi:[0,1]
	v_pk_add_f32 v[22:23], v[10:11], v[20:21]
	v_mov_b32_e32 v13, v10
	v_mov_b32_e32 v19, v23
	v_pk_add_f32 v[24:25], v[12:13], v[18:19] neg_lo:[0,1] neg_hi:[0,1]
	v_pk_add_f32 v[12:13], v[12:13], v[18:19]
	v_mov_b32_e32 v20, v21
	v_pk_add_f32 v[18:19], v[12:13], v[10:11] op_sel:[1,0] op_sel_hi:[0,1] neg_lo:[0,1] neg_hi:[0,1]
	v_pk_add_f32 v[26:27], v[22:23], v[18:19] op_sel_hi:[1,0] neg_lo:[0,1] neg_hi:[0,1]
	v_mov_b32_e32 v22, v23
	v_mov_b32_e32 v23, v13
	v_pk_mov_b32 v[18:19], v[10:11], v[18:19] op_sel:[1,0]
	v_mov_b32_e32 v21, v10
	v_pk_add_f32 v[18:19], v[22:23], v[18:19] neg_lo:[0,1] neg_hi:[0,1]
	v_mov_b32_e32 v26, v24
	v_pk_add_f32 v[10:11], v[20:21], v[18:19] neg_lo:[0,1] neg_hi:[0,1]
	v_mov_b32_e32 v25, v13
	v_pk_add_f32 v[18:19], v[26:27], v[10:11]
	v_cmp_neq_f32_e32 vcc, s27, v17
	v_pk_add_f32 v[20:21], v[18:19], v[18:19] op_sel:[0,1] op_sel_hi:[1,0]
	s_mov_b32 s27, 0x33800000
	v_pk_add_f32 v[12:13], v[12:13], v[20:21] op_sel:[1,0] op_sel_hi:[0,1]
	v_mov_b32_e32 v19, v12
	v_pk_add_f32 v[22:23], v[18:19], v[24:25] neg_lo:[0,1] neg_hi:[0,1]
	v_mov_b32_e32 v11, v20
	v_sub_f32_e32 v13, v18, v22
	v_pk_add_f32 v[10:11], v[10:11], v[22:23] neg_lo:[0,1] neg_hi:[0,1]
	v_sub_f32_e32 v13, v24, v13
	v_add_f32_e32 v10, v10, v13
	v_add_f32_e32 v10, v10, v11
	v_add_f32_e32 v10, v12, v10
	v_cndmask_b32_e32 v10, v237, v10, vcc
	v_cmp_ngt_f32_e32 vcc, -1.0, v17
	s_nop 1
	v_cndmask_b32_e32 v10, v238, v10, vcc
	v_cmp_neq_f32_e32 vcc, -1.0, v17
	s_nop 1
	v_cndmask_b32_e32 v10, v239, v10, vcc
	v_cmp_lt_f32_e64 vcc, |v17|, s27
	s_nop 1
	v_cndmask_b32_e32 v10, v10, v17, vcc
	v_sub_f32_e32 v10, v0, v10

.LBB0_1213:
	s_andn2_b64 vcc, exec, s[4:5]
	s_cbranch_vccnz .LBB0_1235
	s_and_saveexec_b64 s[0:1], s[10:11]
	s_xor_b64 s[0:1], exec, s[0:1]
	s_cbranch_execz .LBB0_1232
	v_readlane_b32 s4, v254, 26
	v_readlane_b32 s5, v254, 27
	s_nop 4
	s_load_dword s4, s[4:5], 0x0
	s_waitcnt lgkmcnt(0)
	v_mov_b32_e32 v0, s4
	v_add_f32_e32 v0, v2, v0
	v_cmp_nlt_f32_e32 vcc, 0, v0
	s_and_saveexec_b64 s[4:5], vcc
	s_xor_b64 s[4:5], exec, s[4:5]
	s_cbranch_execz .LBB0_1217
	v_mul_f32_e32 v2, 0x3fb8aa3b, v0
	v_exp_f32_e32 v2, v2
	s_mov_b32 s8, 0x3f2aaaab
	v_add_f32_e32 v8, 1.0, v2
	v_frexp_mant_f32_e32 v10, v8
	v_cvt_f64_f32_e32 v[6:7], v8
	v_frexp_exp_i32_f64_e32 v6, v[6:7]
	v_cmp_gt_f32_e32 vcc, s8, v10
	v_add_f32_e32 v9, -1.0, v8
	v_sub_f32_e32 v11, v9, v8
	v_subbrev_co_u32_e32 v14, vcc, 0, v6, vcc
	v_sub_u32_e32 v6, 0, v14
	v_sub_f32_e32 v9, v2, v9
	v_add_f32_e32 v11, 1.0, v11
	v_ldexp_f32 v7, v8, v6
	v_add_f32_e32 v9, v9, v11
	v_add_f32_e32 v8, -1.0, v7
	v_add_f32_e32 v10, 1.0, v7
	v_ldexp_f32 v6, v9, v6
	v_add_f32_e32 v9, 1.0, v8
	v_add_f32_e32 v11, -1.0, v10
	v_sub_f32_e32 v9, v7, v9
	v_sub_f32_e32 v7, v7, v11
	v_add_f32_e32 v9, v6, v9
	v_add_f32_e32 v6, v6, v7
	v_add_f32_e32 v15, v10, v6
	v_rcp_f32_e32 v17, v15
	v_sub_f32_e32 v7, v15, v10
	v_sub_f32_e32 v16, v6, v7
	v_add_f32_e32 v7, v8, v9
	v_mul_f32_e32 v19, v7, v17
	v_sub_f32_e32 v6, v7, v8
	v_mul_f32_e32 v8, v15, v19
	v_fma_f32 v10, v19, v15, -v8
	v_fmac_f32_e32 v10, v19, v16
	v_sub_f32_e32 v18, v9, v6
	v_add_f32_e32 v6, v8, v10
	v_sub_f32_e32 v9, v7, v6
	v_pk_add_f32 v[12:13], v[6:7], v[8:9] neg_lo:[0,1] neg_hi:[0,1]
	v_mov_b32_e32 v11, v6
	v_pk_add_f32 v[6:7], v[12:13], v[10:11] neg_lo:[0,1] neg_hi:[0,1]
	s_mov_b32 s8, 0x3f317218
	v_add_f32_e32 v7, v18, v7
	v_add_f32_e32 v6, v6, v7
	v_add_f32_e32 v7, v9, v6
	v_mul_f32_e32 v18, v17, v7
	v_mul_f32_e32 v8, v15, v18
	v_fma_f32 v10, v18, v15, -v8
	v_fmac_f32_e32 v10, v18, v16
	v_sub_f32_e32 v9, v9, v7
	v_add_f32_e32 v15, v6, v9
	v_add_f32_e32 v6, v8, v10
	v_sub_f32_e32 v9, v7, v6
	v_pk_add_f32 v[12:13], v[6:7], v[8:9] neg_lo:[0,1] neg_hi:[0,1]
	v_mov_b32_e32 v11, v6
	v_pk_add_f32 v[6:7], v[12:13], v[10:11] neg_lo:[0,1] neg_hi:[0,1]
	s_nop 0
	v_add_f32_e32 v7, v15, v7
	v_add_f32_e32 v6, v6, v7
	v_add_f32_e32 v7, v19, v18
	v_add_f32_e32 v6, v9, v6
	v_sub_f32_e32 v8, v7, v19
	v_mul_f32_e32 v6, v17, v6
	v_sub_f32_e32 v8, v18, v8
	v_add_f32_e32 v8, v8, v6
	v_add_f32_e32 v10, v7, v8
	v_mul_f32_e32 v11, v10, v10
	v_fmamk_f32 v6, v11, 0x3e9b6dac, v236
	v_fmaak_f32 v205, v11, v6, 0x3f2aaada
	v_cvt_f32_i32_e32 v6, v14
	v_sub_f32_e32 v7, v10, v7
	v_sub_f32_e32 v7, v8, v7
	v_ldexp_f32 v12, v7, 1
	v_mul_f32_e32 v7, v10, v11
	v_ldexp_f32 v9, v10, 1
	v_pk_mul_f32 v[10:11], v[6:7], v[204:205]
	s_nop 0
	v_fma_f32 v8, v6, s8, -v10
	v_fmac_f32_e32 v8, 0xb102e308, v6
	v_pk_add_f32 v[6:7], v[10:11], v[8:9]
	s_mov_b32 s8, 0x7f800000
	v_sub_f32_e32 v9, v7, v9
	v_sub_f32_e32 v9, v11, v9
	v_add_f32_e32 v13, v12, v9
	v_mov_b32_e32 v12, v10
	v_pk_add_f32 v[10:11], v[6:7], v[10:11] neg_lo:[0,1] neg_hi:[0,1]
	v_pk_add_f32 v[14:15], v[6:7], v[12:13]
	v_mov_b32_e32 v9, v6
	v_mov_b32_e32 v11, v15
	v_pk_add_f32 v[16:17], v[8:9], v[10:11] neg_lo:[0,1] neg_hi:[0,1]
	v_pk_add_f32 v[8:9], v[8:9], v[10:11]
	v_mov_b32_e32 v12, v13
	v_pk_add_f32 v[10:11], v[8:9], v[6:7] op_sel:[1,0] op_sel_hi:[0,1] neg_lo:[0,1] neg_hi:[0,1]
	v_pk_add_f32 v[18:19], v[14:15], v[10:11] op_sel_hi:[1,0] neg_lo:[0,1] neg_hi:[0,1]
	v_mov_b32_e32 v14, v15
	v_mov_b32_e32 v15, v9
	v_pk_mov_b32 v[10:11], v[6:7], v[10:11] op_sel:[1,0]
	v_mov_b32_e32 v13, v6
	v_pk_add_f32 v[10:11], v[14:15], v[10:11] neg_lo:[0,1] neg_hi:[0,1]
	v_mov_b32_e32 v18, v16
	v_pk_add_f32 v[6:7], v[12:13], v[10:11] neg_lo:[0,1] neg_hi:[0,1]
	v_mov_b32_e32 v17, v9
	v_pk_add_f32 v[10:11], v[18:19], v[6:7]
	v_cmp_neq_f32_e32 vcc, s8, v2
	v_pk_add_f32 v[12:13], v[10:11], v[10:11] op_sel:[0,1] op_sel_hi:[1,0]
	s_mov_b32 s8, 0x33800000
	v_pk_add_f32 v[8:9], v[8:9], v[12:13] op_sel:[1,0] op_sel_hi:[0,1]
	v_mov_b32_e32 v11, v8
	v_pk_add_f32 v[14:15], v[10:11], v[16:17] neg_lo:[0,1] neg_hi:[0,1]
	v_mov_b32_e32 v7, v12
	v_sub_f32_e32 v9, v10, v14
	v_pk_add_f32 v[6:7], v[6:7], v[14:15] neg_lo:[0,1] neg_hi:[0,1]
	v_sub_f32_e32 v9, v16, v9
	v_add_f32_e32 v6, v6, v9
	v_add_f32_e32 v6, v6, v7
	v_add_f32_e32 v6, v8, v6
	v_cndmask_b32_e32 v6, v237, v6, vcc
	v_cmp_ngt_f32_e32 vcc, -1.0, v2
	s_nop 1
	v_cndmask_b32_e32 v6, v238, v6, vcc
	v_cmp_neq_f32_e32 vcc, -1.0, v2
	s_nop 1
	v_cndmask_b32_e32 v6, v239, v6, vcc
	v_cmp_lt_f32_e64 vcc, |v2|, s8
	s_nop 1
	v_cndmask_b32_e32 v2, v6, v2, vcc
	v_sub_f32_e32 v2, v0, v2

.LBB0_1219:
	s_or_b64 exec, exec, s[4:5]
	v_lshlrev_b32_e32 v8, 2, v21
	v_lshlrev_b32_e32 v0, 2, v22
	v_ashrrev_i32_e32 v9, 31, v8
	v_lshl_add_u64 v[6:7], s[84:85], 0, v[0:1]
	v_lshlrev_b64 v[10:11], 13, v[8:9]
	v_lshl_add_u64 v[10:11], v[6:7], 0, v[10:11]
	v_readlane_b32 s4, v254, 26
	global_store_dword v[10:11], v2, off
	v_readlane_b32 s5, v254, 27
	s_nop 4
	s_load_dword s4, s[4:5], 0x4
	s_waitcnt lgkmcnt(0)
	v_mov_b32_e32 v0, s4
	v_add_f32_e32 v0, v3, v0
	v_cmp_nlt_f32_e32 vcc, 0, v0
	s_and_saveexec_b64 s[4:5], vcc
	s_xor_b64 s[4:5], exec, s[4:5]
	s_cbranch_execz .LBB0_1221
	v_mul_f32_e32 v2, 0x3fb8aa3b, v0
	v_exp_f32_e32 v9, v2
	s_mov_b32 s8, 0x3f2aaaab
	v_add_f32_e32 v10, 1.0, v9
	v_frexp_mant_f32_e32 v12, v10
	v_cvt_f64_f32_e32 v[2:3], v10
	v_frexp_exp_i32_f64_e32 v2, v[2:3]
	v_cmp_gt_f32_e32 vcc, s8, v12
	v_add_f32_e32 v11, -1.0, v10
	v_sub_f32_e32 v13, v11, v10
	v_subbrev_co_u32_e32 v16, vcc, 0, v2, vcc
	v_sub_u32_e32 v2, 0, v16
	v_sub_f32_e32 v11, v9, v11
	v_add_f32_e32 v13, 1.0, v13
	v_ldexp_f32 v3, v10, v2
	v_add_f32_e32 v11, v11, v13
	v_add_f32_e32 v10, -1.0, v3
	v_add_f32_e32 v12, 1.0, v3
	v_ldexp_f32 v2, v11, v2
	v_add_f32_e32 v11, 1.0, v10
	v_add_f32_e32 v13, -1.0, v12
	v_sub_f32_e32 v11, v3, v11
	v_sub_f32_e32 v3, v3, v13
	v_add_f32_e32 v11, v2, v11
	v_add_f32_e32 v2, v2, v3
	v_add_f32_e32 v17, v12, v2
	v_rcp_f32_e32 v19, v17
	v_sub_f32_e32 v3, v17, v12
	v_sub_f32_e32 v18, v2, v3
	v_add_f32_e32 v3, v10, v11
	v_mul_f32_e32 v21, v3, v19
	v_sub_f32_e32 v2, v3, v10
	v_mul_f32_e32 v10, v17, v21
	v_fma_f32 v12, v21, v17, -v10
	v_fmac_f32_e32 v12, v21, v18
	v_sub_f32_e32 v20, v11, v2
	v_add_f32_e32 v2, v10, v12
	v_sub_f32_e32 v11, v3, v2
	v_pk_add_f32 v[14:15], v[2:3], v[10:11] neg_lo:[0,1] neg_hi:[0,1]
	v_mov_b32_e32 v13, v2
	v_pk_add_f32 v[2:3], v[14:15], v[12:13] neg_lo:[0,1] neg_hi:[0,1]
	s_mov_b32 s8, 0x3f317218
	v_add_f32_e32 v3, v20, v3
	v_add_f32_e32 v2, v2, v3
	v_add_f32_e32 v3, v11, v2
	v_mul_f32_e32 v20, v19, v3
	v_mul_f32_e32 v10, v17, v20
	v_fma_f32 v12, v20, v17, -v10
	v_fmac_f32_e32 v12, v20, v18
	v_sub_f32_e32 v11, v11, v3
	v_add_f32_e32 v17, v2, v11
	v_add_f32_e32 v2, v10, v12
	v_sub_f32_e32 v11, v3, v2
	v_pk_add_f32 v[14:15], v[2:3], v[10:11] neg_lo:[0,1] neg_hi:[0,1]
	v_mov_b32_e32 v13, v2
	v_pk_add_f32 v[2:3], v[14:15], v[12:13] neg_lo:[0,1] neg_hi:[0,1]
	s_nop 0
	v_add_f32_e32 v3, v17, v3
	v_add_f32_e32 v2, v2, v3
	v_add_f32_e32 v3, v21, v20
	v_add_f32_e32 v2, v11, v2
	v_sub_f32_e32 v10, v3, v21
	v_mul_f32_e32 v2, v19, v2
	v_sub_f32_e32 v10, v20, v10
	v_add_f32_e32 v10, v10, v2
	v_add_f32_e32 v12, v3, v10
	v_mul_f32_e32 v13, v12, v12
	v_fmamk_f32 v2, v13, 0x3e9b6dac, v236
	v_fmaak_f32 v205, v13, v2, 0x3f2aaada
	v_cvt_f32_i32_e32 v2, v16
	v_sub_f32_e32 v3, v12, v3
	v_sub_f32_e32 v3, v10, v3
	v_ldexp_f32 v14, v3, 1
	v_mul_f32_e32 v3, v12, v13
	v_ldexp_f32 v11, v12, 1
	v_pk_mul_f32 v[12:13], v[2:3], v[204:205]
	s_nop 0
	v_fma_f32 v10, v2, s8, -v12
	v_fmac_f32_e32 v10, 0xb102e308, v2
	v_pk_add_f32 v[2:3], v[12:13], v[10:11]
	s_mov_b32 s8, 0x7f800000
	v_sub_f32_e32 v11, v3, v11
	v_sub_f32_e32 v11, v13, v11
	v_add_f32_e32 v15, v14, v11
	v_mov_b32_e32 v14, v12
	v_pk_add_f32 v[12:13], v[2:3], v[12:13] neg_lo:[0,1] neg_hi:[0,1]
	v_pk_add_f32 v[16:17], v[2:3], v[14:15]
	v_mov_b32_e32 v11, v2
	v_mov_b32_e32 v13, v17
	v_pk_add_f32 v[18:19], v[10:11], v[12:13] neg_lo:[0,1] neg_hi:[0,1]
	v_pk_add_f32 v[10:11], v[10:11], v[12:13]
	v_mov_b32_e32 v14, v15
	v_pk_add_f32 v[12:13], v[10:11], v[2:3] op_sel:[1,0] op_sel_hi:[0,1] neg_lo:[0,1] neg_hi:[0,1]
	v_pk_add_f32 v[20:21], v[16:17], v[12:13] op_sel_hi:[1,0] neg_lo:[0,1] neg_hi:[0,1]
	v_mov_b32_e32 v16, v17
	v_mov_b32_e32 v17, v11
	v_pk_mov_b32 v[12:13], v[2:3], v[12:13] op_sel:[1,0]
	v_mov_b32_e32 v15, v2
	v_pk_add_f32 v[12:13], v[16:17], v[12:13] neg_lo:[0,1] neg_hi:[0,1]
	v_mov_b32_e32 v20, v18
	v_pk_add_f32 v[2:3], v[14:15], v[12:13] neg_lo:[0,1] neg_hi:[0,1]
	v_mov_b32_e32 v19, v11
	v_pk_add_f32 v[12:13], v[20:21], v[2:3]
	v_cmp_neq_f32_e32 vcc, s8, v9
	v_pk_add_f32 v[14:15], v[12:13], v[12:13] op_sel:[0,1] op_sel_hi:[1,0]
	s_mov_b32 s8, 0x33800000
	v_pk_add_f32 v[10:11], v[10:11], v[14:15] op_sel:[1,0] op_sel_hi:[0,1]
	v_mov_b32_e32 v13, v10
	v_pk_add_f32 v[16:17], v[12:13], v[18:19] neg_lo:[0,1] neg_hi:[0,1]
	v_mov_b32_e32 v3, v14
	v_sub_f32_e32 v11, v12, v16
	v_pk_add_f32 v[2:3], v[2:3], v[16:17] neg_lo:[0,1] neg_hi:[0,1]
	v_sub_f32_e32 v11, v18, v11
	v_add_f32_e32 v2, v2, v11
	v_add_f32_e32 v2, v2, v3
	v_add_f32_e32 v2, v10, v2
	v_cndmask_b32_e32 v2, v237, v2, vcc
	v_cmp_ngt_f32_e32 vcc, -1.0, v9
	s_nop 1
	v_cndmask_b32_e32 v2, v238, v2, vcc
	v_cmp_neq_f32_e32 vcc, -1.0, v9
	s_nop 1
	v_cndmask_b32_e32 v2, v239, v2, vcc
	v_cmp_lt_f32_e64 vcc, |v9|, s8
	s_nop 1
	v_cndmask_b32_e32 v2, v2, v9, vcc
	v_sub_f32_e32 v2, v0, v2

.LBB0_1223:
	s_or_b64 exec, exec, s[4:5]
	v_or_b32_e32 v10, 1, v8
	v_ashrrev_i32_e32 v11, 31, v10
	v_lshlrev_b64 v[10:11], 13, v[10:11]
	v_lshl_add_u64 v[10:11], v[6:7], 0, v[10:11]
	v_readlane_b32 s4, v254, 26
	global_store_dword v[10:11], v2, off
	v_readlane_b32 s5, v254, 27
	s_nop 4
	s_load_dword s4, s[4:5], 0x8
	s_waitcnt lgkmcnt(0)
	v_mov_b32_e32 v0, s4
	v_add_f32_e32 v0, v4, v0
	v_cmp_nlt_f32_e32 vcc, 0, v0
	s_and_saveexec_b64 s[4:5], vcc
	s_xor_b64 s[4:5], exec, s[4:5]
	s_cbranch_execz .LBB0_1225
	v_mul_f32_e32 v2, 0x3fb8aa3b, v0
	v_exp_f32_e32 v4, v2
	s_mov_b32 s8, 0x3f2aaaab
	v_add_f32_e32 v9, 1.0, v4
	v_frexp_mant_f32_e32 v11, v9
	v_cvt_f64_f32_e32 v[2:3], v9
	v_frexp_exp_i32_f64_e32 v2, v[2:3]
	v_cmp_gt_f32_e32 vcc, s8, v11
	v_add_f32_e32 v10, -1.0, v9
	v_sub_f32_e32 v12, v10, v9
	v_subbrev_co_u32_e32 v16, vcc, 0, v2, vcc
	v_sub_u32_e32 v2, 0, v16
	v_sub_f32_e32 v10, v4, v10
	v_add_f32_e32 v12, 1.0, v12
	v_ldexp_f32 v3, v9, v2
	v_add_f32_e32 v10, v10, v12
	v_add_f32_e32 v9, -1.0, v3
	v_add_f32_e32 v11, 1.0, v3
	v_ldexp_f32 v2, v10, v2
	v_add_f32_e32 v10, 1.0, v9
	v_add_f32_e32 v12, -1.0, v11
	v_sub_f32_e32 v10, v3, v10
	v_sub_f32_e32 v3, v3, v12
	v_add_f32_e32 v10, v2, v10
	v_add_f32_e32 v2, v2, v3
	v_add_f32_e32 v17, v11, v2
	v_rcp_f32_e32 v19, v17
	v_sub_f32_e32 v3, v17, v11
	v_sub_f32_e32 v18, v2, v3
	v_add_f32_e32 v3, v9, v10
	v_sub_f32_e32 v2, v3, v9
	v_mul_f32_e32 v20, v3, v19
	v_sub_f32_e32 v9, v10, v2
	v_mul_f32_e32 v10, v17, v20
	v_fma_f32 v12, v20, v17, -v10
	v_fmac_f32_e32 v12, v20, v18
	v_add_f32_e32 v2, v10, v12
	v_sub_f32_e32 v11, v3, v2
	v_pk_add_f32 v[14:15], v[2:3], v[10:11] neg_lo:[0,1] neg_hi:[0,1]
	v_mov_b32_e32 v13, v2
	v_pk_add_f32 v[2:3], v[14:15], v[12:13] neg_lo:[0,1] neg_hi:[0,1]
	s_mov_b32 s8, 0x3f317218
	v_add_f32_e32 v3, v9, v3
	v_add_f32_e32 v2, v2, v3
	v_add_f32_e32 v3, v11, v2
	v_mul_f32_e32 v9, v19, v3
	v_mul_f32_e32 v10, v17, v9
	v_fma_f32 v12, v9, v17, -v10
	v_fmac_f32_e32 v12, v9, v18
	v_sub_f32_e32 v11, v11, v3
	v_add_f32_e32 v17, v2, v11
	v_add_f32_e32 v2, v10, v12
	v_sub_f32_e32 v11, v3, v2
	v_pk_add_f32 v[14:15], v[2:3], v[10:11] neg_lo:[0,1] neg_hi:[0,1]
	v_mov_b32_e32 v13, v2
	v_pk_add_f32 v[2:3], v[14:15], v[12:13] neg_lo:[0,1] neg_hi:[0,1]
	s_nop 0
	v_add_f32_e32 v3, v17, v3
	v_add_f32_e32 v2, v2, v3
	v_add_f32_e32 v3, v20, v9
	v_add_f32_e32 v2, v11, v2
	v_sub_f32_e32 v10, v3, v20
	v_mul_f32_e32 v2, v19, v2
	v_sub_f32_e32 v9, v9, v10
	v_add_f32_e32 v9, v9, v2
	v_add_f32_e32 v10, v3, v9
	v_mul_f32_e32 v12, v10, v10
	v_fmamk_f32 v2, v12, 0x3e9b6dac, v236
	v_fmaak_f32 v205, v12, v2, 0x3f2aaada
	v_cvt_f32_i32_e32 v2, v16
	v_sub_f32_e32 v3, v10, v3
	v_sub_f32_e32 v3, v9, v3
	v_ldexp_f32 v9, v3, 1
	v_mul_f32_e32 v3, v10, v12
	v_pk_mul_f32 v[12:13], v[2:3], v[204:205]
	v_ldexp_f32 v11, v10, 1
	v_fma_f32 v10, v2, s8, -v12
	v_fmac_f32_e32 v10, 0xb102e308, v2
	v_pk_add_f32 v[2:3], v[12:13], v[10:11]
	v_mov_b32_e32 v14, v12
	v_sub_f32_e32 v11, v3, v11
	v_sub_f32_e32 v11, v13, v11
	v_add_f32_e32 v15, v9, v11
	v_pk_add_f32 v[12:13], v[2:3], v[12:13] neg_lo:[0,1] neg_hi:[0,1]
	v_pk_add_f32 v[16:17], v[2:3], v[14:15]
	v_mov_b32_e32 v11, v2
	v_mov_b32_e32 v13, v17
	v_pk_add_f32 v[18:19], v[10:11], v[12:13] neg_lo:[0,1] neg_hi:[0,1]
	v_pk_add_f32 v[10:11], v[10:11], v[12:13]
	v_mov_b32_e32 v14, v15
	v_pk_add_f32 v[12:13], v[10:11], v[2:3] op_sel:[1,0] op_sel_hi:[0,1] neg_lo:[0,1] neg_hi:[0,1]
	v_pk_add_f32 v[20:21], v[16:17], v[12:13] op_sel_hi:[1,0] neg_lo:[0,1] neg_hi:[0,1]
	v_mov_b32_e32 v16, v17
	v_mov_b32_e32 v17, v11
	v_pk_mov_b32 v[12:13], v[2:3], v[12:13] op_sel:[1,0]
	v_mov_b32_e32 v15, v2
	v_pk_add_f32 v[12:13], v[16:17], v[12:13] neg_lo:[0,1] neg_hi:[0,1]
	v_mov_b32_e32 v20, v18
	v_pk_add_f32 v[2:3], v[14:15], v[12:13] neg_lo:[0,1] neg_hi:[0,1]
	v_mov_b32_e32 v19, v11
	v_pk_add_f32 v[12:13], v[20:21], v[2:3]
	s_mov_b32 s8, 0x7f800000
	v_pk_add_f32 v[14:15], v[12:13], v[12:13] op_sel:[0,1] op_sel_hi:[1,0]
	v_cmp_neq_f32_e32 vcc, s8, v4
	v_pk_add_f32 v[10:11], v[10:11], v[14:15] op_sel:[1,0] op_sel_hi:[0,1]
	v_mov_b32_e32 v13, v10
	v_pk_add_f32 v[16:17], v[12:13], v[18:19] neg_lo:[0,1] neg_hi:[0,1]
	v_mov_b32_e32 v3, v14
	v_sub_f32_e32 v9, v12, v16
	v_pk_add_f32 v[2:3], v[2:3], v[16:17] neg_lo:[0,1] neg_hi:[0,1]
	v_sub_f32_e32 v9, v18, v9
	v_add_f32_e32 v2, v2, v9
	v_add_f32_e32 v2, v2, v3
	v_add_f32_e32 v2, v10, v2
	v_cndmask_b32_e32 v2, v237, v2, vcc
	v_cmp_ngt_f32_e32 vcc, -1.0, v4
	s_mov_b32 s8, 0x33800000
	s_nop 0
	v_cndmask_b32_e32 v2, v238, v2, vcc
	v_cmp_neq_f32_e32 vcc, -1.0, v4
	s_nop 1
	v_cndmask_b32_e32 v2, v239, v2, vcc
	v_cmp_lt_f32_e64 vcc, |v4|, s8
	s_nop 1
	v_cndmask_b32_e32 v2, v2, v4, vcc
	v_sub_f32_e32 v2, v0, v2

.LBB0_1227:
	s_or_b64 exec, exec, s[4:5]
	v_or_b32_e32 v10, 2, v8
	v_ashrrev_i32_e32 v11, 31, v10
	v_lshlrev_b64 v[10:11], 13, v[10:11]
	v_lshl_add_u64 v[10:11], v[6:7], 0, v[10:11]
	v_readlane_b32 s4, v254, 26
	global_store_dword v[10:11], v2, off
	v_readlane_b32 s5, v254, 27
	s_nop 4
	s_load_dword s4, s[4:5], 0xc
	s_waitcnt lgkmcnt(0)
	v_mov_b32_e32 v0, s4
	v_add_f32_e32 v0, v5, v0
	v_cmp_nlt_f32_e32 vcc, 0, v0
	s_and_saveexec_b64 s[4:5], vcc
	s_xor_b64 s[4:5], exec, s[4:5]
	s_cbranch_execz .LBB0_1229
	v_mul_f32_e32 v2, 0x3fb8aa3b, v0
	v_exp_f32_e32 v9, v2
	s_mov_b32 s8, 0x3f2aaaab
	v_add_f32_e32 v4, 1.0, v9
	v_frexp_mant_f32_e32 v10, v4
	v_cvt_f64_f32_e32 v[2:3], v4
	v_frexp_exp_i32_f64_e32 v2, v[2:3]
	v_cmp_gt_f32_e32 vcc, s8, v10
	v_add_f32_e32 v5, -1.0, v4
	v_sub_f32_e32 v11, v5, v4
	v_subbrev_co_u32_e32 v14, vcc, 0, v2, vcc
	v_sub_u32_e32 v2, 0, v14
	v_sub_f32_e32 v5, v9, v5
	v_add_f32_e32 v11, 1.0, v11
	v_ldexp_f32 v3, v4, v2
	v_add_f32_e32 v5, v5, v11
	v_add_f32_e32 v4, -1.0, v3
	v_add_f32_e32 v10, 1.0, v3
	v_ldexp_f32 v2, v5, v2
	v_add_f32_e32 v5, 1.0, v4
	v_add_f32_e32 v11, -1.0, v10
	v_sub_f32_e32 v5, v3, v5
	v_sub_f32_e32 v3, v3, v11
	v_add_f32_e32 v5, v2, v5
	v_add_f32_e32 v2, v2, v3
	v_add_f32_e32 v15, v10, v2
	v_rcp_f32_e32 v17, v15
	v_sub_f32_e32 v3, v15, v10
	v_sub_f32_e32 v16, v2, v3
	v_add_f32_e32 v3, v4, v5
	v_mul_f32_e32 v19, v3, v17
	v_sub_f32_e32 v2, v3, v4
	v_mul_f32_e32 v4, v15, v19
	v_fma_f32 v10, v19, v15, -v4
	v_fmac_f32_e32 v10, v19, v16
	v_sub_f32_e32 v18, v5, v2
	v_add_f32_e32 v2, v4, v10
	v_sub_f32_e32 v5, v3, v2
	v_pk_add_f32 v[12:13], v[2:3], v[4:5] neg_lo:[0,1] neg_hi:[0,1]
	v_mov_b32_e32 v11, v2
	v_pk_add_f32 v[2:3], v[12:13], v[10:11] neg_lo:[0,1] neg_hi:[0,1]
	s_mov_b32 s8, 0x3f317218
	v_add_f32_e32 v3, v18, v3
	v_add_f32_e32 v2, v2, v3
	v_add_f32_e32 v3, v5, v2
	v_mul_f32_e32 v18, v17, v3
	v_mul_f32_e32 v4, v15, v18
	v_fma_f32 v10, v18, v15, -v4
	v_fmac_f32_e32 v10, v18, v16
	v_sub_f32_e32 v5, v5, v3
	v_add_f32_e32 v15, v2, v5
	v_add_f32_e32 v2, v4, v10
	v_sub_f32_e32 v5, v3, v2
	v_pk_add_f32 v[12:13], v[2:3], v[4:5] neg_lo:[0,1] neg_hi:[0,1]
	v_mov_b32_e32 v11, v2
	v_pk_add_f32 v[2:3], v[12:13], v[10:11] neg_lo:[0,1] neg_hi:[0,1]
	s_nop 0
	v_add_f32_e32 v3, v15, v3
	v_add_f32_e32 v2, v2, v3
	v_add_f32_e32 v3, v19, v18
	v_add_f32_e32 v2, v5, v2
	v_sub_f32_e32 v4, v3, v19
	v_mul_f32_e32 v2, v17, v2
	v_sub_f32_e32 v4, v18, v4
	v_add_f32_e32 v4, v4, v2
	v_add_f32_e32 v10, v3, v4
	v_mul_f32_e32 v11, v10, v10
	v_fmamk_f32 v2, v11, 0x3e9b6dac, v236
	v_fmaak_f32 v205, v11, v2, 0x3f2aaada
	v_cvt_f32_i32_e32 v2, v14
	v_sub_f32_e32 v3, v10, v3
	v_sub_f32_e32 v3, v4, v3
	v_ldexp_f32 v12, v3, 1
	v_mul_f32_e32 v3, v10, v11
	v_ldexp_f32 v5, v10, 1
	v_pk_mul_f32 v[10:11], v[2:3], v[204:205]
	s_nop 0
	v_fma_f32 v4, v2, s8, -v10
	v_fmac_f32_e32 v4, 0xb102e308, v2
	v_pk_add_f32 v[2:3], v[10:11], v[4:5]
	s_mov_b32 s8, 0x7f800000
	v_sub_f32_e32 v5, v3, v5
	v_sub_f32_e32 v5, v11, v5
	v_add_f32_e32 v13, v12, v5
	v_mov_b32_e32 v12, v10
	v_pk_add_f32 v[10:11], v[2:3], v[10:11] neg_lo:[0,1] neg_hi:[0,1]
	v_pk_add_f32 v[14:15], v[2:3], v[12:13]
	v_mov_b32_e32 v5, v2
	v_mov_b32_e32 v11, v15
	v_pk_add_f32 v[16:17], v[4:5], v[10:11] neg_lo:[0,1] neg_hi:[0,1]
	v_pk_add_f32 v[4:5], v[4:5], v[10:11]
	v_mov_b32_e32 v12, v13
	v_pk_add_f32 v[10:11], v[4:5], v[2:3] op_sel:[1,0] op_sel_hi:[0,1] neg_lo:[0,1] neg_hi:[0,1]
	v_pk_add_f32 v[18:19], v[14:15], v[10:11] op_sel_hi:[1,0] neg_lo:[0,1] neg_hi:[0,1]
	v_mov_b32_e32 v14, v15
	v_mov_b32_e32 v15, v5
	v_pk_mov_b32 v[10:11], v[2:3], v[10:11] op_sel:[1,0]
	v_mov_b32_e32 v13, v2
	v_pk_add_f32 v[10:11], v[14:15], v[10:11] neg_lo:[0,1] neg_hi:[0,1]
	v_mov_b32_e32 v18, v16
	v_pk_add_f32 v[2:3], v[12:13], v[10:11] neg_lo:[0,1] neg_hi:[0,1]
	v_mov_b32_e32 v17, v5
	v_pk_add_f32 v[10:11], v[18:19], v[2:3]
	v_cmp_neq_f32_e32 vcc, s8, v9
	v_pk_add_f32 v[12:13], v[10:11], v[10:11] op_sel:[0,1] op_sel_hi:[1,0]
	s_mov_b32 s8, 0x33800000
	v_pk_add_f32 v[4:5], v[4:5], v[12:13] op_sel:[1,0] op_sel_hi:[0,1]
	v_mov_b32_e32 v11, v4
	v_pk_add_f32 v[14:15], v[10:11], v[16:17] neg_lo:[0,1] neg_hi:[0,1]
	v_mov_b32_e32 v3, v12
	v_sub_f32_e32 v5, v10, v14
	v_pk_add_f32 v[2:3], v[2:3], v[14:15] neg_lo:[0,1] neg_hi:[0,1]
	v_sub_f32_e32 v5, v16, v5
	v_add_f32_e32 v2, v2, v5
	v_add_f32_e32 v2, v2, v3
	v_add_f32_e32 v2, v4, v2
	v_cndmask_b32_e32 v2, v237, v2, vcc
	v_cmp_ngt_f32_e32 vcc, -1.0, v9
	s_nop 1
	v_cndmask_b32_e32 v2, v238, v2, vcc
	v_cmp_neq_f32_e32 vcc, -1.0, v9
	s_nop 1
	v_cndmask_b32_e32 v2, v239, v2, vcc
	v_cmp_lt_f32_e64 vcc, |v9|, s8
	s_nop 1
	v_cndmask_b32_e32 v2, v2, v9, vcc
	v_sub_f32_e32 v2, v0, v2
